# GEMM K-loops: s_setprio 1 issued before the segment barrier and s_setprio 0 after the closing barrier, so no priority instruction sits between a barrier release and the MFMA segment
# speedup vs baseline: 1.0041x; 1.0041x over previous
; #define PG8_STAGE(bufoff, gbase, voff) do { _Pragma("unroll") for (int _i = 0; _i < 2; ++_i) \
;     __builtin_amdgcn_global_load_lds((const unsigned*)((const char*)(gbase) + (voff)[_i]), (PG8_LAS unsigned*)(lds + (bufoff) + ldsw + _i * 8192), 16, 0, 0); } while (0)
; #define PG8_LDA(dst, b, h) do { _Pragma("unroll") for (int m = 0; m < 4; ++m) _Pragma("unroll") for (int k = 0; k < 2; ++k) dst[m][k] = *(const PG8_LAS bf16x8*)(lds + PG8_SA(b, h) + aoff + m * 2048 + k * 1024); } while (0)
; #define PG8_LDB(dst, b, h) do { _Pragma("unroll") for (int n = 0; n < 2; ++n) _Pragma("unroll") for (int k = 0; k < 2; ++k) dst[n][k] = *(const PG8_LAS bf16x8*)(lds + PG8_SB(b, h) + boff + n * 2048 + k * 1024); } while (0)
; #define PG8_BAR __builtin_amdgcn_s_barrier()
; template <class Epi>
; DI void gemm_phase(PG8_LAS unsigned char* lds, const Gemm g, const StaticOrder& S, const Epi& E, const int wv) {
;     ...
;     for (int t = 0; t < nt; t += 2) {
;       const bool last = (t == nt - 2);
;       const char* a1 = cA + (size_t)(t + 1) * kstep;
;       const char* a2 = last ? nA : cA + (size_t)(t + 2) * kstep; const char* b2 = last ? nB : cB + (size_t)(t + 2) * kstep;
;       const char* a3 = a2 + kstep; const char* b3 = b2 + kstep;
;       PG8_LDB(B0, 0, 0); PG8_SCHED; PG8_LDA(At, 0, 0); PG8_STAGE(PG8_SA(1, 1), a1 + hstep, voffA);
;       PG8_WAIT_L(8); PG8_BAR; PG8_WAIT_L(0); PG8_MMA(0, 0, At, B0); PG8_BAR; PG8_SCHED;
;       PG8_LDB(B1, 0, 1); PG8_STAGE(PG8_SB(0, 0), b2, voffB);
;       PG8_BAR; PG8_WAIT_L(0); PG8_MMA(0, 1, At, B1); PG8_BAR;
;       PG8_LDA(At, 0, 1); PG8_STAGE(PG8_SA(0, 0), a2, voffA);
;       PG8_BAR; PG8_WAIT_L(0); PG8_MMA(1, 0, At, B0); PG8_BAR; PG8_SCHED;
;       PG8_STAGE(PG8_SB(0, 1), b2 + hstep, voffB);
;       PG8_WAIT_V(6); PG8_BAR; PG8_MMA(1, 1, At, B1); PG8_BAR;
;       PG8_LDB(B0, 1, 0); PG8_SCHED; PG8_LDA(At, 1, 0); PG8_STAGE(PG8_SA(0, 1), a2 + hstep, voffA);
;       PG8_WAIT_L(8); PG8_BAR; PG8_WAIT_L(0); PG8_MMA(0, 0, At, B0); PG8_BAR; PG8_SCHED;
;       PG8_LDB(B1, 1, 1); PG8_STAGE(PG8_SB(1, 0), b3, voffB);
;       PG8_BAR; PG8_WAIT_L(0); PG8_MMA(0, 1, At, B1); PG8_BAR;
;       PG8_LDA(At, 1, 1); PG8_STAGE(PG8_SA(1, 0), a3, voffA);
;       PG8_BAR; PG8_WAIT_L(0); PG8_MMA(1, 0, At, B0); PG8_BAR; PG8_SCHED;
;       PG8_STAGE(PG8_SB(1, 1), b3 + hstep, voffB);
;       PG8_WAIT_V(6); PG8_BAR; PG8_MMA(1, 1, At, B1); PG8_BAR;
.LBB0_89:
	ds_read_b128 v[128:131], v165
	ds_read_b128 v[148:151], v165 offset:1024
	ds_read_b128 v[152:155], v165 offset:2048
	ds_read_b128 v[156:159], v165 offset:3072
	s_add_u32 s8, s6, 0xfffc0080
	s_addc_u32 s9, s7, -1
	s_cmp_eq_u32 s49, 12
	s_cselect_b32 s43, s19, s9
	s_cselect_b32 s42, s44, s8
	s_cselect_b32 s9, s17, s47
	s_cselect_b32 s8, s45, s46
	v_lshl_add_u64 v[202:203], s[6:7], 0, v[142:143]
	s_add_i32 m0, s62, 0xc000
	ds_read_b128 v[170:173], v166
	ds_read_b128 v[174:177], v166 offset:1024
	ds_read_b128 v[178:181], v166 offset:2048
	ds_read_b128 v[182:185], v166 offset:3072
	ds_read_b128 v[186:189], v166 offset:4096
	ds_read_b128 v[190:193], v166 offset:5120
	ds_read_b128 v[194:197], v166 offset:6144
	ds_read_b128 v[198:201], v166 offset:7168
	global_load_lds_dwordx4 v[202:203], off
	v_lshl_add_u64 v[202:203], s[6:7], 0, v[144:145]
	s_add_i32 m0, s62, 0xe000
	s_nop 0
	global_load_lds_dwordx4 v[202:203], off
	s_waitcnt lgkmcnt(8)
	s_setprio 1
	s_barrier
	s_waitcnt lgkmcnt(0)
	s_waitcnt lgkmcnt(0)
	v_mfma_f32_16x16x32_bf16 v[124:127], v[128:131], v[170:173], v[124:127]
	v_mfma_f32_16x16x32_bf16 v[120:123], v[152:155], v[170:173], v[120:123]
	v_mfma_f32_16x16x32_bf16 v[108:111], v[128:131], v[178:181], v[108:111]
	v_mfma_f32_16x16x32_bf16 v[104:107], v[152:155], v[178:181], v[104:107]
	v_mfma_f32_16x16x32_bf16 v[92:95], v[128:131], v[186:189], v[92:95]
	v_mfma_f32_16x16x32_bf16 v[88:91], v[152:155], v[186:189], v[88:91]
	v_mfma_f32_16x16x32_bf16 v[76:79], v[128:131], v[194:197], v[76:79]
	v_mfma_f32_16x16x32_bf16 v[72:75], v[152:155], v[194:197], v[72:75]
	v_mfma_f32_16x16x32_bf16 v[124:127], v[148:151], v[174:177], v[124:127]
	v_mfma_f32_16x16x32_bf16 v[120:123], v[156:159], v[174:177], v[120:123]
	v_mfma_f32_16x16x32_bf16 v[108:111], v[148:151], v[182:185], v[108:111]
	v_mfma_f32_16x16x32_bf16 v[104:107], v[156:159], v[182:185], v[104:107]
	v_mfma_f32_16x16x32_bf16 v[92:95], v[148:151], v[190:193], v[92:95]
	v_mfma_f32_16x16x32_bf16 v[88:91], v[156:159], v[190:193], v[88:91]
	v_mfma_f32_16x16x32_bf16 v[76:79], v[148:151], v[198:201], v[76:79]
	v_mfma_f32_16x16x32_bf16 v[72:75], v[156:159], v[198:201], v[72:75]
	s_barrier
	s_setprio 0
	s_add_i32 s50, s73, s61
	v_lshl_add_u64 v[220:221], s[8:9], 0, v[134:135]
	s_mov_b32 m0, s50
	ds_read_b128 v[202:205], v167
	ds_read_b128 v[206:209], v167 offset:1024
	ds_read_b128 v[210:213], v167 offset:2048
	ds_read_b128 v[214:217], v167 offset:3072
	global_load_lds_dwordx4 v[220:221], off
	v_lshl_add_u64 v[222:223], s[8:9], 0, v[138:139]
	s_add_i32 m0, s50, 0x2000
	s_nop 0
	global_load_lds_dwordx4 v[222:223], off
	s_setprio 1
	s_barrier
	s_waitcnt lgkmcnt(0)
	v_mfma_f32_16x16x32_bf16 v[116:119], v[202:205], v[170:173], v[116:119]
	v_mfma_f32_16x16x32_bf16 v[112:115], v[210:213], v[170:173], v[112:115]
	v_mfma_f32_16x16x32_bf16 v[100:103], v[202:205], v[178:181], v[100:103]
	v_mfma_f32_16x16x32_bf16 v[96:99], v[210:213], v[178:181], v[96:99]
	v_mfma_f32_16x16x32_bf16 v[84:87], v[202:205], v[186:189], v[84:87]
	v_mfma_f32_16x16x32_bf16 v[80:83], v[210:213], v[186:189], v[80:83]
	v_mfma_f32_16x16x32_bf16 v[68:71], v[202:205], v[194:197], v[68:71]
	v_mfma_f32_16x16x32_bf16 v[64:67], v[210:213], v[194:197], v[64:67]
	v_mfma_f32_16x16x32_bf16 v[116:119], v[206:209], v[174:177], v[116:119]
	v_mfma_f32_16x16x32_bf16 v[112:115], v[214:217], v[174:177], v[112:115]
	v_mfma_f32_16x16x32_bf16 v[100:103], v[206:209], v[182:185], v[100:103]
	v_mfma_f32_16x16x32_bf16 v[96:99], v[214:217], v[182:185], v[96:99]
	v_mfma_f32_16x16x32_bf16 v[84:87], v[206:209], v[190:193], v[84:87]
	v_mfma_f32_16x16x32_bf16 v[80:83], v[214:217], v[190:193], v[80:83]
	v_mfma_f32_16x16x32_bf16 v[68:71], v[206:209], v[198:201], v[68:71]
	v_mfma_f32_16x16x32_bf16 v[64:67], v[214:217], v[198:201], v[64:67]
	s_mov_b32 m0, s62
	v_lshl_add_u64 v[224:225], s[42:43], 0, v[132:133]
	s_barrier
	s_setprio 0
	ds_read_b128 v[170:173], v166 offset:16384
	ds_read_b128 v[174:177], v166 offset:17408
	ds_read_b128 v[178:181], v166 offset:18432
	ds_read_b128 v[182:185], v166 offset:19456
	ds_read_b128 v[186:189], v166 offset:20480
	ds_read_b128 v[190:193], v166 offset:21504
	ds_read_b128 v[194:197], v166 offset:22528
	ds_read_b128 v[198:201], v166 offset:23552
	global_load_lds_dwordx4 v[224:225], off
	v_lshl_add_u64 v[226:227], s[42:43], 0, v[136:137]
	s_mov_b32 m0, s63
	s_nop 0
	global_load_lds_dwordx4 v[226:227], off
	s_setprio 1
	s_barrier
	s_waitcnt lgkmcnt(0)
	v_mfma_f32_16x16x32_bf16 v[60:63], v[128:131], v[170:173], v[60:63]
	v_mfma_f32_16x16x32_bf16 v[56:59], v[152:155], v[170:173], v[56:59]
	v_mfma_f32_16x16x32_bf16 v[44:47], v[128:131], v[178:181], v[44:47]
	v_mfma_f32_16x16x32_bf16 v[40:43], v[152:155], v[178:181], v[40:43]
	v_mfma_f32_16x16x32_bf16 v[28:31], v[128:131], v[186:189], v[28:31]
	v_mfma_f32_16x16x32_bf16 v[24:27], v[152:155], v[186:189], v[24:27]
	v_mfma_f32_16x16x32_bf16 v[12:15], v[128:131], v[194:197], v[12:15]
	v_mfma_f32_16x16x32_bf16 v[8:11], v[152:155], v[194:197], v[8:11]
	v_mfma_f32_16x16x32_bf16 v[60:63], v[148:151], v[174:177], v[60:63]
	v_mfma_f32_16x16x32_bf16 v[56:59], v[156:159], v[174:177], v[56:59]
	v_mfma_f32_16x16x32_bf16 v[44:47], v[148:151], v[182:185], v[44:47]
	v_mfma_f32_16x16x32_bf16 v[40:43], v[156:159], v[182:185], v[40:43]
	v_mfma_f32_16x16x32_bf16 v[28:31], v[148:151], v[190:193], v[28:31]
	v_mfma_f32_16x16x32_bf16 v[24:27], v[156:159], v[190:193], v[24:27]
	v_mfma_f32_16x16x32_bf16 v[12:15], v[148:151], v[198:201], v[12:15]
	v_mfma_f32_16x16x32_bf16 v[8:11], v[156:159], v[198:201], v[8:11]
	s_barrier
; #define PG8_STAGE(bufoff, gbase, voff) do { _Pragma("unroll") for (int _i = 0; _i < 2; ++_i) \
;     __builtin_amdgcn_global_load_lds((const unsigned*)((const char*)(gbase) + (voff)[_i]), (PG8_LAS unsigned*)(lds + (bufoff) + ldsw + _i * 8192), 16, 0, 0); } while (0)
; #define PG8_LDA(dst, b, h) do { _Pragma("unroll") for (int m = 0; m < 4; ++m) _Pragma("unroll") for (int k = 0; k < 2; ++k) dst[m][k] = *(const PG8_LAS bf16x8*)(lds + PG8_SA(b, h) + aoff + m * 2048 + k * 1024); } while (0)
; #define PG8_LDB(dst, b, h) do { _Pragma("unroll") for (int n = 0; n < 2; ++n) _Pragma("unroll") for (int k = 0; k < 2; ++k) dst[n][k] = *(const PG8_LAS bf16x8*)(lds + PG8_SB(b, h) + boff + n * 2048 + k * 1024); } while (0)
; #define PG8_MMA(ai, bj, At, Bt) do { __builtin_amdgcn_s_setprio(1); _Pragma("unroll") for (int m = 0; m < 4; ++m) _Pragma("unroll") for (int n = 0; n < 2; ++n) _Pragma("unroll") for (int k = 0; k < 2; ++k) \
;     acc[ai][bj][m][n] = __builtin_amdgcn_mfma_f32_16x16x32_bf16(Bt[n][k], At[m][k], acc[ai][bj][m][n], 0, 0, 0); __builtin_amdgcn_s_setprio(0); } while (0)
; #define PG8_WAIT_V(n) asm volatile("s_waitcnt vmcnt(" #n ")" ::: "memory")
; #define PG8_WAIT_L(n) asm volatile("s_waitcnt lgkmcnt(" #n ")" ::: "memory")
; #define PG8_BAR __builtin_amdgcn_s_barrier()
; #define PG8_SCHED __builtin_amdgcn_sched_barrier(0)
; template <class Epi>
; DI void gemm_phase(PG8_LAS unsigned char* lds, const Gemm g, const StaticOrder& S, const Epi& E, const int wv) {
;     ...
;       PG8_BAR; PG8_WAIT_L(0); PG8_MMA(0, 1, At, B1); PG8_BAR;
;       PG8_LDA(At, 0, 1); PG8_STAGE(PG8_SA(0, 0), a2, voffA);
;       PG8_BAR; PG8_WAIT_L(0); PG8_MMA(1, 0, At, B0); PG8_BAR; PG8_SCHED;
;       PG8_STAGE(PG8_SB(0, 1), b2 + hstep, voffB);
;       PG8_WAIT_V(6); PG8_BAR; PG8_MMA(1, 1, At, B1); PG8_BAR;
;       PG8_LDB(B0, 1, 0); PG8_SCHED; PG8_LDA(At, 1, 0); PG8_STAGE(PG8_SA(0, 1), a2 + hstep, voffA);
;       PG8_WAIT_L(8); PG8_BAR; PG8_WAIT_L(0); PG8_MMA(0, 0, At, B0); PG8_BAR; PG8_SCHED;
;       PG8_LDB(B1, 1, 1); PG8_STAGE(PG8_SB(1, 0), b3, voffB);
;       PG8_BAR; PG8_WAIT_L(0); PG8_MMA(0, 1, At, B1); PG8_BAR;
;       PG8_LDA(At, 1, 1); PG8_STAGE(PG8_SA(1, 0), a3, voffA);
;       PG8_BAR; PG8_WAIT_L(0); PG8_MMA(1, 0, At, B0); PG8_BAR; PG8_SCHED;
;       PG8_STAGE(PG8_SB(1, 1), b3 + hstep, voffB);
;       PG8_WAIT_V(6); PG8_BAR; PG8_MMA(1, 1, At, B1); PG8_BAR;
	s_setprio 0
	s_add_u32 s50, s8, 0x40000
	s_addc_u32 s51, s9, 0
	s_add_i32 s52, s74, s61
	v_lshl_add_u64 v[128:129], s[50:51], 0, v[134:135]
	s_mov_b32 m0, s52
	s_nop 0
	global_load_lds_dwordx4 v[128:129], off
	v_lshl_add_u64 v[128:129], s[50:51], 0, v[138:139]
	s_add_i32 m0, s52, 0x2000
	s_nop 0
	global_load_lds_dwordx4 v[128:129], off
	s_waitcnt vmcnt(6)
	s_setprio 1
	s_barrier
	v_mfma_f32_16x16x32_bf16 v[52:55], v[202:205], v[170:173], v[52:55]
	v_mfma_f32_16x16x32_bf16 v[48:51], v[210:213], v[170:173], v[48:51]
	v_mfma_f32_16x16x32_bf16 v[36:39], v[202:205], v[178:181], v[36:39]
	v_mfma_f32_16x16x32_bf16 v[32:35], v[210:213], v[178:181], v[32:35]
	v_mfma_f32_16x16x32_bf16 v[20:23], v[202:205], v[186:189], v[20:23]
	v_mfma_f32_16x16x32_bf16 v[16:19], v[210:213], v[186:189], v[16:19]
	v_mfma_f32_16x16x32_bf16 v[4:7], v[202:205], v[194:197], v[4:7]
	v_mfma_f32_16x16x32_bf16 v[0:3], v[210:213], v[194:197], v[0:3]
	v_mfma_f32_16x16x32_bf16 v[52:55], v[206:209], v[174:177], v[52:55]
	v_mfma_f32_16x16x32_bf16 v[48:51], v[214:217], v[174:177], v[48:51]
	v_mfma_f32_16x16x32_bf16 v[36:39], v[206:209], v[182:185], v[36:39]
	v_mfma_f32_16x16x32_bf16 v[32:35], v[214:217], v[182:185], v[32:35]
	v_mfma_f32_16x16x32_bf16 v[20:23], v[206:209], v[190:193], v[20:23]
	v_mfma_f32_16x16x32_bf16 v[16:19], v[214:217], v[190:193], v[16:19]
	v_mfma_f32_16x16x32_bf16 v[4:7], v[206:209], v[198:201], v[4:7]
	v_mfma_f32_16x16x32_bf16 v[0:3], v[214:217], v[198:201], v[0:3]
	s_add_i32 s50, 0, 0x18000
	v_add_u32_e32 v140, s50, v163
	s_barrier
	s_setprio 0
	ds_read_b128 v[128:131], v140
	ds_read_b128 v[148:151], v140 offset:1024
	ds_read_b128 v[152:155], v140 offset:2048
	ds_read_b128 v[156:159], v140 offset:3072
	s_add_u32 s42, s42, 0x40000
	s_addc_u32 s43, s43, 0
	s_mov_b32 m0, s64
	v_lshl_add_u64 v[202:203], s[42:43], 0, v[132:133]
	ds_read_b128 v[170:173], v166 offset:32768
	ds_read_b128 v[174:177], v166 offset:33792
	ds_read_b128 v[178:181], v166 offset:34816
	ds_read_b128 v[182:185], v166 offset:35840
	ds_read_b128 v[186:189], v166 offset:36864
	ds_read_b128 v[190:193], v166 offset:37888
	ds_read_b128 v[194:197], v166 offset:38912
	ds_read_b128 v[198:201], v166 offset:39936
	global_load_lds_dwordx4 v[202:203], off
	v_lshl_add_u64 v[202:203], s[42:43], 0, v[136:137]
	s_mov_b32 m0, s65
	s_nop 0
	global_load_lds_dwordx4 v[202:203], off
	s_waitcnt lgkmcnt(8)
	s_setprio 1
	s_barrier
	s_waitcnt lgkmcnt(0)
	s_waitcnt lgkmcnt(0)
	v_mfma_f32_16x16x32_bf16 v[124:127], v[128:131], v[170:173], v[124:127]
	v_mfma_f32_16x16x32_bf16 v[120:123], v[152:155], v[170:173], v[120:123]
	v_mfma_f32_16x16x32_bf16 v[108:111], v[128:131], v[178:181], v[108:111]
	v_mfma_f32_16x16x32_bf16 v[104:107], v[152:155], v[178:181], v[104:107]
	v_mfma_f32_16x16x32_bf16 v[92:95], v[128:131], v[186:189], v[92:95]
	v_mfma_f32_16x16x32_bf16 v[88:91], v[152:155], v[186:189], v[88:91]
	v_mfma_f32_16x16x32_bf16 v[76:79], v[128:131], v[194:197], v[76:79]
	v_mfma_f32_16x16x32_bf16 v[72:75], v[152:155], v[194:197], v[72:75]
	v_mfma_f32_16x16x32_bf16 v[124:127], v[148:151], v[174:177], v[124:127]
	v_mfma_f32_16x16x32_bf16 v[120:123], v[156:159], v[174:177], v[120:123]
	v_mfma_f32_16x16x32_bf16 v[108:111], v[148:151], v[182:185], v[108:111]
	v_mfma_f32_16x16x32_bf16 v[104:107], v[156:159], v[182:185], v[104:107]
	v_mfma_f32_16x16x32_bf16 v[92:95], v[148:151], v[190:193], v[92:95]
	v_mfma_f32_16x16x32_bf16 v[88:91], v[156:159], v[190:193], v[88:91]
	v_mfma_f32_16x16x32_bf16 v[76:79], v[148:151], v[198:201], v[76:79]
	v_mfma_f32_16x16x32_bf16 v[72:75], v[156:159], v[198:201], v[72:75]
	s_barrier
	s_setprio 0
	s_add_i32 s42, 0, 0x1c000
	s_add_i32 s43, s50, s61
	v_add_u32_e32 v140, s42, v163
	v_lshl_add_u64 v[220:221], v[220:221], 0, s[34:35]
	s_mov_b32 m0, s43
	ds_read_b128 v[202:205], v140
	ds_read_b128 v[206:209], v140 offset:1024
	ds_read_b128 v[210:213], v140 offset:2048
	ds_read_b128 v[214:217], v140 offset:3072
	global_load_lds_dwordx4 v[220:221], off
	v_lshl_add_u64 v[220:221], v[222:223], 0, s[34:35]
	s_add_i32 m0, s43, 0x2000
	s_nop 0
	global_load_lds_dwordx4 v[220:221], off
	s_setprio 1
	s_barrier
	s_waitcnt lgkmcnt(0)
	s_waitcnt lgkmcnt(0)
	v_mfma_f32_16x16x32_bf16 v[116:119], v[202:205], v[170:173], v[116:119]
	v_mfma_f32_16x16x32_bf16 v[112:115], v[210:213], v[170:173], v[112:115]
	v_mfma_f32_16x16x32_bf16 v[100:103], v[202:205], v[178:181], v[100:103]
	v_mfma_f32_16x16x32_bf16 v[96:99], v[210:213], v[178:181], v[96:99]
	v_mfma_f32_16x16x32_bf16 v[84:87], v[202:205], v[186:189], v[84:87]
	v_mfma_f32_16x16x32_bf16 v[80:83], v[210:213], v[186:189], v[80:83]
	v_mfma_f32_16x16x32_bf16 v[68:71], v[202:205], v[194:197], v[68:71]
	v_mfma_f32_16x16x32_bf16 v[64:67], v[210:213], v[194:197], v[64:67]
	v_mfma_f32_16x16x32_bf16 v[116:119], v[206:209], v[174:177], v[116:119]
	v_mfma_f32_16x16x32_bf16 v[112:115], v[214:217], v[174:177], v[112:115]
	v_mfma_f32_16x16x32_bf16 v[100:103], v[206:209], v[182:185], v[100:103]
	v_mfma_f32_16x16x32_bf16 v[96:99], v[214:217], v[182:185], v[96:99]
	v_mfma_f32_16x16x32_bf16 v[84:87], v[206:209], v[190:193], v[84:87]
	v_mfma_f32_16x16x32_bf16 v[80:83], v[214:217], v[190:193], v[80:83]
	v_mfma_f32_16x16x32_bf16 v[68:71], v[206:209], v[198:201], v[68:71]
	v_mfma_f32_16x16x32_bf16 v[64:67], v[214:217], v[198:201], v[64:67]
	s_mov_b32 m0, s68
	v_lshl_add_u64 v[220:221], v[224:225], 0, s[34:35]
	s_barrier
; #define PG8_STAGE(bufoff, gbase, voff) do { _Pragma("unroll") for (int _i = 0; _i < 2; ++_i) \
;     __builtin_amdgcn_global_load_lds((const unsigned*)((const char*)(gbase) + (voff)[_i]), (PG8_LAS unsigned*)(lds + (bufoff) + ldsw + _i * 8192), 16, 0, 0); } while (0)
; #define PG8_LDA(dst, b, h) do { _Pragma("unroll") for (int m = 0; m < 4; ++m) _Pragma("unroll") for (int k = 0; k < 2; ++k) dst[m][k] = *(const PG8_LAS bf16x8*)(lds + PG8_SA(b, h) + aoff + m * 2048 + k * 1024); } while (0)
; #define PG8_LDB(dst, b, h) do { _Pragma("unroll") for (int n = 0; n < 2; ++n) _Pragma("unroll") for (int k = 0; k < 2; ++k) dst[n][k] = *(const PG8_LAS bf16x8*)(lds + PG8_SB(b, h) + boff + n * 2048 + k * 1024); } while (0)
; #define PG8_MMA(ai, bj, At, Bt) do { __builtin_amdgcn_s_setprio(1); _Pragma("unroll") for (int m = 0; m < 4; ++m) _Pragma("unroll") for (int n = 0; n < 2; ++n) _Pragma("unroll") for (int k = 0; k < 2; ++k) \
;     acc[ai][bj][m][n] = __builtin_amdgcn_mfma_f32_16x16x32_bf16(Bt[n][k], At[m][k], acc[ai][bj][m][n], 0, 0, 0); __builtin_amdgcn_s_setprio(0); } while (0)
; #define PG8_WAIT_V(n) asm volatile("s_waitcnt vmcnt(" #n ")" ::: "memory")
; #define PG8_WAIT_L(n) asm volatile("s_waitcnt lgkmcnt(" #n ")" ::: "memory")
; template <class Epi>
; DI void gemm_phase(PG8_LAS unsigned char* lds, const Gemm g, const StaticOrder& S, const Epi& E, const int wv) {
;     ...
;       PG8_WAIT_V(6); PG8_BAR; PG8_MMA(1, 1, At, B1); PG8_BAR;
;       PG8_LDB(B0, 1, 0); PG8_SCHED; PG8_LDA(At, 1, 0); PG8_STAGE(PG8_SA(0, 1), a2 + hstep, voffA);
;       PG8_WAIT_L(8); PG8_BAR; PG8_WAIT_L(0); PG8_MMA(0, 0, At, B0); PG8_BAR; PG8_SCHED;
;       PG8_LDB(B1, 1, 1); PG8_STAGE(PG8_SB(1, 0), b3, voffB);
;       PG8_BAR; PG8_WAIT_L(0); PG8_MMA(0, 1, At, B1); PG8_BAR;
;       PG8_LDA(At, 1, 1); PG8_STAGE(PG8_SA(1, 0), a3, voffA);
;       PG8_BAR; PG8_WAIT_L(0); PG8_MMA(1, 0, At, B0); PG8_BAR; PG8_SCHED;
;       PG8_STAGE(PG8_SB(1, 1), b3 + hstep, voffB);
;       PG8_WAIT_V(6); PG8_BAR; PG8_MMA(1, 1, At, B1); PG8_BAR;
;     }
;     E(acc, cur, wr, wc, fr, fq);
;   DI void operator()(AccRef acc, const pg8::Unit& u, int wr, int wc, int fr, int fq) const {
;     ...
;         } else {
;           const int col0 = 1216 + (u.pn - 5) * 128 + wc * 32 + 8 * fq;
;           *(u32x4*)(rp + col0) = pack8v(acc[ai][0][m][0] * acc[ai][1][m][0], acc[ai][0][m][1] * acc[ai][1][m][1]);
;         }
	s_setprio 0
	ds_read_b128 v[170:173], v166 offset:49152
	ds_read_b128 v[174:177], v166 offset:50176
	ds_read_b128 v[178:181], v166 offset:51200
	ds_read_b128 v[182:185], v166 offset:52224
	ds_read_b128 v[186:189], v166 offset:53248
	ds_read_b128 v[190:193], v166 offset:54272
	ds_read_b128 v[194:197], v166 offset:55296
	ds_read_b128 v[198:201], v166 offset:56320
	global_load_lds_dwordx4 v[220:221], off
	v_lshl_add_u64 v[220:221], v[226:227], 0, s[34:35]
	s_mov_b32 m0, s69
	s_nop 0
	global_load_lds_dwordx4 v[220:221], off
	s_setprio 1
	s_barrier
	s_waitcnt lgkmcnt(0)
	v_mfma_f32_16x16x32_bf16 v[60:63], v[128:131], v[170:173], v[60:63]
	v_mfma_f32_16x16x32_bf16 v[56:59], v[152:155], v[170:173], v[56:59]
	v_mfma_f32_16x16x32_bf16 v[44:47], v[128:131], v[178:181], v[44:47]
	v_mfma_f32_16x16x32_bf16 v[40:43], v[152:155], v[178:181], v[40:43]
	v_mfma_f32_16x16x32_bf16 v[28:31], v[128:131], v[186:189], v[28:31]
	v_mfma_f32_16x16x32_bf16 v[24:27], v[152:155], v[186:189], v[24:27]
	v_mfma_f32_16x16x32_bf16 v[12:15], v[128:131], v[194:197], v[12:15]
	v_mfma_f32_16x16x32_bf16 v[8:11], v[152:155], v[194:197], v[8:11]
	v_mfma_f32_16x16x32_bf16 v[60:63], v[148:151], v[174:177], v[60:63]
	v_mfma_f32_16x16x32_bf16 v[56:59], v[156:159], v[174:177], v[56:59]
	v_mfma_f32_16x16x32_bf16 v[44:47], v[148:151], v[182:185], v[44:47]
	v_mfma_f32_16x16x32_bf16 v[40:43], v[156:159], v[182:185], v[40:43]
	v_mfma_f32_16x16x32_bf16 v[28:31], v[148:151], v[190:193], v[28:31]
	v_mfma_f32_16x16x32_bf16 v[24:27], v[156:159], v[190:193], v[24:27]
	v_mfma_f32_16x16x32_bf16 v[12:15], v[148:151], v[198:201], v[12:15]
	v_mfma_f32_16x16x32_bf16 v[8:11], v[156:159], v[198:201], v[8:11]
	s_barrier
	s_setprio 0
	s_add_u32 s8, s8, 0x40080
	s_addc_u32 s9, s9, 0
	s_add_i32 s42, s42, s61
	v_lshl_add_u64 v[128:129], s[8:9], 0, v[134:135]
	s_mov_b32 m0, s42
	s_nop 0
	global_load_lds_dwordx4 v[128:129], off
	v_lshl_add_u64 v[128:129], s[8:9], 0, v[138:139]
	s_add_i32 m0, s42, 0x2000
	s_nop 0
	global_load_lds_dwordx4 v[128:129], off
	s_waitcnt vmcnt(6)
	s_setprio 1
	s_barrier
	v_mfma_f32_16x16x32_bf16 v[52:55], v[202:205], v[170:173], v[52:55]
	v_mfma_f32_16x16x32_bf16 v[48:51], v[210:213], v[170:173], v[48:51]
	v_mfma_f32_16x16x32_bf16 v[36:39], v[202:205], v[178:181], v[36:39]
	v_mfma_f32_16x16x32_bf16 v[32:35], v[210:213], v[178:181], v[32:35]
	v_mfma_f32_16x16x32_bf16 v[20:23], v[202:205], v[186:189], v[20:23]
	v_mfma_f32_16x16x32_bf16 v[16:19], v[210:213], v[186:189], v[16:19]
	v_mfma_f32_16x16x32_bf16 v[4:7], v[202:205], v[194:197], v[4:7]
	v_mfma_f32_16x16x32_bf16 v[0:3], v[210:213], v[194:197], v[0:3]
	v_mfma_f32_16x16x32_bf16 v[52:55], v[206:209], v[174:177], v[52:55]
	v_mfma_f32_16x16x32_bf16 v[48:51], v[214:217], v[174:177], v[48:51]
	v_mfma_f32_16x16x32_bf16 v[36:39], v[206:209], v[182:185], v[36:39]
	v_mfma_f32_16x16x32_bf16 v[32:35], v[214:217], v[182:185], v[32:35]
	v_mfma_f32_16x16x32_bf16 v[20:23], v[206:209], v[190:193], v[20:23]
	v_mfma_f32_16x16x32_bf16 v[16:19], v[214:217], v[190:193], v[16:19]
	v_mfma_f32_16x16x32_bf16 v[4:7], v[206:209], v[198:201], v[4:7]
	v_mfma_f32_16x16x32_bf16 v[0:3], v[214:217], v[198:201], v[0:3]
	s_add_i32 s49, s49, 2
	s_add_u32 s6, s6, 0x100
	s_addc_u32 s7, s7, 0
	s_add_u32 s46, s46, 0x100
	s_addc_u32 s47, s47, 0
	s_cmp_gt_u32 s49, 13
	s_barrier
	s_setprio 0
	s_cbranch_scc0 .LBB0_89
	s_cmp_gt_i32 s48, 4
	s_cselect_b64 s[8:9], -1, 0
	s_lshl_b32 s19, s48, 8
	s_or_b32 s17, s19, s67
	s_cmp_lt_i32 s48, 3
	s_cselect_b64 s[46:47], -1, 0
	s_cmp_lg_u32 s48, 2
	s_cselect_b64 s[6:7], -1, 0
	s_and_b64 s[44:45], s[4:5], s[6:7]
	s_cmp_gt_i32 s48, 0
	s_cselect_b64 s[6:7], -1, 0
	s_and_b64 s[42:43], s[4:5], s[6:7]
	v_lshl_add_u32 v150, s81, 8, v161
	v_lshl_add_u32 v140, s48, 7, v164
	s_cmpk_gt_i32 s81, 0x181
	v_or_b32_e32 v148, s17, v162
	s_cbranch_scc1 .LBB0_239
	v_mov_b64_e32 v[128:129], s[20:21]
	v_mad_i64_i32 v[152:153], s[6:7], v150, s75, v[128:129]
	s_mov_b64 s[6:7], -1
	s_and_b64 vcc, exec, s[8:9]
	s_cbranch_vccz .LBB0_93
	v_pk_mul_f32 v[130:131], v[126:127], v[118:119]
	v_pk_mul_f32 v[128:129], v[124:125], v[116:117]
	v_pk_mul_f32 v[154:155], v[122:123], v[114:115]
	v_pk_mul_f32 v[156:157], v[120:121], v[112:113]
	v_cvt_pk_bf16_f32 v128, v128, v129
	v_cvt_pk_bf16_f32 v129, v130, v131
	v_cvt_pk_bf16_f32 v130, v156, v157
	v_cvt_pk_bf16_f32 v131, v154, v155
	v_lshl_add_u64 v[154:155], v[140:141], 1, v[152:153]
	global_store_dwordx4 v[154:155], v[128:131], off
	s_mov_b64 s[6:7], 0

; #define PG8_STAGE(bufoff, gbase, voff) do { _Pragma("unroll") for (int _i = 0; _i < 2; ++_i) \
;     __builtin_amdgcn_global_load_lds((const unsigned*)((const char*)(gbase) + (voff)[_i]), (PG8_LAS unsigned*)(lds + (bufoff) + ldsw + _i * 8192), 16, 0, 0); } while (0)
; #define PG8_LDA(dst, b, h) do { _Pragma("unroll") for (int m = 0; m < 4; ++m) _Pragma("unroll") for (int k = 0; k < 2; ++k) dst[m][k] = *(const PG8_LAS bf16x8*)(lds + PG8_SA(b, h) + aoff + m * 2048 + k * 1024); } while (0)
; #define PG8_LDB(dst, b, h) do { _Pragma("unroll") for (int n = 0; n < 2; ++n) _Pragma("unroll") for (int k = 0; k < 2; ++k) dst[n][k] = *(const PG8_LAS bf16x8*)(lds + PG8_SB(b, h) + boff + n * 2048 + k * 1024); } while (0)
; #define PG8_BAR __builtin_amdgcn_s_barrier()
; template <class Epi>
; DI void gemm_phase(PG8_LAS unsigned char* lds, const Gemm g, const StaticOrder& S, const Epi& E, const int wv) {
;     ...
;     for (int t = 0; t < nt; t += 2) {
;       const bool last = (t == nt - 2);
;       const char* a1 = cA + (size_t)(t + 1) * kstep;
;       const char* a2 = last ? nA : cA + (size_t)(t + 2) * kstep; const char* b2 = last ? nB : cB + (size_t)(t + 2) * kstep;
;       const char* a3 = a2 + kstep; const char* b3 = b2 + kstep;
;       PG8_LDB(B0, 0, 0); PG8_SCHED; PG8_LDA(At, 0, 0); PG8_STAGE(PG8_SA(1, 1), a1 + hstep, voffA);
;       PG8_WAIT_L(8); PG8_BAR; PG8_WAIT_L(0); PG8_MMA(0, 0, At, B0); PG8_BAR; PG8_SCHED;
;       PG8_LDB(B1, 0, 1); PG8_STAGE(PG8_SB(0, 0), b2, voffB);
;       PG8_BAR; PG8_WAIT_L(0); PG8_MMA(0, 1, At, B1); PG8_BAR;
;       PG8_LDA(At, 0, 1); PG8_STAGE(PG8_SA(0, 0), a2, voffA);
;       PG8_BAR; PG8_WAIT_L(0); PG8_MMA(1, 0, At, B0); PG8_BAR; PG8_SCHED;
;       PG8_STAGE(PG8_SB(0, 1), b2 + hstep, voffB);
;       PG8_WAIT_V(6); PG8_BAR; PG8_MMA(1, 1, At, B1); PG8_BAR;
;       PG8_LDB(B0, 1, 0); PG8_SCHED; PG8_LDA(At, 1, 0); PG8_STAGE(PG8_SA(0, 1), a2 + hstep, voffA);
;       PG8_WAIT_L(8); PG8_BAR; PG8_WAIT_L(0); PG8_MMA(0, 0, At, B0); PG8_BAR; PG8_SCHED;
;       PG8_LDB(B1, 1, 1); PG8_STAGE(PG8_SB(1, 0), b3, voffB);
;       PG8_BAR; PG8_WAIT_L(0); PG8_MMA(0, 1, At, B1); PG8_BAR;
;       PG8_LDA(At, 1, 1); PG8_STAGE(PG8_SA(1, 0), a3, voffA);
;       PG8_BAR; PG8_WAIT_L(0); PG8_MMA(1, 0, At, B0); PG8_BAR; PG8_SCHED;
;       PG8_STAGE(PG8_SB(1, 1), b3 + hstep, voffB);
;       PG8_WAIT_V(6); PG8_BAR; PG8_MMA(1, 1, At, B1); PG8_BAR;
.LBB0_521:
	ds_read_b128 v[142:145], v149
	ds_read_b128 v[154:157], v149 offset:1024
	ds_read_b128 v[162:165], v149 offset:2048
	ds_read_b128 v[166:169], v149 offset:3072
	s_add_u32 s4, s6, 0x100
	s_addc_u32 s5, s7, 0
	s_cmp_eq_u32 s58, 2
	s_cselect_b32 s27, s23, s5
	s_cselect_b32 s26, s22, s4
	s_cselect_b32 s9, s25, s57
	s_cselect_b32 s8, s24, s55
	v_lshl_add_u64 v[158:159], s[6:7], 0, v[136:137]
	s_add_i32 m0, s38, 0xc000
	ds_read_b128 v[170:173], v150
	ds_read_b128 v[174:177], v150 offset:1024
	ds_read_b128 v[178:181], v150 offset:2048
	ds_read_b128 v[182:185], v150 offset:3072
	ds_read_b128 v[186:189], v150 offset:4096
	ds_read_b128 v[190:193], v150 offset:5120
	ds_read_b128 v[194:197], v150 offset:6144
	ds_read_b128 v[198:201], v150 offset:7168
	global_load_lds_dwordx4 v[158:159], off
	v_lshl_add_u64 v[158:159], s[6:7], 0, v[138:139]
	s_add_i32 m0, s38, 0xe000
	s_nop 0
	global_load_lds_dwordx4 v[158:159], off
	s_waitcnt lgkmcnt(8)
	s_setprio 1
	s_barrier
	s_waitcnt lgkmcnt(0)
	s_waitcnt lgkmcnt(0)
	v_mfma_f32_16x16x32_bf16 v[124:127], v[142:145], v[170:173], v[124:127]
	v_mfma_f32_16x16x32_bf16 v[120:123], v[162:165], v[170:173], v[120:123]
	v_mfma_f32_16x16x32_bf16 v[116:119], v[142:145], v[178:181], v[116:119]
	v_mfma_f32_16x16x32_bf16 v[112:115], v[162:165], v[178:181], v[112:115]
	v_mfma_f32_16x16x32_bf16 v[100:103], v[142:145], v[186:189], v[100:103]
	v_mfma_f32_16x16x32_bf16 v[96:99], v[162:165], v[186:189], v[96:99]
	v_mfma_f32_16x16x32_bf16 v[84:87], v[142:145], v[194:197], v[84:87]
	v_mfma_f32_16x16x32_bf16 v[76:79], v[162:165], v[194:197], v[76:79]
	v_mfma_f32_16x16x32_bf16 v[124:127], v[154:157], v[174:177], v[124:127]
	v_mfma_f32_16x16x32_bf16 v[120:123], v[166:169], v[174:177], v[120:123]
	v_mfma_f32_16x16x32_bf16 v[116:119], v[154:157], v[182:185], v[116:119]
	v_mfma_f32_16x16x32_bf16 v[112:115], v[166:169], v[182:185], v[112:115]
	v_mfma_f32_16x16x32_bf16 v[100:103], v[154:157], v[190:193], v[100:103]
	v_mfma_f32_16x16x32_bf16 v[96:99], v[166:169], v[190:193], v[96:99]
	v_mfma_f32_16x16x32_bf16 v[84:87], v[154:157], v[198:201], v[84:87]
	v_mfma_f32_16x16x32_bf16 v[76:79], v[166:169], v[198:201], v[76:79]
	s_barrier
	s_setprio 0
	s_add_i32 s6, s47, s37
	v_lshl_add_u64 v[158:159], s[8:9], 0, v[130:131]
	s_mov_b32 m0, s6
	ds_read_b128 v[202:205], v151
	ds_read_b128 v[206:209], v151 offset:1024
	ds_read_b128 v[210:213], v151 offset:2048
	ds_read_b128 v[214:217], v151 offset:3072
	global_load_lds_dwordx4 v[158:159], off
	v_lshl_add_u64 v[220:221], s[8:9], 0, v[134:135]
	s_add_i32 m0, s6, 0x2000
	s_nop 0
	global_load_lds_dwordx4 v[220:221], off
	s_setprio 1
	s_barrier
	s_waitcnt lgkmcnt(0)
	v_mfma_f32_16x16x32_bf16 v[108:111], v[202:205], v[170:173], v[108:111]
	v_mfma_f32_16x16x32_bf16 v[104:107], v[210:213], v[170:173], v[104:107]
	v_mfma_f32_16x16x32_bf16 v[92:95], v[202:205], v[178:181], v[92:95]
	v_mfma_f32_16x16x32_bf16 v[88:91], v[210:213], v[178:181], v[88:91]
	v_mfma_f32_16x16x32_bf16 v[80:83], v[202:205], v[186:189], v[80:83]
	v_mfma_f32_16x16x32_bf16 v[72:75], v[210:213], v[186:189], v[72:75]
	v_mfma_f32_16x16x32_bf16 v[68:71], v[202:205], v[194:197], v[68:71]
	v_mfma_f32_16x16x32_bf16 v[64:67], v[210:213], v[194:197], v[64:67]
	v_mfma_f32_16x16x32_bf16 v[108:111], v[206:209], v[174:177], v[108:111]
	v_mfma_f32_16x16x32_bf16 v[104:107], v[214:217], v[174:177], v[104:107]
	v_mfma_f32_16x16x32_bf16 v[92:95], v[206:209], v[182:185], v[92:95]
	v_mfma_f32_16x16x32_bf16 v[88:91], v[214:217], v[182:185], v[88:91]
	v_mfma_f32_16x16x32_bf16 v[80:83], v[206:209], v[190:193], v[80:83]
	v_mfma_f32_16x16x32_bf16 v[72:75], v[214:217], v[190:193], v[72:75]
	v_mfma_f32_16x16x32_bf16 v[68:71], v[206:209], v[198:201], v[68:71]
	v_mfma_f32_16x16x32_bf16 v[64:67], v[214:217], v[198:201], v[64:67]
	s_mov_b32 m0, s38
	v_lshl_add_u64 v[222:223], s[26:27], 0, v[128:129]
	s_barrier
	s_setprio 0
	ds_read_b128 v[170:173], v150 offset:16384
	ds_read_b128 v[174:177], v150 offset:17408
	ds_read_b128 v[178:181], v150 offset:18432
	ds_read_b128 v[182:185], v150 offset:19456
	ds_read_b128 v[186:189], v150 offset:20480
	ds_read_b128 v[190:193], v150 offset:21504
	ds_read_b128 v[194:197], v150 offset:22528
	ds_read_b128 v[198:201], v150 offset:23552
	global_load_lds_dwordx4 v[222:223], off
	v_lshl_add_u64 v[224:225], s[26:27], 0, v[132:133]
	s_mov_b32 m0, s39
	s_nop 0
	global_load_lds_dwordx4 v[224:225], off
	s_setprio 1
	s_barrier
	s_waitcnt lgkmcnt(0)
	v_mfma_f32_16x16x32_bf16 v[60:63], v[142:145], v[170:173], v[60:63]
	v_mfma_f32_16x16x32_bf16 v[56:59], v[162:165], v[170:173], v[56:59]
	v_mfma_f32_16x16x32_bf16 v[52:55], v[142:145], v[178:181], v[52:55]
	v_mfma_f32_16x16x32_bf16 v[48:51], v[162:165], v[178:181], v[48:51]
	v_mfma_f32_16x16x32_bf16 v[44:47], v[142:145], v[186:189], v[44:47]
	v_mfma_f32_16x16x32_bf16 v[32:35], v[162:165], v[186:189], v[32:35]
	v_mfma_f32_16x16x32_bf16 v[20:23], v[142:145], v[194:197], v[20:23]
	v_mfma_f32_16x16x32_bf16 v[12:15], v[162:165], v[194:197], v[12:15]
	v_mfma_f32_16x16x32_bf16 v[60:63], v[154:157], v[174:177], v[60:63]
	v_mfma_f32_16x16x32_bf16 v[56:59], v[166:169], v[174:177], v[56:59]
	v_mfma_f32_16x16x32_bf16 v[52:55], v[154:157], v[182:185], v[52:55]
	v_mfma_f32_16x16x32_bf16 v[48:51], v[166:169], v[182:185], v[48:51]
	v_mfma_f32_16x16x32_bf16 v[44:47], v[154:157], v[190:193], v[44:47]
	v_mfma_f32_16x16x32_bf16 v[32:35], v[166:169], v[190:193], v[32:35]
	v_mfma_f32_16x16x32_bf16 v[20:23], v[154:157], v[198:201], v[20:23]
	v_mfma_f32_16x16x32_bf16 v[12:15], v[166:169], v[198:201], v[12:15]
	s_barrier
; #define PG8_STAGE(bufoff, gbase, voff) do { _Pragma("unroll") for (int _i = 0; _i < 2; ++_i) \
;     __builtin_amdgcn_global_load_lds((const unsigned*)((const char*)(gbase) + (voff)[_i]), (PG8_LAS unsigned*)(lds + (bufoff) + ldsw + _i * 8192), 16, 0, 0); } while (0)
; #define PG8_LDA(dst, b, h) do { _Pragma("unroll") for (int m = 0; m < 4; ++m) _Pragma("unroll") for (int k = 0; k < 2; ++k) dst[m][k] = *(const PG8_LAS bf16x8*)(lds + PG8_SA(b, h) + aoff + m * 2048 + k * 1024); } while (0)
; #define PG8_LDB(dst, b, h) do { _Pragma("unroll") for (int n = 0; n < 2; ++n) _Pragma("unroll") for (int k = 0; k < 2; ++k) dst[n][k] = *(const PG8_LAS bf16x8*)(lds + PG8_SB(b, h) + boff + n * 2048 + k * 1024); } while (0)
; #define PG8_MMA(ai, bj, At, Bt) do { __builtin_amdgcn_s_setprio(1); _Pragma("unroll") for (int m = 0; m < 4; ++m) _Pragma("unroll") for (int n = 0; n < 2; ++n) _Pragma("unroll") for (int k = 0; k < 2; ++k) \
;     acc[ai][bj][m][n] = __builtin_amdgcn_mfma_f32_16x16x32_bf16(Bt[n][k], At[m][k], acc[ai][bj][m][n], 0, 0, 0); __builtin_amdgcn_s_setprio(0); } while (0)
; #define PG8_WAIT_V(n) asm volatile("s_waitcnt vmcnt(" #n ")" ::: "memory")
; #define PG8_WAIT_L(n) asm volatile("s_waitcnt lgkmcnt(" #n ")" ::: "memory")
; #define PG8_BAR __builtin_amdgcn_s_barrier()
; #define PG8_SCHED __builtin_amdgcn_sched_barrier(0)
; template <class Epi>
; DI void gemm_phase(PG8_LAS unsigned char* lds, const Gemm g, const StaticOrder& S, const Epi& E, const int wv) {
;     ...
;       PG8_BAR; PG8_WAIT_L(0); PG8_MMA(0, 1, At, B1); PG8_BAR;
;       PG8_LDA(At, 0, 1); PG8_STAGE(PG8_SA(0, 0), a2, voffA);
;       PG8_BAR; PG8_WAIT_L(0); PG8_MMA(1, 0, At, B0); PG8_BAR; PG8_SCHED;
;       PG8_STAGE(PG8_SB(0, 1), b2 + hstep, voffB);
;       PG8_WAIT_V(6); PG8_BAR; PG8_MMA(1, 1, At, B1); PG8_BAR;
;       PG8_LDB(B0, 1, 0); PG8_SCHED; PG8_LDA(At, 1, 0); PG8_STAGE(PG8_SA(0, 1), a2 + hstep, voffA);
;       PG8_WAIT_L(8); PG8_BAR; PG8_WAIT_L(0); PG8_MMA(0, 0, At, B0); PG8_BAR; PG8_SCHED;
;       PG8_LDB(B1, 1, 1); PG8_STAGE(PG8_SB(1, 0), b3, voffB);
;       PG8_BAR; PG8_WAIT_L(0); PG8_MMA(0, 1, At, B1); PG8_BAR;
;       PG8_LDA(At, 1, 1); PG8_STAGE(PG8_SA(1, 0), a3, voffA);
;       PG8_BAR; PG8_WAIT_L(0); PG8_MMA(1, 0, At, B0); PG8_BAR; PG8_SCHED;
;       PG8_STAGE(PG8_SB(1, 1), b3 + hstep, voffB);
;       PG8_WAIT_V(6); PG8_BAR; PG8_MMA(1, 1, At, B1); PG8_BAR;
	s_setprio 0
	s_add_u32 s6, s8, 0x18000
	s_addc_u32 s7, s9, 0
	s_add_i32 s59, s48, s37
	v_lshl_add_u64 v[142:143], s[6:7], 0, v[130:131]
	s_mov_b32 m0, s59
	s_nop 0
	global_load_lds_dwordx4 v[142:143], off
	v_lshl_add_u64 v[142:143], s[6:7], 0, v[134:135]
	s_add_i32 m0, s59, 0x2000
	s_nop 0
	global_load_lds_dwordx4 v[142:143], off
	s_waitcnt vmcnt(6)
	s_setprio 1
	s_barrier
	v_mfma_f32_16x16x32_bf16 v[40:43], v[202:205], v[170:173], v[40:43]
	v_mfma_f32_16x16x32_bf16 v[36:39], v[210:213], v[170:173], v[36:39]
	v_mfma_f32_16x16x32_bf16 v[28:31], v[202:205], v[178:181], v[28:31]
	v_mfma_f32_16x16x32_bf16 v[24:27], v[210:213], v[178:181], v[24:27]
	v_mfma_f32_16x16x32_bf16 v[16:19], v[202:205], v[186:189], v[16:19]
	v_mfma_f32_16x16x32_bf16 v[8:11], v[210:213], v[186:189], v[8:11]
	v_mfma_f32_16x16x32_bf16 v[4:7], v[202:205], v[194:197], v[4:7]
	v_mfma_f32_16x16x32_bf16 v[0:3], v[210:213], v[194:197], v[0:3]
	v_mfma_f32_16x16x32_bf16 v[40:43], v[206:209], v[174:177], v[40:43]
	v_mfma_f32_16x16x32_bf16 v[36:39], v[214:217], v[174:177], v[36:39]
	v_mfma_f32_16x16x32_bf16 v[28:31], v[206:209], v[182:185], v[28:31]
	v_mfma_f32_16x16x32_bf16 v[24:27], v[214:217], v[182:185], v[24:27]
	v_mfma_f32_16x16x32_bf16 v[16:19], v[206:209], v[190:193], v[16:19]
	v_mfma_f32_16x16x32_bf16 v[8:11], v[214:217], v[190:193], v[8:11]
	v_mfma_f32_16x16x32_bf16 v[4:7], v[206:209], v[198:201], v[4:7]
	v_mfma_f32_16x16x32_bf16 v[0:3], v[214:217], v[198:201], v[0:3]
	s_add_i32 s59, 0, 0x18000
	v_add_u32_e32 v153, s59, v147
	s_barrier
	s_setprio 0
	ds_read_b128 v[142:145], v153
	ds_read_b128 v[154:157], v153 offset:1024
	ds_read_b128 v[162:165], v153 offset:2048
	ds_read_b128 v[166:169], v153 offset:3072
	s_add_u32 s6, s26, 0x18000
	s_addc_u32 s7, s27, 0
	s_mov_b32 m0, s40
	v_lshl_add_u64 v[202:203], s[6:7], 0, v[128:129]
	ds_read_b128 v[170:173], v150 offset:32768
	ds_read_b128 v[174:177], v150 offset:33792
	ds_read_b128 v[178:181], v150 offset:34816
	ds_read_b128 v[182:185], v150 offset:35840
	ds_read_b128 v[186:189], v150 offset:36864
	ds_read_b128 v[190:193], v150 offset:37888
	ds_read_b128 v[194:197], v150 offset:38912
	ds_read_b128 v[198:201], v150 offset:39936
	global_load_lds_dwordx4 v[202:203], off
	v_lshl_add_u64 v[202:203], s[6:7], 0, v[132:133]
	s_mov_b32 m0, s41
	s_nop 0
	global_load_lds_dwordx4 v[202:203], off
	s_waitcnt lgkmcnt(8)
	s_setprio 1
	s_barrier
	s_waitcnt lgkmcnt(0)
	s_waitcnt lgkmcnt(0)
	v_mfma_f32_16x16x32_bf16 v[124:127], v[142:145], v[170:173], v[124:127]
	v_mfma_f32_16x16x32_bf16 v[120:123], v[162:165], v[170:173], v[120:123]
	v_mfma_f32_16x16x32_bf16 v[116:119], v[142:145], v[178:181], v[116:119]
	v_mfma_f32_16x16x32_bf16 v[112:115], v[162:165], v[178:181], v[112:115]
	v_mfma_f32_16x16x32_bf16 v[100:103], v[142:145], v[186:189], v[100:103]
	v_mfma_f32_16x16x32_bf16 v[96:99], v[162:165], v[186:189], v[96:99]
	v_mfma_f32_16x16x32_bf16 v[84:87], v[142:145], v[194:197], v[84:87]
	v_mfma_f32_16x16x32_bf16 v[76:79], v[162:165], v[194:197], v[76:79]
	v_mfma_f32_16x16x32_bf16 v[124:127], v[154:157], v[174:177], v[124:127]
	v_mfma_f32_16x16x32_bf16 v[120:123], v[166:169], v[174:177], v[120:123]
	v_mfma_f32_16x16x32_bf16 v[116:119], v[154:157], v[182:185], v[116:119]
	v_mfma_f32_16x16x32_bf16 v[112:115], v[166:169], v[182:185], v[112:115]
	v_mfma_f32_16x16x32_bf16 v[100:103], v[154:157], v[190:193], v[100:103]
	v_mfma_f32_16x16x32_bf16 v[96:99], v[166:169], v[190:193], v[96:99]
	v_mfma_f32_16x16x32_bf16 v[84:87], v[154:157], v[198:201], v[84:87]
	v_mfma_f32_16x16x32_bf16 v[76:79], v[166:169], v[198:201], v[76:79]
	s_barrier
	s_setprio 0
	s_add_i32 s26, 0, 0x1c000
	s_add_i32 s6, s59, s37
	v_add_u32_e32 v153, s26, v147
	v_lshl_add_u64 v[158:159], v[158:159], 0, s[18:19]
	s_mov_b32 m0, s6
	ds_read_b128 v[202:205], v153
	ds_read_b128 v[206:209], v153 offset:1024
	ds_read_b128 v[210:213], v153 offset:2048
	ds_read_b128 v[214:217], v153 offset:3072
	global_load_lds_dwordx4 v[158:159], off
	v_lshl_add_u64 v[158:159], v[220:221], 0, s[18:19]
	s_add_i32 m0, s6, 0x2000
	s_nop 0
	global_load_lds_dwordx4 v[158:159], off
	s_setprio 1
	s_barrier
	s_waitcnt lgkmcnt(0)
	s_waitcnt lgkmcnt(0)
	v_mfma_f32_16x16x32_bf16 v[108:111], v[202:205], v[170:173], v[108:111]
	v_mfma_f32_16x16x32_bf16 v[104:107], v[210:213], v[170:173], v[104:107]
	v_mfma_f32_16x16x32_bf16 v[92:95], v[202:205], v[178:181], v[92:95]
	v_mfma_f32_16x16x32_bf16 v[88:91], v[210:213], v[178:181], v[88:91]
	v_mfma_f32_16x16x32_bf16 v[80:83], v[202:205], v[186:189], v[80:83]
	v_mfma_f32_16x16x32_bf16 v[72:75], v[210:213], v[186:189], v[72:75]
	v_mfma_f32_16x16x32_bf16 v[68:71], v[202:205], v[194:197], v[68:71]
	v_mfma_f32_16x16x32_bf16 v[64:67], v[210:213], v[194:197], v[64:67]
	v_mfma_f32_16x16x32_bf16 v[108:111], v[206:209], v[174:177], v[108:111]
	v_mfma_f32_16x16x32_bf16 v[104:107], v[214:217], v[174:177], v[104:107]
	v_mfma_f32_16x16x32_bf16 v[92:95], v[206:209], v[182:185], v[92:95]
	v_mfma_f32_16x16x32_bf16 v[88:91], v[214:217], v[182:185], v[88:91]
	v_mfma_f32_16x16x32_bf16 v[80:83], v[206:209], v[190:193], v[80:83]
	v_mfma_f32_16x16x32_bf16 v[72:75], v[214:217], v[190:193], v[72:75]
	v_mfma_f32_16x16x32_bf16 v[68:71], v[206:209], v[198:201], v[68:71]
	v_mfma_f32_16x16x32_bf16 v[64:67], v[214:217], v[198:201], v[64:67]
	s_mov_b32 m0, s43
	v_lshl_add_u64 v[158:159], v[222:223], 0, s[18:19]
	s_barrier
	s_setprio 0
	ds_read_b128 v[170:173], v150 offset:49152
	ds_read_b128 v[174:177], v150 offset:50176
	ds_read_b128 v[178:181], v150 offset:51200
	ds_read_b128 v[182:185], v150 offset:52224
	ds_read_b128 v[186:189], v150 offset:53248
	ds_read_b128 v[190:193], v150 offset:54272
	ds_read_b128 v[194:197], v150 offset:55296
	ds_read_b128 v[198:201], v150 offset:56320
	global_load_lds_dwordx4 v[158:159], off
	v_lshl_add_u64 v[158:159], v[224:225], 0, s[18:19]
	s_mov_b32 m0, s44
	s_nop 0
	global_load_lds_dwordx4 v[158:159], off
	s_setprio 1
	s_barrier
; #define PG8_STAGE(bufoff, gbase, voff) do { _Pragma("unroll") for (int _i = 0; _i < 2; ++_i) \
;     __builtin_amdgcn_global_load_lds((const unsigned*)((const char*)(gbase) + (voff)[_i]), (PG8_LAS unsigned*)(lds + (bufoff) + ldsw + _i * 8192), 16, 0, 0); } while (0)
; #define PG8_LDA(dst, b, h) do { _Pragma("unroll") for (int m = 0; m < 4; ++m) _Pragma("unroll") for (int k = 0; k < 2; ++k) dst[m][k] = *(const PG8_LAS bf16x8*)(lds + PG8_SA(b, h) + aoff + m * 2048 + k * 1024); } while (0)
; #define PG8_MMA(ai, bj, At, Bt) do { __builtin_amdgcn_s_setprio(1); _Pragma("unroll") for (int m = 0; m < 4; ++m) _Pragma("unroll") for (int n = 0; n < 2; ++n) _Pragma("unroll") for (int k = 0; k < 2; ++k) \
;     acc[ai][bj][m][n] = __builtin_amdgcn_mfma_f32_16x16x32_bf16(Bt[n][k], At[m][k], acc[ai][bj][m][n], 0, 0, 0); __builtin_amdgcn_s_setprio(0); } while (0)
; #define PG8_WAIT_V(n) asm volatile("s_waitcnt vmcnt(" #n ")" ::: "memory")
; #define PG8_WAIT_L(n) asm volatile("s_waitcnt lgkmcnt(" #n ")" ::: "memory")
; #define PG8_BAR __builtin_amdgcn_s_barrier()
; #define PG8_SCHED __builtin_amdgcn_sched_barrier(0)
; template <class Epi>
; DI void gemm_phase(PG8_LAS unsigned char* lds, const Gemm g, const StaticOrder& S, const Epi& E, const int wv) {
;     ...
;       PG8_BAR; PG8_WAIT_L(0); PG8_MMA(0, 1, At, B1); PG8_BAR;
;       PG8_LDA(At, 1, 1); PG8_STAGE(PG8_SA(1, 0), a3, voffA);
;       PG8_BAR; PG8_WAIT_L(0); PG8_MMA(1, 0, At, B0); PG8_BAR; PG8_SCHED;
;       PG8_STAGE(PG8_SB(1, 1), b3 + hstep, voffB);
;       PG8_WAIT_V(6); PG8_BAR; PG8_MMA(1, 1, At, B1); PG8_BAR;
;     }
;     E(acc, cur, wr, wc, fr, fq);
;   DI void operator()(AccRef acc, const pg8::Unit& u, int wr, int wc, int fr, int fq) const {
;     const int row0 = u.pm * 256 + wr * 64 + fr, col0 = u.pn * 256 + wc * 32 + 8 * fq;
	s_waitcnt lgkmcnt(0)
	v_mfma_f32_16x16x32_bf16 v[60:63], v[142:145], v[170:173], v[60:63]
	v_mfma_f32_16x16x32_bf16 v[56:59], v[162:165], v[170:173], v[56:59]
	v_mfma_f32_16x16x32_bf16 v[52:55], v[142:145], v[178:181], v[52:55]
	v_mfma_f32_16x16x32_bf16 v[48:51], v[162:165], v[178:181], v[48:51]
	v_mfma_f32_16x16x32_bf16 v[44:47], v[142:145], v[186:189], v[44:47]
	v_mfma_f32_16x16x32_bf16 v[32:35], v[162:165], v[186:189], v[32:35]
	v_mfma_f32_16x16x32_bf16 v[20:23], v[142:145], v[194:197], v[20:23]
	v_mfma_f32_16x16x32_bf16 v[12:15], v[162:165], v[194:197], v[12:15]
	v_mfma_f32_16x16x32_bf16 v[60:63], v[154:157], v[174:177], v[60:63]
	v_mfma_f32_16x16x32_bf16 v[56:59], v[166:169], v[174:177], v[56:59]
	v_mfma_f32_16x16x32_bf16 v[52:55], v[154:157], v[182:185], v[52:55]
	v_mfma_f32_16x16x32_bf16 v[48:51], v[166:169], v[182:185], v[48:51]
	v_mfma_f32_16x16x32_bf16 v[44:47], v[154:157], v[190:193], v[44:47]
	v_mfma_f32_16x16x32_bf16 v[32:35], v[166:169], v[190:193], v[32:35]
	v_mfma_f32_16x16x32_bf16 v[20:23], v[154:157], v[198:201], v[20:23]
	v_mfma_f32_16x16x32_bf16 v[12:15], v[166:169], v[198:201], v[12:15]
	s_barrier
	s_setprio 0
	s_add_u32 s6, s8, 0x18080
	s_addc_u32 s7, s9, 0
	s_add_i32 s8, s26, s37
	v_lshl_add_u64 v[142:143], s[6:7], 0, v[130:131]
	s_mov_b32 m0, s8
	s_nop 0
	global_load_lds_dwordx4 v[142:143], off
	v_lshl_add_u64 v[142:143], s[6:7], 0, v[134:135]
	s_add_i32 m0, s8, 0x2000
	s_nop 0
	global_load_lds_dwordx4 v[142:143], off
	s_waitcnt vmcnt(6)
	s_setprio 1
	s_barrier
	v_mfma_f32_16x16x32_bf16 v[40:43], v[202:205], v[170:173], v[40:43]
	v_mfma_f32_16x16x32_bf16 v[36:39], v[210:213], v[170:173], v[36:39]
	v_mfma_f32_16x16x32_bf16 v[28:31], v[202:205], v[178:181], v[28:31]
	v_mfma_f32_16x16x32_bf16 v[24:27], v[210:213], v[178:181], v[24:27]
	v_mfma_f32_16x16x32_bf16 v[16:19], v[202:205], v[186:189], v[16:19]
	v_mfma_f32_16x16x32_bf16 v[8:11], v[210:213], v[186:189], v[8:11]
	v_mfma_f32_16x16x32_bf16 v[4:7], v[202:205], v[194:197], v[4:7]
	v_mfma_f32_16x16x32_bf16 v[0:3], v[210:213], v[194:197], v[0:3]
	v_mfma_f32_16x16x32_bf16 v[40:43], v[206:209], v[174:177], v[40:43]
	v_mfma_f32_16x16x32_bf16 v[36:39], v[214:217], v[174:177], v[36:39]
	v_mfma_f32_16x16x32_bf16 v[28:31], v[206:209], v[182:185], v[28:31]
	v_mfma_f32_16x16x32_bf16 v[24:27], v[214:217], v[182:185], v[24:27]
	v_mfma_f32_16x16x32_bf16 v[16:19], v[206:209], v[190:193], v[16:19]
	v_mfma_f32_16x16x32_bf16 v[8:11], v[214:217], v[190:193], v[8:11]
	v_mfma_f32_16x16x32_bf16 v[4:7], v[206:209], v[198:201], v[4:7]
	v_mfma_f32_16x16x32_bf16 v[0:3], v[214:217], v[198:201], v[0:3]
	s_add_i32 s58, s58, 2
	s_add_u32 s55, s55, 0x100
	s_addc_u32 s57, s57, 0
	s_cmp_gt_u32 s58, 3
	s_mov_b64 s[6:7], s[4:5]
	s_barrier
	s_setprio 0
	s_cbranch_scc0 .LBB0_521
	v_lshl_or_b32 v142, s54, 8, v148
	v_ashrrev_i32_e32 v143, 31, v142
	v_lshl_add_u32 v144, s53, 8, v146
	s_cmpk_gt_i32 s53, 0x181
	v_lshlrev_b64 v[142:143], 1, v[142:143]
	s_cbranch_scc1 .LBB0_524
; DI u32x4 pack8v(f32x4 a, f32x4 b) { return u32x4{cvtpk(a[0], a[1]), cvtpk(a[2], a[3]), cvtpk(b[0], b[1]), cvtpk(b[2], b[3])}; }
; #define EPI_ROWS_BEGIN() \
;   _Pragma("unroll") for (int ai = 0; ai < 2; ++ai) { if (u.pm * 256 + ai * 128 >= T) continue;
;   DI void operator()(AccRef acc, const pg8::Unit& u, int wr, int wc, int fr, int fq) const {
;     const int row0 = u.pm * 256 + wr * 64 + fr, col0 = u.pn * 256 + wc * 32 + 8 * fq;
;     EPI_ROWS_BEGIN()
;       float rs[4];
; #pragma unroll
;       for (int m = 0; m < 4; ++m) rs[m] = ss[row0 + ai * 128 + m * 16];
; #pragma unroll
;       for (int m = 0; m < 4; ++m) rs[m] = rsqrtf(rs[m] * inv_k + EPS);
; #pragma unroll
;       for (int m = 0; m < 4; ++m) {
;         u16* rp = out + (size_t)(row0 + ai * 128 + m * 16) * ldc + col0;
; #pragma unroll
;         for (int bj = 0; bj < 2; ++bj) *(u32x4*)(rp + bj * 128) = pack8v(acc[ai][bj][m][0] * rs[m], acc[ai][bj][m][1] * rs[m]);
;       }
	v_ashrrev_i32_e32 v145, 31, v144
	v_lshl_add_u64 v[154:155], v[144:145], 2, s[16:17]
	global_load_dword v145, v[154:155], off
	v_or_b32_e32 v154, 16, v144
	v_ashrrev_i32_e32 v155, 31, v154
	v_or_b32_e32 v158, 32, v144
	v_or_b32_e32 v164, 48, v144
	v_lshl_add_u64 v[156:157], v[154:155], 2, s[16:17]
	v_ashrrev_i32_e32 v159, 31, v158
	v_ashrrev_i32_e32 v165, 31, v164
	v_lshl_add_u64 v[162:163], v[158:159], 2, s[16:17]
	v_lshl_add_u64 v[166:167], v[164:165], 2, s[16:17]
	global_load_dword v153, v[156:157], off
	global_load_dword v161, v[162:163], off
	global_load_dword v165, v[166:167], off
	v_mov_b64_e32 v[156:157], s[14:15]
	v_mad_i64_i32 v[162:163], s[4:5], v144, s50, v[156:157]
	v_mad_i64_i32 v[154:155], s[4:5], v154, s50, v[156:157]
	v_mad_i64_i32 v[158:159], s[4:5], v158, s50, v[156:157]
	v_lshl_add_u64 v[162:163], v[162:163], 0, v[142:143]
	v_lshl_add_u64 v[154:155], v[154:155], 0, v[142:143]
	v_lshl_add_u64 v[158:159], v[158:159], 0, v[142:143]
	s_waitcnt vmcnt(0)
	v_fmamk_f32 v145, v145, 0x3b2aaaab, v152
	v_mul_f32_e32 v166, 0x4b800000, v145
	v_cmp_gt_f32_e32 vcc, s49, v145
	v_fmamk_f32 v153, v153, 0x3b2aaaab, v152
	v_fmamk_f32 v161, v161, 0x3b2aaaab, v152
	v_fmamk_f32 v165, v165, 0x3b2aaaab, v152
	v_cndmask_b32_e32 v145, v145, v166, vcc
	v_mul_f32_e32 v166, 0x4b800000, v153
	v_cmp_gt_f32_e64 s[4:5], s49, v153
	v_mul_f32_e32 v167, 0x4b800000, v161
	v_mul_f32_e32 v168, 0x4b800000, v165
	v_rsq_f32_e32 v145, v145
	v_cndmask_b32_e64 v153, v153, v166, s[4:5]
	v_cmp_gt_f32_e64 s[6:7], s49, v161
	v_cmp_gt_f32_e64 s[8:9], s49, v165
	v_rsq_f32_e32 v153, v153
	v_cndmask_b32_e64 v161, v161, v167, s[6:7]
	v_cndmask_b32_e64 v165, v165, v168, s[8:9]
	v_rsq_f32_e32 v161, v161
	v_rsq_f32_e32 v165, v165
	v_mul_f32_e32 v166, 0x45800000, v145
	v_cndmask_b32_e32 v166, v145, v166, vcc
	v_mul_f32_e32 v145, 0x45800000, v153
	v_mul_f32_e32 v167, 0x45800000, v161
	v_mul_f32_e32 v169, 0x45800000, v165
	v_cndmask_b32_e64 v168, v153, v145, s[4:5]
	v_pk_mul_f32 v[126:127], v[126:127], v[166:167] op_sel_hi:[1,0]
	v_pk_mul_f32 v[124:125], v[124:125], v[166:167] op_sel_hi:[1,0]
	v_pk_mul_f32 v[122:123], v[122:123], v[166:167] op_sel_hi:[1,0]
	v_pk_mul_f32 v[120:121], v[120:121], v[166:167] op_sel_hi:[1,0]
	v_pk_mul_f32 v[118:119], v[118:119], v[168:169] op_sel_hi:[1,0]
	v_pk_mul_f32 v[116:117], v[116:117], v[168:169] op_sel_hi:[1,0]
	v_pk_mul_f32 v[114:115], v[114:115], v[168:169] op_sel_hi:[1,0]
	v_pk_mul_f32 v[112:113], v[112:113], v[168:169] op_sel_hi:[1,0]
	v_cndmask_b32_e64 v170, v161, v167, s[6:7]
	v_pk_mul_f32 v[110:111], v[110:111], v[166:167] op_sel_hi:[1,0]
	v_pk_mul_f32 v[108:109], v[108:109], v[166:167] op_sel_hi:[1,0]
	v_pk_mul_f32 v[174:175], v[106:107], v[166:167] op_sel_hi:[1,0]
	v_pk_mul_f32 v[166:167], v[104:105], v[166:167] op_sel_hi:[1,0]
	v_cvt_pk_bf16_f32 v104, v124, v125
	v_cvt_pk_bf16_f32 v105, v126, v127
	v_cvt_pk_bf16_f32 v106, v120, v121
	v_cvt_pk_bf16_f32 v107, v122, v123
	v_pk_mul_f32 v[94:95], v[94:95], v[168:169] op_sel_hi:[1,0]
	v_pk_mul_f32 v[92:93], v[92:93], v[168:169] op_sel_hi:[1,0]
	v_pk_mul_f32 v[120:121], v[90:91], v[168:169] op_sel_hi:[1,0]
	v_pk_mul_f32 v[122:123], v[88:89], v[168:169] op_sel_hi:[1,0]
	v_cvt_pk_bf16_f32 v88, v116, v117
	v_cvt_pk_bf16_f32 v89, v118, v119
	v_cvt_pk_bf16_f32 v90, v112, v113
	v_cvt_pk_bf16_f32 v91, v114, v115
	v_cvt_pk_bf16_f32 v108, v108, v109
	v_cvt_pk_bf16_f32 v109, v110, v111
	v_cvt_pk_bf16_f32 v110, v166, v167
	v_cvt_pk_bf16_f32 v111, v174, v175
	global_store_dwordx4 v[162:163], v[104:107], off
	global_store_dwordx4 v[162:163], v[108:111], off offset:256
	v_cvt_pk_bf16_f32 v92, v92, v93
	v_cvt_pk_bf16_f32 v93, v94, v95
	v_cvt_pk_bf16_f32 v94, v122, v123
	v_cvt_pk_bf16_f32 v95, v120, v121
	global_store_dwordx4 v[154:155], v[88:91], off
	global_store_dwordx4 v[154:155], v[92:95], off offset:256
	v_pk_mul_f32 v[82:83], v[82:83], v[170:171] op_sel_hi:[1,0]
	v_pk_mul_f32 v[80:81], v[80:81], v[170:171] op_sel_hi:[1,0]
	v_pk_mul_f32 v[88:89], v[74:75], v[170:171] op_sel_hi:[1,0]
	v_pk_mul_f32 v[74:75], v[72:73], v[170:171] op_sel_hi:[1,0]
	v_cvt_pk_bf16_f32 v72, v80, v81
	v_cvt_pk_bf16_f32 v73, v82, v83
	v_cvt_pk_bf16_f32 v74, v74, v75
	v_cvt_pk_bf16_f32 v75, v88, v89
	v_cndmask_b32_e64 v172, v165, v169, s[8:9]
	global_store_dwordx4 v[158:159], v[72:75], off offset:256
	v_pk_mul_f32 v[78:79], v[78:79], v[172:173] op_sel_hi:[1,0]
	v_pk_mul_f32 v[76:77], v[76:77], v[172:173] op_sel_hi:[1,0]
	v_mad_i64_i32 v[72:73], s[4:5], v164, s50, v[156:157]
	v_lshl_add_u64 v[80:81], v[72:73], 0, v[142:143]
	v_pk_mul_f32 v[74:75], v[86:87], v[172:173] op_sel_hi:[1,0]
	v_pk_mul_f32 v[72:73], v[84:85], v[172:173] op_sel_hi:[1,0]
	v_pk_mul_f32 v[102:103], v[102:103], v[170:171] op_sel_hi:[1,0]
	v_cvt_pk_bf16_f32 v72, v72, v73
	v_cvt_pk_bf16_f32 v73, v74, v75
	v_cvt_pk_bf16_f32 v74, v76, v77
	v_cvt_pk_bf16_f32 v75, v78, v79
	v_pk_mul_f32 v[100:101], v[100:101], v[170:171] op_sel_hi:[1,0]
	v_pk_mul_f32 v[124:125], v[98:99], v[170:171] op_sel_hi:[1,0]
	v_pk_mul_f32 v[98:99], v[96:97], v[170:171] op_sel_hi:[1,0]
	global_store_dwordx4 v[80:81], v[72:75], off
	v_pk_mul_f32 v[70:71], v[70:71], v[172:173] op_sel_hi:[1,0]
	v_pk_mul_f32 v[68:69], v[68:69], v[172:173] op_sel_hi:[1,0]
	v_pk_mul_f32 v[72:73], v[66:67], v[172:173] op_sel_hi:[1,0]
	v_pk_mul_f32 v[66:67], v[64:65], v[172:173] op_sel_hi:[1,0]
	v_cvt_pk_bf16_f32 v96, v100, v101
	v_cvt_pk_bf16_f32 v97, v102, v103
	v_cvt_pk_bf16_f32 v98, v98, v99
	v_cvt_pk_bf16_f32 v99, v124, v125
	v_cvt_pk_bf16_f32 v64, v68, v69
	v_cvt_pk_bf16_f32 v65, v70, v71
	v_cvt_pk_bf16_f32 v66, v66, v67
	v_cvt_pk_bf16_f32 v67, v72, v73
	global_store_dwordx4 v[158:159], v[96:99], off
	global_store_dwordx4 v[80:81], v[64:67], off offset:256

; #define PG8_STAGE(bufoff, gbase, voff) do { _Pragma("unroll") for (int _i = 0; _i < 2; ++_i) \
;     __builtin_amdgcn_global_load_lds((const unsigned*)((const char*)(gbase) + (voff)[_i]), (PG8_LAS unsigned*)(lds + (bufoff) + ldsw + _i * 8192), 16, 0, 0); } while (0)
; #define PG8_LDA(dst, b, h) do { _Pragma("unroll") for (int m = 0; m < 4; ++m) _Pragma("unroll") for (int k = 0; k < 2; ++k) dst[m][k] = *(const PG8_LAS bf16x8*)(lds + PG8_SA(b, h) + aoff + m * 2048 + k * 1024); } while (0)
; #define PG8_LDB(dst, b, h) do { _Pragma("unroll") for (int n = 0; n < 2; ++n) _Pragma("unroll") for (int k = 0; k < 2; ++k) dst[n][k] = *(const PG8_LAS bf16x8*)(lds + PG8_SB(b, h) + boff + n * 2048 + k * 1024); } while (0)
; #define PG8_MMA(ai, bj, At, Bt) do { __builtin_amdgcn_s_setprio(1); _Pragma("unroll") for (int m = 0; m < 4; ++m) _Pragma("unroll") for (int n = 0; n < 2; ++n) _Pragma("unroll") for (int k = 0; k < 2; ++k) \
;     acc[ai][bj][m][n] = __builtin_amdgcn_mfma_f32_16x16x32_bf16(Bt[n][k], At[m][k], acc[ai][bj][m][n], 0, 0, 0); __builtin_amdgcn_s_setprio(0); } while (0)
; template <class Epi>
; DI void gemm_phase(PG8_LAS unsigned char* lds, const Gemm g, const StaticOrder& S, const Epi& E, const int wv) {
;     ...
;   for (;;) {
;     const bool has_next = S.next(ui + 1, nxt);
;     const char* nA = has_next ? (const char*)g.A + (size_t)nxt.pm * tstep : cA; const char* nB = has_next ? (const char*)g.Bt + (size_t)nxt.pn * tstep : cB;
; #pragma nounroll
;     for (int t = 0; t < nt; t += 2) {
;       const bool last = (t == nt - 2);
;       const char* a1 = cA + (size_t)(t + 1) * kstep;
;       const char* a2 = last ? nA : cA + (size_t)(t + 2) * kstep; const char* b2 = last ? nB : cB + (size_t)(t + 2) * kstep;
;       const char* a3 = a2 + kstep; const char* b3 = b2 + kstep;
;       PG8_LDB(B0, 0, 0); PG8_SCHED; PG8_LDA(At, 0, 0); PG8_STAGE(PG8_SA(1, 1), a1 + hstep, voffA);
;       PG8_WAIT_L(8); PG8_BAR; PG8_WAIT_L(0); PG8_MMA(0, 0, At, B0); PG8_BAR; PG8_SCHED;
;       PG8_LDB(B1, 0, 1); PG8_STAGE(PG8_SB(0, 0), b2, voffB);
;       PG8_BAR; PG8_WAIT_L(0); PG8_MMA(0, 1, At, B1); PG8_BAR;
;       PG8_LDA(At, 0, 1); PG8_STAGE(PG8_SA(0, 0), a2, voffA);
;       PG8_BAR; PG8_WAIT_L(0); PG8_MMA(1, 0, At, B0); PG8_BAR; PG8_SCHED;
;       PG8_STAGE(PG8_SB(0, 1), b2 + hstep, voffB);
;       PG8_WAIT_V(6); PG8_BAR; PG8_MMA(1, 1, At, B1); PG8_BAR;
.LBB0_537:
	s_add_u32 s48, s8, s40
	s_addc_u32 s49, s9, s41
	s_add_u32 s44, s48, 0x100
	s_addc_u32 s45, s49, 0
	s_and_b64 s[42:43], s[38:39], exec
	s_cselect_b32 s45, s5, s45
	s_cselect_b32 s44, s27, s44
	s_add_u32 s40, s6, s40
	s_addc_u32 s41, s7, s41
	s_add_u32 s40, s40, 0x100
	s_addc_u32 s41, s41, 0
	s_and_b64 s[38:39], s[38:39], exec
	s_cselect_b32 s47, s25, s41
	s_cselect_b32 s46, s35, s40
	s_add_u32 s48, s48, 0x10080
	s_addc_u32 s49, s49, 0
	s_add_i32 s92, s74, s57
	s_add_i32 m0, s60, 0xc000
	s_add_i32 s91, s60, 0xe000
	s_add_i32 s90, s92, 0x2000
	s_add_u32 s42, s46, 0x10000
	s_addc_u32 s43, s47, 0
	s_add_i32 s87, s77, s57
	ds_read_b128 v[142:145], v153
	ds_read_b128 v[162:165], v153 offset:1024
	ds_read_b128 v[166:169], v153 offset:2048
	ds_read_b128 v[170:173], v153 offset:3072
	s_add_i32 s86, s87, 0x2000
	s_add_i32 s85, 0, 0x18000
	s_add_u32 s40, s44, 0x10000
	s_addc_u32 s41, s45, 0
	s_add_i32 s84, s85, s57
	s_add_i32 s83, 0, 0x1c000
	s_add_i32 s82, s84, 0x2000
	s_add_u32 s38, s46, 0x10080
	s_addc_u32 s39, s47, 0
	s_add_i32 s89, s83, s57
	s_add_i32 s88, s89, 0x2000
	v_lshl_add_u64 v[146:147], s[48:49], 0, v[134:135]
	ds_read_b128 v[174:177], v154
	ds_read_b128 v[178:181], v154 offset:1024
	ds_read_b128 v[182:185], v154 offset:2048
	ds_read_b128 v[186:189], v154 offset:3072
	ds_read_b128 v[190:193], v154 offset:4096
	ds_read_b128 v[194:197], v154 offset:5120
	ds_read_b128 v[198:201], v154 offset:6144
	ds_read_b128 v[202:205], v154 offset:7168
	global_load_lds_dwordx4 v[146:147], off
	v_lshl_add_u64 v[146:147], s[48:49], 0, v[130:131]
	s_mov_b32 m0, s91
	s_nop 0
	global_load_lds_dwordx4 v[146:147], off
	s_waitcnt lgkmcnt(8)
	s_setprio 1
	s_barrier
	s_waitcnt lgkmcnt(0)
	v_mfma_f32_16x16x32_bf16 v[124:127], v[142:145], v[174:177], v[124:127]
	v_mfma_f32_16x16x32_bf16 v[120:123], v[166:169], v[174:177], v[120:123]
	v_mfma_f32_16x16x32_bf16 v[112:115], v[142:145], v[182:185], v[112:115]
	v_mfma_f32_16x16x32_bf16 v[108:111], v[166:169], v[182:185], v[108:111]
	v_mfma_f32_16x16x32_bf16 v[96:99], v[142:145], v[190:193], v[96:99]
	v_mfma_f32_16x16x32_bf16 v[92:95], v[166:169], v[190:193], v[92:95]
	v_mfma_f32_16x16x32_bf16 v[80:83], v[142:145], v[198:201], v[80:83]
	v_mfma_f32_16x16x32_bf16 v[76:79], v[166:169], v[198:201], v[76:79]
	v_mfma_f32_16x16x32_bf16 v[124:127], v[162:165], v[178:181], v[124:127]
	v_mfma_f32_16x16x32_bf16 v[120:123], v[170:173], v[178:181], v[120:123]
	v_mfma_f32_16x16x32_bf16 v[112:115], v[162:165], v[186:189], v[112:115]
	v_mfma_f32_16x16x32_bf16 v[108:111], v[170:173], v[186:189], v[108:111]
	v_mfma_f32_16x16x32_bf16 v[96:99], v[162:165], v[194:197], v[96:99]
	v_mfma_f32_16x16x32_bf16 v[92:95], v[170:173], v[194:197], v[92:95]
	v_mfma_f32_16x16x32_bf16 v[80:83], v[162:165], v[202:205], v[80:83]
	v_mfma_f32_16x16x32_bf16 v[76:79], v[170:173], v[202:205], v[76:79]
	s_barrier
	s_setprio 0
	s_mov_b32 m0, s92
	v_lshl_add_u64 v[146:147], s[46:47], 0, v[132:133]
	ds_read_b128 v[206:209], v155
	ds_read_b128 v[210:213], v155 offset:1024
	ds_read_b128 v[214:217], v155 offset:2048
	ds_read_b128 v[220:223], v155 offset:3072
	global_load_lds_dwordx4 v[146:147], off
	v_lshl_add_u64 v[150:151], s[46:47], 0, v[128:129]
	s_mov_b32 m0, s90
	s_nop 0
	global_load_lds_dwordx4 v[150:151], off
	s_setprio 1
	s_barrier
	s_waitcnt lgkmcnt(0)
	v_mfma_f32_16x16x32_bf16 v[116:119], v[206:209], v[174:177], v[116:119]
	v_mfma_f32_16x16x32_bf16 v[104:107], v[214:217], v[174:177], v[104:107]
	v_mfma_f32_16x16x32_bf16 v[100:103], v[206:209], v[182:185], v[100:103]
	v_mfma_f32_16x16x32_bf16 v[88:91], v[214:217], v[182:185], v[88:91]
	v_mfma_f32_16x16x32_bf16 v[84:87], v[206:209], v[190:193], v[84:87]
	v_mfma_f32_16x16x32_bf16 v[72:75], v[214:217], v[190:193], v[72:75]
	v_mfma_f32_16x16x32_bf16 v[68:71], v[206:209], v[198:201], v[68:71]
	v_mfma_f32_16x16x32_bf16 v[64:67], v[214:217], v[198:201], v[64:67]
	v_mfma_f32_16x16x32_bf16 v[116:119], v[210:213], v[178:181], v[116:119]
	v_mfma_f32_16x16x32_bf16 v[104:107], v[220:223], v[178:181], v[104:107]
	v_mfma_f32_16x16x32_bf16 v[100:103], v[210:213], v[186:189], v[100:103]
	v_mfma_f32_16x16x32_bf16 v[88:91], v[220:223], v[186:189], v[88:91]
	v_mfma_f32_16x16x32_bf16 v[84:87], v[210:213], v[194:197], v[84:87]
	v_mfma_f32_16x16x32_bf16 v[72:75], v[220:223], v[194:197], v[72:75]
	v_mfma_f32_16x16x32_bf16 v[68:71], v[210:213], v[202:205], v[68:71]
	v_mfma_f32_16x16x32_bf16 v[64:67], v[220:223], v[202:205], v[64:67]
	s_mov_b32 m0, s60
	v_lshl_add_u64 v[158:159], s[44:45], 0, v[134:135]
	s_barrier
	s_setprio 0
	ds_read_b128 v[174:177], v154 offset:16384
	ds_read_b128 v[178:181], v154 offset:17408
	ds_read_b128 v[182:185], v154 offset:18432
	ds_read_b128 v[186:189], v154 offset:19456
	ds_read_b128 v[190:193], v154 offset:20480
	ds_read_b128 v[194:197], v154 offset:21504
	ds_read_b128 v[198:201], v154 offset:22528
	ds_read_b128 v[202:205], v154 offset:23552
	global_load_lds_dwordx4 v[158:159], off
	v_lshl_add_u64 v[224:225], s[44:45], 0, v[130:131]
	s_mov_b32 m0, s61
	s_nop 0
	global_load_lds_dwordx4 v[224:225], off
	s_setprio 1
	s_barrier
	s_waitcnt lgkmcnt(0)
	v_mfma_f32_16x16x32_bf16 v[60:63], v[142:145], v[174:177], v[60:63]
	v_mfma_f32_16x16x32_bf16 v[56:59], v[166:169], v[174:177], v[56:59]
	v_mfma_f32_16x16x32_bf16 v[48:51], v[142:145], v[182:185], v[48:51]
	v_mfma_f32_16x16x32_bf16 v[44:47], v[166:169], v[182:185], v[44:47]
	v_mfma_f32_16x16x32_bf16 v[32:35], v[142:145], v[190:193], v[32:35]
	v_mfma_f32_16x16x32_bf16 v[28:31], v[166:169], v[190:193], v[28:31]
	v_mfma_f32_16x16x32_bf16 v[16:19], v[142:145], v[198:201], v[16:19]
	v_mfma_f32_16x16x32_bf16 v[12:15], v[166:169], v[198:201], v[12:15]
	v_mfma_f32_16x16x32_bf16 v[60:63], v[162:165], v[178:181], v[60:63]
	v_mfma_f32_16x16x32_bf16 v[56:59], v[170:173], v[178:181], v[56:59]
	v_mfma_f32_16x16x32_bf16 v[48:51], v[162:165], v[186:189], v[48:51]
	v_mfma_f32_16x16x32_bf16 v[44:47], v[170:173], v[186:189], v[44:47]
	v_mfma_f32_16x16x32_bf16 v[32:35], v[162:165], v[194:197], v[32:35]
	v_mfma_f32_16x16x32_bf16 v[28:31], v[170:173], v[194:197], v[28:31]
	v_mfma_f32_16x16x32_bf16 v[16:19], v[162:165], v[202:205], v[16:19]
	v_mfma_f32_16x16x32_bf16 v[12:15], v[170:173], v[202:205], v[12:15]
	s_barrier
; #define PG8_STAGE(bufoff, gbase, voff) do { _Pragma("unroll") for (int _i = 0; _i < 2; ++_i) \
;     __builtin_amdgcn_global_load_lds((const unsigned*)((const char*)(gbase) + (voff)[_i]), (PG8_LAS unsigned*)(lds + (bufoff) + ldsw + _i * 8192), 16, 0, 0); } while (0)
; #define PG8_LDA(dst, b, h) do { _Pragma("unroll") for (int m = 0; m < 4; ++m) _Pragma("unroll") for (int k = 0; k < 2; ++k) dst[m][k] = *(const PG8_LAS bf16x8*)(lds + PG8_SA(b, h) + aoff + m * 2048 + k * 1024); } while (0)
; #define PG8_LDB(dst, b, h) do { _Pragma("unroll") for (int n = 0; n < 2; ++n) _Pragma("unroll") for (int k = 0; k < 2; ++k) dst[n][k] = *(const PG8_LAS bf16x8*)(lds + PG8_SB(b, h) + boff + n * 2048 + k * 1024); } while (0)
; #define PG8_MMA(ai, bj, At, Bt) do { __builtin_amdgcn_s_setprio(1); _Pragma("unroll") for (int m = 0; m < 4; ++m) _Pragma("unroll") for (int n = 0; n < 2; ++n) _Pragma("unroll") for (int k = 0; k < 2; ++k) \
;     acc[ai][bj][m][n] = __builtin_amdgcn_mfma_f32_16x16x32_bf16(Bt[n][k], At[m][k], acc[ai][bj][m][n], 0, 0, 0); __builtin_amdgcn_s_setprio(0); } while (0)
; template <class Epi>
; DI void gemm_phase(PG8_LAS unsigned char* lds, const Gemm g, const StaticOrder& S, const Epi& E, const int wv) {
;     ...
;       PG8_LDB(B0, 0, 0); PG8_SCHED; PG8_LDA(At, 0, 0); PG8_STAGE(PG8_SA(1, 1), a1 + hstep, voffA);
;       PG8_WAIT_L(8); PG8_BAR; PG8_WAIT_L(0); PG8_MMA(0, 0, At, B0); PG8_BAR; PG8_SCHED;
;       PG8_LDB(B1, 0, 1); PG8_STAGE(PG8_SB(0, 0), b2, voffB);
;       PG8_BAR; PG8_WAIT_L(0); PG8_MMA(0, 1, At, B1); PG8_BAR;
;       PG8_LDA(At, 0, 1); PG8_STAGE(PG8_SA(0, 0), a2, voffA);
;       PG8_BAR; PG8_WAIT_L(0); PG8_MMA(1, 0, At, B0); PG8_BAR; PG8_SCHED;
;       PG8_STAGE(PG8_SB(0, 1), b2 + hstep, voffB);
;       PG8_WAIT_V(6); PG8_BAR; PG8_MMA(1, 1, At, B1); PG8_BAR;
;       PG8_LDB(B0, 1, 0); PG8_SCHED; PG8_LDA(At, 1, 0); PG8_STAGE(PG8_SA(0, 1), a2 + hstep, voffA);
;       PG8_WAIT_L(8); PG8_BAR; PG8_WAIT_L(0); PG8_MMA(0, 0, At, B0); PG8_BAR; PG8_SCHED;
;       PG8_LDB(B1, 1, 1); PG8_STAGE(PG8_SB(1, 0), b3, voffB);
;       PG8_BAR; PG8_WAIT_L(0); PG8_MMA(0, 1, At, B1); PG8_BAR;
;       PG8_LDA(At, 1, 1); PG8_STAGE(PG8_SA(1, 0), a3, voffA);
;       PG8_BAR; PG8_WAIT_L(0); PG8_MMA(1, 0, At, B0); PG8_BAR; PG8_SCHED;
;       PG8_STAGE(PG8_SB(1, 1), b3 + hstep, voffB);
;       PG8_WAIT_V(6); PG8_BAR; PG8_MMA(1, 1, At, B1); PG8_BAR;
	s_setprio 0
	s_mov_b32 m0, s87
	v_lshl_add_u64 v[142:143], s[42:43], 0, v[132:133]
	global_load_lds_dwordx4 v[142:143], off
	v_lshl_add_u64 v[142:143], s[42:43], 0, v[128:129]
	s_mov_b32 m0, s86
	s_nop 0
	global_load_lds_dwordx4 v[142:143], off
	s_waitcnt vmcnt(6)
	s_setprio 1
	s_barrier
	v_mfma_f32_16x16x32_bf16 v[52:55], v[206:209], v[174:177], v[52:55]
	v_mfma_f32_16x16x32_bf16 v[40:43], v[214:217], v[174:177], v[40:43]
	v_mfma_f32_16x16x32_bf16 v[36:39], v[206:209], v[182:185], v[36:39]
	v_mfma_f32_16x16x32_bf16 v[24:27], v[214:217], v[182:185], v[24:27]
	v_mfma_f32_16x16x32_bf16 v[20:23], v[206:209], v[190:193], v[20:23]
	v_mfma_f32_16x16x32_bf16 v[8:11], v[214:217], v[190:193], v[8:11]
	v_mfma_f32_16x16x32_bf16 v[4:7], v[206:209], v[198:201], v[4:7]
	v_mfma_f32_16x16x32_bf16 v[0:3], v[214:217], v[198:201], v[0:3]
	v_mfma_f32_16x16x32_bf16 v[52:55], v[210:213], v[178:181], v[52:55]
	v_mfma_f32_16x16x32_bf16 v[40:43], v[220:223], v[178:181], v[40:43]
	v_mfma_f32_16x16x32_bf16 v[36:39], v[210:213], v[186:189], v[36:39]
	v_mfma_f32_16x16x32_bf16 v[24:27], v[220:223], v[186:189], v[24:27]
	v_mfma_f32_16x16x32_bf16 v[20:23], v[210:213], v[194:197], v[20:23]
	v_mfma_f32_16x16x32_bf16 v[8:11], v[220:223], v[194:197], v[8:11]
	v_mfma_f32_16x16x32_bf16 v[4:7], v[210:213], v[202:205], v[4:7]
	v_mfma_f32_16x16x32_bf16 v[0:3], v[220:223], v[202:205], v[0:3]
	v_add_u32_e32 v136, s85, v149
	s_barrier
	s_setprio 0
	ds_read_b128 v[142:145], v136
	ds_read_b128 v[162:165], v136 offset:1024
	ds_read_b128 v[166:169], v136 offset:2048
	ds_read_b128 v[170:173], v136 offset:3072
	s_mov_b32 m0, s62
	v_lshl_add_u64 v[206:207], s[40:41], 0, v[134:135]
	ds_read_b128 v[174:177], v154 offset:32768
	ds_read_b128 v[178:181], v154 offset:33792
	ds_read_b128 v[182:185], v154 offset:34816
	ds_read_b128 v[186:189], v154 offset:35840
	ds_read_b128 v[190:193], v154 offset:36864
	ds_read_b128 v[194:197], v154 offset:37888
	ds_read_b128 v[198:201], v154 offset:38912
	ds_read_b128 v[202:205], v154 offset:39936
	global_load_lds_dwordx4 v[206:207], off
	v_lshl_add_u64 v[206:207], s[40:41], 0, v[130:131]
	s_mov_b32 m0, s63
	s_nop 0
	global_load_lds_dwordx4 v[206:207], off
	s_waitcnt lgkmcnt(8)
	s_setprio 1
	s_barrier
	s_waitcnt lgkmcnt(0)
	v_mfma_f32_16x16x32_bf16 v[124:127], v[142:145], v[174:177], v[124:127]
	v_mfma_f32_16x16x32_bf16 v[120:123], v[166:169], v[174:177], v[120:123]
	v_mfma_f32_16x16x32_bf16 v[112:115], v[142:145], v[182:185], v[112:115]
	v_mfma_f32_16x16x32_bf16 v[108:111], v[166:169], v[182:185], v[108:111]
	v_mfma_f32_16x16x32_bf16 v[96:99], v[142:145], v[190:193], v[96:99]
	v_mfma_f32_16x16x32_bf16 v[92:95], v[166:169], v[190:193], v[92:95]
	v_mfma_f32_16x16x32_bf16 v[80:83], v[142:145], v[198:201], v[80:83]
	v_mfma_f32_16x16x32_bf16 v[76:79], v[166:169], v[198:201], v[76:79]
	v_mfma_f32_16x16x32_bf16 v[124:127], v[162:165], v[178:181], v[124:127]
	v_mfma_f32_16x16x32_bf16 v[120:123], v[170:173], v[178:181], v[120:123]
	v_mfma_f32_16x16x32_bf16 v[112:115], v[162:165], v[186:189], v[112:115]
	v_mfma_f32_16x16x32_bf16 v[108:111], v[170:173], v[186:189], v[108:111]
	v_mfma_f32_16x16x32_bf16 v[96:99], v[162:165], v[194:197], v[96:99]
	v_mfma_f32_16x16x32_bf16 v[92:95], v[170:173], v[194:197], v[92:95]
	v_mfma_f32_16x16x32_bf16 v[80:83], v[162:165], v[202:205], v[80:83]
	v_mfma_f32_16x16x32_bf16 v[76:79], v[170:173], v[202:205], v[76:79]
	s_barrier
	s_setprio 0
	s_mov_b32 m0, s84
	v_add_u32_e32 v136, s83, v149
	v_lshl_add_u64 v[146:147], v[146:147], 0, s[20:21]
	ds_read_b128 v[206:209], v136
	ds_read_b128 v[210:213], v136 offset:1024
	ds_read_b128 v[214:217], v136 offset:2048
	ds_read_b128 v[220:223], v136 offset:3072
	global_load_lds_dwordx4 v[146:147], off
	v_lshl_add_u64 v[146:147], v[150:151], 0, s[20:21]
	s_mov_b32 m0, s82
	s_nop 0
	global_load_lds_dwordx4 v[146:147], off
	s_setprio 1
	s_barrier
	s_waitcnt lgkmcnt(0)
	s_waitcnt lgkmcnt(0)
	v_mfma_f32_16x16x32_bf16 v[116:119], v[206:209], v[174:177], v[116:119]
	v_mfma_f32_16x16x32_bf16 v[104:107], v[214:217], v[174:177], v[104:107]
	v_mfma_f32_16x16x32_bf16 v[100:103], v[206:209], v[182:185], v[100:103]
	v_mfma_f32_16x16x32_bf16 v[88:91], v[214:217], v[182:185], v[88:91]
	v_mfma_f32_16x16x32_bf16 v[84:87], v[206:209], v[190:193], v[84:87]
	v_mfma_f32_16x16x32_bf16 v[72:75], v[214:217], v[190:193], v[72:75]
	v_mfma_f32_16x16x32_bf16 v[68:71], v[206:209], v[198:201], v[68:71]
	v_mfma_f32_16x16x32_bf16 v[64:67], v[214:217], v[198:201], v[64:67]
	v_mfma_f32_16x16x32_bf16 v[116:119], v[210:213], v[178:181], v[116:119]
	v_mfma_f32_16x16x32_bf16 v[104:107], v[220:223], v[178:181], v[104:107]
	v_mfma_f32_16x16x32_bf16 v[100:103], v[210:213], v[186:189], v[100:103]
	v_mfma_f32_16x16x32_bf16 v[88:91], v[220:223], v[186:189], v[88:91]
	v_mfma_f32_16x16x32_bf16 v[84:87], v[210:213], v[194:197], v[84:87]
	v_mfma_f32_16x16x32_bf16 v[72:75], v[220:223], v[194:197], v[72:75]
	v_mfma_f32_16x16x32_bf16 v[68:71], v[210:213], v[202:205], v[68:71]
	v_mfma_f32_16x16x32_bf16 v[64:67], v[220:223], v[202:205], v[64:67]
	s_mov_b32 m0, s67
	v_lshl_add_u64 v[146:147], v[158:159], 0, s[20:21]
	s_barrier
	s_setprio 0
	ds_read_b128 v[174:177], v154 offset:49152
	ds_read_b128 v[178:181], v154 offset:50176
	ds_read_b128 v[182:185], v154 offset:51200
	ds_read_b128 v[186:189], v154 offset:52224
	ds_read_b128 v[190:193], v154 offset:53248
	ds_read_b128 v[194:197], v154 offset:54272
	ds_read_b128 v[198:201], v154 offset:55296
	ds_read_b128 v[202:205], v154 offset:56320
	global_load_lds_dwordx4 v[146:147], off
	v_lshl_add_u64 v[146:147], v[224:225], 0, s[20:21]
	s_mov_b32 m0, s68
	s_nop 0
	global_load_lds_dwordx4 v[146:147], off
	s_setprio 1
	s_barrier
; #define PG8_STAGE(bufoff, gbase, voff) do { _Pragma("unroll") for (int _i = 0; _i < 2; ++_i) \
;     __builtin_amdgcn_global_load_lds((const unsigned*)((const char*)(gbase) + (voff)[_i]), (PG8_LAS unsigned*)(lds + (bufoff) + ldsw + _i * 8192), 16, 0, 0); } while (0)
; #define PG8_LDA(dst, b, h) do { _Pragma("unroll") for (int m = 0; m < 4; ++m) _Pragma("unroll") for (int k = 0; k < 2; ++k) dst[m][k] = *(const PG8_LAS bf16x8*)(lds + PG8_SA(b, h) + aoff + m * 2048 + k * 1024); } while (0)
; #define PG8_LDB(dst, b, h) do { _Pragma("unroll") for (int n = 0; n < 2; ++n) _Pragma("unroll") for (int k = 0; k < 2; ++k) dst[n][k] = *(const PG8_LAS bf16x8*)(lds + PG8_SB(b, h) + boff + n * 2048 + k * 1024); } while (0)
; #define PG8_WAIT_V(n) asm volatile("s_waitcnt vmcnt(" #n ")" ::: "memory")
; #define PG8_WAIT_L(n) asm volatile("s_waitcnt lgkmcnt(" #n ")" ::: "memory")
; #define PG8_BAR __builtin_amdgcn_s_barrier()
; template <class Epi>
; DI void gemm_phase(PG8_LAS unsigned char* lds, const Gemm g, const StaticOrder& S, const Epi& E, const int wv) {
;     ...
;       PG8_WAIT_V(6); PG8_BAR; PG8_MMA(1, 1, At, B1); PG8_BAR;
;       PG8_LDB(B0, 1, 0); PG8_SCHED; PG8_LDA(At, 1, 0); PG8_STAGE(PG8_SA(0, 1), a2 + hstep, voffA);
;       PG8_WAIT_L(8); PG8_BAR; PG8_WAIT_L(0); PG8_MMA(0, 0, At, B0); PG8_BAR; PG8_SCHED;
;       PG8_LDB(B1, 1, 1); PG8_STAGE(PG8_SB(1, 0), b3, voffB);
;       PG8_BAR; PG8_WAIT_L(0); PG8_MMA(0, 1, At, B1); PG8_BAR;
;       PG8_LDA(At, 1, 1); PG8_STAGE(PG8_SA(1, 0), a3, voffA);
;       PG8_BAR; PG8_WAIT_L(0); PG8_MMA(1, 0, At, B0); PG8_BAR; PG8_SCHED;
;       PG8_STAGE(PG8_SB(1, 1), b3 + hstep, voffB);
;       PG8_WAIT_V(6); PG8_BAR; PG8_MMA(1, 1, At, B1); PG8_BAR;
;   DI void operator()(AccRef acc, const pg8::Unit& u, int wr, int wc, int fr, int fq) const {
;     ...
;     EPI_ROWS_BEGIN()
;       float rs[4];
; #pragma unroll
;       for (int m = 0; m < 4; ++m) rs[m] = ss[row0 + ai * 128 + m * 16];
; #pragma unroll
;       for (int m = 0; m < 4; ++m) rs[m] = rsqrtf(rs[m] * (1.f / 256.f) + EPS);
; #pragma unroll
;       for (int m = 0; m < 4; ++m) {
;         const int row = row0 + ai * 128 + m * 16;
;         const int s = row / L, p = row - s * L;
;         *(u32x4*)(kn + (size_t)row * 512 + head * 128 + w0) = pack8v(acc[ai][0][m][0] * rs[m], acc[ai][0][m][1] * rs[m]);
;         u16* vp = vt + (size_t)((s * 4 + head) * 128 + w0) * LP + vt_pos(p);
	s_waitcnt lgkmcnt(0)
	v_mfma_f32_16x16x32_bf16 v[60:63], v[142:145], v[174:177], v[60:63]
	v_mfma_f32_16x16x32_bf16 v[56:59], v[166:169], v[174:177], v[56:59]
	v_mfma_f32_16x16x32_bf16 v[48:51], v[142:145], v[182:185], v[48:51]
	v_mfma_f32_16x16x32_bf16 v[44:47], v[166:169], v[182:185], v[44:47]
	v_mfma_f32_16x16x32_bf16 v[32:35], v[142:145], v[190:193], v[32:35]
	v_mfma_f32_16x16x32_bf16 v[28:31], v[166:169], v[190:193], v[28:31]
	v_mfma_f32_16x16x32_bf16 v[16:19], v[142:145], v[198:201], v[16:19]
	v_mfma_f32_16x16x32_bf16 v[12:15], v[166:169], v[198:201], v[12:15]
	v_mfma_f32_16x16x32_bf16 v[60:63], v[162:165], v[178:181], v[60:63]
	v_mfma_f32_16x16x32_bf16 v[56:59], v[170:173], v[178:181], v[56:59]
	v_mfma_f32_16x16x32_bf16 v[48:51], v[162:165], v[186:189], v[48:51]
	v_mfma_f32_16x16x32_bf16 v[44:47], v[170:173], v[186:189], v[44:47]
	v_mfma_f32_16x16x32_bf16 v[32:35], v[162:165], v[194:197], v[32:35]
	v_mfma_f32_16x16x32_bf16 v[28:31], v[170:173], v[194:197], v[28:31]
	v_mfma_f32_16x16x32_bf16 v[16:19], v[162:165], v[202:205], v[16:19]
	v_mfma_f32_16x16x32_bf16 v[12:15], v[170:173], v[202:205], v[12:15]
	s_barrier
	s_setprio 0
	s_mov_b32 m0, s89
	v_lshl_add_u64 v[142:143], s[38:39], 0, v[132:133]
	global_load_lds_dwordx4 v[142:143], off
	v_lshl_add_u64 v[142:143], s[38:39], 0, v[128:129]
	s_mov_b32 m0, s88
	s_nop 0
	global_load_lds_dwordx4 v[142:143], off
	s_waitcnt vmcnt(6)
	s_setprio 1
	s_barrier
	v_mfma_f32_16x16x32_bf16 v[52:55], v[206:209], v[174:177], v[52:55]
	v_mfma_f32_16x16x32_bf16 v[40:43], v[214:217], v[174:177], v[40:43]
	v_mfma_f32_16x16x32_bf16 v[36:39], v[206:209], v[182:185], v[36:39]
	v_mfma_f32_16x16x32_bf16 v[24:27], v[214:217], v[182:185], v[24:27]
	v_mfma_f32_16x16x32_bf16 v[20:23], v[206:209], v[190:193], v[20:23]
	v_mfma_f32_16x16x32_bf16 v[8:11], v[214:217], v[190:193], v[8:11]
	v_mfma_f32_16x16x32_bf16 v[4:7], v[206:209], v[198:201], v[4:7]
	v_mfma_f32_16x16x32_bf16 v[0:3], v[214:217], v[198:201], v[0:3]
	v_mfma_f32_16x16x32_bf16 v[52:55], v[210:213], v[178:181], v[52:55]
	v_mfma_f32_16x16x32_bf16 v[40:43], v[220:223], v[178:181], v[40:43]
	v_mfma_f32_16x16x32_bf16 v[36:39], v[210:213], v[186:189], v[36:39]
	v_mfma_f32_16x16x32_bf16 v[24:27], v[220:223], v[186:189], v[24:27]
	v_mfma_f32_16x16x32_bf16 v[20:23], v[210:213], v[194:197], v[20:23]
	v_mfma_f32_16x16x32_bf16 v[8:11], v[220:223], v[194:197], v[8:11]
	v_mfma_f32_16x16x32_bf16 v[4:7], v[210:213], v[202:205], v[4:7]
	v_mfma_f32_16x16x32_bf16 v[0:3], v[220:223], v[202:205], v[0:3]
	s_andn2_b64 vcc, exec, s[36:37]
	s_mov_b64 s[38:39], -1
	s_mov_b64 s[36:37], 0
	s_mov_b64 s[40:41], 0x100
	s_barrier
	s_setprio 0
	s_cbranch_vccz .LBB0_537
	s_lshl_b32 s36, s4, 7
	s_ashr_i32 s37, s36, 31
	v_lshl_add_u32 v142, s34, 8, v139
	v_or_b32_e32 v157, s36, v138
	s_cmpk_gt_i32 s34, 0x181
	v_lshlrev_b32_e32 v136, 1, v138
	s_cbranch_scc1 .LBB0_540
	v_ashrrev_i32_e32 v143, 31, v142
	v_lshl_add_u64 v[144:145], v[142:143], 2, s[18:19]
	v_or_b32_e32 v158, 16, v142
	global_load_dword v148, v[144:145], off
	v_ashrrev_i32_e32 v159, 31, v158
	v_or_b32_e32 v150, 32, v142
	v_or_b32_e32 v144, 48, v142
	v_lshl_add_u64 v[146:147], v[158:159], 2, s[18:19]
	v_ashrrev_i32_e32 v151, 31, v150
	v_ashrrev_i32_e32 v145, 31, v144
	v_lshl_add_u64 v[162:163], v[150:151], 2, s[18:19]
	v_lshl_add_u64 v[164:165], v[144:145], 2, s[18:19]
	global_load_dword v161, v[146:147], off
	global_load_dword v172, v[162:163], off
	global_load_dword v173, v[164:165], off
	v_mul_hi_i32 v162, v142, s79
	v_lshrrev_b32_e32 v164, 31, v162
	v_ashrrev_i32_e32 v165, 11, v162
	v_lshlrev_b64 v[162:163], 10, v[142:143]
	v_add_u32_e32 v143, v165, v164
	v_mad_i32_i24 v166, v143, s80, v142
	v_mov_b64_e32 v[146:147], s[16:17]
	v_lshl_add_u32 v143, v143, 9, v157
	v_and_or_b32 v166, v166, -13, v152
	v_mad_i64_i32 v[164:165], s[4:5], v143, s81, v[146:147]
	v_ashrrev_i32_e32 v167, 31, v166
	v_lshl_add_u64 v[164:165], v[166:167], 1, v[164:165]
	v_add_co_u32_e32 v166, vcc, s64, v164
	s_lshl_b64 s[38:39], s[36:37], 1
	s_nop 0
	v_addc_co_u32_e32 v167, vcc, 0, v165, vcc
	v_add_co_u32_e32 v168, vcc, s65, v164
	v_lshl_add_u64 v[162:163], s[14:15], 0, v[162:163]
	s_nop 0
	v_addc_co_u32_e32 v169, vcc, 0, v165, vcc
	v_add_co_u32_e32 v170, vcc, s66, v164
	v_lshl_add_u64 v[162:163], v[162:163], 0, s[38:39]
	s_nop 0
	v_addc_co_u32_e32 v171, vcc, 0, v165, vcc
	v_lshl_add_u64 v[162:163], v[162:163], 0, v[136:137]
	s_waitcnt vmcnt(0)
; DI u16 f2bf(float x) { return (u16)(cvtpk(x, 0.f) & 0xffffu); }
; DI u32x4 pack8v(f32x4 a, f32x4 b) { return u32x4{cvtpk(a[0], a[1]), cvtpk(a[2], a[3]), cvtpk(b[0], b[1]), cvtpk(b[2], b[3])}; }
; DI int vt_pos(int p) { return (p & ~12) | ((p & 4) << 1) | ((p & 8) >> 1); }
;   DI void operator()(AccRef acc, const pg8::Unit& u, int wr, int wc, int fr, int fq) const {
;     ...
;       for (int m = 0; m < 4; ++m) rs[m] = ss[row0 + ai * 128 + m * 16];
; #pragma unroll
;       for (int m = 0; m < 4; ++m) rs[m] = rsqrtf(rs[m] * (1.f / 256.f) + EPS);
; #pragma unroll
;       for (int m = 0; m < 4; ++m) {
;         const int row = row0 + ai * 128 + m * 16;
;         const int s = row / L, p = row - s * L;
;         *(u32x4*)(kn + (size_t)row * 512 + head * 128 + w0) = pack8v(acc[ai][0][m][0] * rs[m], acc[ai][0][m][1] * rs[m]);
;         u16* vp = vt + (size_t)((s * 4 + head) * 128 + w0) * LP + vt_pos(p);
; #pragma unroll
;         for (int n = 0; n < 2; ++n)
; #pragma unroll
;           for (int e = 0; e < 4; ++e) vp[(size_t)(4 * n + e) * LP] = f2bf(acc[ai][1][m][n][e] * rs[m]);
;         asm volatile("" ::: "memory");
	v_fmamk_f32 v143, v148, 0x3b800000, v156
	v_mul_f32_e32 v148, 0x4b800000, v143
	v_cmp_gt_f32_e32 vcc, s78, v143
	v_fmamk_f32 v161, v161, 0x3b800000, v156
	v_fmamk_f32 v172, v172, 0x3b800000, v156
	v_fmamk_f32 v173, v173, 0x3b800000, v156
	v_cndmask_b32_e32 v143, v143, v148, vcc
	v_mul_f32_e32 v148, 0x4b800000, v161
	v_mul_f32_e32 v174, 0x4b800000, v172
	v_mul_f32_e32 v175, 0x4b800000, v173
	v_rsq_f32_e32 v143, v143
	v_cmp_gt_f32_e64 s[4:5], s78, v161
	v_cmp_gt_f32_e64 s[6:7], s78, v172
	v_cmp_gt_f32_e64 s[8:9], s78, v173
	v_cndmask_b32_e64 v148, v161, v148, s[4:5]
	v_cndmask_b32_e64 v161, v172, v174, s[6:7]
	v_cndmask_b32_e64 v172, v173, v175, s[8:9]
	v_rsq_f32_e32 v148, v148
	v_rsq_f32_e32 v161, v161
	v_rsq_f32_e32 v173, v172
	v_mul_f32_e32 v172, 0x45800000, v143
	v_cndmask_b32_e32 v172, v143, v172, vcc
	v_mul_f32_e32 v143, 0x45800000, v148
	v_mul_f32_e32 v175, 0x45800000, v161
	v_mul_f32_e32 v177, 0x45800000, v173
	v_pk_mul_f32 v[126:127], v[126:127], v[172:173] op_sel_hi:[1,0]
	v_pk_mul_f32 v[124:125], v[124:125], v[172:173] op_sel_hi:[1,0]
	v_pk_mul_f32 v[122:123], v[122:123], v[172:173] op_sel_hi:[1,0]
	v_pk_mul_f32 v[120:121], v[120:121], v[172:173] op_sel_hi:[1,0]
	v_cndmask_b32_e64 v174, v148, v143, s[4:5]
	v_cndmask_b32_e64 v176, v161, v175, s[6:7]
	v_cndmask_b32_e64 v148, v173, v177, s[8:9]
	v_mul_f32_e32 v143, v116, v172
	v_mul_f32_e32 v161, v117, v172
	v_mul_f32_e32 v173, v118, v172
	v_mul_f32_e32 v175, v119, v172
	v_cvt_pk_bf16_f32 v116, v124, v125
	v_cvt_pk_bf16_f32 v117, v126, v127
	v_cvt_pk_bf16_f32 v118, v120, v121
	v_cvt_pk_bf16_f32 v119, v122, v123
	v_mul_f32_e32 v104, v104, v172
	v_cvt_pk_bf16_f32 v120, v143, s0
	v_cvt_pk_bf16_f32 v121, v161, s0
	v_cvt_pk_bf16_f32 v122, v173, s0
	v_cvt_pk_bf16_f32 v123, v175, s0
	global_store_dwordx4 v[162:163], v[116:119], off
	global_store_short v[164:165], v120, off
	global_store_short v[166:167], v121, off offset:128
	global_store_short v[168:169], v122, off offset:256
	global_store_short v[170:171], v123, off offset:384
	v_add_co_u32_e32 v116, vcc, s70, v164
	v_cvt_pk_bf16_f32 v104, v104, s0
	s_nop 0
	v_addc_co_u32_e32 v117, vcc, 0, v165, vcc
	global_store_short v[116:117], v104, off offset:512
	v_mul_f32_e32 v104, v105, v172
	v_cvt_pk_bf16_f32 v116, v104, s0
	v_add_co_u32_e32 v104, vcc, s71, v164
	v_pk_mul_f32 v[108:109], v[108:109], v[174:175] op_sel_hi:[1,0]
	s_nop 0
	v_addc_co_u32_e32 v105, vcc, 0, v165, vcc
	global_store_short v[104:105], v116, off offset:640
	v_mul_f32_e32 v104, v106, v172
	v_cvt_pk_bf16_f32 v106, v104, s0
	v_add_co_u32_e32 v104, vcc, s75, v164
	v_pk_mul_f32 v[110:111], v[110:111], v[174:175] op_sel_hi:[1,0]
	s_nop 0
	v_addc_co_u32_e32 v105, vcc, 0, v165, vcc
	global_store_short v[104:105], v106, off offset:768
	v_mul_f32_e32 v104, v107, v172
	v_cvt_pk_bf16_f32 v106, v104, s0
	v_add_co_u32_e32 v104, vcc, s76, v164
	v_mul_f32_e32 v100, v100, v174
	s_nop 0
	v_addc_co_u32_e32 v105, vcc, 0, v165, vcc
	global_store_short v[104:105], v106, off offset:896
	v_mul_hi_i32 v104, v158, s79
	v_lshrrev_b32_e32 v105, 31, v104
	v_ashrrev_i32_e32 v104, 11, v104
	v_add_u32_e32 v116, v104, v105
	v_pk_mul_f32 v[106:107], v[114:115], v[174:175] op_sel_hi:[1,0]
	v_pk_mul_f32 v[104:105], v[112:113], v[174:175] op_sel_hi:[1,0]
	v_mad_i32_i24 v117, v116, s80, v158
	v_cvt_pk_bf16_f32 v104, v104, v105
	v_cvt_pk_bf16_f32 v105, v106, v107
	v_cvt_pk_bf16_f32 v106, v108, v109
	v_lshlrev_b64 v[108:109], 10, v[158:159]
	v_lshl_add_u64 v[108:109], s[14:15], 0, v[108:109]
	v_lshl_add_u64 v[108:109], v[108:109], 0, s[38:39]
	v_cvt_pk_bf16_f32 v107, v110, v111
	v_lshl_add_u64 v[108:109], v[108:109], 0, v[136:137]
	global_store_dwordx4 v[108:109], v[104:107], off
	v_cvt_pk_bf16_f32 v100, v100, s0
	v_mul_f32_e32 v88, v88, v174
	v_lshl_add_u32 v104, v116, 9, v157
	v_and_or_b32 v106, v117, -13, v152
	v_mad_i64_i32 v[104:105], s[4:5], v104, s81, v[146:147]
	v_ashrrev_i32_e32 v107, 31, v106
	v_lshl_add_u64 v[104:105], v[106:107], 1, v[104:105]
	global_store_short v[104:105], v100, off
	v_mul_f32_e32 v100, v101, v174
	v_cvt_pk_bf16_f32 v106, v100, s0
	v_add_co_u32_e32 v100, vcc, s64, v104
	v_cvt_pk_bf16_f32 v88, v88, s0
	s_nop 0
	v_addc_co_u32_e32 v101, vcc, 0, v105, vcc
	global_store_short v[100:101], v106, off offset:128
	v_mul_f32_e32 v100, v102, v174
	v_cvt_pk_bf16_f32 v102, v100, s0
	v_add_co_u32_e32 v100, vcc, s65, v104
	v_pk_mul_f32 v[92:93], v[92:93], v[176:177] op_sel_hi:[1,0]
	s_nop 0
	v_addc_co_u32_e32 v101, vcc, 0, v105, vcc
	global_store_short v[100:101], v102, off offset:256
	v_mul_f32_e32 v100, v103, v174
	v_cvt_pk_bf16_f32 v102, v100, s0
	v_add_co_u32_e32 v100, vcc, s66, v104
	v_pk_mul_f32 v[94:95], v[94:95], v[176:177] op_sel_hi:[1,0]
	s_nop 0
	v_addc_co_u32_e32 v101, vcc, 0, v105, vcc
	global_store_short v[100:101], v102, off offset:384
	v_add_co_u32_e32 v100, vcc, s70, v104
	v_mul_f32_e32 v84, v84, v176
	s_nop 0
	v_addc_co_u32_e32 v101, vcc, 0, v105, vcc
	global_store_short v[100:101], v88, off offset:512
	v_mul_f32_e32 v88, v89, v174
	v_cvt_pk_bf16_f32 v100, v88, s0
	v_add_co_u32_e32 v88, vcc, s71, v104
	v_cvt_pk_bf16_f32 v84, v84, s0
	s_nop 0
	v_addc_co_u32_e32 v89, vcc, 0, v105, vcc
	global_store_short v[88:89], v100, off offset:640
; DI u16 f2bf(float x) { return (u16)(cvtpk(x, 0.f) & 0xffffu); }
; DI u32x4 pack8v(f32x4 a, f32x4 b) { return u32x4{cvtpk(a[0], a[1]), cvtpk(a[2], a[3]), cvtpk(b[0], b[1]), cvtpk(b[2], b[3])}; }
; DI int vt_pos(int p) { return (p & ~12) | ((p & 4) << 1) | ((p & 8) >> 1); }
;   DI void operator()(AccRef acc, const pg8::Unit& u, int wr, int wc, int fr, int fq) const {
;     ...
;       for (int m = 0; m < 4; ++m) {
;         const int row = row0 + ai * 128 + m * 16;
;         const int s = row / L, p = row - s * L;
;         *(u32x4*)(kn + (size_t)row * 512 + head * 128 + w0) = pack8v(acc[ai][0][m][0] * rs[m], acc[ai][0][m][1] * rs[m]);
;         u16* vp = vt + (size_t)((s * 4 + head) * 128 + w0) * LP + vt_pos(p);
; #pragma unroll
;         for (int n = 0; n < 2; ++n)
; #pragma unroll
;           for (int e = 0; e < 4; ++e) vp[(size_t)(4 * n + e) * LP] = f2bf(acc[ai][1][m][n][e] * rs[m]);
;         asm volatile("" ::: "memory");
	v_mul_f32_e32 v88, v90, v174
	v_cvt_pk_bf16_f32 v90, v88, s0
	v_add_co_u32_e32 v88, vcc, s75, v104
	v_mul_f32_e32 v72, v72, v176
	s_nop 0
	v_addc_co_u32_e32 v89, vcc, 0, v105, vcc
	global_store_short v[88:89], v90, off offset:768
	v_mul_f32_e32 v88, v91, v174
	v_cvt_pk_bf16_f32 v90, v88, s0
	v_add_co_u32_e32 v88, vcc, s76, v104
	v_cvt_pk_bf16_f32 v72, v72, s0
	s_nop 0
	v_addc_co_u32_e32 v89, vcc, 0, v105, vcc
	global_store_short v[88:89], v90, off offset:896
	v_mul_hi_i32 v88, v150, s79
	v_lshrrev_b32_e32 v89, 31, v88
	v_ashrrev_i32_e32 v88, 11, v88
	v_add_u32_e32 v100, v88, v89
	v_pk_mul_f32 v[90:91], v[98:99], v[176:177] op_sel_hi:[1,0]
	v_pk_mul_f32 v[88:89], v[96:97], v[176:177] op_sel_hi:[1,0]
	v_mad_i32_i24 v101, v100, s80, v150
	v_cvt_pk_bf16_f32 v88, v88, v89
	v_cvt_pk_bf16_f32 v89, v90, v91
	v_cvt_pk_bf16_f32 v90, v92, v93
	v_lshlrev_b64 v[92:93], 10, v[150:151]
	v_lshl_add_u64 v[92:93], s[14:15], 0, v[92:93]
	v_lshl_add_u64 v[92:93], v[92:93], 0, s[38:39]
	v_cvt_pk_bf16_f32 v91, v94, v95
	v_lshl_add_u64 v[92:93], v[92:93], 0, v[136:137]
	global_store_dwordx4 v[92:93], v[88:91], off
	v_pk_mul_f32 v[76:77], v[76:77], v[148:149] op_sel_hi:[1,0]
	v_pk_mul_f32 v[78:79], v[78:79], v[148:149] op_sel_hi:[1,0]
	v_lshl_add_u32 v88, v100, 9, v157
	v_and_or_b32 v90, v101, -13, v152
	v_mad_i64_i32 v[88:89], s[4:5], v88, s81, v[146:147]
	v_ashrrev_i32_e32 v91, 31, v90
	v_lshl_add_u64 v[88:89], v[90:91], 1, v[88:89]
	global_store_short v[88:89], v84, off
	v_mul_f32_e32 v84, v85, v176
	v_cvt_pk_bf16_f32 v90, v84, s0
	v_add_co_u32_e32 v84, vcc, s64, v88
	v_mul_f32_e32 v68, v68, v148
	s_nop 0
	v_addc_co_u32_e32 v85, vcc, 0, v89, vcc
	global_store_short v[84:85], v90, off offset:128
	v_mul_f32_e32 v84, v86, v176
	v_cvt_pk_bf16_f32 v86, v84, s0
	v_add_co_u32_e32 v84, vcc, s65, v88
	v_cvt_pk_bf16_f32 v68, v68, s0
	s_nop 0
	v_addc_co_u32_e32 v85, vcc, 0, v89, vcc
	global_store_short v[84:85], v86, off offset:256
	v_mul_f32_e32 v84, v87, v176
	v_cvt_pk_bf16_f32 v86, v84, s0
	v_add_co_u32_e32 v84, vcc, s66, v88
	v_mul_f32_e32 v64, v64, v148
	s_nop 0
	v_addc_co_u32_e32 v85, vcc, 0, v89, vcc
	global_store_short v[84:85], v86, off offset:384
	v_add_co_u32_e32 v84, vcc, s70, v88
	v_cvt_pk_bf16_f32 v64, v64, s0
	s_nop 0
	v_addc_co_u32_e32 v85, vcc, 0, v89, vcc
	global_store_short v[84:85], v72, off offset:512
	v_mul_f32_e32 v72, v73, v176
	v_cvt_pk_bf16_f32 v84, v72, s0
	v_add_co_u32_e32 v72, vcc, s71, v88
	s_nop 1
	v_addc_co_u32_e32 v73, vcc, 0, v89, vcc
	global_store_short v[72:73], v84, off offset:640
	v_mul_f32_e32 v72, v74, v176
	v_cvt_pk_bf16_f32 v74, v72, s0
	v_add_co_u32_e32 v72, vcc, s75, v88
	s_nop 1
	v_addc_co_u32_e32 v73, vcc, 0, v89, vcc
	global_store_short v[72:73], v74, off offset:768
	v_mul_f32_e32 v72, v75, v176
	v_cvt_pk_bf16_f32 v74, v72, s0
	v_add_co_u32_e32 v72, vcc, s76, v88
	s_nop 1
	v_addc_co_u32_e32 v73, vcc, 0, v89, vcc
	global_store_short v[72:73], v74, off offset:896
	v_mul_hi_i32 v72, v144, s79
	v_lshrrev_b32_e32 v73, 31, v72
	v_ashrrev_i32_e32 v72, 11, v72
	v_add_u32_e32 v84, v72, v73
	v_pk_mul_f32 v[74:75], v[82:83], v[148:149] op_sel_hi:[1,0]
	v_pk_mul_f32 v[72:73], v[80:81], v[148:149] op_sel_hi:[1,0]
	v_mad_i32_i24 v85, v84, s80, v144
	v_cvt_pk_bf16_f32 v72, v72, v73
	v_cvt_pk_bf16_f32 v73, v74, v75
	v_cvt_pk_bf16_f32 v74, v76, v77
	v_lshlrev_b64 v[76:77], 10, v[144:145]
	v_lshl_add_u64 v[76:77], s[14:15], 0, v[76:77]
	v_lshl_add_u64 v[76:77], v[76:77], 0, s[38:39]
	v_cvt_pk_bf16_f32 v75, v78, v79
	v_lshl_add_u64 v[76:77], v[76:77], 0, v[136:137]
	global_store_dwordx4 v[76:77], v[72:75], off
	s_nop 1
	v_lshl_add_u32 v72, v84, 9, v157
	v_and_or_b32 v74, v85, -13, v152
	v_mad_i64_i32 v[72:73], s[4:5], v72, s81, v[146:147]
	v_ashrrev_i32_e32 v75, 31, v74
	v_lshl_add_u64 v[72:73], v[74:75], 1, v[72:73]
	global_store_short v[72:73], v68, off
	v_mul_f32_e32 v68, v69, v148
	v_cvt_pk_bf16_f32 v74, v68, s0
	v_add_co_u32_e32 v68, vcc, s64, v72
	s_nop 1
	v_addc_co_u32_e32 v69, vcc, 0, v73, vcc
	global_store_short v[68:69], v74, off offset:128
	v_mul_f32_e32 v68, v70, v148
	v_cvt_pk_bf16_f32 v70, v68, s0
	v_add_co_u32_e32 v68, vcc, s65, v72
	s_nop 1
	v_addc_co_u32_e32 v69, vcc, 0, v73, vcc
	global_store_short v[68:69], v70, off offset:256
	v_mul_f32_e32 v68, v71, v148
	v_cvt_pk_bf16_f32 v70, v68, s0
	v_add_co_u32_e32 v68, vcc, s66, v72
	s_nop 1
	v_addc_co_u32_e32 v69, vcc, 0, v73, vcc
	global_store_short v[68:69], v70, off offset:384
	v_add_co_u32_e32 v68, vcc, s70, v72
	s_nop 1
	v_addc_co_u32_e32 v69, vcc, 0, v73, vcc
	global_store_short v[68:69], v64, off offset:512
	v_mul_f32_e32 v64, v65, v148
	v_cvt_pk_bf16_f32 v68, v64, s0
	v_add_co_u32_e32 v64, vcc, s71, v72
	s_nop 1
	v_addc_co_u32_e32 v65, vcc, 0, v73, vcc
	global_store_short v[64:65], v68, off offset:640
	v_mul_f32_e32 v64, v66, v148
	v_cvt_pk_bf16_f32 v66, v64, s0
	v_add_co_u32_e32 v64, vcc, 0xc000, v72
	s_nop 1
	v_addc_co_u32_e32 v65, vcc, 0, v73, vcc
	global_store_short v[64:65], v66, off offset:768
	v_mul_f32_e32 v64, v67, v148
	v_cvt_pk_bf16_f32 v66, v64, s0
	v_add_co_u32_e32 v64, vcc, 0xe000, v72
	s_nop 1
	v_addc_co_u32_e32 v65, vcc, 0, v73, vcc
	global_store_short v[64:65], v66, off offset:896

; #define PG8_STAGE(bufoff, gbase, voff) do { _Pragma("unroll") for (int _i = 0; _i < 2; ++_i) \
;     __builtin_amdgcn_global_load_lds((const unsigned*)((const char*)(gbase) + (voff)[_i]), (PG8_LAS unsigned*)(lds + (bufoff) + ldsw + _i * 8192), 16, 0, 0); } while (0)
; #define PG8_LDA(dst, b, h) do { _Pragma("unroll") for (int m = 0; m < 4; ++m) _Pragma("unroll") for (int k = 0; k < 2; ++k) dst[m][k] = *(const PG8_LAS bf16x8*)(lds + PG8_SA(b, h) + aoff + m * 2048 + k * 1024); } while (0)
; #define PG8_LDB(dst, b, h) do { _Pragma("unroll") for (int n = 0; n < 2; ++n) _Pragma("unroll") for (int k = 0; k < 2; ++k) dst[n][k] = *(const PG8_LAS bf16x8*)(lds + PG8_SB(b, h) + boff + n * 2048 + k * 1024); } while (0)
; #define PG8_MMA(ai, bj, At, Bt) do { __builtin_amdgcn_s_setprio(1); _Pragma("unroll") for (int m = 0; m < 4; ++m) _Pragma("unroll") for (int n = 0; n < 2; ++n) _Pragma("unroll") for (int k = 0; k < 2; ++k) \
;     acc[ai][bj][m][n] = __builtin_amdgcn_mfma_f32_16x16x32_bf16(Bt[n][k], At[m][k], acc[ai][bj][m][n], 0, 0, 0); __builtin_amdgcn_s_setprio(0); } while (0)
; template <class Epi>
; DI void gemm_phase(PG8_LAS unsigned char* lds, const Gemm g, const StaticOrder& S, const Epi& E, const int wv) {
;     ...
;       PG8_LDB(B0, 0, 0); PG8_SCHED; PG8_LDA(At, 0, 0); PG8_STAGE(PG8_SA(1, 1), a1 + hstep, voffA);
;       PG8_WAIT_L(8); PG8_BAR; PG8_WAIT_L(0); PG8_MMA(0, 0, At, B0); PG8_BAR; PG8_SCHED;
;       PG8_LDB(B1, 0, 1); PG8_STAGE(PG8_SB(0, 0), b2, voffB);
;       PG8_BAR; PG8_WAIT_L(0); PG8_MMA(0, 1, At, B1); PG8_BAR;
;       PG8_LDA(At, 0, 1); PG8_STAGE(PG8_SA(0, 0), a2, voffA);
;       PG8_BAR; PG8_WAIT_L(0); PG8_MMA(1, 0, At, B0); PG8_BAR; PG8_SCHED;
;       PG8_STAGE(PG8_SB(0, 1), b2 + hstep, voffB);
;       PG8_WAIT_V(6); PG8_BAR; PG8_MMA(1, 1, At, B1); PG8_BAR;
;       PG8_LDB(B0, 1, 0); PG8_SCHED; PG8_LDA(At, 1, 0); PG8_STAGE(PG8_SA(0, 1), a2 + hstep, voffA);
;       PG8_WAIT_L(8); PG8_BAR; PG8_WAIT_L(0); PG8_MMA(0, 0, At, B0); PG8_BAR; PG8_SCHED;
;       PG8_LDB(B1, 1, 1); PG8_STAGE(PG8_SB(1, 0), b3, voffB);
;       PG8_BAR; PG8_WAIT_L(0); PG8_MMA(0, 1, At, B1); PG8_BAR;
;       PG8_LDA(At, 1, 1); PG8_STAGE(PG8_SA(1, 0), a3, voffA);
;       PG8_BAR; PG8_WAIT_L(0); PG8_MMA(1, 0, At, B0); PG8_BAR; PG8_SCHED;
;       PG8_STAGE(PG8_SB(1, 1), b3 + hstep, voffB);
;       PG8_WAIT_V(6); PG8_BAR; PG8_MMA(1, 1, At, B1); PG8_BAR;
.LBB0_770:
	ds_read_b128 v[128:131], v223
	ds_read_b128 v[132:135], v223 offset:1024
	ds_read_b128 v[136:139], v223 offset:2048
	ds_read_b128 v[140:143], v223 offset:3072
	s_add_u32 s42, s40, 0xfffc0080
	s_addc_u32 s43, s41, -1
	s_cmp_eq_u32 s76, 12
	s_cselect_b32 s45, s29, s43
	s_cselect_b32 s44, s37, s42
	s_cselect_b32 s43, s27, s75
	s_cselect_b32 s42, s39, s74
	v_lshl_add_u64 v[176:177], s[40:41], 0, v[202:203]
	s_add_i32 m0, s53, 0xc000
	ds_read_b128 v[144:147], v224
	ds_read_b128 v[148:151], v224 offset:1024
	ds_read_b128 v[152:155], v224 offset:2048
	ds_read_b128 v[156:159], v224 offset:3072
	ds_read_b128 v[160:163], v224 offset:4096
	ds_read_b128 v[164:167], v224 offset:5120
	ds_read_b128 v[168:171], v224 offset:6144
	ds_read_b128 v[172:175], v224 offset:7168
	global_load_lds_dwordx4 v[176:177], off
	v_lshl_add_u64 v[176:177], s[40:41], 0, v[204:205]
	s_add_i32 m0, s53, 0xe000
	s_nop 0
	global_load_lds_dwordx4 v[176:177], off
	s_waitcnt lgkmcnt(8)
	s_setprio 1
	s_barrier
	s_waitcnt lgkmcnt(0)
	s_waitcnt lgkmcnt(0)
	v_mfma_f32_16x16x32_bf16 v[124:127], v[128:131], v[144:147], v[124:127]
	v_mfma_f32_16x16x32_bf16 v[120:123], v[136:139], v[144:147], v[120:123]
	v_mfma_f32_16x16x32_bf16 v[108:111], v[128:131], v[152:155], v[108:111]
	v_mfma_f32_16x16x32_bf16 v[104:107], v[136:139], v[152:155], v[104:107]
	v_mfma_f32_16x16x32_bf16 v[92:95], v[128:131], v[160:163], v[92:95]
	v_mfma_f32_16x16x32_bf16 v[88:91], v[136:139], v[160:163], v[88:91]
	v_mfma_f32_16x16x32_bf16 v[76:79], v[128:131], v[168:171], v[76:79]
	v_mfma_f32_16x16x32_bf16 v[72:75], v[136:139], v[168:171], v[72:75]
	v_mfma_f32_16x16x32_bf16 v[124:127], v[132:135], v[148:151], v[124:127]
	v_mfma_f32_16x16x32_bf16 v[120:123], v[140:143], v[148:151], v[120:123]
	v_mfma_f32_16x16x32_bf16 v[108:111], v[132:135], v[156:159], v[108:111]
	v_mfma_f32_16x16x32_bf16 v[104:107], v[140:143], v[156:159], v[104:107]
	v_mfma_f32_16x16x32_bf16 v[92:95], v[132:135], v[164:167], v[92:95]
	v_mfma_f32_16x16x32_bf16 v[88:91], v[140:143], v[164:167], v[88:91]
	v_mfma_f32_16x16x32_bf16 v[76:79], v[132:135], v[172:175], v[76:79]
	v_mfma_f32_16x16x32_bf16 v[72:75], v[140:143], v[172:175], v[72:75]
	s_barrier
	s_setprio 0
	s_add_i32 s77, s66, s52
	v_lshl_add_u64 v[208:209], s[42:43], 0, v[194:195]
	s_mov_b32 m0, s77
	ds_read_b128 v[176:179], v225
	ds_read_b128 v[180:183], v225 offset:1024
	ds_read_b128 v[184:187], v225 offset:2048
	ds_read_b128 v[188:191], v225 offset:3072
	global_load_lds_dwordx4 v[208:209], off
	v_lshl_add_u64 v[210:211], s[42:43], 0, v[198:199]
	s_add_i32 m0, s77, 0x2000
	s_nop 0
	global_load_lds_dwordx4 v[210:211], off
	s_setprio 1
	s_barrier
	s_waitcnt lgkmcnt(0)
	v_mfma_f32_16x16x32_bf16 v[116:119], v[176:179], v[144:147], v[116:119]
	v_mfma_f32_16x16x32_bf16 v[112:115], v[184:187], v[144:147], v[112:115]
	v_mfma_f32_16x16x32_bf16 v[100:103], v[176:179], v[152:155], v[100:103]
	v_mfma_f32_16x16x32_bf16 v[96:99], v[184:187], v[152:155], v[96:99]
	v_mfma_f32_16x16x32_bf16 v[84:87], v[176:179], v[160:163], v[84:87]
	v_mfma_f32_16x16x32_bf16 v[80:83], v[184:187], v[160:163], v[80:83]
	v_mfma_f32_16x16x32_bf16 v[68:71], v[176:179], v[168:171], v[68:71]
	v_mfma_f32_16x16x32_bf16 v[64:67], v[184:187], v[168:171], v[64:67]
	v_mfma_f32_16x16x32_bf16 v[116:119], v[180:183], v[148:151], v[116:119]
	v_mfma_f32_16x16x32_bf16 v[112:115], v[188:191], v[148:151], v[112:115]
	v_mfma_f32_16x16x32_bf16 v[100:103], v[180:183], v[156:159], v[100:103]
	v_mfma_f32_16x16x32_bf16 v[96:99], v[188:191], v[156:159], v[96:99]
	v_mfma_f32_16x16x32_bf16 v[84:87], v[180:183], v[164:167], v[84:87]
	v_mfma_f32_16x16x32_bf16 v[80:83], v[188:191], v[164:167], v[80:83]
	v_mfma_f32_16x16x32_bf16 v[68:71], v[180:183], v[172:175], v[68:71]
	v_mfma_f32_16x16x32_bf16 v[64:67], v[188:191], v[172:175], v[64:67]
	s_mov_b32 m0, s53
	v_lshl_add_u64 v[212:213], s[44:45], 0, v[192:193]
	s_barrier
	s_setprio 0
	ds_read_b128 v[144:147], v224 offset:16384
	ds_read_b128 v[148:151], v224 offset:17408
	ds_read_b128 v[152:155], v224 offset:18432
	ds_read_b128 v[156:159], v224 offset:19456
	ds_read_b128 v[160:163], v224 offset:20480
	ds_read_b128 v[164:167], v224 offset:21504
	ds_read_b128 v[168:171], v224 offset:22528
	ds_read_b128 v[172:175], v224 offset:23552
	global_load_lds_dwordx4 v[212:213], off
	v_lshl_add_u64 v[214:215], s[44:45], 0, v[196:197]
	s_mov_b32 m0, s54
	s_nop 0
	global_load_lds_dwordx4 v[214:215], off
	s_setprio 1
	s_barrier
	s_waitcnt lgkmcnt(0)
	v_mfma_f32_16x16x32_bf16 v[60:63], v[128:131], v[144:147], v[60:63]
	v_mfma_f32_16x16x32_bf16 v[56:59], v[136:139], v[144:147], v[56:59]
	v_mfma_f32_16x16x32_bf16 v[44:47], v[128:131], v[152:155], v[44:47]
	v_mfma_f32_16x16x32_bf16 v[40:43], v[136:139], v[152:155], v[40:43]
	v_mfma_f32_16x16x32_bf16 v[28:31], v[128:131], v[160:163], v[28:31]
	v_mfma_f32_16x16x32_bf16 v[24:27], v[136:139], v[160:163], v[24:27]
	v_mfma_f32_16x16x32_bf16 v[12:15], v[128:131], v[168:171], v[12:15]
	v_mfma_f32_16x16x32_bf16 v[8:11], v[136:139], v[168:171], v[8:11]
	v_mfma_f32_16x16x32_bf16 v[60:63], v[132:135], v[148:151], v[60:63]
	v_mfma_f32_16x16x32_bf16 v[56:59], v[140:143], v[148:151], v[56:59]
	v_mfma_f32_16x16x32_bf16 v[44:47], v[132:135], v[156:159], v[44:47]
	v_mfma_f32_16x16x32_bf16 v[40:43], v[140:143], v[156:159], v[40:43]
	v_mfma_f32_16x16x32_bf16 v[28:31], v[132:135], v[164:167], v[28:31]
	v_mfma_f32_16x16x32_bf16 v[24:27], v[140:143], v[164:167], v[24:27]
	v_mfma_f32_16x16x32_bf16 v[12:15], v[132:135], v[172:175], v[12:15]
	v_mfma_f32_16x16x32_bf16 v[8:11], v[140:143], v[172:175], v[8:11]
	s_barrier
; #define PG8_STAGE(bufoff, gbase, voff) do { _Pragma("unroll") for (int _i = 0; _i < 2; ++_i) \
;     __builtin_amdgcn_global_load_lds((const unsigned*)((const char*)(gbase) + (voff)[_i]), (PG8_LAS unsigned*)(lds + (bufoff) + ldsw + _i * 8192), 16, 0, 0); } while (0)
; #define PG8_LDA(dst, b, h) do { _Pragma("unroll") for (int m = 0; m < 4; ++m) _Pragma("unroll") for (int k = 0; k < 2; ++k) dst[m][k] = *(const PG8_LAS bf16x8*)(lds + PG8_SA(b, h) + aoff + m * 2048 + k * 1024); } while (0)
; #define PG8_LDB(dst, b, h) do { _Pragma("unroll") for (int n = 0; n < 2; ++n) _Pragma("unroll") for (int k = 0; k < 2; ++k) dst[n][k] = *(const PG8_LAS bf16x8*)(lds + PG8_SB(b, h) + boff + n * 2048 + k * 1024); } while (0)
; #define PG8_MMA(ai, bj, At, Bt) do { __builtin_amdgcn_s_setprio(1); _Pragma("unroll") for (int m = 0; m < 4; ++m) _Pragma("unroll") for (int n = 0; n < 2; ++n) _Pragma("unroll") for (int k = 0; k < 2; ++k) \
;     acc[ai][bj][m][n] = __builtin_amdgcn_mfma_f32_16x16x32_bf16(Bt[n][k], At[m][k], acc[ai][bj][m][n], 0, 0, 0); __builtin_amdgcn_s_setprio(0); } while (0)
; template <class Epi>
; DI void gemm_phase(PG8_LAS unsigned char* lds, const Gemm g, const StaticOrder& S, const Epi& E, const int wv) {
;     ...
;       PG8_LDB(B0, 0, 0); PG8_SCHED; PG8_LDA(At, 0, 0); PG8_STAGE(PG8_SA(1, 1), a1 + hstep, voffA);
;       PG8_WAIT_L(8); PG8_BAR; PG8_WAIT_L(0); PG8_MMA(0, 0, At, B0); PG8_BAR; PG8_SCHED;
;       PG8_LDB(B1, 0, 1); PG8_STAGE(PG8_SB(0, 0), b2, voffB);
;       PG8_BAR; PG8_WAIT_L(0); PG8_MMA(0, 1, At, B1); PG8_BAR;
;       PG8_LDA(At, 0, 1); PG8_STAGE(PG8_SA(0, 0), a2, voffA);
;       PG8_BAR; PG8_WAIT_L(0); PG8_MMA(1, 0, At, B0); PG8_BAR; PG8_SCHED;
;       PG8_STAGE(PG8_SB(0, 1), b2 + hstep, voffB);
;       PG8_WAIT_V(6); PG8_BAR; PG8_MMA(1, 1, At, B1); PG8_BAR;
;       PG8_LDB(B0, 1, 0); PG8_SCHED; PG8_LDA(At, 1, 0); PG8_STAGE(PG8_SA(0, 1), a2 + hstep, voffA);
;       PG8_WAIT_L(8); PG8_BAR; PG8_WAIT_L(0); PG8_MMA(0, 0, At, B0); PG8_BAR; PG8_SCHED;
;       PG8_LDB(B1, 1, 1); PG8_STAGE(PG8_SB(1, 0), b3, voffB);
;       PG8_BAR; PG8_WAIT_L(0); PG8_MMA(0, 1, At, B1); PG8_BAR;
;       PG8_LDA(At, 1, 1); PG8_STAGE(PG8_SA(1, 0), a3, voffA);
;       PG8_BAR; PG8_WAIT_L(0); PG8_MMA(1, 0, At, B0); PG8_BAR; PG8_SCHED;
;       PG8_STAGE(PG8_SB(1, 1), b3 + hstep, voffB);
;       PG8_WAIT_V(6); PG8_BAR; PG8_MMA(1, 1, At, B1); PG8_BAR;
	s_setprio 0
	s_add_u32 s78, s42, 0x40000
	s_addc_u32 s79, s43, 0
	s_add_i32 s77, s67, s52
	v_lshl_add_u64 v[128:129], s[78:79], 0, v[194:195]
	s_mov_b32 m0, s77
	s_nop 0
	global_load_lds_dwordx4 v[128:129], off
	v_lshl_add_u64 v[128:129], s[78:79], 0, v[198:199]
	s_add_i32 m0, s77, 0x2000
	s_nop 0
	global_load_lds_dwordx4 v[128:129], off
	s_waitcnt vmcnt(6)
	s_setprio 1
	s_barrier
	v_mfma_f32_16x16x32_bf16 v[52:55], v[176:179], v[144:147], v[52:55]
	v_mfma_f32_16x16x32_bf16 v[48:51], v[184:187], v[144:147], v[48:51]
	v_mfma_f32_16x16x32_bf16 v[36:39], v[176:179], v[152:155], v[36:39]
	v_mfma_f32_16x16x32_bf16 v[32:35], v[184:187], v[152:155], v[32:35]
	v_mfma_f32_16x16x32_bf16 v[20:23], v[176:179], v[160:163], v[20:23]
	v_mfma_f32_16x16x32_bf16 v[16:19], v[184:187], v[160:163], v[16:19]
	v_mfma_f32_16x16x32_bf16 v[4:7], v[176:179], v[168:171], v[4:7]
	v_mfma_f32_16x16x32_bf16 v[0:3], v[184:187], v[168:171], v[0:3]
	v_mfma_f32_16x16x32_bf16 v[52:55], v[180:183], v[148:151], v[52:55]
	v_mfma_f32_16x16x32_bf16 v[48:51], v[188:191], v[148:151], v[48:51]
	v_mfma_f32_16x16x32_bf16 v[36:39], v[180:183], v[156:159], v[36:39]
	v_mfma_f32_16x16x32_bf16 v[32:35], v[188:191], v[156:159], v[32:35]
	v_mfma_f32_16x16x32_bf16 v[20:23], v[180:183], v[164:167], v[20:23]
	v_mfma_f32_16x16x32_bf16 v[16:19], v[188:191], v[164:167], v[16:19]
	v_mfma_f32_16x16x32_bf16 v[4:7], v[180:183], v[172:175], v[4:7]
	v_mfma_f32_16x16x32_bf16 v[0:3], v[188:191], v[172:175], v[0:3]
	s_add_i32 s77, 0, 0x18000
	v_add_u32_e32 v140, s77, v221
	s_barrier
	s_setprio 0
	ds_read_b128 v[128:131], v140
	ds_read_b128 v[132:135], v140 offset:1024
	ds_read_b128 v[136:139], v140 offset:2048
	ds_read_b128 v[140:143], v140 offset:3072
	s_add_u32 s44, s44, 0x40000
	s_addc_u32 s45, s45, 0
	s_mov_b32 m0, s55
	v_lshl_add_u64 v[176:177], s[44:45], 0, v[192:193]
	ds_read_b128 v[144:147], v224 offset:32768
	ds_read_b128 v[148:151], v224 offset:33792
	ds_read_b128 v[152:155], v224 offset:34816
	ds_read_b128 v[156:159], v224 offset:35840
	ds_read_b128 v[160:163], v224 offset:36864
	ds_read_b128 v[164:167], v224 offset:37888
	ds_read_b128 v[168:171], v224 offset:38912
	ds_read_b128 v[172:175], v224 offset:39936
	global_load_lds_dwordx4 v[176:177], off
	v_lshl_add_u64 v[176:177], s[44:45], 0, v[196:197]
	s_mov_b32 m0, s57
	s_nop 0
	global_load_lds_dwordx4 v[176:177], off
	s_waitcnt lgkmcnt(8)
	s_setprio 1
	s_barrier
	s_waitcnt lgkmcnt(0)
	s_waitcnt lgkmcnt(0)
	v_mfma_f32_16x16x32_bf16 v[124:127], v[128:131], v[144:147], v[124:127]
	v_mfma_f32_16x16x32_bf16 v[120:123], v[136:139], v[144:147], v[120:123]
	v_mfma_f32_16x16x32_bf16 v[108:111], v[128:131], v[152:155], v[108:111]
	v_mfma_f32_16x16x32_bf16 v[104:107], v[136:139], v[152:155], v[104:107]
	v_mfma_f32_16x16x32_bf16 v[92:95], v[128:131], v[160:163], v[92:95]
	v_mfma_f32_16x16x32_bf16 v[88:91], v[136:139], v[160:163], v[88:91]
	v_mfma_f32_16x16x32_bf16 v[76:79], v[128:131], v[168:171], v[76:79]
	v_mfma_f32_16x16x32_bf16 v[72:75], v[136:139], v[168:171], v[72:75]
	v_mfma_f32_16x16x32_bf16 v[124:127], v[132:135], v[148:151], v[124:127]
	v_mfma_f32_16x16x32_bf16 v[120:123], v[140:143], v[148:151], v[120:123]
	v_mfma_f32_16x16x32_bf16 v[108:111], v[132:135], v[156:159], v[108:111]
	v_mfma_f32_16x16x32_bf16 v[104:107], v[140:143], v[156:159], v[104:107]
	v_mfma_f32_16x16x32_bf16 v[92:95], v[132:135], v[164:167], v[92:95]
	v_mfma_f32_16x16x32_bf16 v[88:91], v[140:143], v[164:167], v[88:91]
	v_mfma_f32_16x16x32_bf16 v[76:79], v[132:135], v[172:175], v[76:79]
	v_mfma_f32_16x16x32_bf16 v[72:75], v[140:143], v[172:175], v[72:75]
	s_barrier
	s_setprio 0
	s_add_i32 s44, 0, 0x1c000
	s_add_i32 s45, s77, s52
	v_add_u32_e32 v188, s44, v221
	v_lshl_add_u64 v[208:209], v[208:209], 0, s[22:23]
	s_mov_b32 m0, s45
	ds_read_b128 v[176:179], v188
	ds_read_b128 v[180:183], v188 offset:1024
	ds_read_b128 v[184:187], v188 offset:2048
	ds_read_b128 v[188:191], v188 offset:3072
	global_load_lds_dwordx4 v[208:209], off
	v_lshl_add_u64 v[208:209], v[210:211], 0, s[22:23]
	s_add_i32 m0, s45, 0x2000
	s_nop 0
	global_load_lds_dwordx4 v[208:209], off
	s_setprio 1
	s_barrier
	s_waitcnt lgkmcnt(0)
	s_waitcnt lgkmcnt(0)
	v_mfma_f32_16x16x32_bf16 v[116:119], v[176:179], v[144:147], v[116:119]
	v_mfma_f32_16x16x32_bf16 v[112:115], v[184:187], v[144:147], v[112:115]
	v_mfma_f32_16x16x32_bf16 v[100:103], v[176:179], v[152:155], v[100:103]
	v_mfma_f32_16x16x32_bf16 v[96:99], v[184:187], v[152:155], v[96:99]
	v_mfma_f32_16x16x32_bf16 v[84:87], v[176:179], v[160:163], v[84:87]
	v_mfma_f32_16x16x32_bf16 v[80:83], v[184:187], v[160:163], v[80:83]
	v_mfma_f32_16x16x32_bf16 v[68:71], v[176:179], v[168:171], v[68:71]
	v_mfma_f32_16x16x32_bf16 v[64:67], v[184:187], v[168:171], v[64:67]
	v_mfma_f32_16x16x32_bf16 v[116:119], v[180:183], v[148:151], v[116:119]
	v_mfma_f32_16x16x32_bf16 v[112:115], v[188:191], v[148:151], v[112:115]
	v_mfma_f32_16x16x32_bf16 v[100:103], v[180:183], v[156:159], v[100:103]
	v_mfma_f32_16x16x32_bf16 v[96:99], v[188:191], v[156:159], v[96:99]
	v_mfma_f32_16x16x32_bf16 v[84:87], v[180:183], v[164:167], v[84:87]
	v_mfma_f32_16x16x32_bf16 v[80:83], v[188:191], v[164:167], v[80:83]
	v_mfma_f32_16x16x32_bf16 v[68:71], v[180:183], v[172:175], v[68:71]
	v_mfma_f32_16x16x32_bf16 v[64:67], v[188:191], v[172:175], v[64:67]
	s_mov_b32 m0, s59
	v_lshl_add_u64 v[208:209], v[212:213], 0, s[22:23]
	s_barrier
; #define PG8_STAGE(bufoff, gbase, voff) do { _Pragma("unroll") for (int _i = 0; _i < 2; ++_i) \
;     __builtin_amdgcn_global_load_lds((const unsigned*)((const char*)(gbase) + (voff)[_i]), (PG8_LAS unsigned*)(lds + (bufoff) + ldsw + _i * 8192), 16, 0, 0); } while (0)
; #define PG8_LDA(dst, b, h) do { _Pragma("unroll") for (int m = 0; m < 4; ++m) _Pragma("unroll") for (int k = 0; k < 2; ++k) dst[m][k] = *(const PG8_LAS bf16x8*)(lds + PG8_SA(b, h) + aoff + m * 2048 + k * 1024); } while (0)
; #define PG8_LDB(dst, b, h) do { _Pragma("unroll") for (int n = 0; n < 2; ++n) _Pragma("unroll") for (int k = 0; k < 2; ++k) dst[n][k] = *(const PG8_LAS bf16x8*)(lds + PG8_SB(b, h) + boff + n * 2048 + k * 1024); } while (0)
; #define PG8_MMA(ai, bj, At, Bt) do { __builtin_amdgcn_s_setprio(1); _Pragma("unroll") for (int m = 0; m < 4; ++m) _Pragma("unroll") for (int n = 0; n < 2; ++n) _Pragma("unroll") for (int k = 0; k < 2; ++k) \
;     acc[ai][bj][m][n] = __builtin_amdgcn_mfma_f32_16x16x32_bf16(Bt[n][k], At[m][k], acc[ai][bj][m][n], 0, 0, 0); __builtin_amdgcn_s_setprio(0); } while (0)
; #define PG8_WAIT_V(n) asm volatile("s_waitcnt vmcnt(" #n ")" ::: "memory")
; #define PG8_WAIT_L(n) asm volatile("s_waitcnt lgkmcnt(" #n ")" ::: "memory")
; #define PG8_BAR __builtin_amdgcn_s_barrier()
; DI const float* xrow(const Params& P, int t) {
;   int s = t / L, p = t - s * L;
;   if (p < NMETA) return P.meta + p * DM;
;   const float* base = s < 8 ? P.xp + (size_t)(s * SEQ) * DM : P.xs + (size_t)((s - 8) * SEQ) * DM;
;   return base + (size_t)(p - NMETA) * DM;
; }
; template <class Epi>
; DI void gemm_phase(PG8_LAS unsigned char* lds, const Gemm g, const StaticOrder& S, const Epi& E, const int wv) {
;     ...
;       PG8_WAIT_V(6); PG8_BAR; PG8_MMA(1, 1, At, B1); PG8_BAR;
;       PG8_LDB(B0, 1, 0); PG8_SCHED; PG8_LDA(At, 1, 0); PG8_STAGE(PG8_SA(0, 1), a2 + hstep, voffA);
;       PG8_WAIT_L(8); PG8_BAR; PG8_WAIT_L(0); PG8_MMA(0, 0, At, B0); PG8_BAR; PG8_SCHED;
;       PG8_LDB(B1, 1, 1); PG8_STAGE(PG8_SB(1, 0), b3, voffB);
;       PG8_BAR; PG8_WAIT_L(0); PG8_MMA(0, 1, At, B1); PG8_BAR;
;       PG8_LDA(At, 1, 1); PG8_STAGE(PG8_SA(1, 0), a3, voffA);
;       PG8_BAR; PG8_WAIT_L(0); PG8_MMA(1, 0, At, B0); PG8_BAR; PG8_SCHED;
;       PG8_STAGE(PG8_SB(1, 1), b3 + hstep, voffB);
;       PG8_WAIT_V(6); PG8_BAR; PG8_MMA(1, 1, At, B1); PG8_BAR;
;     }
;     E(acc, cur, wr, wc, fr, fq);
	s_setprio 0
	ds_read_b128 v[144:147], v224 offset:49152
	ds_read_b128 v[148:151], v224 offset:50176
	ds_read_b128 v[152:155], v224 offset:51200
	ds_read_b128 v[156:159], v224 offset:52224
	ds_read_b128 v[160:163], v224 offset:53248
	ds_read_b128 v[164:167], v224 offset:54272
	ds_read_b128 v[168:171], v224 offset:55296
	ds_read_b128 v[172:175], v224 offset:56320
	global_load_lds_dwordx4 v[208:209], off
	v_lshl_add_u64 v[208:209], v[214:215], 0, s[22:23]
	s_mov_b32 m0, s60
	s_nop 0
	global_load_lds_dwordx4 v[208:209], off
	s_setprio 1
	s_barrier
	s_waitcnt lgkmcnt(0)
	v_mfma_f32_16x16x32_bf16 v[60:63], v[128:131], v[144:147], v[60:63]
	v_mfma_f32_16x16x32_bf16 v[56:59], v[136:139], v[144:147], v[56:59]
	v_mfma_f32_16x16x32_bf16 v[44:47], v[128:131], v[152:155], v[44:47]
	v_mfma_f32_16x16x32_bf16 v[40:43], v[136:139], v[152:155], v[40:43]
	v_mfma_f32_16x16x32_bf16 v[28:31], v[128:131], v[160:163], v[28:31]
	v_mfma_f32_16x16x32_bf16 v[24:27], v[136:139], v[160:163], v[24:27]
	v_mfma_f32_16x16x32_bf16 v[12:15], v[128:131], v[168:171], v[12:15]
	v_mfma_f32_16x16x32_bf16 v[8:11], v[136:139], v[168:171], v[8:11]
	v_mfma_f32_16x16x32_bf16 v[60:63], v[132:135], v[148:151], v[60:63]
	v_mfma_f32_16x16x32_bf16 v[56:59], v[140:143], v[148:151], v[56:59]
	v_mfma_f32_16x16x32_bf16 v[44:47], v[132:135], v[156:159], v[44:47]
	v_mfma_f32_16x16x32_bf16 v[40:43], v[140:143], v[156:159], v[40:43]
	v_mfma_f32_16x16x32_bf16 v[28:31], v[132:135], v[164:167], v[28:31]
	v_mfma_f32_16x16x32_bf16 v[24:27], v[140:143], v[164:167], v[24:27]
	v_mfma_f32_16x16x32_bf16 v[12:15], v[132:135], v[172:175], v[12:15]
	v_mfma_f32_16x16x32_bf16 v[8:11], v[140:143], v[172:175], v[8:11]
	s_barrier
	s_setprio 0
	s_add_u32 s42, s42, 0x40080
	s_addc_u32 s43, s43, 0
	s_add_i32 s44, s44, s52
	v_lshl_add_u64 v[128:129], s[42:43], 0, v[194:195]
	s_mov_b32 m0, s44
	s_nop 0
	global_load_lds_dwordx4 v[128:129], off
	v_lshl_add_u64 v[128:129], s[42:43], 0, v[198:199]
	s_add_i32 m0, s44, 0x2000
	s_nop 0
	global_load_lds_dwordx4 v[128:129], off
	s_waitcnt vmcnt(6)
	s_setprio 1
	s_barrier
	v_mfma_f32_16x16x32_bf16 v[52:55], v[176:179], v[144:147], v[52:55]
	v_mfma_f32_16x16x32_bf16 v[48:51], v[184:187], v[144:147], v[48:51]
	v_mfma_f32_16x16x32_bf16 v[36:39], v[176:179], v[152:155], v[36:39]
	v_mfma_f32_16x16x32_bf16 v[32:35], v[184:187], v[152:155], v[32:35]
	v_mfma_f32_16x16x32_bf16 v[20:23], v[176:179], v[160:163], v[20:23]
	v_mfma_f32_16x16x32_bf16 v[16:19], v[184:187], v[160:163], v[16:19]
	v_mfma_f32_16x16x32_bf16 v[4:7], v[176:179], v[168:171], v[4:7]
	v_mfma_f32_16x16x32_bf16 v[0:3], v[184:187], v[168:171], v[0:3]
	v_mfma_f32_16x16x32_bf16 v[52:55], v[180:183], v[148:151], v[52:55]
	v_mfma_f32_16x16x32_bf16 v[48:51], v[188:191], v[148:151], v[48:51]
	v_mfma_f32_16x16x32_bf16 v[36:39], v[180:183], v[156:159], v[36:39]
	v_mfma_f32_16x16x32_bf16 v[32:35], v[188:191], v[156:159], v[32:35]
	v_mfma_f32_16x16x32_bf16 v[20:23], v[180:183], v[164:167], v[20:23]
	v_mfma_f32_16x16x32_bf16 v[16:19], v[188:191], v[164:167], v[16:19]
	v_mfma_f32_16x16x32_bf16 v[4:7], v[180:183], v[172:175], v[4:7]
	v_mfma_f32_16x16x32_bf16 v[0:3], v[188:191], v[172:175], v[0:3]
	s_add_i32 s76, s76, 2
	s_add_u32 s40, s40, 0x100
	s_addc_u32 s41, s41, 0
	s_add_u32 s74, s74, 0x100
	s_addc_u32 s75, s75, 0
	s_cmp_gt_u32 s76, 13
	s_barrier
	s_setprio 0
	s_cbranch_scc0 .LBB0_770
	v_lshl_or_b32 v208, s38, 8, v222
	v_lshl_add_u32 v210, s36, 8, v220
	s_cmpk_gt_i32 s36, 0x181
	v_ashrrev_i32_e32 v209, 31, v208
	s_cbranch_scc1 .LBB0_797
	v_mul_hi_i32 v128, v210, s68
	v_lshrrev_b32_e32 v129, 31, v128
	v_ashrrev_i32_e32 v128, 11, v128
	v_add_u32_e32 v131, v128, v129
	v_mad_i32_i24 v130, v131, s69, v210
	v_cmp_lt_i32_e32 vcc, 15, v130
	s_and_saveexec_b64 s[38:39], vcc
	s_xor_b64 s[38:39], exec, s[38:39]
	s_cbranch_execz .LBB0_774
	v_lshlrev_b32_e32 v128, 12, v131
	v_add_u32_e32 v131, 0xffff8000, v128
	v_cmp_gt_i32_e32 vcc, s70, v210
	v_ashrrev_i32_e32 v129, 31, v128
	v_mov_b32_e32 v132, s7
	v_cndmask_b32_e32 v128, v131, v128, vcc
	v_mov_b32_e32 v131, s9
	v_cndmask_b32_e32 v129, 0, v129, vcc
	v_cndmask_b32_e32 v133, v131, v132, vcc
	v_mov_b32_e32 v131, s8
	v_mov_b32_e32 v132, s6
	v_cndmask_b32_e32 v132, v131, v132, vcc
	v_lshlrev_b64 v[128:129], 12, v[128:129]
	v_add_u32_e32 v200, -16, v130
	v_lshl_add_u64 v[128:129], v[132:133], 0, v[128:129]
	v_lshlrev_b64 v[130:131], 12, v[200:201]
	v_lshl_add_u64 v[128:129], v[128:129], 0, v[130:131]

; #define PG8_STAGE(bufoff, gbase, voff) do { _Pragma("unroll") for (int _i = 0; _i < 2; ++_i) \
;     __builtin_amdgcn_global_load_lds((const unsigned*)((const char*)(gbase) + (voff)[_i]), (PG8_LAS unsigned*)(lds + (bufoff) + ldsw + _i * 8192), 16, 0, 0); } while (0)
; #define PG8_LDA(dst, b, h) do { _Pragma("unroll") for (int m = 0; m < 4; ++m) _Pragma("unroll") for (int k = 0; k < 2; ++k) dst[m][k] = *(const PG8_LAS bf16x8*)(lds + PG8_SA(b, h) + aoff + m * 2048 + k * 1024); } while (0)
; #define PG8_LDB(dst, b, h) do { _Pragma("unroll") for (int n = 0; n < 2; ++n) _Pragma("unroll") for (int k = 0; k < 2; ++k) dst[n][k] = *(const PG8_LAS bf16x8*)(lds + PG8_SB(b, h) + boff + n * 2048 + k * 1024); } while (0)
; #define PG8_MMA(ai, bj, At, Bt) do { __builtin_amdgcn_s_setprio(1); _Pragma("unroll") for (int m = 0; m < 4; ++m) _Pragma("unroll") for (int n = 0; n < 2; ++n) _Pragma("unroll") for (int k = 0; k < 2; ++k) \
;     acc[ai][bj][m][n] = __builtin_amdgcn_mfma_f32_16x16x32_bf16(Bt[n][k], At[m][k], acc[ai][bj][m][n], 0, 0, 0); __builtin_amdgcn_s_setprio(0); } while (0)
; template <class Epi>
; DI void gemm_phase(PG8_LAS unsigned char* lds, const Gemm g, const StaticOrder& S, const Epi& E, const int wv) {
;     ...
;       PG8_LDB(B0, 0, 0); PG8_SCHED; PG8_LDA(At, 0, 0); PG8_STAGE(PG8_SA(1, 1), a1 + hstep, voffA);
;       PG8_WAIT_L(8); PG8_BAR; PG8_WAIT_L(0); PG8_MMA(0, 0, At, B0); PG8_BAR; PG8_SCHED;
;       PG8_LDB(B1, 0, 1); PG8_STAGE(PG8_SB(0, 0), b2, voffB);
;       PG8_BAR; PG8_WAIT_L(0); PG8_MMA(0, 1, At, B1); PG8_BAR;
;       PG8_LDA(At, 0, 1); PG8_STAGE(PG8_SA(0, 0), a2, voffA);
;       PG8_BAR; PG8_WAIT_L(0); PG8_MMA(1, 0, At, B0); PG8_BAR; PG8_SCHED;
;       PG8_STAGE(PG8_SB(0, 1), b2 + hstep, voffB);
;       PG8_WAIT_V(6); PG8_BAR; PG8_MMA(1, 1, At, B1); PG8_BAR;
;       PG8_LDB(B0, 1, 0); PG8_SCHED; PG8_LDA(At, 1, 0); PG8_STAGE(PG8_SA(0, 1), a2 + hstep, voffA);
;       PG8_WAIT_L(8); PG8_BAR; PG8_WAIT_L(0); PG8_MMA(0, 0, At, B0); PG8_BAR; PG8_SCHED;
;       PG8_LDB(B1, 1, 1); PG8_STAGE(PG8_SB(1, 0), b3, voffB);
;       PG8_BAR; PG8_WAIT_L(0); PG8_MMA(0, 1, At, B1); PG8_BAR;
;       PG8_LDA(At, 1, 1); PG8_STAGE(PG8_SA(1, 0), a3, voffA);
;       PG8_BAR; PG8_WAIT_L(0); PG8_MMA(1, 0, At, B0); PG8_BAR; PG8_SCHED;
;       PG8_STAGE(PG8_SB(1, 1), b3 + hstep, voffB);
;       PG8_WAIT_V(6); PG8_BAR; PG8_MMA(1, 1, At, B1); PG8_BAR;
.LBB0_893:
	ds_read_b128 v[142:145], v155
	ds_read_b128 v[146:149], v155 offset:1024
	ds_read_b128 v[160:163], v155 offset:2048
	ds_read_b128 v[164:167], v155 offset:3072
	s_add_u32 s8, s6, 0xfffc0080
	s_addc_u32 s9, s7, -1
	s_cmp_eq_u32 s62, 12
	s_cselect_b32 s37, s5, s9
	s_cselect_b32 s36, s27, s8
	s_cselect_b32 s9, s25, s61
	s_cselect_b32 s8, s59, s60
	v_lshl_add_u64 v[150:151], s[6:7], 0, v[136:137]
	s_add_i32 m0, s35, 0xc000
	ds_read_b128 v[168:171], v156
	ds_read_b128 v[172:175], v156 offset:1024
	ds_read_b128 v[176:179], v156 offset:2048
	ds_read_b128 v[180:183], v156 offset:3072
	ds_read_b128 v[184:187], v156 offset:4096
	ds_read_b128 v[188:191], v156 offset:5120
	ds_read_b128 v[192:195], v156 offset:6144
	ds_read_b128 v[196:199], v156 offset:7168
	global_load_lds_dwordx4 v[150:151], off
	v_lshl_add_u64 v[150:151], s[6:7], 0, v[138:139]
	s_add_i32 m0, s35, 0xe000
	s_nop 0
	global_load_lds_dwordx4 v[150:151], off
	s_waitcnt lgkmcnt(8)
	s_setprio 1
	s_barrier
	s_waitcnt lgkmcnt(0)
	s_waitcnt lgkmcnt(0)
	v_mfma_f32_16x16x32_bf16 v[116:119], v[142:145], v[168:171], v[116:119]
	v_mfma_f32_16x16x32_bf16 v[112:115], v[160:163], v[168:171], v[112:115]
	v_mfma_f32_16x16x32_bf16 v[108:111], v[142:145], v[176:179], v[108:111]
	v_mfma_f32_16x16x32_bf16 v[100:103], v[160:163], v[176:179], v[100:103]
	v_mfma_f32_16x16x32_bf16 v[92:95], v[142:145], v[184:187], v[92:95]
	v_mfma_f32_16x16x32_bf16 v[84:87], v[160:163], v[184:187], v[84:87]
	v_mfma_f32_16x16x32_bf16 v[76:79], v[142:145], v[192:195], v[76:79]
	v_mfma_f32_16x16x32_bf16 v[68:71], v[160:163], v[192:195], v[68:71]
	v_mfma_f32_16x16x32_bf16 v[116:119], v[146:149], v[172:175], v[116:119]
	v_mfma_f32_16x16x32_bf16 v[112:115], v[164:167], v[172:175], v[112:115]
	v_mfma_f32_16x16x32_bf16 v[108:111], v[146:149], v[180:183], v[108:111]
	v_mfma_f32_16x16x32_bf16 v[100:103], v[164:167], v[180:183], v[100:103]
	v_mfma_f32_16x16x32_bf16 v[92:95], v[146:149], v[188:191], v[92:95]
	v_mfma_f32_16x16x32_bf16 v[84:87], v[164:167], v[188:191], v[84:87]
	v_mfma_f32_16x16x32_bf16 v[76:79], v[146:149], v[196:199], v[76:79]
	v_mfma_f32_16x16x32_bf16 v[68:71], v[164:167], v[196:199], v[68:71]
	s_barrier
	s_setprio 0
	s_add_i32 s63, s54, s45
	v_lshl_add_u64 v[150:151], s[8:9], 0, v[130:131]
	s_mov_b32 m0, s63
	ds_read_b128 v[200:203], v157
	ds_read_b128 v[204:207], v157 offset:1024
	ds_read_b128 v[208:211], v157 offset:2048
	ds_read_b128 v[212:215], v157 offset:3072
	global_load_lds_dwordx4 v[150:151], off
	v_lshl_add_u64 v[216:217], s[8:9], 0, v[134:135]
	s_add_i32 m0, s63, 0x2000
	s_nop 0
	global_load_lds_dwordx4 v[216:217], off
	s_setprio 1
	s_barrier
	s_waitcnt lgkmcnt(0)
	v_mfma_f32_16x16x32_bf16 v[124:127], v[200:203], v[168:171], v[124:127]
	v_mfma_f32_16x16x32_bf16 v[120:123], v[208:211], v[168:171], v[120:123]
	v_mfma_f32_16x16x32_bf16 v[104:107], v[200:203], v[176:179], v[104:107]
	v_mfma_f32_16x16x32_bf16 v[96:99], v[208:211], v[176:179], v[96:99]
	v_mfma_f32_16x16x32_bf16 v[88:91], v[200:203], v[184:187], v[88:91]
	v_mfma_f32_16x16x32_bf16 v[80:83], v[208:211], v[184:187], v[80:83]
	v_mfma_f32_16x16x32_bf16 v[72:75], v[200:203], v[192:195], v[72:75]
	v_mfma_f32_16x16x32_bf16 v[64:67], v[208:211], v[192:195], v[64:67]
	v_mfma_f32_16x16x32_bf16 v[124:127], v[204:207], v[172:175], v[124:127]
	v_mfma_f32_16x16x32_bf16 v[120:123], v[212:215], v[172:175], v[120:123]
	v_mfma_f32_16x16x32_bf16 v[104:107], v[204:207], v[180:183], v[104:107]
	v_mfma_f32_16x16x32_bf16 v[96:99], v[212:215], v[180:183], v[96:99]
	v_mfma_f32_16x16x32_bf16 v[88:91], v[204:207], v[188:191], v[88:91]
	v_mfma_f32_16x16x32_bf16 v[80:83], v[212:215], v[188:191], v[80:83]
	v_mfma_f32_16x16x32_bf16 v[72:75], v[204:207], v[196:199], v[72:75]
	v_mfma_f32_16x16x32_bf16 v[64:67], v[212:215], v[196:199], v[64:67]
	s_mov_b32 m0, s35
	v_lshl_add_u64 v[220:221], s[36:37], 0, v[128:129]
	s_barrier
	s_setprio 0
	ds_read_b128 v[168:171], v156 offset:16384
	ds_read_b128 v[172:175], v156 offset:17408
	ds_read_b128 v[176:179], v156 offset:18432
	ds_read_b128 v[180:183], v156 offset:19456
	ds_read_b128 v[184:187], v156 offset:20480
	ds_read_b128 v[188:191], v156 offset:21504
	ds_read_b128 v[192:195], v156 offset:22528
	ds_read_b128 v[196:199], v156 offset:23552
	global_load_lds_dwordx4 v[220:221], off
	v_lshl_add_u64 v[222:223], s[36:37], 0, v[132:133]
	s_mov_b32 m0, s46
	s_nop 0
	global_load_lds_dwordx4 v[222:223], off
	s_setprio 1
	s_barrier
	s_waitcnt lgkmcnt(0)
	v_mfma_f32_16x16x32_bf16 v[52:55], v[142:145], v[168:171], v[52:55]
	v_mfma_f32_16x16x32_bf16 v[48:51], v[160:163], v[168:171], v[48:51]
	v_mfma_f32_16x16x32_bf16 v[44:47], v[142:145], v[176:179], v[44:47]
	v_mfma_f32_16x16x32_bf16 v[36:39], v[160:163], v[176:179], v[36:39]
	v_mfma_f32_16x16x32_bf16 v[28:31], v[142:145], v[184:187], v[28:31]
	v_mfma_f32_16x16x32_bf16 v[20:23], v[160:163], v[184:187], v[20:23]
	v_mfma_f32_16x16x32_bf16 v[12:15], v[142:145], v[192:195], v[12:15]
	v_mfma_f32_16x16x32_bf16 v[4:7], v[160:163], v[192:195], v[4:7]
	v_mfma_f32_16x16x32_bf16 v[52:55], v[146:149], v[172:175], v[52:55]
	v_mfma_f32_16x16x32_bf16 v[48:51], v[164:167], v[172:175], v[48:51]
	v_mfma_f32_16x16x32_bf16 v[44:47], v[146:149], v[180:183], v[44:47]
	v_mfma_f32_16x16x32_bf16 v[36:39], v[164:167], v[180:183], v[36:39]
	v_mfma_f32_16x16x32_bf16 v[28:31], v[146:149], v[188:191], v[28:31]
	v_mfma_f32_16x16x32_bf16 v[20:23], v[164:167], v[188:191], v[20:23]
	v_mfma_f32_16x16x32_bf16 v[12:15], v[146:149], v[196:199], v[12:15]
	v_mfma_f32_16x16x32_bf16 v[4:7], v[164:167], v[196:199], v[4:7]
	s_barrier
; #define PG8_STAGE(bufoff, gbase, voff) do { _Pragma("unroll") for (int _i = 0; _i < 2; ++_i) \
;     __builtin_amdgcn_global_load_lds((const unsigned*)((const char*)(gbase) + (voff)[_i]), (PG8_LAS unsigned*)(lds + (bufoff) + ldsw + _i * 8192), 16, 0, 0); } while (0)
; #define PG8_LDA(dst, b, h) do { _Pragma("unroll") for (int m = 0; m < 4; ++m) _Pragma("unroll") for (int k = 0; k < 2; ++k) dst[m][k] = *(const PG8_LAS bf16x8*)(lds + PG8_SA(b, h) + aoff + m * 2048 + k * 1024); } while (0)
; #define PG8_LDB(dst, b, h) do { _Pragma("unroll") for (int n = 0; n < 2; ++n) _Pragma("unroll") for (int k = 0; k < 2; ++k) dst[n][k] = *(const PG8_LAS bf16x8*)(lds + PG8_SB(b, h) + boff + n * 2048 + k * 1024); } while (0)
; #define PG8_MMA(ai, bj, At, Bt) do { __builtin_amdgcn_s_setprio(1); _Pragma("unroll") for (int m = 0; m < 4; ++m) _Pragma("unroll") for (int n = 0; n < 2; ++n) _Pragma("unroll") for (int k = 0; k < 2; ++k) \
;     acc[ai][bj][m][n] = __builtin_amdgcn_mfma_f32_16x16x32_bf16(Bt[n][k], At[m][k], acc[ai][bj][m][n], 0, 0, 0); __builtin_amdgcn_s_setprio(0); } while (0)
; template <class Epi>
; DI void gemm_phase(PG8_LAS unsigned char* lds, const Gemm g, const StaticOrder& S, const Epi& E, const int wv) {
;     ...
;       PG8_LDB(B0, 0, 0); PG8_SCHED; PG8_LDA(At, 0, 0); PG8_STAGE(PG8_SA(1, 1), a1 + hstep, voffA);
;       PG8_WAIT_L(8); PG8_BAR; PG8_WAIT_L(0); PG8_MMA(0, 0, At, B0); PG8_BAR; PG8_SCHED;
;       PG8_LDB(B1, 0, 1); PG8_STAGE(PG8_SB(0, 0), b2, voffB);
;       PG8_BAR; PG8_WAIT_L(0); PG8_MMA(0, 1, At, B1); PG8_BAR;
;       PG8_LDA(At, 0, 1); PG8_STAGE(PG8_SA(0, 0), a2, voffA);
;       PG8_BAR; PG8_WAIT_L(0); PG8_MMA(1, 0, At, B0); PG8_BAR; PG8_SCHED;
;       PG8_STAGE(PG8_SB(0, 1), b2 + hstep, voffB);
;       PG8_WAIT_V(6); PG8_BAR; PG8_MMA(1, 1, At, B1); PG8_BAR;
;       PG8_LDB(B0, 1, 0); PG8_SCHED; PG8_LDA(At, 1, 0); PG8_STAGE(PG8_SA(0, 1), a2 + hstep, voffA);
;       PG8_WAIT_L(8); PG8_BAR; PG8_WAIT_L(0); PG8_MMA(0, 0, At, B0); PG8_BAR; PG8_SCHED;
;       PG8_LDB(B1, 1, 1); PG8_STAGE(PG8_SB(1, 0), b3, voffB);
;       PG8_BAR; PG8_WAIT_L(0); PG8_MMA(0, 1, At, B1); PG8_BAR;
;       PG8_LDA(At, 1, 1); PG8_STAGE(PG8_SA(1, 0), a3, voffA);
;       PG8_BAR; PG8_WAIT_L(0); PG8_MMA(1, 0, At, B0); PG8_BAR; PG8_SCHED;
;       PG8_STAGE(PG8_SB(1, 1), b3 + hstep, voffB);
;       PG8_WAIT_V(6); PG8_BAR; PG8_MMA(1, 1, At, B1); PG8_BAR;
	s_setprio 0
	s_add_u32 s64, s8, 0x40000
	s_addc_u32 s65, s9, 0
	s_add_i32 s63, s55, s45
	v_lshl_add_u64 v[142:143], s[64:65], 0, v[130:131]
	s_mov_b32 m0, s63
	s_nop 0
	global_load_lds_dwordx4 v[142:143], off
	v_lshl_add_u64 v[142:143], s[64:65], 0, v[134:135]
	s_add_i32 m0, s63, 0x2000
	s_nop 0
	global_load_lds_dwordx4 v[142:143], off
	s_waitcnt vmcnt(6)
	s_setprio 1
	s_barrier
	v_mfma_f32_16x16x32_bf16 v[60:63], v[200:203], v[168:171], v[60:63]
	v_mfma_f32_16x16x32_bf16 v[56:59], v[208:211], v[168:171], v[56:59]
	v_mfma_f32_16x16x32_bf16 v[40:43], v[200:203], v[176:179], v[40:43]
	v_mfma_f32_16x16x32_bf16 v[32:35], v[208:211], v[176:179], v[32:35]
	v_mfma_f32_16x16x32_bf16 v[24:27], v[200:203], v[184:187], v[24:27]
	v_mfma_f32_16x16x32_bf16 v[16:19], v[208:211], v[184:187], v[16:19]
	v_mfma_f32_16x16x32_bf16 v[8:11], v[200:203], v[192:195], v[8:11]
	v_mfma_f32_16x16x32_bf16 v[0:3], v[208:211], v[192:195], v[0:3]
	v_mfma_f32_16x16x32_bf16 v[60:63], v[204:207], v[172:175], v[60:63]
	v_mfma_f32_16x16x32_bf16 v[56:59], v[212:215], v[172:175], v[56:59]
	v_mfma_f32_16x16x32_bf16 v[40:43], v[204:207], v[180:183], v[40:43]
	v_mfma_f32_16x16x32_bf16 v[32:35], v[212:215], v[180:183], v[32:35]
	v_mfma_f32_16x16x32_bf16 v[24:27], v[204:207], v[188:191], v[24:27]
	v_mfma_f32_16x16x32_bf16 v[16:19], v[212:215], v[188:191], v[16:19]
	v_mfma_f32_16x16x32_bf16 v[8:11], v[204:207], v[196:199], v[8:11]
	v_mfma_f32_16x16x32_bf16 v[0:3], v[212:215], v[196:199], v[0:3]
	s_add_i32 s63, 0, 0x18000
	v_add_u32_e32 v159, s63, v153
	s_barrier
	s_setprio 0
	ds_read_b128 v[142:145], v159
	ds_read_b128 v[146:149], v159 offset:1024
	ds_read_b128 v[160:163], v159 offset:2048
	ds_read_b128 v[164:167], v159 offset:3072
	s_add_u32 s36, s36, 0x40000
	s_addc_u32 s37, s37, 0
	s_mov_b32 m0, s47
	v_lshl_add_u64 v[200:201], s[36:37], 0, v[128:129]
	ds_read_b128 v[168:171], v156 offset:32768
	ds_read_b128 v[172:175], v156 offset:33792
	ds_read_b128 v[176:179], v156 offset:34816
	ds_read_b128 v[180:183], v156 offset:35840
	ds_read_b128 v[184:187], v156 offset:36864
	ds_read_b128 v[188:191], v156 offset:37888
	ds_read_b128 v[192:195], v156 offset:38912
	ds_read_b128 v[196:199], v156 offset:39936
	global_load_lds_dwordx4 v[200:201], off
	v_lshl_add_u64 v[200:201], s[36:37], 0, v[132:133]
	s_mov_b32 m0, s48
	s_nop 0
	global_load_lds_dwordx4 v[200:201], off
	s_waitcnt lgkmcnt(8)
	s_setprio 1
	s_barrier
	s_waitcnt lgkmcnt(0)
	s_waitcnt lgkmcnt(0)
	v_mfma_f32_16x16x32_bf16 v[116:119], v[142:145], v[168:171], v[116:119]
	v_mfma_f32_16x16x32_bf16 v[112:115], v[160:163], v[168:171], v[112:115]
	v_mfma_f32_16x16x32_bf16 v[108:111], v[142:145], v[176:179], v[108:111]
	v_mfma_f32_16x16x32_bf16 v[100:103], v[160:163], v[176:179], v[100:103]
	v_mfma_f32_16x16x32_bf16 v[92:95], v[142:145], v[184:187], v[92:95]
	v_mfma_f32_16x16x32_bf16 v[84:87], v[160:163], v[184:187], v[84:87]
	v_mfma_f32_16x16x32_bf16 v[76:79], v[142:145], v[192:195], v[76:79]
	v_mfma_f32_16x16x32_bf16 v[68:71], v[160:163], v[192:195], v[68:71]
	v_mfma_f32_16x16x32_bf16 v[116:119], v[146:149], v[172:175], v[116:119]
	v_mfma_f32_16x16x32_bf16 v[112:115], v[164:167], v[172:175], v[112:115]
	v_mfma_f32_16x16x32_bf16 v[108:111], v[146:149], v[180:183], v[108:111]
	v_mfma_f32_16x16x32_bf16 v[100:103], v[164:167], v[180:183], v[100:103]
	v_mfma_f32_16x16x32_bf16 v[92:95], v[146:149], v[188:191], v[92:95]
	v_mfma_f32_16x16x32_bf16 v[84:87], v[164:167], v[188:191], v[84:87]
	v_mfma_f32_16x16x32_bf16 v[76:79], v[146:149], v[196:199], v[76:79]
	v_mfma_f32_16x16x32_bf16 v[68:71], v[164:167], v[196:199], v[68:71]
	s_barrier
	s_setprio 0
	s_add_i32 s36, 0, 0x1c000
	s_add_i32 s37, s63, s45
	v_add_u32_e32 v159, s36, v153
	v_lshl_add_u64 v[150:151], v[150:151], 0, s[20:21]
	s_mov_b32 m0, s37
	ds_read_b128 v[200:203], v159
	ds_read_b128 v[204:207], v159 offset:1024
	ds_read_b128 v[208:211], v159 offset:2048
	ds_read_b128 v[212:215], v159 offset:3072
	global_load_lds_dwordx4 v[150:151], off
	v_lshl_add_u64 v[150:151], v[216:217], 0, s[20:21]
	s_add_i32 m0, s37, 0x2000
	s_nop 0
	global_load_lds_dwordx4 v[150:151], off
	s_setprio 1
	s_barrier
	s_waitcnt lgkmcnt(0)
	s_waitcnt lgkmcnt(0)
	v_mfma_f32_16x16x32_bf16 v[124:127], v[200:203], v[168:171], v[124:127]
	v_mfma_f32_16x16x32_bf16 v[120:123], v[208:211], v[168:171], v[120:123]
	v_mfma_f32_16x16x32_bf16 v[104:107], v[200:203], v[176:179], v[104:107]
	v_mfma_f32_16x16x32_bf16 v[96:99], v[208:211], v[176:179], v[96:99]
	v_mfma_f32_16x16x32_bf16 v[88:91], v[200:203], v[184:187], v[88:91]
	v_mfma_f32_16x16x32_bf16 v[80:83], v[208:211], v[184:187], v[80:83]
	v_mfma_f32_16x16x32_bf16 v[72:75], v[200:203], v[192:195], v[72:75]
	v_mfma_f32_16x16x32_bf16 v[64:67], v[208:211], v[192:195], v[64:67]
	v_mfma_f32_16x16x32_bf16 v[124:127], v[204:207], v[172:175], v[124:127]
	v_mfma_f32_16x16x32_bf16 v[120:123], v[212:215], v[172:175], v[120:123]
	v_mfma_f32_16x16x32_bf16 v[104:107], v[204:207], v[180:183], v[104:107]
	v_mfma_f32_16x16x32_bf16 v[96:99], v[212:215], v[180:183], v[96:99]
	v_mfma_f32_16x16x32_bf16 v[88:91], v[204:207], v[188:191], v[88:91]
	v_mfma_f32_16x16x32_bf16 v[80:83], v[212:215], v[188:191], v[80:83]
	v_mfma_f32_16x16x32_bf16 v[72:75], v[204:207], v[196:199], v[72:75]
	v_mfma_f32_16x16x32_bf16 v[64:67], v[212:215], v[196:199], v[64:67]
	s_mov_b32 m0, s50
	v_lshl_add_u64 v[150:151], v[220:221], 0, s[20:21]
	s_barrier
; #define PG8_STAGE(bufoff, gbase, voff) do { _Pragma("unroll") for (int _i = 0; _i < 2; ++_i) \
;     __builtin_amdgcn_global_load_lds((const unsigned*)((const char*)(gbase) + (voff)[_i]), (PG8_LAS unsigned*)(lds + (bufoff) + ldsw + _i * 8192), 16, 0, 0); } while (0)
; #define PG8_LDA(dst, b, h) do { _Pragma("unroll") for (int m = 0; m < 4; ++m) _Pragma("unroll") for (int k = 0; k < 2; ++k) dst[m][k] = *(const PG8_LAS bf16x8*)(lds + PG8_SA(b, h) + aoff + m * 2048 + k * 1024); } while (0)
; #define PG8_LDB(dst, b, h) do { _Pragma("unroll") for (int n = 0; n < 2; ++n) _Pragma("unroll") for (int k = 0; k < 2; ++k) dst[n][k] = *(const PG8_LAS bf16x8*)(lds + PG8_SB(b, h) + boff + n * 2048 + k * 1024); } while (0)
; template <class Epi>
; DI void gemm_phase(PG8_LAS unsigned char* lds, const Gemm g, const StaticOrder& S, const Epi& E, const int wv) {
;     ...
;       PG8_WAIT_V(6); PG8_BAR; PG8_MMA(1, 1, At, B1); PG8_BAR;
;       PG8_LDB(B0, 1, 0); PG8_SCHED; PG8_LDA(At, 1, 0); PG8_STAGE(PG8_SA(0, 1), a2 + hstep, voffA);
;       PG8_WAIT_L(8); PG8_BAR; PG8_WAIT_L(0); PG8_MMA(0, 0, At, B0); PG8_BAR; PG8_SCHED;
;       PG8_LDB(B1, 1, 1); PG8_STAGE(PG8_SB(1, 0), b3, voffB);
;       PG8_BAR; PG8_WAIT_L(0); PG8_MMA(0, 1, At, B1); PG8_BAR;
;       PG8_LDA(At, 1, 1); PG8_STAGE(PG8_SA(1, 0), a3, voffA);
;       PG8_BAR; PG8_WAIT_L(0); PG8_MMA(1, 0, At, B0); PG8_BAR; PG8_SCHED;
;       PG8_STAGE(PG8_SB(1, 1), b3 + hstep, voffB);
;       PG8_WAIT_V(6); PG8_BAR; PG8_MMA(1, 1, At, B1); PG8_BAR;
;     }
;     E(acc, cur, wr, wc, fr, fq);
;   DI void operator()(AccRef acc, const pg8::Unit& u, int wr, int wc, int fr, int fq) const {
;     ...
;     EPI_ROWS_BEGIN()
;       float rs[4];
; #pragma unroll
;       for (int m = 0; m < 4; ++m) rs[m] = ss[row0 + ai * 128 + m * 16];
; #pragma unroll
;       for (int m = 0; m < 4; ++m) rs[m] = rsqrtf(rs[m] * (1.f / DM) + EPS);
; #pragma unroll
;       for (int m = 0; m < 4; ++m) {
;         const int row = row0 + ai * 128 + m * 16;
;         const float ne = rs[m] * -1.4426950408889634f, r2 = rs[m] * rs[m];
;         f32x4 y[2];
; #pragma unroll
;         for (int n = 0; n < 2; ++n)
; #pragma unroll
;           for (int e = 0; e < 4; ++e) {
;             const float a = acc[ai][0][m][n][e], b = acc[ai][1][m][n][e];
;             y[n][e] = a * b * r2 * __builtin_amdgcn_rcpf(1.f + __builtin_amdgcn_exp2f(a * ne));
	s_setprio 0
	ds_read_b128 v[168:171], v156 offset:49152
	ds_read_b128 v[172:175], v156 offset:50176
	ds_read_b128 v[176:179], v156 offset:51200
	ds_read_b128 v[180:183], v156 offset:52224
	ds_read_b128 v[184:187], v156 offset:53248
	ds_read_b128 v[188:191], v156 offset:54272
	ds_read_b128 v[192:195], v156 offset:55296
	ds_read_b128 v[196:199], v156 offset:56320
	global_load_lds_dwordx4 v[150:151], off
	v_lshl_add_u64 v[150:151], v[222:223], 0, s[20:21]
	s_mov_b32 m0, s51
	s_nop 0
	global_load_lds_dwordx4 v[150:151], off
	s_setprio 1
	s_barrier
	s_waitcnt lgkmcnt(0)
	v_mfma_f32_16x16x32_bf16 v[52:55], v[142:145], v[168:171], v[52:55]
	v_mfma_f32_16x16x32_bf16 v[48:51], v[160:163], v[168:171], v[48:51]
	v_mfma_f32_16x16x32_bf16 v[44:47], v[142:145], v[176:179], v[44:47]
	v_mfma_f32_16x16x32_bf16 v[36:39], v[160:163], v[176:179], v[36:39]
	v_mfma_f32_16x16x32_bf16 v[28:31], v[142:145], v[184:187], v[28:31]
	v_mfma_f32_16x16x32_bf16 v[20:23], v[160:163], v[184:187], v[20:23]
	v_mfma_f32_16x16x32_bf16 v[12:15], v[142:145], v[192:195], v[12:15]
	v_mfma_f32_16x16x32_bf16 v[4:7], v[160:163], v[192:195], v[4:7]
	v_mfma_f32_16x16x32_bf16 v[52:55], v[146:149], v[172:175], v[52:55]
	v_mfma_f32_16x16x32_bf16 v[48:51], v[164:167], v[172:175], v[48:51]
	v_mfma_f32_16x16x32_bf16 v[44:47], v[146:149], v[180:183], v[44:47]
	v_mfma_f32_16x16x32_bf16 v[36:39], v[164:167], v[180:183], v[36:39]
	v_mfma_f32_16x16x32_bf16 v[28:31], v[146:149], v[188:191], v[28:31]
	v_mfma_f32_16x16x32_bf16 v[20:23], v[164:167], v[188:191], v[20:23]
	v_mfma_f32_16x16x32_bf16 v[12:15], v[146:149], v[196:199], v[12:15]
	v_mfma_f32_16x16x32_bf16 v[4:7], v[164:167], v[196:199], v[4:7]
	s_barrier
	s_setprio 0
	s_add_u32 s8, s8, 0x40080
	s_addc_u32 s9, s9, 0
	s_add_i32 s36, s36, s45
	v_lshl_add_u64 v[142:143], s[8:9], 0, v[130:131]
	s_mov_b32 m0, s36
	s_nop 0
	global_load_lds_dwordx4 v[142:143], off
	v_lshl_add_u64 v[142:143], s[8:9], 0, v[134:135]
	s_add_i32 m0, s36, 0x2000
	s_nop 0
	global_load_lds_dwordx4 v[142:143], off
	s_waitcnt vmcnt(6)
	s_setprio 1
	s_barrier
	v_mfma_f32_16x16x32_bf16 v[60:63], v[200:203], v[168:171], v[60:63]
	v_mfma_f32_16x16x32_bf16 v[56:59], v[208:211], v[168:171], v[56:59]
	v_mfma_f32_16x16x32_bf16 v[40:43], v[200:203], v[176:179], v[40:43]
	v_mfma_f32_16x16x32_bf16 v[32:35], v[208:211], v[176:179], v[32:35]
	v_mfma_f32_16x16x32_bf16 v[24:27], v[200:203], v[184:187], v[24:27]
	v_mfma_f32_16x16x32_bf16 v[16:19], v[208:211], v[184:187], v[16:19]
	v_mfma_f32_16x16x32_bf16 v[8:11], v[200:203], v[192:195], v[8:11]
	v_mfma_f32_16x16x32_bf16 v[0:3], v[208:211], v[192:195], v[0:3]
	v_mfma_f32_16x16x32_bf16 v[60:63], v[204:207], v[172:175], v[60:63]
	v_mfma_f32_16x16x32_bf16 v[56:59], v[212:215], v[172:175], v[56:59]
	v_mfma_f32_16x16x32_bf16 v[40:43], v[204:207], v[180:183], v[40:43]
	v_mfma_f32_16x16x32_bf16 v[32:35], v[212:215], v[180:183], v[32:35]
	v_mfma_f32_16x16x32_bf16 v[24:27], v[204:207], v[188:191], v[24:27]
	v_mfma_f32_16x16x32_bf16 v[16:19], v[212:215], v[188:191], v[16:19]
	v_mfma_f32_16x16x32_bf16 v[8:11], v[204:207], v[196:199], v[8:11]
	v_mfma_f32_16x16x32_bf16 v[0:3], v[212:215], v[196:199], v[0:3]
	s_add_i32 s62, s62, 2
	s_add_u32 s6, s6, 0x100
	s_addc_u32 s7, s7, 0
	s_add_u32 s60, s60, 0x100
	s_addc_u32 s61, s61, 0
	s_cmp_gt_u32 s62, 13
	s_barrier
	s_setprio 0
	s_cbranch_scc0 .LBB0_893
	v_lshl_or_b32 v142, s4, 7, v154
	v_ashrrev_i32_e32 v143, 31, v142
	v_lshl_add_u32 v144, s34, 8, v152
	s_cmpk_gt_i32 s34, 0x181
	v_lshlrev_b64 v[142:143], 1, v[142:143]
	s_cbranch_scc1 .LBB0_896
	v_ashrrev_i32_e32 v145, 31, v144
	v_lshl_add_u64 v[146:147], v[144:145], 2, s[18:19]
	v_or_b32_e32 v150, 16, v144
	global_load_dword v145, v[146:147], off
	v_ashrrev_i32_e32 v151, 31, v150
	v_or_b32_e32 v148, 32, v144
	v_or_b32_e32 v146, 48, v144
	v_lshl_add_u64 v[160:161], v[150:151], 2, s[18:19]
	v_ashrrev_i32_e32 v149, 31, v148
	v_ashrrev_i32_e32 v147, 31, v146
	v_lshl_add_u64 v[162:163], v[148:149], 2, s[18:19]
	v_lshl_add_u64 v[164:165], v[146:147], 2, s[18:19]
	global_load_dword v147, v[160:161], off
	global_load_dword v149, v[162:163], off
	global_load_dword v151, v[164:165], off
	v_add_u32_e32 v224, 0x80, v144
	v_ashrrev_i32_e32 v225, 31, v224
	v_lshl_add_u64 v[226:227], v[224:225], 2, s[18:19]
	global_load_dword v250, v[226:227], off
	global_load_dword v251, v[226:227], off offset:64
	global_load_dword v252, v[226:227], off offset:128
	global_load_dword v253, v[226:227], off offset:192
	v_pk_mul_f32 v[160:161], v[112:113], v[120:121]
	v_mov_b64_e32 v[120:121], s[16:17]
	v_mad_i64_i32 v[162:163], s[4:5], v144, s58, v[120:121]
	v_pk_mul_f32 v[126:127], v[118:119], v[126:127]
	v_pk_mul_f32 v[124:125], v[116:117], v[124:125]
	v_pk_mul_f32 v[122:123], v[114:115], v[122:123]
	v_pk_mul_f32 v[104:105], v[108:109], v[104:105]
	v_pk_mul_f32 v[106:107], v[110:111], v[106:107]
	v_pk_mul_f32 v[98:99], v[102:103], v[98:99]
	v_lshl_add_u64 v[162:163], v[162:163], 0, v[142:143]
	v_pk_mul_f32 v[96:97], v[100:101], v[96:97]
	v_pk_mul_f32 v[88:89], v[92:93], v[88:89]
	v_pk_mul_f32 v[90:91], v[94:95], v[90:91]
	v_pk_mul_f32 v[82:83], v[86:87], v[82:83]
	v_pk_mul_f32 v[80:81], v[84:85], v[80:81]
	v_pk_mul_f32 v[72:73], v[76:77], v[72:73]
	v_pk_mul_f32 v[74:75], v[78:79], v[74:75]
	v_pk_mul_f32 v[66:67], v[70:71], v[66:67]
	v_pk_mul_f32 v[64:65], v[68:69], v[64:65]
	s_waitcnt vmcnt(4)
; DI u32x4 pack8v(f32x4 a, f32x4 b) { return u32x4{cvtpk(a[0], a[1]), cvtpk(a[2], a[3]), cvtpk(b[0], b[1]), cvtpk(b[2], b[3])}; }
;   DI void operator()(AccRef acc, const pg8::Unit& u, int wr, int wc, int fr, int fq) const {
;     ...
;       float rs[4];
; #pragma unroll
;       for (int m = 0; m < 4; ++m) rs[m] = ss[row0 + ai * 128 + m * 16];
; #pragma unroll
;       for (int m = 0; m < 4; ++m) rs[m] = rsqrtf(rs[m] * (1.f / DM) + EPS);
; #pragma unroll
;       for (int m = 0; m < 4; ++m) {
;         const int row = row0 + ai * 128 + m * 16;
;         const float ne = rs[m] * -1.4426950408889634f, r2 = rs[m] * rs[m];
;         f32x4 y[2];
; #pragma unroll
;         for (int n = 0; n < 2; ++n)
; #pragma unroll
;           for (int e = 0; e < 4; ++e) {
;             const float a = acc[ai][0][m][n][e], b = acc[ai][1][m][n][e];
;             y[n][e] = a * b * r2 * __builtin_amdgcn_rcpf(1.f + __builtin_amdgcn_exp2f(a * ne));
;           }
;         *(u32x4*)(act + (size_t)row * FFN + col0) = pack8v(y[0], y[1]);
	v_fmamk_f32 v145, v145, 0x3a800000, v158
	v_mul_f32_e32 v159, 0x4b800000, v145
	v_cmp_gt_f32_e32 vcc, s57, v145
	v_fmamk_f32 v147, v147, 0x3a800000, v158
	v_fmamk_f32 v149, v149, 0x3a800000, v158
	v_fmamk_f32 v151, v151, 0x3a800000, v158
	v_cndmask_b32_e32 v145, v145, v159, vcc
	v_mul_f32_e32 v159, 0x4b800000, v147
	v_cmp_gt_f32_e64 s[4:5], s57, v147
	v_mul_f32_e32 v164, 0x4b800000, v149
	v_mul_f32_e32 v165, 0x4b800000, v151
	v_rsq_f32_e32 v145, v145
	v_cndmask_b32_e64 v147, v147, v159, s[4:5]
	v_cmp_gt_f32_e64 s[6:7], s57, v149
	v_cmp_gt_f32_e64 s[8:9], s57, v151
	v_rsq_f32_e32 v147, v147
	v_cndmask_b32_e64 v149, v149, v164, s[6:7]
	v_cndmask_b32_e64 v151, v151, v165, s[8:9]
	v_rsq_f32_e32 v149, v149
	v_rsq_f32_e32 v151, v151
	v_mul_f32_e32 v159, 0x45800000, v145
	v_cndmask_b32_e32 v145, v145, v159, vcc
	v_mul_f32_e32 v159, 0x45800000, v147
	v_mul_f32_e32 v164, 0x45800000, v149
	v_mul_f32_e32 v165, 0x45800000, v151
	v_cndmask_b32_e64 v147, v147, v159, s[4:5]
	v_mul_f32_e32 v159, 0xbfb8aa3b, v145
	v_cndmask_b32_e64 v149, v149, v164, s[6:7]
	v_cndmask_b32_e64 v151, v151, v165, s[8:9]
	v_mul_f32_e32 v164, v145, v145
	v_mul_f32_e32 v165, v117, v159
	v_mul_f32_e32 v145, v116, v159
	v_pk_mul_f32 v[116:117], v[124:125], v[164:165] op_sel_hi:[1,0]
	v_mul_f32_e32 v124, v118, v159
	v_mul_f32_e32 v125, v119, v159
	v_pk_mul_f32 v[118:119], v[126:127], v[164:165] op_sel_hi:[1,0]
	v_mul_f32_e32 v126, v112, v159
	v_mul_f32_e32 v127, v113, v159
	v_pk_mul_f32 v[112:113], v[160:161], v[164:165] op_sel_hi:[1,0]
	v_mul_f32_e32 v160, v114, v159
	v_mul_f32_e32 v159, v115, v159
	v_pk_mul_f32 v[114:115], v[122:123], v[164:165] op_sel_hi:[1,0]
	v_mul_f32_e32 v123, 0xbfb8aa3b, v147
	v_mul_f32_e32 v161, v108, v123
	v_mul_f32_e32 v164, v109, v123
	v_mul_f32_e32 v108, v110, v123
	v_mul_f32_e32 v109, v111, v123
	v_mul_f32_e32 v122, v147, v147
	v_exp_f32_e32 v145, v145
	v_exp_f32_e32 v147, v165
	v_exp_f32_e32 v124, v124
	v_exp_f32_e32 v125, v125
	v_exp_f32_e32 v126, v126
	v_exp_f32_e32 v127, v127
	v_exp_f32_e32 v160, v160
	v_exp_f32_e32 v159, v159
	v_exp_f32_e32 v108, v108
	v_exp_f32_e32 v109, v109
	v_exp_f32_e32 v166, v161
	v_exp_f32_e32 v167, v164
	v_add_f32_e32 v145, 1.0, v145
	v_add_f32_e32 v147, 1.0, v147
	v_add_f32_e32 v161, 1.0, v124
	v_add_f32_e32 v164, 1.0, v125
	v_add_f32_e32 v165, 1.0, v126
	v_add_f32_e32 v168, 1.0, v127
	v_add_f32_e32 v169, 1.0, v160
	v_add_f32_e32 v159, 1.0, v159
	v_add_f32_e32 v108, 1.0, v108
	v_add_f32_e32 v109, 1.0, v109
	v_mul_f32_e32 v110, v100, v123
	v_mul_f32_e32 v111, v101, v123
	v_rcp_f32_e32 v124, v145
	v_rcp_f32_e32 v125, v147
	v_rcp_f32_e32 v126, v161
	v_rcp_f32_e32 v127, v164
	v_rcp_f32_e32 v160, v165
	v_rcp_f32_e32 v161, v168
	v_rcp_f32_e32 v164, v169
	v_rcp_f32_e32 v165, v159
	v_rcp_f32_e32 v108, v108
	v_rcp_f32_e32 v109, v109
	v_exp_f32_e32 v110, v110
	v_exp_f32_e32 v111, v111
	v_mul_f32_e32 v102, v102, v123
	v_mul_f32_e32 v103, v103, v123
	v_exp_f32_e32 v102, v102
	v_exp_f32_e32 v103, v103
	v_pk_mul_f32 v[106:107], v[106:107], v[122:123] op_sel_hi:[1,0]
	v_pk_mul_f32 v[116:117], v[116:117], v[124:125]
	v_pk_mul_f32 v[118:119], v[118:119], v[126:127]
	v_pk_mul_f32 v[124:125], v[112:113], v[160:161]
	v_pk_mul_f32 v[126:127], v[114:115], v[164:165]
	v_pk_mul_f32 v[106:107], v[106:107], v[108:109]
	v_add_f32_e32 v108, 1.0, v110
	v_add_f32_e32 v109, 1.0, v111
	v_cvt_pk_bf16_f32 v112, v116, v117
	v_cvt_pk_bf16_f32 v113, v118, v119
	v_cvt_pk_bf16_f32 v114, v124, v125
	v_cvt_pk_bf16_f32 v115, v126, v127
	v_rcp_f32_e32 v108, v108
	v_rcp_f32_e32 v109, v109
	v_add_f32_e32 v100, 1.0, v102
	v_add_f32_e32 v101, 1.0, v103
	v_add_f32_e32 v145, 1.0, v166
	global_store_dwordx4 v[162:163], v[112:115], off
	v_rcp_f32_e32 v100, v100
	v_rcp_f32_e32 v101, v101
	v_add_f32_e32 v113, 1.0, v167
	v_rcp_f32_e32 v112, v145
	v_rcp_f32_e32 v113, v113
; DI u32x4 pack8v(f32x4 a, f32x4 b) { return u32x4{cvtpk(a[0], a[1]), cvtpk(a[2], a[3]), cvtpk(b[0], b[1]), cvtpk(b[2], b[3])}; }
;   DI void operator()(AccRef acc, const pg8::Unit& u, int wr, int wc, int fr, int fq) const {
;     ...
;       for (int m = 0; m < 4; ++m) {
;         const int row = row0 + ai * 128 + m * 16;
;         const float ne = rs[m] * -1.4426950408889634f, r2 = rs[m] * rs[m];
;         f32x4 y[2];
; #pragma unroll
;         for (int n = 0; n < 2; ++n)
; #pragma unroll
;           for (int e = 0; e < 4; ++e) {
;             const float a = acc[ai][0][m][n][e], b = acc[ai][1][m][n][e];
;             y[n][e] = a * b * r2 * __builtin_amdgcn_rcpf(1.f + __builtin_amdgcn_exp2f(a * ne));
;           }
;         *(u32x4*)(act + (size_t)row * FFN + col0) = pack8v(y[0], y[1]);
	v_pk_mul_f32 v[96:97], v[96:97], v[122:123] op_sel_hi:[1,0]
	v_pk_mul_f32 v[104:105], v[104:105], v[122:123] op_sel_hi:[1,0]
	v_pk_mul_f32 v[102:103], v[96:97], v[108:109]
	v_pk_mul_f32 v[96:97], v[98:99], v[122:123] op_sel_hi:[1,0]
	v_pk_mul_f32 v[104:105], v[104:105], v[112:113]
	v_pk_mul_f32 v[100:101], v[96:97], v[100:101]
	v_cvt_pk_bf16_f32 v96, v104, v105
	v_cvt_pk_bf16_f32 v99, v100, v101
	v_mad_i64_i32 v[100:101], s[4:5], v150, s58, v[120:121]
	v_cvt_pk_bf16_f32 v97, v106, v107
	v_cvt_pk_bf16_f32 v98, v102, v103
	v_lshl_add_u64 v[100:101], v[100:101], 0, v[142:143]
	global_store_dwordx4 v[100:101], v[96:99], off
	s_nop 1
	v_mul_f32_e32 v97, 0xbfb8aa3b, v149
	v_mul_f32_e32 v96, v92, v97
	v_exp_f32_e32 v98, v96
	v_mul_f32_e32 v96, v93, v97
	v_mul_f32_e32 v92, v94, v97
	v_mul_f32_e32 v93, v95, v97
	v_exp_f32_e32 v92, v92
	v_exp_f32_e32 v93, v93
	v_mul_f32_e32 v94, v84, v97
	v_mul_f32_e32 v95, v85, v97
	v_add_f32_e32 v92, 1.0, v92
	v_add_f32_e32 v93, 1.0, v93
	v_rcp_f32_e32 v92, v92
	v_rcp_f32_e32 v93, v93
	v_exp_f32_e32 v94, v94
	v_exp_f32_e32 v95, v95
	v_mul_f32_e32 v86, v86, v97
	v_mul_f32_e32 v87, v87, v97
	v_exp_f32_e32 v86, v86
	v_exp_f32_e32 v87, v87
	v_exp_f32_e32 v99, v96
	v_mul_f32_e32 v96, v149, v149
	v_pk_mul_f32 v[90:91], v[90:91], v[96:97] op_sel_hi:[1,0]
	v_add_f32_e32 v84, 1.0, v86
	v_pk_mul_f32 v[90:91], v[90:91], v[92:93]
	v_add_f32_e32 v92, 1.0, v94
	v_add_f32_e32 v93, 1.0, v95
	v_rcp_f32_e32 v92, v92
	v_rcp_f32_e32 v93, v93
	v_add_f32_e32 v85, 1.0, v87
	v_add_f32_e32 v98, 1.0, v98
	v_add_f32_e32 v99, 1.0, v99
	v_rcp_f32_e32 v84, v84
	v_rcp_f32_e32 v85, v85
	v_rcp_f32_e32 v98, v98
	v_rcp_f32_e32 v99, v99
	v_pk_mul_f32 v[80:81], v[80:81], v[96:97] op_sel_hi:[1,0]
	v_pk_mul_f32 v[88:89], v[88:89], v[96:97] op_sel_hi:[1,0]
	v_pk_mul_f32 v[86:87], v[80:81], v[92:93]
	v_pk_mul_f32 v[80:81], v[82:83], v[96:97] op_sel_hi:[1,0]
	v_pk_mul_f32 v[88:89], v[88:89], v[98:99]
	v_pk_mul_f32 v[84:85], v[80:81], v[84:85]
	v_cvt_pk_bf16_f32 v80, v88, v89
	v_cvt_pk_bf16_f32 v83, v84, v85
	v_mad_i64_i32 v[84:85], s[4:5], v148, s58, v[120:121]
	v_cvt_pk_bf16_f32 v81, v90, v91
	v_cvt_pk_bf16_f32 v82, v86, v87
	v_lshl_add_u64 v[84:85], v[84:85], 0, v[142:143]
	global_store_dwordx4 v[84:85], v[80:83], off
	s_nop 1
	v_mul_f32_e32 v81, 0xbfb8aa3b, v151
	v_mul_f32_e32 v80, v76, v81
	v_exp_f32_e32 v82, v80
	v_mul_f32_e32 v80, v77, v81
	v_mul_f32_e32 v76, v78, v81
	v_mul_f32_e32 v77, v79, v81
	v_exp_f32_e32 v76, v76
	v_exp_f32_e32 v77, v77
	v_mul_f32_e32 v78, v68, v81
	v_mul_f32_e32 v79, v69, v81
	v_add_f32_e32 v76, 1.0, v76
	v_add_f32_e32 v77, 1.0, v77
	v_rcp_f32_e32 v76, v76
	v_rcp_f32_e32 v77, v77
	v_exp_f32_e32 v78, v78
	v_exp_f32_e32 v79, v79
	v_mul_f32_e32 v70, v70, v81
	v_mul_f32_e32 v71, v71, v81
	v_exp_f32_e32 v70, v70
	v_exp_f32_e32 v71, v71
	v_exp_f32_e32 v83, v80
	v_mul_f32_e32 v80, v151, v151
	v_pk_mul_f32 v[74:75], v[74:75], v[80:81] op_sel_hi:[1,0]
	v_add_f32_e32 v68, 1.0, v70
	v_pk_mul_f32 v[74:75], v[74:75], v[76:77]
	v_add_f32_e32 v76, 1.0, v78
	v_add_f32_e32 v77, 1.0, v79
	v_rcp_f32_e32 v76, v76
	v_rcp_f32_e32 v77, v77
	v_add_f32_e32 v69, 1.0, v71
	v_add_f32_e32 v82, 1.0, v82
	v_add_f32_e32 v83, 1.0, v83
	v_rcp_f32_e32 v68, v68
	v_rcp_f32_e32 v69, v69
	v_rcp_f32_e32 v82, v82
	v_rcp_f32_e32 v83, v83
	v_pk_mul_f32 v[64:65], v[64:65], v[80:81] op_sel_hi:[1,0]
	v_pk_mul_f32 v[72:73], v[72:73], v[80:81] op_sel_hi:[1,0]
	v_pk_mul_f32 v[70:71], v[64:65], v[76:77]
	v_pk_mul_f32 v[64:65], v[66:67], v[80:81] op_sel_hi:[1,0]
	v_pk_mul_f32 v[72:73], v[72:73], v[82:83]
	v_pk_mul_f32 v[68:69], v[64:65], v[68:69]
	v_cvt_pk_bf16_f32 v64, v72, v73
	v_cvt_pk_bf16_f32 v67, v68, v69
	v_mad_i64_i32 v[68:69], s[4:5], v146, s58, v[120:121]
	v_cvt_pk_bf16_f32 v65, v74, v75
	v_cvt_pk_bf16_f32 v66, v70, v71
	v_lshl_add_u64 v[68:69], v[68:69], 0, v[142:143]
	global_store_dwordx4 v[68:69], v[64:67], off

; #define PG8_STAGE(bufoff, gbase, voff) do { _Pragma("unroll") for (int _i = 0; _i < 2; ++_i) \
;     __builtin_amdgcn_global_load_lds((const unsigned*)((const char*)(gbase) + (voff)[_i]), (PG8_LAS unsigned*)(lds + (bufoff) + ldsw + _i * 8192), 16, 0, 0); } while (0)
; #define PG8_LDA(dst, b, h) do { _Pragma("unroll") for (int m = 0; m < 4; ++m) _Pragma("unroll") for (int k = 0; k < 2; ++k) dst[m][k] = *(const PG8_LAS bf16x8*)(lds + PG8_SA(b, h) + aoff + m * 2048 + k * 1024); } while (0)
; #define PG8_LDB(dst, b, h) do { _Pragma("unroll") for (int n = 0; n < 2; ++n) _Pragma("unroll") for (int k = 0; k < 2; ++k) dst[n][k] = *(const PG8_LAS bf16x8*)(lds + PG8_SB(b, h) + boff + n * 2048 + k * 1024); } while (0)
; #define PG8_MMA(ai, bj, At, Bt) do { __builtin_amdgcn_s_setprio(1); _Pragma("unroll") for (int m = 0; m < 4; ++m) _Pragma("unroll") for (int n = 0; n < 2; ++n) _Pragma("unroll") for (int k = 0; k < 2; ++k) \
;     acc[ai][bj][m][n] = __builtin_amdgcn_mfma_f32_16x16x32_bf16(Bt[n][k], At[m][k], acc[ai][bj][m][n], 0, 0, 0); __builtin_amdgcn_s_setprio(0); } while (0)
; template <class Epi>
; DI void gemm_phase(PG8_LAS unsigned char* lds, const Gemm g, const StaticOrder& S, const Epi& E, const int wv) {
;     ...
;       PG8_LDB(B0, 0, 0); PG8_SCHED; PG8_LDA(At, 0, 0); PG8_STAGE(PG8_SA(1, 1), a1 + hstep, voffA);
;       PG8_WAIT_L(8); PG8_BAR; PG8_WAIT_L(0); PG8_MMA(0, 0, At, B0); PG8_BAR; PG8_SCHED;
;       PG8_LDB(B1, 0, 1); PG8_STAGE(PG8_SB(0, 0), b2, voffB);
;       PG8_BAR; PG8_WAIT_L(0); PG8_MMA(0, 1, At, B1); PG8_BAR;
;       PG8_LDA(At, 0, 1); PG8_STAGE(PG8_SA(0, 0), a2, voffA);
;       PG8_BAR; PG8_WAIT_L(0); PG8_MMA(1, 0, At, B0); PG8_BAR; PG8_SCHED;
;       PG8_STAGE(PG8_SB(0, 1), b2 + hstep, voffB);
;       PG8_WAIT_V(6); PG8_BAR; PG8_MMA(1, 1, At, B1); PG8_BAR;
;       PG8_LDB(B0, 1, 0); PG8_SCHED; PG8_LDA(At, 1, 0); PG8_STAGE(PG8_SA(0, 1), a2 + hstep, voffA);
;       PG8_WAIT_L(8); PG8_BAR; PG8_WAIT_L(0); PG8_MMA(0, 0, At, B0); PG8_BAR; PG8_SCHED;
;       PG8_LDB(B1, 1, 1); PG8_STAGE(PG8_SB(1, 0), b3, voffB);
;       PG8_BAR; PG8_WAIT_L(0); PG8_MMA(0, 1, At, B1); PG8_BAR;
;       PG8_LDA(At, 1, 1); PG8_STAGE(PG8_SA(1, 0), a3, voffA);
;       PG8_BAR; PG8_WAIT_L(0); PG8_MMA(1, 0, At, B0); PG8_BAR; PG8_SCHED;
;       PG8_STAGE(PG8_SB(1, 1), b3 + hstep, voffB);
;       PG8_WAIT_V(6); PG8_BAR; PG8_MMA(1, 1, At, B1); PG8_BAR;
.LBB0_968:
	ds_read_b128 v[128:131], v189
	ds_read_b128 v[132:135], v189 offset:1024
	ds_read_b128 v[136:139], v189 offset:2048
	ds_read_b128 v[140:143], v189 offset:3072
	s_add_u32 s28, s26, 0x100
	s_addc_u32 s29, s27, 0
	s_cmp_eq_u32 s63, 40
	s_cselect_b32 s35, s25, s29
	s_cselect_b32 s34, s24, s28
	s_cselect_b32 s31, s7, s62
	s_cselect_b32 s30, s6, s61
	v_lshl_add_u64 v[198:199], s[26:27], 0, v[160:161]
	s_add_i32 m0, s43, 0xc000
	ds_read_b128 v[144:147], v190
	ds_read_b128 v[148:151], v190 offset:1024
	ds_read_b128 v[166:169], v190 offset:2048
	ds_read_b128 v[170:173], v190 offset:3072
	ds_read_b128 v[174:177], v190 offset:4096
	ds_read_b128 v[178:181], v190 offset:5120
	ds_read_b128 v[182:185], v190 offset:6144
	ds_read_b128 v[194:197], v190 offset:7168
	global_load_lds_dwordx4 v[198:199], off
	v_lshl_add_u64 v[198:199], s[26:27], 0, v[162:163]
	s_add_i32 m0, s43, 0xe000
	s_nop 0
	global_load_lds_dwordx4 v[198:199], off
	s_waitcnt lgkmcnt(8)
	s_setprio 1
	s_barrier
	s_waitcnt lgkmcnt(0)
	s_waitcnt lgkmcnt(0)
	v_mfma_f32_16x16x32_bf16 v[124:127], v[128:131], v[144:147], v[124:127]
	v_mfma_f32_16x16x32_bf16 v[120:123], v[136:139], v[144:147], v[120:123]
	v_mfma_f32_16x16x32_bf16 v[108:111], v[128:131], v[166:169], v[108:111]
	v_mfma_f32_16x16x32_bf16 v[104:107], v[136:139], v[166:169], v[104:107]
	v_mfma_f32_16x16x32_bf16 v[92:95], v[128:131], v[174:177], v[92:95]
	v_mfma_f32_16x16x32_bf16 v[88:91], v[136:139], v[174:177], v[88:91]
	v_mfma_f32_16x16x32_bf16 v[76:79], v[128:131], v[182:185], v[76:79]
	v_mfma_f32_16x16x32_bf16 v[72:75], v[136:139], v[182:185], v[72:75]
	v_mfma_f32_16x16x32_bf16 v[124:127], v[132:135], v[148:151], v[124:127]
	v_mfma_f32_16x16x32_bf16 v[120:123], v[140:143], v[148:151], v[120:123]
	v_mfma_f32_16x16x32_bf16 v[108:111], v[132:135], v[170:173], v[108:111]
	v_mfma_f32_16x16x32_bf16 v[104:107], v[140:143], v[170:173], v[104:107]
	v_mfma_f32_16x16x32_bf16 v[92:95], v[132:135], v[178:181], v[92:95]
	v_mfma_f32_16x16x32_bf16 v[88:91], v[140:143], v[178:181], v[88:91]
	v_mfma_f32_16x16x32_bf16 v[76:79], v[132:135], v[194:197], v[76:79]
	v_mfma_f32_16x16x32_bf16 v[72:75], v[140:143], v[194:197], v[72:75]
	s_barrier
	s_setprio 0
	s_add_i32 s26, s54, s42
	v_lshl_add_u64 v[214:215], s[30:31], 0, v[154:155]
	s_mov_b32 m0, s26
	ds_read_b128 v[198:201], v191
	ds_read_b128 v[202:205], v191 offset:1024
	ds_read_b128 v[206:209], v191 offset:2048
	ds_read_b128 v[210:213], v191 offset:3072
	global_load_lds_dwordx4 v[214:215], off
	v_lshl_add_u64 v[216:217], s[30:31], 0, v[158:159]
	s_add_i32 m0, s26, 0x2000
	s_nop 0
	global_load_lds_dwordx4 v[216:217], off
	s_setprio 1
	s_barrier
	s_waitcnt lgkmcnt(0)
	v_mfma_f32_16x16x32_bf16 v[116:119], v[198:201], v[144:147], v[116:119]
	v_mfma_f32_16x16x32_bf16 v[112:115], v[206:209], v[144:147], v[112:115]
	v_mfma_f32_16x16x32_bf16 v[100:103], v[198:201], v[166:169], v[100:103]
	v_mfma_f32_16x16x32_bf16 v[96:99], v[206:209], v[166:169], v[96:99]
	v_mfma_f32_16x16x32_bf16 v[84:87], v[198:201], v[174:177], v[84:87]
	v_mfma_f32_16x16x32_bf16 v[80:83], v[206:209], v[174:177], v[80:83]
	v_mfma_f32_16x16x32_bf16 v[68:71], v[198:201], v[182:185], v[68:71]
	v_mfma_f32_16x16x32_bf16 v[64:67], v[206:209], v[182:185], v[64:67]
	v_mfma_f32_16x16x32_bf16 v[116:119], v[202:205], v[148:151], v[116:119]
	v_mfma_f32_16x16x32_bf16 v[112:115], v[210:213], v[148:151], v[112:115]
	v_mfma_f32_16x16x32_bf16 v[100:103], v[202:205], v[170:173], v[100:103]
	v_mfma_f32_16x16x32_bf16 v[96:99], v[210:213], v[170:173], v[96:99]
	v_mfma_f32_16x16x32_bf16 v[84:87], v[202:205], v[178:181], v[84:87]
	v_mfma_f32_16x16x32_bf16 v[80:83], v[210:213], v[178:181], v[80:83]
	v_mfma_f32_16x16x32_bf16 v[68:71], v[202:205], v[194:197], v[68:71]
	v_mfma_f32_16x16x32_bf16 v[64:67], v[210:213], v[194:197], v[64:67]
	s_mov_b32 m0, s43
	v_lshl_add_u64 v[220:221], s[34:35], 0, v[152:153]
	s_barrier
	s_setprio 0
	ds_read_b128 v[144:147], v190 offset:16384
	ds_read_b128 v[148:151], v190 offset:17408
	ds_read_b128 v[166:169], v190 offset:18432
	ds_read_b128 v[170:173], v190 offset:19456
	ds_read_b128 v[174:177], v190 offset:20480
	ds_read_b128 v[178:181], v190 offset:21504
	ds_read_b128 v[182:185], v190 offset:22528
	ds_read_b128 v[194:197], v190 offset:23552
	global_load_lds_dwordx4 v[220:221], off
	v_lshl_add_u64 v[222:223], s[34:35], 0, v[156:157]
	s_mov_b32 m0, s44
	s_nop 0
	global_load_lds_dwordx4 v[222:223], off
	s_setprio 1
	s_barrier
	s_waitcnt lgkmcnt(0)
	v_mfma_f32_16x16x32_bf16 v[60:63], v[128:131], v[144:147], v[60:63]
	v_mfma_f32_16x16x32_bf16 v[56:59], v[136:139], v[144:147], v[56:59]
	v_mfma_f32_16x16x32_bf16 v[44:47], v[128:131], v[166:169], v[44:47]
	v_mfma_f32_16x16x32_bf16 v[40:43], v[136:139], v[166:169], v[40:43]
	v_mfma_f32_16x16x32_bf16 v[28:31], v[128:131], v[174:177], v[28:31]
	v_mfma_f32_16x16x32_bf16 v[24:27], v[136:139], v[174:177], v[24:27]
	v_mfma_f32_16x16x32_bf16 v[12:15], v[128:131], v[182:185], v[12:15]
	v_mfma_f32_16x16x32_bf16 v[8:11], v[136:139], v[182:185], v[8:11]
	v_mfma_f32_16x16x32_bf16 v[60:63], v[132:135], v[148:151], v[60:63]
	v_mfma_f32_16x16x32_bf16 v[56:59], v[140:143], v[148:151], v[56:59]
	v_mfma_f32_16x16x32_bf16 v[44:47], v[132:135], v[170:173], v[44:47]
	v_mfma_f32_16x16x32_bf16 v[40:43], v[140:143], v[170:173], v[40:43]
	v_mfma_f32_16x16x32_bf16 v[28:31], v[132:135], v[178:181], v[28:31]
	v_mfma_f32_16x16x32_bf16 v[24:27], v[140:143], v[178:181], v[24:27]
	v_mfma_f32_16x16x32_bf16 v[12:15], v[132:135], v[194:197], v[12:15]
	v_mfma_f32_16x16x32_bf16 v[8:11], v[140:143], v[194:197], v[8:11]
	s_barrier
; #define PG8_STAGE(bufoff, gbase, voff) do { _Pragma("unroll") for (int _i = 0; _i < 2; ++_i) \
;     __builtin_amdgcn_global_load_lds((const unsigned*)((const char*)(gbase) + (voff)[_i]), (PG8_LAS unsigned*)(lds + (bufoff) + ldsw + _i * 8192), 16, 0, 0); } while (0)
; #define PG8_LDA(dst, b, h) do { _Pragma("unroll") for (int m = 0; m < 4; ++m) _Pragma("unroll") for (int k = 0; k < 2; ++k) dst[m][k] = *(const PG8_LAS bf16x8*)(lds + PG8_SA(b, h) + aoff + m * 2048 + k * 1024); } while (0)
; #define PG8_LDB(dst, b, h) do { _Pragma("unroll") for (int n = 0; n < 2; ++n) _Pragma("unroll") for (int k = 0; k < 2; ++k) dst[n][k] = *(const PG8_LAS bf16x8*)(lds + PG8_SB(b, h) + boff + n * 2048 + k * 1024); } while (0)
; #define PG8_MMA(ai, bj, At, Bt) do { __builtin_amdgcn_s_setprio(1); _Pragma("unroll") for (int m = 0; m < 4; ++m) _Pragma("unroll") for (int n = 0; n < 2; ++n) _Pragma("unroll") for (int k = 0; k < 2; ++k) \
;     acc[ai][bj][m][n] = __builtin_amdgcn_mfma_f32_16x16x32_bf16(Bt[n][k], At[m][k], acc[ai][bj][m][n], 0, 0, 0); __builtin_amdgcn_s_setprio(0); } while (0)
; template <class Epi>
; DI void gemm_phase(PG8_LAS unsigned char* lds, const Gemm g, const StaticOrder& S, const Epi& E, const int wv) {
;     ...
;       PG8_LDB(B0, 0, 0); PG8_SCHED; PG8_LDA(At, 0, 0); PG8_STAGE(PG8_SA(1, 1), a1 + hstep, voffA);
;       PG8_WAIT_L(8); PG8_BAR; PG8_WAIT_L(0); PG8_MMA(0, 0, At, B0); PG8_BAR; PG8_SCHED;
;       PG8_LDB(B1, 0, 1); PG8_STAGE(PG8_SB(0, 0), b2, voffB);
;       PG8_BAR; PG8_WAIT_L(0); PG8_MMA(0, 1, At, B1); PG8_BAR;
;       PG8_LDA(At, 0, 1); PG8_STAGE(PG8_SA(0, 0), a2, voffA);
;       PG8_BAR; PG8_WAIT_L(0); PG8_MMA(1, 0, At, B0); PG8_BAR; PG8_SCHED;
;       PG8_STAGE(PG8_SB(0, 1), b2 + hstep, voffB);
;       PG8_WAIT_V(6); PG8_BAR; PG8_MMA(1, 1, At, B1); PG8_BAR;
;       PG8_LDB(B0, 1, 0); PG8_SCHED; PG8_LDA(At, 1, 0); PG8_STAGE(PG8_SA(0, 1), a2 + hstep, voffA);
;       PG8_WAIT_L(8); PG8_BAR; PG8_WAIT_L(0); PG8_MMA(0, 0, At, B0); PG8_BAR; PG8_SCHED;
;       PG8_LDB(B1, 1, 1); PG8_STAGE(PG8_SB(1, 0), b3, voffB);
;       PG8_BAR; PG8_WAIT_L(0); PG8_MMA(0, 1, At, B1); PG8_BAR;
;       PG8_LDA(At, 1, 1); PG8_STAGE(PG8_SA(1, 0), a3, voffA);
;       PG8_BAR; PG8_WAIT_L(0); PG8_MMA(1, 0, At, B0); PG8_BAR; PG8_SCHED;
;       PG8_STAGE(PG8_SB(1, 1), b3 + hstep, voffB);
;       PG8_WAIT_V(6); PG8_BAR; PG8_MMA(1, 1, At, B1); PG8_BAR;
	s_setprio 0
	s_add_u32 s26, s30, 0xb0000
	s_addc_u32 s27, s31, 0
	s_add_i32 s64, s55, s42
	v_lshl_add_u64 v[128:129], s[26:27], 0, v[154:155]
	s_mov_b32 m0, s64
	s_nop 0
	global_load_lds_dwordx4 v[128:129], off
	v_lshl_add_u64 v[128:129], s[26:27], 0, v[158:159]
	s_add_i32 m0, s64, 0x2000
	s_nop 0
	global_load_lds_dwordx4 v[128:129], off
	s_waitcnt vmcnt(6)
	s_setprio 1
	s_barrier
	v_mfma_f32_16x16x32_bf16 v[52:55], v[198:201], v[144:147], v[52:55]
	v_mfma_f32_16x16x32_bf16 v[48:51], v[206:209], v[144:147], v[48:51]
	v_mfma_f32_16x16x32_bf16 v[36:39], v[198:201], v[166:169], v[36:39]
	v_mfma_f32_16x16x32_bf16 v[32:35], v[206:209], v[166:169], v[32:35]
	v_mfma_f32_16x16x32_bf16 v[20:23], v[198:201], v[174:177], v[20:23]
	v_mfma_f32_16x16x32_bf16 v[16:19], v[206:209], v[174:177], v[16:19]
	v_mfma_f32_16x16x32_bf16 v[4:7], v[198:201], v[182:185], v[4:7]
	v_mfma_f32_16x16x32_bf16 v[0:3], v[206:209], v[182:185], v[0:3]
	v_mfma_f32_16x16x32_bf16 v[52:55], v[202:205], v[148:151], v[52:55]
	v_mfma_f32_16x16x32_bf16 v[48:51], v[210:213], v[148:151], v[48:51]
	v_mfma_f32_16x16x32_bf16 v[36:39], v[202:205], v[170:173], v[36:39]
	v_mfma_f32_16x16x32_bf16 v[32:35], v[210:213], v[170:173], v[32:35]
	v_mfma_f32_16x16x32_bf16 v[20:23], v[202:205], v[178:181], v[20:23]
	v_mfma_f32_16x16x32_bf16 v[16:19], v[210:213], v[178:181], v[16:19]
	v_mfma_f32_16x16x32_bf16 v[4:7], v[202:205], v[194:197], v[4:7]
	v_mfma_f32_16x16x32_bf16 v[0:3], v[210:213], v[194:197], v[0:3]
	s_add_i32 s64, 0, 0x18000
	v_add_u32_e32 v140, s64, v187
	s_barrier
	s_setprio 0
	ds_read_b128 v[128:131], v140
	ds_read_b128 v[132:135], v140 offset:1024
	ds_read_b128 v[136:139], v140 offset:2048
	ds_read_b128 v[140:143], v140 offset:3072
	s_add_u32 s26, s34, 0xb0000
	s_addc_u32 s27, s35, 0
	s_mov_b32 m0, s45
	v_lshl_add_u64 v[198:199], s[26:27], 0, v[152:153]
	ds_read_b128 v[144:147], v190 offset:32768
	ds_read_b128 v[148:151], v190 offset:33792
	ds_read_b128 v[166:169], v190 offset:34816
	ds_read_b128 v[170:173], v190 offset:35840
	ds_read_b128 v[174:177], v190 offset:36864
	ds_read_b128 v[178:181], v190 offset:37888
	ds_read_b128 v[182:185], v190 offset:38912
	ds_read_b128 v[194:197], v190 offset:39936
	global_load_lds_dwordx4 v[198:199], off
	v_lshl_add_u64 v[198:199], s[26:27], 0, v[156:157]
	s_mov_b32 m0, s46
	s_nop 0
	global_load_lds_dwordx4 v[198:199], off
	s_waitcnt lgkmcnt(8)
	s_setprio 1
	s_barrier
	s_waitcnt lgkmcnt(0)
	s_waitcnt lgkmcnt(0)
	v_mfma_f32_16x16x32_bf16 v[124:127], v[128:131], v[144:147], v[124:127]
	v_mfma_f32_16x16x32_bf16 v[120:123], v[136:139], v[144:147], v[120:123]
	v_mfma_f32_16x16x32_bf16 v[108:111], v[128:131], v[166:169], v[108:111]
	v_mfma_f32_16x16x32_bf16 v[104:107], v[136:139], v[166:169], v[104:107]
	v_mfma_f32_16x16x32_bf16 v[92:95], v[128:131], v[174:177], v[92:95]
	v_mfma_f32_16x16x32_bf16 v[88:91], v[136:139], v[174:177], v[88:91]
	v_mfma_f32_16x16x32_bf16 v[76:79], v[128:131], v[182:185], v[76:79]
	v_mfma_f32_16x16x32_bf16 v[72:75], v[136:139], v[182:185], v[72:75]
	v_mfma_f32_16x16x32_bf16 v[124:127], v[132:135], v[148:151], v[124:127]
	v_mfma_f32_16x16x32_bf16 v[120:123], v[140:143], v[148:151], v[120:123]
	v_mfma_f32_16x16x32_bf16 v[108:111], v[132:135], v[170:173], v[108:111]
	v_mfma_f32_16x16x32_bf16 v[104:107], v[140:143], v[170:173], v[104:107]
	v_mfma_f32_16x16x32_bf16 v[92:95], v[132:135], v[178:181], v[92:95]
	v_mfma_f32_16x16x32_bf16 v[88:91], v[140:143], v[178:181], v[88:91]
	v_mfma_f32_16x16x32_bf16 v[76:79], v[132:135], v[194:197], v[76:79]
	v_mfma_f32_16x16x32_bf16 v[72:75], v[140:143], v[194:197], v[72:75]
	s_barrier
	s_setprio 0
	s_add_i32 s34, 0, 0x1c000
	s_add_i32 s26, s64, s42
	v_add_u32_e32 v193, s34, v187
	v_lshl_add_u64 v[214:215], v[214:215], 0, s[20:21]
	s_mov_b32 m0, s26
	ds_read_b128 v[198:201], v193
	ds_read_b128 v[202:205], v193 offset:1024
	ds_read_b128 v[206:209], v193 offset:2048
	ds_read_b128 v[210:213], v193 offset:3072
	global_load_lds_dwordx4 v[214:215], off
	v_lshl_add_u64 v[214:215], v[216:217], 0, s[20:21]
	s_add_i32 m0, s26, 0x2000
	s_nop 0
	global_load_lds_dwordx4 v[214:215], off
	s_setprio 1
	s_barrier
	s_waitcnt lgkmcnt(0)
	s_waitcnt lgkmcnt(0)
	v_mfma_f32_16x16x32_bf16 v[116:119], v[198:201], v[144:147], v[116:119]
	v_mfma_f32_16x16x32_bf16 v[112:115], v[206:209], v[144:147], v[112:115]
	v_mfma_f32_16x16x32_bf16 v[100:103], v[198:201], v[166:169], v[100:103]
	v_mfma_f32_16x16x32_bf16 v[96:99], v[206:209], v[166:169], v[96:99]
	v_mfma_f32_16x16x32_bf16 v[84:87], v[198:201], v[174:177], v[84:87]
	v_mfma_f32_16x16x32_bf16 v[80:83], v[206:209], v[174:177], v[80:83]
	v_mfma_f32_16x16x32_bf16 v[68:71], v[198:201], v[182:185], v[68:71]
	v_mfma_f32_16x16x32_bf16 v[64:67], v[206:209], v[182:185], v[64:67]
	v_mfma_f32_16x16x32_bf16 v[116:119], v[202:205], v[148:151], v[116:119]
	v_mfma_f32_16x16x32_bf16 v[112:115], v[210:213], v[148:151], v[112:115]
	v_mfma_f32_16x16x32_bf16 v[100:103], v[202:205], v[170:173], v[100:103]
	v_mfma_f32_16x16x32_bf16 v[96:99], v[210:213], v[170:173], v[96:99]
	v_mfma_f32_16x16x32_bf16 v[84:87], v[202:205], v[178:181], v[84:87]
	v_mfma_f32_16x16x32_bf16 v[80:83], v[210:213], v[178:181], v[80:83]
	v_mfma_f32_16x16x32_bf16 v[68:71], v[202:205], v[194:197], v[68:71]
	v_mfma_f32_16x16x32_bf16 v[64:67], v[210:213], v[194:197], v[64:67]
	s_mov_b32 m0, s48
	v_lshl_add_u64 v[214:215], v[220:221], 0, s[20:21]
	s_barrier
; #define PG8_STAGE(bufoff, gbase, voff) do { _Pragma("unroll") for (int _i = 0; _i < 2; ++_i) \
;     __builtin_amdgcn_global_load_lds((const unsigned*)((const char*)(gbase) + (voff)[_i]), (PG8_LAS unsigned*)(lds + (bufoff) + ldsw + _i * 8192), 16, 0, 0); } while (0)
; #define PG8_LDA(dst, b, h) do { _Pragma("unroll") for (int m = 0; m < 4; ++m) _Pragma("unroll") for (int k = 0; k < 2; ++k) dst[m][k] = *(const PG8_LAS bf16x8*)(lds + PG8_SA(b, h) + aoff + m * 2048 + k * 1024); } while (0)
; #define PG8_LDB(dst, b, h) do { _Pragma("unroll") for (int n = 0; n < 2; ++n) _Pragma("unroll") for (int k = 0; k < 2; ++k) dst[n][k] = *(const PG8_LAS bf16x8*)(lds + PG8_SB(b, h) + boff + n * 2048 + k * 1024); } while (0)
; #define PG8_MMA(ai, bj, At, Bt) do { __builtin_amdgcn_s_setprio(1); _Pragma("unroll") for (int m = 0; m < 4; ++m) _Pragma("unroll") for (int n = 0; n < 2; ++n) _Pragma("unroll") for (int k = 0; k < 2; ++k) \
;     acc[ai][bj][m][n] = __builtin_amdgcn_mfma_f32_16x16x32_bf16(Bt[n][k], At[m][k], acc[ai][bj][m][n], 0, 0, 0); __builtin_amdgcn_s_setprio(0); } while (0)
; #define PG8_WAIT_V(n) asm volatile("s_waitcnt vmcnt(" #n ")" ::: "memory")
; #define PG8_WAIT_L(n) asm volatile("s_waitcnt lgkmcnt(" #n ")" ::: "memory")
; #define PG8_BAR __builtin_amdgcn_s_barrier()
; #define PG8_SCHED __builtin_amdgcn_sched_barrier(0)
; template <class Epi>
; DI void gemm_phase(PG8_LAS unsigned char* lds, const Gemm g, const StaticOrder& S, const Epi& E, const int wv) {
;     ...
;       PG8_WAIT_V(6); PG8_BAR; PG8_MMA(1, 1, At, B1); PG8_BAR;
;       PG8_LDB(B0, 1, 0); PG8_SCHED; PG8_LDA(At, 1, 0); PG8_STAGE(PG8_SA(0, 1), a2 + hstep, voffA);
;       PG8_WAIT_L(8); PG8_BAR; PG8_WAIT_L(0); PG8_MMA(0, 0, At, B0); PG8_BAR; PG8_SCHED;
;       PG8_LDB(B1, 1, 1); PG8_STAGE(PG8_SB(1, 0), b3, voffB);
;       PG8_BAR; PG8_WAIT_L(0); PG8_MMA(0, 1, At, B1); PG8_BAR;
;       PG8_LDA(At, 1, 1); PG8_STAGE(PG8_SA(1, 0), a3, voffA);
;       PG8_BAR; PG8_WAIT_L(0); PG8_MMA(1, 0, At, B0); PG8_BAR; PG8_SCHED;
;       PG8_STAGE(PG8_SB(1, 1), b3 + hstep, voffB);
;       PG8_WAIT_V(6); PG8_BAR; PG8_MMA(1, 1, At, B1); PG8_BAR;
;     }
;     E(acc, cur, wr, wc, fr, fq);
;   DI void operator()(AccRef acc, const pg8::Unit& u, int wr, int wc, int fr, int fq) const {
;     const int row0 = u.pm * 256 + wr * 64 + fr, col0 = u.pn * 256 + wc * 32 + 8 * fq;
;     EPI_ROWS_BEGIN()
	s_setprio 0
	ds_read_b128 v[144:147], v190 offset:49152
	ds_read_b128 v[148:151], v190 offset:50176
	ds_read_b128 v[166:169], v190 offset:51200
	ds_read_b128 v[170:173], v190 offset:52224
	ds_read_b128 v[174:177], v190 offset:53248
	ds_read_b128 v[178:181], v190 offset:54272
	ds_read_b128 v[182:185], v190 offset:55296
	ds_read_b128 v[194:197], v190 offset:56320
	global_load_lds_dwordx4 v[214:215], off
	v_lshl_add_u64 v[214:215], v[222:223], 0, s[20:21]
	s_mov_b32 m0, s49
	s_nop 0
	global_load_lds_dwordx4 v[214:215], off
	s_setprio 1
	s_barrier
	s_waitcnt lgkmcnt(0)
	v_mfma_f32_16x16x32_bf16 v[60:63], v[128:131], v[144:147], v[60:63]
	v_mfma_f32_16x16x32_bf16 v[56:59], v[136:139], v[144:147], v[56:59]
	v_mfma_f32_16x16x32_bf16 v[44:47], v[128:131], v[166:169], v[44:47]
	v_mfma_f32_16x16x32_bf16 v[40:43], v[136:139], v[166:169], v[40:43]
	v_mfma_f32_16x16x32_bf16 v[28:31], v[128:131], v[174:177], v[28:31]
	v_mfma_f32_16x16x32_bf16 v[24:27], v[136:139], v[174:177], v[24:27]
	v_mfma_f32_16x16x32_bf16 v[12:15], v[128:131], v[182:185], v[12:15]
	v_mfma_f32_16x16x32_bf16 v[8:11], v[136:139], v[182:185], v[8:11]
	v_mfma_f32_16x16x32_bf16 v[60:63], v[132:135], v[148:151], v[60:63]
	v_mfma_f32_16x16x32_bf16 v[56:59], v[140:143], v[148:151], v[56:59]
	v_mfma_f32_16x16x32_bf16 v[44:47], v[132:135], v[170:173], v[44:47]
	v_mfma_f32_16x16x32_bf16 v[40:43], v[140:143], v[170:173], v[40:43]
	v_mfma_f32_16x16x32_bf16 v[28:31], v[132:135], v[178:181], v[28:31]
	v_mfma_f32_16x16x32_bf16 v[24:27], v[140:143], v[178:181], v[24:27]
	v_mfma_f32_16x16x32_bf16 v[12:15], v[132:135], v[194:197], v[12:15]
	v_mfma_f32_16x16x32_bf16 v[8:11], v[140:143], v[194:197], v[8:11]
	s_barrier
	s_setprio 0
	s_add_u32 s26, s30, 0xb0080
	s_addc_u32 s27, s31, 0
	s_add_i32 s30, s34, s42
	v_lshl_add_u64 v[128:129], s[26:27], 0, v[154:155]
	s_mov_b32 m0, s30
	s_nop 0
	global_load_lds_dwordx4 v[128:129], off
	v_lshl_add_u64 v[128:129], s[26:27], 0, v[158:159]
	s_add_i32 m0, s30, 0x2000
	s_nop 0
	global_load_lds_dwordx4 v[128:129], off
	s_waitcnt vmcnt(6)
	s_setprio 1
	s_barrier
	v_mfma_f32_16x16x32_bf16 v[52:55], v[198:201], v[144:147], v[52:55]
	v_mfma_f32_16x16x32_bf16 v[48:51], v[206:209], v[144:147], v[48:51]
	v_mfma_f32_16x16x32_bf16 v[36:39], v[198:201], v[166:169], v[36:39]
	v_mfma_f32_16x16x32_bf16 v[32:35], v[206:209], v[166:169], v[32:35]
	v_mfma_f32_16x16x32_bf16 v[20:23], v[198:201], v[174:177], v[20:23]
	v_mfma_f32_16x16x32_bf16 v[16:19], v[206:209], v[174:177], v[16:19]
	v_mfma_f32_16x16x32_bf16 v[4:7], v[198:201], v[182:185], v[4:7]
	v_mfma_f32_16x16x32_bf16 v[0:3], v[206:209], v[182:185], v[0:3]
	v_mfma_f32_16x16x32_bf16 v[52:55], v[202:205], v[148:151], v[52:55]
	v_mfma_f32_16x16x32_bf16 v[48:51], v[210:213], v[148:151], v[48:51]
	v_mfma_f32_16x16x32_bf16 v[36:39], v[202:205], v[170:173], v[36:39]
	v_mfma_f32_16x16x32_bf16 v[32:35], v[210:213], v[170:173], v[32:35]
	v_mfma_f32_16x16x32_bf16 v[20:23], v[202:205], v[178:181], v[20:23]
	v_mfma_f32_16x16x32_bf16 v[16:19], v[210:213], v[178:181], v[16:19]
	v_mfma_f32_16x16x32_bf16 v[4:7], v[202:205], v[194:197], v[4:7]
	v_mfma_f32_16x16x32_bf16 v[0:3], v[210:213], v[194:197], v[0:3]
	s_add_i32 s63, s63, 2
	s_add_u32 s61, s61, 0x100
	s_addc_u32 s62, s62, 0
	s_cmp_gt_u32 s63, 41
	s_mov_b64 s[26:27], s[28:29]
	s_barrier
	s_setprio 0
	s_cbranch_scc0 .LBB0_968
	v_lshl_or_b32 v166, s60, 8, v188
	v_ashrrev_i32_e32 v167, 31, v166
	v_lshlrev_b64 v[168:169], 1, v[166:167]
	v_lshl_add_u32 v172, s59, 8, v186
	s_cmpk_gt_i32 s59, 0x181
	v_lshl_add_u64 v[170:171], s[8:9], 0, v[168:169]
	s_cbranch_scc1 .LBB0_979
; DI float bf_lo(unsigned u) { return __uint_as_float(u << 16); }
;   DI void operator()(AccRef acc, const pg8::Unit& u, int wr, int wc, int fr, int fq) const {
;     ...
;         u32x4 rb[4][2];
; #pragma unroll
;         for (int m = 0; m < 4; ++m)
; #pragma unroll
;           for (int bj = 0; bj < 2; ++bj) {
;             const int rr = row0 + ai * 128 + m * 16;
;             const int sr = (MODE == 3) ? rr + NMETA * ((rr >> 12) + 1) : rr;
;             rb[m][bj] = *(const u32x4*)(hsrc + (size_t)sr * DM + col0 + bj * 128);
;           }
; #pragma unroll
;         for (int m = 0; m < 4; ++m)
; #pragma unroll
;           for (int bj = 0; bj < 2; ++bj) {
;             r[m][bj][0] = f32x4{bf_lo(rb[m][bj][0]), bf_hi(rb[m][bj][0]), bf_lo(rb[m][bj][1]), bf_hi(rb[m][bj][1])};
;             r[m][bj][1] = f32x4{bf_lo(rb[m][bj][2]), bf_hi(rb[m][bj][2]), bf_lo(rb[m][bj][3]), bf_hi(rb[m][bj][3])};
;           }
;       }
; #pragma unroll
;       for (int m = 0; m < 4; ++m) {
;         const int row = row0 + ai * 128 + m * 16;
;         if constexpr (MODE == 4) {
;           float* dst = P.out + (size_t)row * DM + col0;
; #pragma unroll
;           for (int bj = 0; bj < 2; ++bj) {
;             *(f32x4*)(dst + bj * 128) = r[m][bj][0] + acc[ai][bj][m][0];
;             *(f32x4*)(dst + bj * 128 + 4) = r[m][bj][1] + acc[ai][bj][m][1];
;           }
;         } else if constexpr (MODE == 2) {
;           const int s = row / L, p = row - s * L;
;           if (p >= NMETA) {
;             float* dst = P.out + ((size_t)s * SEQ + (p - NMETA)) * DM + col0;
; #pragma unroll
;             for (int bj = 0; bj < 2; ++bj) {
;               *(f32x4*)(dst + bj * 128) = r[m][bj][0] + acc[ai][bj][m][0];
;               *(f32x4*)(dst + bj * 128 + 4) = r[m][bj][1] + acc[ai][bj][m][1];
;             }
;           }
;         } else {
;           float s2 = 0.f;
; #pragma unroll
;           for (int bj = 0; bj < 2; ++bj) {
;             const f32x4 r0 = r[m][bj][0] + acc[ai][bj][m][0], r1 = r[m][bj][1] + acc[ai][bj][m][1];
;             *(u32x4*)(hdst + (size_t)row * DM + col0 + bj * 128) = pack8v(r0, r1);
;             s2 += r0[0] * r0[0] + r0[1] * r0[1] + r0[2] * r0[2] + r0[3] * r0[3] + r1[0] * r1[0] + r1[1] * r1[1] + r1[2] * r1[2] + r1[3] * r1[3];
;           }
;           s2 += __shfl_xor(s2, 16);
;           s2 += __shfl_xor(s2, 32);
;           if (fq == 0) atomicAdd(ss + row, s2);
	v_ashrrev_i32_e32 v173, 31, v172
	v_lshlrev_b64 v[204:205], 11, v[172:173]
	v_lshl_add_u64 v[128:129], v[170:171], 0, v[204:205]
	global_load_dwordx4 v[196:199], v[128:129], off
	global_load_dwordx4 v[200:203], v[128:129], off offset:256
	v_or_b32_e32 v182, 16, v172
	v_or_b32_e32 v178, 32, v172
	v_or_b32_e32 v174, 48, v172
	v_ashrrev_i32_e32 v183, 31, v182
	v_ashrrev_i32_e32 v179, 31, v178
	v_ashrrev_i32_e32 v175, 31, v174
	v_lshlrev_b64 v[184:185], 11, v[182:183]
	v_lshlrev_b64 v[180:181], 11, v[178:179]
	v_lshlrev_b64 v[176:177], 11, v[174:175]
	v_lshl_add_u64 v[128:129], v[170:171], 0, v[184:185]
	v_lshl_add_u64 v[130:131], v[170:171], 0, v[180:181]
	v_lshl_add_u64 v[194:195], v[170:171], 0, v[176:177]
	global_load_dwordx4 v[148:151], v[128:129], off
	global_load_dwordx4 v[144:147], v[128:129], off offset:256
	global_load_dwordx4 v[140:143], v[130:131], off
	global_load_dwordx4 v[136:139], v[130:131], off offset:256
	global_load_dwordx4 v[132:135], v[194:195], off
	s_nop 0
	global_load_dwordx4 v[128:131], v[194:195], off offset:256
	v_and_b32_e32 v194, 64, v192
	v_xor_b32_e32 v193, 16, v192
	v_add_u32_e32 v194, 64, v194
	v_xor_b32_e32 v195, 32, v192
	v_cmp_lt_i32_e32 vcc, v193, v194
	s_waitcnt vmcnt(0)
	v_lshlrev_b32_e32 v206, 16, v196
	v_cndmask_b32_e32 v193, v192, v193, vcc
	v_cmp_lt_i32_e32 vcc, v195, v194
	v_and_b32_e32 v207, 0xffff0000, v196
	v_lshlrev_b32_e32 v210, 16, v200
	v_and_b32_e32 v211, 0xffff0000, v200
	v_cndmask_b32_e32 v195, v192, v195, vcc
	v_lshlrev_b32_e32 v208, 16, v198
	v_and_b32_e32 v209, 0xffff0000, v198
	v_lshlrev_b32_e32 v198, 16, v199
	v_and_b32_e32 v199, 0xffff0000, v199
	v_lshlrev_b32_e32 v212, 16, v202
	v_and_b32_e32 v213, 0xffff0000, v202
	v_pk_add_f32 v[124:125], v[124:125], v[206:207]
	v_pk_add_f32 v[116:117], v[116:117], v[210:211]
	v_lshlrev_b32_e32 v194, 2, v193
	v_lshlrev_b32_e32 v193, 2, v195
	v_lshlrev_b32_e32 v196, 16, v197
	v_and_b32_e32 v197, 0xffff0000, v197
	v_lshlrev_b32_e32 v200, 16, v201
	v_and_b32_e32 v201, 0xffff0000, v201
	v_pk_add_f32 v[122:123], v[122:123], v[198:199]
	v_pk_add_f32 v[198:199], v[112:113], v[212:213]
	v_cvt_pk_bf16_f32 v112, v124, v125
	v_mul_f32_e32 v125, v125, v125
	v_mul_f32_e32 v195, v117, v117
	v_pk_add_f32 v[126:127], v[126:127], v[196:197]
	v_pk_add_f32 v[118:119], v[118:119], v[200:201]
	v_fmac_f32_e32 v125, v124, v124
	v_fmac_f32_e32 v195, v116, v116
	v_fmac_f32_e32 v125, v126, v126
	v_fmac_f32_e32 v195, v118, v118
	v_pk_add_f32 v[120:121], v[120:121], v[208:209]
	v_fmac_f32_e32 v125, v127, v127
	v_fmac_f32_e32 v195, v119, v119
	v_lshlrev_b32_e32 v202, 16, v203
	v_and_b32_e32 v203, 0xffff0000, v203
	v_fmac_f32_e32 v125, v120, v120
	v_fmac_f32_e32 v195, v198, v198
	v_pk_add_f32 v[196:197], v[114:115], v[202:203]
	v_fmac_f32_e32 v125, v121, v121
	v_fmac_f32_e32 v195, v199, v199
	v_fmac_f32_e32 v125, v122, v122
	v_fmac_f32_e32 v195, v196, v196
	v_fmac_f32_e32 v125, v123, v123
	v_fmac_f32_e32 v195, v197, v197
	v_cvt_pk_bf16_f32 v115, v122, v123
	v_add_f32_e32 v122, v125, v195
	ds_bpermute_b32 v123, v194, v122
	v_cvt_pk_bf16_f32 v114, v120, v121
	v_lshl_add_u64 v[120:121], s[16:17], 0, v[204:205]
	v_cvt_pk_bf16_f32 v113, v126, v127
	v_lshl_add_u64 v[120:121], v[120:121], 0, v[168:169]
	global_store_dwordx4 v[120:121], v[112:115], off
	s_waitcnt lgkmcnt(0)
	s_nop 0
	v_add_f32_e32 v112, v122, v123
	ds_bpermute_b32 v113, v193, v112
	v_cvt_pk_bf16_f32 v114, v116, v117
	v_cvt_pk_bf16_f32 v115, v118, v119
	v_cvt_pk_bf16_f32 v116, v198, v199
	v_cvt_pk_bf16_f32 v117, v196, v197
	global_store_dwordx4 v[120:121], v[114:117], off offset:256
	s_and_saveexec_b64 s[26:27], s[4:5]
	s_cbranch_execz .LBB0_972
	v_lshl_add_u64 v[114:115], v[172:173], 2, s[18:19]
	s_waitcnt lgkmcnt(0)
	v_add_f32_e32 v112, v112, v113
	global_atomic_add_f32 v[114:115], v112, off

; #define PG8_STAGE(bufoff, gbase, voff) do { _Pragma("unroll") for (int _i = 0; _i < 2; ++_i) \
;     __builtin_amdgcn_global_load_lds((const unsigned*)((const char*)(gbase) + (voff)[_i]), (PG8_LAS unsigned*)(lds + (bufoff) + ldsw + _i * 8192), 16, 0, 0); } while (0)
; #define PG8_LDA(dst, b, h) do { _Pragma("unroll") for (int m = 0; m < 4; ++m) _Pragma("unroll") for (int k = 0; k < 2; ++k) dst[m][k] = *(const PG8_LAS bf16x8*)(lds + PG8_SA(b, h) + aoff + m * 2048 + k * 1024); } while (0)
; #define PG8_LDB(dst, b, h) do { _Pragma("unroll") for (int n = 0; n < 2; ++n) _Pragma("unroll") for (int k = 0; k < 2; ++k) dst[n][k] = *(const PG8_LAS bf16x8*)(lds + PG8_SB(b, h) + boff + n * 2048 + k * 1024); } while (0)
; #define PG8_MMA(ai, bj, At, Bt) do { __builtin_amdgcn_s_setprio(1); _Pragma("unroll") for (int m = 0; m < 4; ++m) _Pragma("unroll") for (int n = 0; n < 2; ++n) _Pragma("unroll") for (int k = 0; k < 2; ++k) \
;     acc[ai][bj][m][n] = __builtin_amdgcn_mfma_f32_16x16x32_bf16(Bt[n][k], At[m][k], acc[ai][bj][m][n], 0, 0, 0); __builtin_amdgcn_s_setprio(0); } while (0)
; template <class Epi>
; DI void gemm_phase(PG8_LAS unsigned char* lds, const Gemm g, const StaticOrder& S, const Epi& E, const int wv) {
;     ...
;       PG8_LDB(B0, 0, 0); PG8_SCHED; PG8_LDA(At, 0, 0); PG8_STAGE(PG8_SA(1, 1), a1 + hstep, voffA);
;       PG8_WAIT_L(8); PG8_BAR; PG8_WAIT_L(0); PG8_MMA(0, 0, At, B0); PG8_BAR; PG8_SCHED;
;       PG8_LDB(B1, 0, 1); PG8_STAGE(PG8_SB(0, 0), b2, voffB);
;       PG8_BAR; PG8_WAIT_L(0); PG8_MMA(0, 1, At, B1); PG8_BAR;
;       PG8_LDA(At, 0, 1); PG8_STAGE(PG8_SA(0, 0), a2, voffA);
;       PG8_BAR; PG8_WAIT_L(0); PG8_MMA(1, 0, At, B0); PG8_BAR; PG8_SCHED;
;       PG8_STAGE(PG8_SB(0, 1), b2 + hstep, voffB);
;       PG8_WAIT_V(6); PG8_BAR; PG8_MMA(1, 1, At, B1); PG8_BAR;
;       PG8_LDB(B0, 1, 0); PG8_SCHED; PG8_LDA(At, 1, 0); PG8_STAGE(PG8_SA(0, 1), a2 + hstep, voffA);
;       PG8_WAIT_L(8); PG8_BAR; PG8_WAIT_L(0); PG8_MMA(0, 0, At, B0); PG8_BAR; PG8_SCHED;
;       PG8_LDB(B1, 1, 1); PG8_STAGE(PG8_SB(1, 0), b3, voffB);
;       PG8_BAR; PG8_WAIT_L(0); PG8_MMA(0, 1, At, B1); PG8_BAR;
;       PG8_LDA(At, 1, 1); PG8_STAGE(PG8_SA(1, 0), a3, voffA);
;       PG8_BAR; PG8_WAIT_L(0); PG8_MMA(1, 0, At, B0); PG8_BAR; PG8_SCHED;
;       PG8_STAGE(PG8_SB(1, 1), b3 + hstep, voffB);
;       PG8_WAIT_V(6); PG8_BAR; PG8_MMA(1, 1, At, B1); PG8_BAR;
.LBB0_1061:
	ds_read_b128 v[146:149], v157
	ds_read_b128 v[150:153], v157 offset:1024
	ds_read_b128 v[162:165], v157 offset:2048
	ds_read_b128 v[166:169], v157 offset:3072
	s_add_u32 s36, s6, 0xfffc0080
	s_addc_u32 s37, s7, -1
	s_cmp_eq_u32 s74, 12
	s_cselect_b32 s39, s5, s37
	s_cselect_b32 s38, s27, s36
	s_cselect_b32 s37, s25, s73
	s_cselect_b32 s36, s71, s72
	v_lshl_add_u64 v[202:203], s[6:7], 0, v[140:141]
	s_add_i32 m0, s35, 0xc000
	ds_read_b128 v[170:173], v158
	ds_read_b128 v[174:177], v158 offset:1024
	ds_read_b128 v[178:181], v158 offset:2048
	ds_read_b128 v[182:185], v158 offset:3072
	ds_read_b128 v[186:189], v158 offset:4096
	ds_read_b128 v[190:193], v158 offset:5120
	ds_read_b128 v[194:197], v158 offset:6144
	ds_read_b128 v[198:201], v158 offset:7168
	global_load_lds_dwordx4 v[202:203], off
	v_lshl_add_u64 v[202:203], s[6:7], 0, v[142:143]
	s_add_i32 m0, s35, 0xe000
	s_nop 0
	global_load_lds_dwordx4 v[202:203], off
	s_waitcnt lgkmcnt(8)
	s_setprio 1
	s_barrier
	s_waitcnt lgkmcnt(0)
	s_waitcnt lgkmcnt(0)
	v_mfma_f32_16x16x32_bf16 v[124:127], v[146:149], v[170:173], v[124:127]
	v_mfma_f32_16x16x32_bf16 v[120:123], v[162:165], v[170:173], v[120:123]
	v_mfma_f32_16x16x32_bf16 v[108:111], v[146:149], v[178:181], v[108:111]
	v_mfma_f32_16x16x32_bf16 v[104:107], v[162:165], v[178:181], v[104:107]
	v_mfma_f32_16x16x32_bf16 v[92:95], v[146:149], v[186:189], v[92:95]
	v_mfma_f32_16x16x32_bf16 v[88:91], v[162:165], v[186:189], v[88:91]
	v_mfma_f32_16x16x32_bf16 v[76:79], v[146:149], v[194:197], v[76:79]
	v_mfma_f32_16x16x32_bf16 v[72:75], v[162:165], v[194:197], v[72:75]
	v_mfma_f32_16x16x32_bf16 v[124:127], v[150:153], v[174:177], v[124:127]
	v_mfma_f32_16x16x32_bf16 v[120:123], v[166:169], v[174:177], v[120:123]
	v_mfma_f32_16x16x32_bf16 v[108:111], v[150:153], v[182:185], v[108:111]
	v_mfma_f32_16x16x32_bf16 v[104:107], v[166:169], v[182:185], v[104:107]
	v_mfma_f32_16x16x32_bf16 v[92:95], v[150:153], v[190:193], v[92:95]
	v_mfma_f32_16x16x32_bf16 v[88:91], v[166:169], v[190:193], v[88:91]
	v_mfma_f32_16x16x32_bf16 v[76:79], v[150:153], v[198:201], v[76:79]
	v_mfma_f32_16x16x32_bf16 v[72:75], v[166:169], v[198:201], v[72:75]
	s_barrier
	s_setprio 0
	s_add_i32 s75, s62, s46
	v_lshl_add_u64 v[220:221], s[36:37], 0, v[130:131]
	s_mov_b32 m0, s75
	ds_read_b128 v[202:205], v159
	ds_read_b128 v[206:209], v159 offset:1024
	ds_read_b128 v[210:213], v159 offset:2048
	ds_read_b128 v[214:217], v159 offset:3072
	global_load_lds_dwordx4 v[220:221], off
	v_lshl_add_u64 v[222:223], s[36:37], 0, v[134:135]
	s_add_i32 m0, s75, 0x2000
	s_nop 0
	global_load_lds_dwordx4 v[222:223], off
	s_setprio 1
	s_barrier
	s_waitcnt lgkmcnt(0)
	v_mfma_f32_16x16x32_bf16 v[116:119], v[202:205], v[170:173], v[116:119]
	v_mfma_f32_16x16x32_bf16 v[112:115], v[210:213], v[170:173], v[112:115]
	v_mfma_f32_16x16x32_bf16 v[100:103], v[202:205], v[178:181], v[100:103]
	v_mfma_f32_16x16x32_bf16 v[96:99], v[210:213], v[178:181], v[96:99]
	v_mfma_f32_16x16x32_bf16 v[84:87], v[202:205], v[186:189], v[84:87]
	v_mfma_f32_16x16x32_bf16 v[80:83], v[210:213], v[186:189], v[80:83]
	v_mfma_f32_16x16x32_bf16 v[68:71], v[202:205], v[194:197], v[68:71]
	v_mfma_f32_16x16x32_bf16 v[64:67], v[210:213], v[194:197], v[64:67]
	v_mfma_f32_16x16x32_bf16 v[116:119], v[206:209], v[174:177], v[116:119]
	v_mfma_f32_16x16x32_bf16 v[112:115], v[214:217], v[174:177], v[112:115]
	v_mfma_f32_16x16x32_bf16 v[100:103], v[206:209], v[182:185], v[100:103]
	v_mfma_f32_16x16x32_bf16 v[96:99], v[214:217], v[182:185], v[96:99]
	v_mfma_f32_16x16x32_bf16 v[84:87], v[206:209], v[190:193], v[84:87]
	v_mfma_f32_16x16x32_bf16 v[80:83], v[214:217], v[190:193], v[80:83]
	v_mfma_f32_16x16x32_bf16 v[68:71], v[206:209], v[198:201], v[68:71]
	v_mfma_f32_16x16x32_bf16 v[64:67], v[214:217], v[198:201], v[64:67]
	s_mov_b32 m0, s35
	v_lshl_add_u64 v[224:225], s[38:39], 0, v[128:129]
	s_barrier
	s_setprio 0
	ds_read_b128 v[170:173], v158 offset:16384
	ds_read_b128 v[174:177], v158 offset:17408
	ds_read_b128 v[178:181], v158 offset:18432
	ds_read_b128 v[182:185], v158 offset:19456
	ds_read_b128 v[186:189], v158 offset:20480
	ds_read_b128 v[190:193], v158 offset:21504
	ds_read_b128 v[194:197], v158 offset:22528
	ds_read_b128 v[198:201], v158 offset:23552
	global_load_lds_dwordx4 v[224:225], off
	v_lshl_add_u64 v[226:227], s[38:39], 0, v[132:133]
	s_mov_b32 m0, s47
	s_nop 0
	global_load_lds_dwordx4 v[226:227], off
	s_setprio 1
	s_barrier
	s_waitcnt lgkmcnt(0)
	v_mfma_f32_16x16x32_bf16 v[60:63], v[146:149], v[170:173], v[60:63]
	v_mfma_f32_16x16x32_bf16 v[56:59], v[162:165], v[170:173], v[56:59]
	v_mfma_f32_16x16x32_bf16 v[44:47], v[146:149], v[178:181], v[44:47]
	v_mfma_f32_16x16x32_bf16 v[40:43], v[162:165], v[178:181], v[40:43]
	v_mfma_f32_16x16x32_bf16 v[28:31], v[146:149], v[186:189], v[28:31]
	v_mfma_f32_16x16x32_bf16 v[24:27], v[162:165], v[186:189], v[24:27]
	v_mfma_f32_16x16x32_bf16 v[12:15], v[146:149], v[194:197], v[12:15]
	v_mfma_f32_16x16x32_bf16 v[8:11], v[162:165], v[194:197], v[8:11]
	v_mfma_f32_16x16x32_bf16 v[60:63], v[150:153], v[174:177], v[60:63]
	v_mfma_f32_16x16x32_bf16 v[56:59], v[166:169], v[174:177], v[56:59]
	v_mfma_f32_16x16x32_bf16 v[44:47], v[150:153], v[182:185], v[44:47]
	v_mfma_f32_16x16x32_bf16 v[40:43], v[166:169], v[182:185], v[40:43]
	v_mfma_f32_16x16x32_bf16 v[28:31], v[150:153], v[190:193], v[28:31]
	v_mfma_f32_16x16x32_bf16 v[24:27], v[166:169], v[190:193], v[24:27]
	v_mfma_f32_16x16x32_bf16 v[12:15], v[150:153], v[198:201], v[12:15]
	v_mfma_f32_16x16x32_bf16 v[8:11], v[166:169], v[198:201], v[8:11]
	s_barrier
; #define PG8_STAGE(bufoff, gbase, voff) do { _Pragma("unroll") for (int _i = 0; _i < 2; ++_i) \
;     __builtin_amdgcn_global_load_lds((const unsigned*)((const char*)(gbase) + (voff)[_i]), (PG8_LAS unsigned*)(lds + (bufoff) + ldsw + _i * 8192), 16, 0, 0); } while (0)
; #define PG8_LDA(dst, b, h) do { _Pragma("unroll") for (int m = 0; m < 4; ++m) _Pragma("unroll") for (int k = 0; k < 2; ++k) dst[m][k] = *(const PG8_LAS bf16x8*)(lds + PG8_SA(b, h) + aoff + m * 2048 + k * 1024); } while (0)
; #define PG8_LDB(dst, b, h) do { _Pragma("unroll") for (int n = 0; n < 2; ++n) _Pragma("unroll") for (int k = 0; k < 2; ++k) dst[n][k] = *(const PG8_LAS bf16x8*)(lds + PG8_SB(b, h) + boff + n * 2048 + k * 1024); } while (0)
; #define PG8_MMA(ai, bj, At, Bt) do { __builtin_amdgcn_s_setprio(1); _Pragma("unroll") for (int m = 0; m < 4; ++m) _Pragma("unroll") for (int n = 0; n < 2; ++n) _Pragma("unroll") for (int k = 0; k < 2; ++k) \
;     acc[ai][bj][m][n] = __builtin_amdgcn_mfma_f32_16x16x32_bf16(Bt[n][k], At[m][k], acc[ai][bj][m][n], 0, 0, 0); __builtin_amdgcn_s_setprio(0); } while (0)
; template <class Epi>
; DI void gemm_phase(PG8_LAS unsigned char* lds, const Gemm g, const StaticOrder& S, const Epi& E, const int wv) {
;     ...
;       PG8_LDB(B0, 0, 0); PG8_SCHED; PG8_LDA(At, 0, 0); PG8_STAGE(PG8_SA(1, 1), a1 + hstep, voffA);
;       PG8_WAIT_L(8); PG8_BAR; PG8_WAIT_L(0); PG8_MMA(0, 0, At, B0); PG8_BAR; PG8_SCHED;
;       PG8_LDB(B1, 0, 1); PG8_STAGE(PG8_SB(0, 0), b2, voffB);
;       PG8_BAR; PG8_WAIT_L(0); PG8_MMA(0, 1, At, B1); PG8_BAR;
;       PG8_LDA(At, 0, 1); PG8_STAGE(PG8_SA(0, 0), a2, voffA);
;       PG8_BAR; PG8_WAIT_L(0); PG8_MMA(1, 0, At, B0); PG8_BAR; PG8_SCHED;
;       PG8_STAGE(PG8_SB(0, 1), b2 + hstep, voffB);
;       PG8_WAIT_V(6); PG8_BAR; PG8_MMA(1, 1, At, B1); PG8_BAR;
;       PG8_LDB(B0, 1, 0); PG8_SCHED; PG8_LDA(At, 1, 0); PG8_STAGE(PG8_SA(0, 1), a2 + hstep, voffA);
;       PG8_WAIT_L(8); PG8_BAR; PG8_WAIT_L(0); PG8_MMA(0, 0, At, B0); PG8_BAR; PG8_SCHED;
;       PG8_LDB(B1, 1, 1); PG8_STAGE(PG8_SB(1, 0), b3, voffB);
;       PG8_BAR; PG8_WAIT_L(0); PG8_MMA(0, 1, At, B1); PG8_BAR;
;       PG8_LDA(At, 1, 1); PG8_STAGE(PG8_SA(1, 0), a3, voffA);
;       PG8_BAR; PG8_WAIT_L(0); PG8_MMA(1, 0, At, B0); PG8_BAR; PG8_SCHED;
;       PG8_STAGE(PG8_SB(1, 1), b3 + hstep, voffB);
;       PG8_WAIT_V(6); PG8_BAR; PG8_MMA(1, 1, At, B1); PG8_BAR;
	s_setprio 0
	s_add_u32 s76, s36, 0x40000
	s_addc_u32 s77, s37, 0
	s_add_i32 s75, s65, s46
	v_lshl_add_u64 v[146:147], s[76:77], 0, v[130:131]
	s_mov_b32 m0, s75
	s_nop 0
	global_load_lds_dwordx4 v[146:147], off
	v_lshl_add_u64 v[146:147], s[76:77], 0, v[134:135]
	s_add_i32 m0, s75, 0x2000
	s_nop 0
	global_load_lds_dwordx4 v[146:147], off
	s_waitcnt vmcnt(6)
	s_setprio 1
	s_barrier
	v_mfma_f32_16x16x32_bf16 v[52:55], v[202:205], v[170:173], v[52:55]
	v_mfma_f32_16x16x32_bf16 v[48:51], v[210:213], v[170:173], v[48:51]
	v_mfma_f32_16x16x32_bf16 v[36:39], v[202:205], v[178:181], v[36:39]
	v_mfma_f32_16x16x32_bf16 v[32:35], v[210:213], v[178:181], v[32:35]
	v_mfma_f32_16x16x32_bf16 v[20:23], v[202:205], v[186:189], v[20:23]
	v_mfma_f32_16x16x32_bf16 v[16:19], v[210:213], v[186:189], v[16:19]
	v_mfma_f32_16x16x32_bf16 v[4:7], v[202:205], v[194:197], v[4:7]
	v_mfma_f32_16x16x32_bf16 v[0:3], v[210:213], v[194:197], v[0:3]
	v_mfma_f32_16x16x32_bf16 v[52:55], v[206:209], v[174:177], v[52:55]
	v_mfma_f32_16x16x32_bf16 v[48:51], v[214:217], v[174:177], v[48:51]
	v_mfma_f32_16x16x32_bf16 v[36:39], v[206:209], v[182:185], v[36:39]
	v_mfma_f32_16x16x32_bf16 v[32:35], v[214:217], v[182:185], v[32:35]
	v_mfma_f32_16x16x32_bf16 v[20:23], v[206:209], v[190:193], v[20:23]
	v_mfma_f32_16x16x32_bf16 v[16:19], v[214:217], v[190:193], v[16:19]
	v_mfma_f32_16x16x32_bf16 v[4:7], v[206:209], v[198:201], v[4:7]
	v_mfma_f32_16x16x32_bf16 v[0:3], v[214:217], v[198:201], v[0:3]
	s_add_i32 s75, 0, 0x18000
	v_add_u32_e32 v136, s75, v155
	s_barrier
	s_setprio 0
	ds_read_b128 v[146:149], v136
	ds_read_b128 v[150:153], v136 offset:1024
	ds_read_b128 v[162:165], v136 offset:2048
	ds_read_b128 v[166:169], v136 offset:3072
	s_add_u32 s38, s38, 0x40000
	s_addc_u32 s39, s39, 0
	s_mov_b32 m0, s48
	v_lshl_add_u64 v[202:203], s[38:39], 0, v[128:129]
	ds_read_b128 v[170:173], v158 offset:32768
	ds_read_b128 v[174:177], v158 offset:33792
	ds_read_b128 v[178:181], v158 offset:34816
	ds_read_b128 v[182:185], v158 offset:35840
	ds_read_b128 v[186:189], v158 offset:36864
	ds_read_b128 v[190:193], v158 offset:37888
	ds_read_b128 v[194:197], v158 offset:38912
	ds_read_b128 v[198:201], v158 offset:39936
	global_load_lds_dwordx4 v[202:203], off
	v_lshl_add_u64 v[202:203], s[38:39], 0, v[132:133]
	s_mov_b32 m0, s49
	s_nop 0
	global_load_lds_dwordx4 v[202:203], off
	s_waitcnt lgkmcnt(8)
	s_setprio 1
	s_barrier
	s_waitcnt lgkmcnt(0)
	s_waitcnt lgkmcnt(0)
	v_mfma_f32_16x16x32_bf16 v[124:127], v[146:149], v[170:173], v[124:127]
	v_mfma_f32_16x16x32_bf16 v[120:123], v[162:165], v[170:173], v[120:123]
	v_mfma_f32_16x16x32_bf16 v[108:111], v[146:149], v[178:181], v[108:111]
	v_mfma_f32_16x16x32_bf16 v[104:107], v[162:165], v[178:181], v[104:107]
	v_mfma_f32_16x16x32_bf16 v[92:95], v[146:149], v[186:189], v[92:95]
	v_mfma_f32_16x16x32_bf16 v[88:91], v[162:165], v[186:189], v[88:91]
	v_mfma_f32_16x16x32_bf16 v[76:79], v[146:149], v[194:197], v[76:79]
	v_mfma_f32_16x16x32_bf16 v[72:75], v[162:165], v[194:197], v[72:75]
	v_mfma_f32_16x16x32_bf16 v[124:127], v[150:153], v[174:177], v[124:127]
	v_mfma_f32_16x16x32_bf16 v[120:123], v[166:169], v[174:177], v[120:123]
	v_mfma_f32_16x16x32_bf16 v[108:111], v[150:153], v[182:185], v[108:111]
	v_mfma_f32_16x16x32_bf16 v[104:107], v[166:169], v[182:185], v[104:107]
	v_mfma_f32_16x16x32_bf16 v[92:95], v[150:153], v[190:193], v[92:95]
	v_mfma_f32_16x16x32_bf16 v[88:91], v[166:169], v[190:193], v[88:91]
	v_mfma_f32_16x16x32_bf16 v[76:79], v[150:153], v[198:201], v[76:79]
	v_mfma_f32_16x16x32_bf16 v[72:75], v[166:169], v[198:201], v[72:75]
	s_barrier
	s_setprio 0
	s_add_i32 s38, 0, 0x1c000
	s_add_i32 s39, s75, s46
	v_add_u32_e32 v136, s38, v155
	v_lshl_add_u64 v[220:221], v[220:221], 0, s[20:21]
	s_mov_b32 m0, s39
	ds_read_b128 v[202:205], v136
	ds_read_b128 v[206:209], v136 offset:1024
	ds_read_b128 v[210:213], v136 offset:2048
	ds_read_b128 v[214:217], v136 offset:3072
	global_load_lds_dwordx4 v[220:221], off
	v_lshl_add_u64 v[220:221], v[222:223], 0, s[20:21]
	s_add_i32 m0, s39, 0x2000
	s_nop 0
	global_load_lds_dwordx4 v[220:221], off
	s_setprio 1
	s_barrier
	s_waitcnt lgkmcnt(0)
	s_waitcnt lgkmcnt(0)
	v_mfma_f32_16x16x32_bf16 v[116:119], v[202:205], v[170:173], v[116:119]
	v_mfma_f32_16x16x32_bf16 v[112:115], v[210:213], v[170:173], v[112:115]
	v_mfma_f32_16x16x32_bf16 v[100:103], v[202:205], v[178:181], v[100:103]
	v_mfma_f32_16x16x32_bf16 v[96:99], v[210:213], v[178:181], v[96:99]
	v_mfma_f32_16x16x32_bf16 v[84:87], v[202:205], v[186:189], v[84:87]
	v_mfma_f32_16x16x32_bf16 v[80:83], v[210:213], v[186:189], v[80:83]
	v_mfma_f32_16x16x32_bf16 v[68:71], v[202:205], v[194:197], v[68:71]
	v_mfma_f32_16x16x32_bf16 v[64:67], v[210:213], v[194:197], v[64:67]
	v_mfma_f32_16x16x32_bf16 v[116:119], v[206:209], v[174:177], v[116:119]
	v_mfma_f32_16x16x32_bf16 v[112:115], v[214:217], v[174:177], v[112:115]
	v_mfma_f32_16x16x32_bf16 v[100:103], v[206:209], v[182:185], v[100:103]
	v_mfma_f32_16x16x32_bf16 v[96:99], v[214:217], v[182:185], v[96:99]
	v_mfma_f32_16x16x32_bf16 v[84:87], v[206:209], v[190:193], v[84:87]
	v_mfma_f32_16x16x32_bf16 v[80:83], v[214:217], v[190:193], v[80:83]
	v_mfma_f32_16x16x32_bf16 v[68:71], v[206:209], v[198:201], v[68:71]
	v_mfma_f32_16x16x32_bf16 v[64:67], v[214:217], v[198:201], v[64:67]
	s_mov_b32 m0, s54
	v_lshl_add_u64 v[220:221], v[224:225], 0, s[20:21]
	s_barrier
; #define PG8_STAGE(bufoff, gbase, voff) do { _Pragma("unroll") for (int _i = 0; _i < 2; ++_i) \
;     __builtin_amdgcn_global_load_lds((const unsigned*)((const char*)(gbase) + (voff)[_i]), (PG8_LAS unsigned*)(lds + (bufoff) + ldsw + _i * 8192), 16, 0, 0); } while (0)
; #define PG8_LDA(dst, b, h) do { _Pragma("unroll") for (int m = 0; m < 4; ++m) _Pragma("unroll") for (int k = 0; k < 2; ++k) dst[m][k] = *(const PG8_LAS bf16x8*)(lds + PG8_SA(b, h) + aoff + m * 2048 + k * 1024); } while (0)
; #define PG8_LDB(dst, b, h) do { _Pragma("unroll") for (int n = 0; n < 2; ++n) _Pragma("unroll") for (int k = 0; k < 2; ++k) dst[n][k] = *(const PG8_LAS bf16x8*)(lds + PG8_SB(b, h) + boff + n * 2048 + k * 1024); } while (0)
; #define PG8_WAIT_V(n) asm volatile("s_waitcnt vmcnt(" #n ")" ::: "memory")
; #define PG8_BAR __builtin_amdgcn_s_barrier()
; template <class Epi>
; DI void gemm_phase(PG8_LAS unsigned char* lds, const Gemm g, const StaticOrder& S, const Epi& E, const int wv) {
;     ...
;       PG8_WAIT_V(6); PG8_BAR; PG8_MMA(1, 1, At, B1); PG8_BAR;
;       PG8_LDB(B0, 1, 0); PG8_SCHED; PG8_LDA(At, 1, 0); PG8_STAGE(PG8_SA(0, 1), a2 + hstep, voffA);
;       PG8_WAIT_L(8); PG8_BAR; PG8_WAIT_L(0); PG8_MMA(0, 0, At, B0); PG8_BAR; PG8_SCHED;
;       PG8_LDB(B1, 1, 1); PG8_STAGE(PG8_SB(1, 0), b3, voffB);
;       PG8_BAR; PG8_WAIT_L(0); PG8_MMA(0, 1, At, B1); PG8_BAR;
;       PG8_LDA(At, 1, 1); PG8_STAGE(PG8_SA(1, 0), a3, voffA);
;       PG8_BAR; PG8_WAIT_L(0); PG8_MMA(1, 0, At, B0); PG8_BAR; PG8_SCHED;
;       PG8_STAGE(PG8_SB(1, 1), b3 + hstep, voffB);
;       PG8_WAIT_V(6); PG8_BAR; PG8_MMA(1, 1, At, B1); PG8_BAR;
;     }
;     E(acc, cur, wr, wc, fr, fq);
;   DI void operator()(AccRef acc, const pg8::Unit& u, int wr, int wc, int fr, int fq) const {
;     ...
;     EPI_ROWS_BEGIN()
;       float rs[4];
; #pragma unroll
;       for (int m = 0; m < 4; ++m) rs[m] = ss[row0 + ai * 128 + m * 16];
; #pragma unroll
;       for (int m = 0; m < 4; ++m) rs[m] = rsqrtf(rs[m] * (1.f / DM) + EPS);
; #pragma unroll
;       for (int m = 0; m < 4; ++m) {
;         const int row = row0 + ai * 128 + m * 16;
;         if (u.pn < 5) {
; #pragma unroll
;           for (int bj = 0; bj < 2; ++bj)
;             *(u32x4*)(qk + (size_t)row * 1280 + u.pn * 256 + bj * 128 + w0) = pack8v(acc[ai][bj][m][0] * rs[m], acc[ai][bj][m][1] * rs[m]);
;         } else {
;           const int s = row / L, p = row - s * L;
	s_setprio 0
	ds_read_b128 v[170:173], v158 offset:49152
	ds_read_b128 v[174:177], v158 offset:50176
	ds_read_b128 v[178:181], v158 offset:51200
	ds_read_b128 v[182:185], v158 offset:52224
	ds_read_b128 v[186:189], v158 offset:53248
	ds_read_b128 v[190:193], v158 offset:54272
	ds_read_b128 v[194:197], v158 offset:55296
	ds_read_b128 v[198:201], v158 offset:56320
	global_load_lds_dwordx4 v[220:221], off
	v_lshl_add_u64 v[220:221], v[226:227], 0, s[20:21]
	s_mov_b32 m0, s55
	s_nop 0
	global_load_lds_dwordx4 v[220:221], off
	s_setprio 1
	s_barrier
	s_waitcnt lgkmcnt(0)
	v_mfma_f32_16x16x32_bf16 v[60:63], v[146:149], v[170:173], v[60:63]
	v_mfma_f32_16x16x32_bf16 v[56:59], v[162:165], v[170:173], v[56:59]
	v_mfma_f32_16x16x32_bf16 v[44:47], v[146:149], v[178:181], v[44:47]
	v_mfma_f32_16x16x32_bf16 v[40:43], v[162:165], v[178:181], v[40:43]
	v_mfma_f32_16x16x32_bf16 v[28:31], v[146:149], v[186:189], v[28:31]
	v_mfma_f32_16x16x32_bf16 v[24:27], v[162:165], v[186:189], v[24:27]
	v_mfma_f32_16x16x32_bf16 v[12:15], v[146:149], v[194:197], v[12:15]
	v_mfma_f32_16x16x32_bf16 v[8:11], v[162:165], v[194:197], v[8:11]
	v_mfma_f32_16x16x32_bf16 v[60:63], v[150:153], v[174:177], v[60:63]
	v_mfma_f32_16x16x32_bf16 v[56:59], v[166:169], v[174:177], v[56:59]
	v_mfma_f32_16x16x32_bf16 v[44:47], v[150:153], v[182:185], v[44:47]
	v_mfma_f32_16x16x32_bf16 v[40:43], v[166:169], v[182:185], v[40:43]
	v_mfma_f32_16x16x32_bf16 v[28:31], v[150:153], v[190:193], v[28:31]
	v_mfma_f32_16x16x32_bf16 v[24:27], v[166:169], v[190:193], v[24:27]
	v_mfma_f32_16x16x32_bf16 v[12:15], v[150:153], v[198:201], v[12:15]
	v_mfma_f32_16x16x32_bf16 v[8:11], v[166:169], v[198:201], v[8:11]
	s_barrier
	s_setprio 0
	s_add_u32 s36, s36, 0x40080
	s_addc_u32 s37, s37, 0
	s_add_i32 s38, s38, s46
	v_lshl_add_u64 v[146:147], s[36:37], 0, v[130:131]
	s_mov_b32 m0, s38
	s_nop 0
	global_load_lds_dwordx4 v[146:147], off
	v_lshl_add_u64 v[146:147], s[36:37], 0, v[134:135]
	s_add_i32 m0, s38, 0x2000
	s_nop 0
	global_load_lds_dwordx4 v[146:147], off
	s_waitcnt vmcnt(6)
	s_setprio 1
	s_barrier
	v_mfma_f32_16x16x32_bf16 v[52:55], v[202:205], v[170:173], v[52:55]
	v_mfma_f32_16x16x32_bf16 v[48:51], v[210:213], v[170:173], v[48:51]
	v_mfma_f32_16x16x32_bf16 v[36:39], v[202:205], v[178:181], v[36:39]
	v_mfma_f32_16x16x32_bf16 v[32:35], v[210:213], v[178:181], v[32:35]
	v_mfma_f32_16x16x32_bf16 v[20:23], v[202:205], v[186:189], v[20:23]
	v_mfma_f32_16x16x32_bf16 v[16:19], v[210:213], v[186:189], v[16:19]
	v_mfma_f32_16x16x32_bf16 v[4:7], v[202:205], v[194:197], v[4:7]
	v_mfma_f32_16x16x32_bf16 v[0:3], v[210:213], v[194:197], v[0:3]
	v_mfma_f32_16x16x32_bf16 v[52:55], v[206:209], v[174:177], v[52:55]
	v_mfma_f32_16x16x32_bf16 v[48:51], v[214:217], v[174:177], v[48:51]
	v_mfma_f32_16x16x32_bf16 v[36:39], v[206:209], v[182:185], v[36:39]
	v_mfma_f32_16x16x32_bf16 v[32:35], v[214:217], v[182:185], v[32:35]
	v_mfma_f32_16x16x32_bf16 v[20:23], v[206:209], v[190:193], v[20:23]
	v_mfma_f32_16x16x32_bf16 v[16:19], v[214:217], v[190:193], v[16:19]
	v_mfma_f32_16x16x32_bf16 v[4:7], v[206:209], v[198:201], v[4:7]
	v_mfma_f32_16x16x32_bf16 v[0:3], v[214:217], v[198:201], v[0:3]
	s_add_i32 s74, s74, 2
	s_add_u32 s6, s6, 0x100
	s_addc_u32 s7, s7, 0
	s_add_u32 s72, s72, 0x100
	s_addc_u32 s73, s73, 0
	s_cmp_gt_u32 s74, 13
	s_barrier
	s_setprio 0
	s_cbranch_scc0 .LBB0_1061
	s_cmp_gt_i32 s4, 4
	s_cselect_b64 s[38:39], -1, 0
	s_lshl_b32 s36, s4, 8
	s_ashr_i32 s37, s36, 31
	s_cmpk_gt_i32 s34, 0x181
	v_lshl_add_u32 v146, s34, 8, v139
	s_cbranch_scc1 .LBB0_1079
	v_ashrrev_i32_e32 v147, 31, v146
	v_lshl_add_u64 v[148:149], v[146:147], 2, s[18:19]
	global_load_dword v136, v[148:149], off
	v_or_b32_e32 v152, 16, v146
	v_or_b32_e32 v150, 32, v146
	v_or_b32_e32 v148, 48, v146
	v_ashrrev_i32_e32 v153, 31, v152
	v_ashrrev_i32_e32 v151, 31, v150
	v_ashrrev_i32_e32 v149, 31, v148
	v_lshl_add_u64 v[162:163], v[152:153], 2, s[18:19]
	v_lshl_add_u64 v[164:165], v[150:151], 2, s[18:19]
	v_lshl_add_u64 v[166:167], v[148:149], 2, s[18:19]
	global_load_dword v151, v[162:163], off
	global_load_dword v149, v[164:165], off
	global_load_dword v147, v[166:167], off
	s_and_b64 s[4:5], exec, s[38:39]
	s_mov_b64 s[6:7], -1
	s_waitcnt vmcnt(0)
	v_fmamk_f32 v136, v136, 0x3a800000, v160
	v_mul_f32_e32 v153, 0x4b800000, v136
	v_cmp_gt_f32_e32 vcc, s66, v136
	s_nop 1
	v_cndmask_b32_e32 v136, v136, v153, vcc
	v_rsq_f32_e32 v136, v136
	s_nop 0
	v_mul_f32_e32 v153, 0x45800000, v136
	v_cndmask_b32_e32 v154, v136, v153, vcc
	s_mov_b64 vcc, s[4:5]
	s_cbranch_vccz .LBB0_1065
; DI u16 f2bf(float x) { return (u16)(cvtpk(x, 0.f) & 0xffffu); }
; DI int vt_pos(int p) { return (p & ~12) | ((p & 4) << 1) | ((p & 8) >> 1); }
;   DI void operator()(AccRef acc, const pg8::Unit& u, int wr, int wc, int fr, int fq) const {
;     ...
;           const int s = row / L, p = row - s * L;
; #pragma unroll
;           for (int bj = 0; bj < 2; ++bj) {
;             u16* vp = vt + (size_t)((s * 2 + bj) * 128 + w0) * LP + vt_pos(p);
; #pragma unroll
;             for (int n = 0; n < 2; ++n)
; #pragma unroll
;               for (int e = 0; e < 4; ++e) vp[(size_t)(4 * n + e) * LP] = f2bf(acc[ai][bj][m][n][e] * rs[m]);
;           }
	v_mul_hi_i32 v136, v146, s67
	v_lshrrev_b32_e32 v153, 31, v136
	v_ashrrev_i32_e32 v136, 11, v136
	v_add_u32_e32 v136, v136, v153
	v_mad_i32_i24 v153, v136, s68, v146
	v_and_or_b32 v162, v153, -13, v156
	v_ashrrev_i32_e32 v163, 31, v162
	v_lshl_or_b32 v136, v136, 8, v138
	v_lshl_add_u64 v[162:163], v[162:163], 1, s[16:17]
	v_mul_f32_e32 v153, v124, v154
	v_mad_i64_i32 v[164:165], s[4:5], v136, s69, v[162:163]
	v_cvt_pk_bf16_f32 v153, v153, s0
	global_store_short v[164:165], v153, off
	v_mul_f32_e32 v153, v125, v154
	v_add_co_u32_e32 v166, vcc, s50, v164
	v_cvt_pk_bf16_f32 v153, v153, s0
	s_nop 0
	v_addc_co_u32_e32 v167, vcc, 0, v165, vcc
	global_store_short v[166:167], v153, off offset:128
	v_mul_f32_e32 v153, v126, v154
	v_add_co_u32_e32 v166, vcc, s52, v164
	v_cvt_pk_bf16_f32 v153, v153, s0
	s_nop 0
	v_addc_co_u32_e32 v167, vcc, 0, v165, vcc
	global_store_short v[166:167], v153, off offset:256
	v_mul_f32_e32 v153, v127, v154
	v_add_co_u32_e32 v166, vcc, s53, v164
	v_cvt_pk_bf16_f32 v153, v153, s0
	s_nop 0
	v_addc_co_u32_e32 v167, vcc, 0, v165, vcc
	global_store_short v[166:167], v153, off offset:384
	v_mul_f32_e32 v153, v120, v154
	v_add_co_u32_e32 v166, vcc, s57, v164
	v_cvt_pk_bf16_f32 v153, v153, s0
	s_nop 0
	v_addc_co_u32_e32 v167, vcc, 0, v165, vcc
	global_store_short v[166:167], v153, off offset:512
	v_mul_f32_e32 v153, v121, v154
	v_add_co_u32_e32 v166, vcc, s58, v164
	v_cvt_pk_bf16_f32 v153, v153, s0
	s_nop 0
	v_addc_co_u32_e32 v167, vcc, 0, v165, vcc
	global_store_short v[166:167], v153, off offset:640
	v_mul_f32_e32 v153, v122, v154
	v_add_co_u32_e32 v166, vcc, s63, v164
	v_cvt_pk_bf16_f32 v153, v153, s0
	s_nop 0
	v_addc_co_u32_e32 v167, vcc, 0, v165, vcc
	v_or_b32_e32 v136, 0x80, v136
	global_store_short v[166:167], v153, off offset:768
	v_mul_f32_e32 v153, v123, v154
	v_add_co_u32_e32 v164, vcc, s64, v164
	v_mad_i64_i32 v[162:163], s[4:5], v136, s69, v[162:163]
	v_mul_f32_e32 v136, v116, v154
	v_cvt_pk_bf16_f32 v153, v153, s0
	v_addc_co_u32_e32 v165, vcc, 0, v165, vcc
	v_cvt_pk_bf16_f32 v136, v136, s0
	global_store_short v[164:165], v153, off offset:896
	global_store_short v[162:163], v136, off
	v_mul_f32_e32 v136, v117, v154
	v_add_co_u32_e32 v164, vcc, s50, v162
	v_cvt_pk_bf16_f32 v136, v136, s0
	s_nop 0
	v_addc_co_u32_e32 v165, vcc, 0, v163, vcc
	global_store_short v[164:165], v136, off offset:128
	v_mul_f32_e32 v136, v118, v154
	v_add_co_u32_e32 v164, vcc, s52, v162
	v_cvt_pk_bf16_f32 v136, v136, s0
	s_nop 0
	v_addc_co_u32_e32 v165, vcc, 0, v163, vcc
	global_store_short v[164:165], v136, off offset:256
	v_mul_f32_e32 v136, v119, v154
	v_add_co_u32_e32 v164, vcc, s53, v162
	v_cvt_pk_bf16_f32 v136, v136, s0
	s_nop 0
	v_addc_co_u32_e32 v165, vcc, 0, v163, vcc
	global_store_short v[164:165], v136, off offset:384
	v_mul_f32_e32 v136, v112, v154
	v_add_co_u32_e32 v164, vcc, s57, v162
	v_cvt_pk_bf16_f32 v136, v136, s0
	s_nop 0
	v_addc_co_u32_e32 v165, vcc, 0, v163, vcc
	global_store_short v[164:165], v136, off offset:512
	v_mul_f32_e32 v136, v113, v154
	v_add_co_u32_e32 v164, vcc, s58, v162
	v_cvt_pk_bf16_f32 v136, v136, s0
	s_nop 0
	v_addc_co_u32_e32 v165, vcc, 0, v163, vcc
	global_store_short v[164:165], v136, off offset:640
	v_mul_f32_e32 v136, v114, v154
	v_add_co_u32_e32 v164, vcc, 0xc000, v162
	v_cvt_pk_bf16_f32 v136, v136, s0
	s_nop 0
	v_addc_co_u32_e32 v165, vcc, 0, v163, vcc
	global_store_short v[164:165], v136, off offset:768
	v_mul_f32_e32 v136, v115, v154
	v_add_co_u32_e32 v162, vcc, 0xe000, v162
	v_cvt_pk_bf16_f32 v136, v136, s0
	s_nop 0
	v_addc_co_u32_e32 v163, vcc, 0, v163, vcc
	global_store_short v[162:163], v136, off offset:896
	s_mov_b64 s[6:7], 0

; #define PG8_STAGE(bufoff, gbase, voff) do { _Pragma("unroll") for (int _i = 0; _i < 2; ++_i) \
;     __builtin_amdgcn_global_load_lds((const unsigned*)((const char*)(gbase) + (voff)[_i]), (PG8_LAS unsigned*)(lds + (bufoff) + ldsw + _i * 8192), 16, 0, 0); } while (0)
; #define PG8_LDA(dst, b, h) do { _Pragma("unroll") for (int m = 0; m < 4; ++m) _Pragma("unroll") for (int k = 0; k < 2; ++k) dst[m][k] = *(const PG8_LAS bf16x8*)(lds + PG8_SA(b, h) + aoff + m * 2048 + k * 1024); } while (0)
; #define PG8_LDB(dst, b, h) do { _Pragma("unroll") for (int n = 0; n < 2; ++n) _Pragma("unroll") for (int k = 0; k < 2; ++k) dst[n][k] = *(const PG8_LAS bf16x8*)(lds + PG8_SB(b, h) + boff + n * 2048 + k * 1024); } while (0)
; #define PG8_MMA(ai, bj, At, Bt) do { __builtin_amdgcn_s_setprio(1); _Pragma("unroll") for (int m = 0; m < 4; ++m) _Pragma("unroll") for (int n = 0; n < 2; ++n) _Pragma("unroll") for (int k = 0; k < 2; ++k) \
;     acc[ai][bj][m][n] = __builtin_amdgcn_mfma_f32_16x16x32_bf16(Bt[n][k], At[m][k], acc[ai][bj][m][n], 0, 0, 0); __builtin_amdgcn_s_setprio(0); } while (0)
; template <class Epi>
; DI void gemm_phase(PG8_LAS unsigned char* lds, const Gemm g, const StaticOrder& S, const Epi& E, const int wv) {
;     ...
;       PG8_LDB(B0, 0, 0); PG8_SCHED; PG8_LDA(At, 0, 0); PG8_STAGE(PG8_SA(1, 1), a1 + hstep, voffA);
;       PG8_WAIT_L(8); PG8_BAR; PG8_WAIT_L(0); PG8_MMA(0, 0, At, B0); PG8_BAR; PG8_SCHED;
;       PG8_LDB(B1, 0, 1); PG8_STAGE(PG8_SB(0, 0), b2, voffB);
;       PG8_BAR; PG8_WAIT_L(0); PG8_MMA(0, 1, At, B1); PG8_BAR;
;       PG8_LDA(At, 0, 1); PG8_STAGE(PG8_SA(0, 0), a2, voffA);
;       PG8_BAR; PG8_WAIT_L(0); PG8_MMA(1, 0, At, B0); PG8_BAR; PG8_SCHED;
;       PG8_STAGE(PG8_SB(0, 1), b2 + hstep, voffB);
;       PG8_WAIT_V(6); PG8_BAR; PG8_MMA(1, 1, At, B1); PG8_BAR;
;       PG8_LDB(B0, 1, 0); PG8_SCHED; PG8_LDA(At, 1, 0); PG8_STAGE(PG8_SA(0, 1), a2 + hstep, voffA);
;       PG8_WAIT_L(8); PG8_BAR; PG8_WAIT_L(0); PG8_MMA(0, 0, At, B0); PG8_BAR; PG8_SCHED;
;       PG8_LDB(B1, 1, 1); PG8_STAGE(PG8_SB(1, 0), b3, voffB);
;       PG8_BAR; PG8_WAIT_L(0); PG8_MMA(0, 1, At, B1); PG8_BAR;
;       PG8_LDA(At, 1, 1); PG8_STAGE(PG8_SA(1, 0), a3, voffA);
;       PG8_BAR; PG8_WAIT_L(0); PG8_MMA(1, 0, At, B0); PG8_BAR; PG8_SCHED;
;       PG8_STAGE(PG8_SB(1, 1), b3 + hstep, voffB);
;       PG8_WAIT_V(6); PG8_BAR; PG8_MMA(1, 1, At, B1); PG8_BAR;
.LBB0_1284:
	ds_read_b128 v[128:131], v179
	ds_read_b128 v[132:135], v179 offset:1024
	ds_read_b128 v[136:139], v179 offset:2048
	ds_read_b128 v[140:143], v179 offset:3072
	s_add_u32 s38, s36, 0xfffc0080
	s_addc_u32 s39, s37, -1
	s_cmp_eq_u32 s64, 12
	s_cselect_b32 s41, s25, s39
	s_cselect_b32 s40, s31, s38
	s_cselect_b32 s39, s23, s63
	s_cselect_b32 s38, s35, s62
	v_lshl_add_u64 v[174:175], s[36:37], 0, v[160:161]
	s_add_i32 m0, s47, 0xc000
	ds_read_b128 v[144:147], v180
	ds_read_b128 v[148:151], v180 offset:1024
	ds_read_b128 v[166:169], v180 offset:2048
	ds_read_b128 v[170:173], v180 offset:3072
	ds_read_b128 v[184:187], v180 offset:4096
	ds_read_b128 v[188:191], v180 offset:5120
	ds_read_b128 v[192:195], v180 offset:6144
	ds_read_b128 v[196:199], v180 offset:7168
	global_load_lds_dwordx4 v[174:175], off
	v_lshl_add_u64 v[174:175], s[36:37], 0, v[162:163]
	s_add_i32 m0, s47, 0xe000
	s_nop 0
	global_load_lds_dwordx4 v[174:175], off
	s_waitcnt lgkmcnt(8)
	s_setprio 1
	s_barrier
	s_waitcnt lgkmcnt(0)
	s_waitcnt lgkmcnt(0)
	v_mfma_f32_16x16x32_bf16 v[124:127], v[128:131], v[144:147], v[124:127]
	v_mfma_f32_16x16x32_bf16 v[120:123], v[136:139], v[144:147], v[120:123]
	v_mfma_f32_16x16x32_bf16 v[108:111], v[128:131], v[166:169], v[108:111]
	v_mfma_f32_16x16x32_bf16 v[104:107], v[136:139], v[166:169], v[104:107]
	v_mfma_f32_16x16x32_bf16 v[92:95], v[128:131], v[184:187], v[92:95]
	v_mfma_f32_16x16x32_bf16 v[88:91], v[136:139], v[184:187], v[88:91]
	v_mfma_f32_16x16x32_bf16 v[76:79], v[128:131], v[192:195], v[76:79]
	v_mfma_f32_16x16x32_bf16 v[72:75], v[136:139], v[192:195], v[72:75]
	v_mfma_f32_16x16x32_bf16 v[124:127], v[132:135], v[148:151], v[124:127]
	v_mfma_f32_16x16x32_bf16 v[120:123], v[140:143], v[148:151], v[120:123]
	v_mfma_f32_16x16x32_bf16 v[108:111], v[132:135], v[170:173], v[108:111]
	v_mfma_f32_16x16x32_bf16 v[104:107], v[140:143], v[170:173], v[104:107]
	v_mfma_f32_16x16x32_bf16 v[92:95], v[132:135], v[188:191], v[92:95]
	v_mfma_f32_16x16x32_bf16 v[88:91], v[140:143], v[188:191], v[88:91]
	v_mfma_f32_16x16x32_bf16 v[76:79], v[132:135], v[196:199], v[76:79]
	v_mfma_f32_16x16x32_bf16 v[72:75], v[140:143], v[196:199], v[72:75]
	s_barrier
	s_setprio 0
	s_add_i32 s65, s60, s46
	v_lshl_add_u64 v[174:175], s[38:39], 0, v[154:155]
	s_mov_b32 m0, s65
	ds_read_b128 v[200:203], v181
	ds_read_b128 v[204:207], v181 offset:1024
	ds_read_b128 v[208:211], v181 offset:2048
	ds_read_b128 v[212:215], v181 offset:3072
	global_load_lds_dwordx4 v[174:175], off
	v_lshl_add_u64 v[216:217], s[38:39], 0, v[158:159]
	s_add_i32 m0, s65, 0x2000
	s_nop 0
	global_load_lds_dwordx4 v[216:217], off
	s_setprio 1
	s_barrier
	s_waitcnt lgkmcnt(0)
	v_mfma_f32_16x16x32_bf16 v[116:119], v[200:203], v[144:147], v[116:119]
	v_mfma_f32_16x16x32_bf16 v[112:115], v[208:211], v[144:147], v[112:115]
	v_mfma_f32_16x16x32_bf16 v[100:103], v[200:203], v[166:169], v[100:103]
	v_mfma_f32_16x16x32_bf16 v[96:99], v[208:211], v[166:169], v[96:99]
	v_mfma_f32_16x16x32_bf16 v[84:87], v[200:203], v[184:187], v[84:87]
	v_mfma_f32_16x16x32_bf16 v[80:83], v[208:211], v[184:187], v[80:83]
	v_mfma_f32_16x16x32_bf16 v[68:71], v[200:203], v[192:195], v[68:71]
	v_mfma_f32_16x16x32_bf16 v[64:67], v[208:211], v[192:195], v[64:67]
	v_mfma_f32_16x16x32_bf16 v[116:119], v[204:207], v[148:151], v[116:119]
	v_mfma_f32_16x16x32_bf16 v[112:115], v[212:215], v[148:151], v[112:115]
	v_mfma_f32_16x16x32_bf16 v[100:103], v[204:207], v[170:173], v[100:103]
	v_mfma_f32_16x16x32_bf16 v[96:99], v[212:215], v[170:173], v[96:99]
	v_mfma_f32_16x16x32_bf16 v[84:87], v[204:207], v[188:191], v[84:87]
	v_mfma_f32_16x16x32_bf16 v[80:83], v[212:215], v[188:191], v[80:83]
	v_mfma_f32_16x16x32_bf16 v[68:71], v[204:207], v[196:199], v[68:71]
	v_mfma_f32_16x16x32_bf16 v[64:67], v[212:215], v[196:199], v[64:67]
	s_mov_b32 m0, s47
	v_lshl_add_u64 v[218:219], s[40:41], 0, v[152:153]
	s_barrier
	s_setprio 0
	ds_read_b128 v[144:147], v180 offset:16384
	ds_read_b128 v[148:151], v180 offset:17408
	ds_read_b128 v[166:169], v180 offset:18432
	ds_read_b128 v[170:173], v180 offset:19456
	ds_read_b128 v[184:187], v180 offset:20480
	ds_read_b128 v[188:191], v180 offset:21504
	ds_read_b128 v[192:195], v180 offset:22528
	ds_read_b128 v[196:199], v180 offset:23552
	global_load_lds_dwordx4 v[218:219], off
	v_lshl_add_u64 v[220:221], s[40:41], 0, v[156:157]
	s_mov_b32 m0, s48
	s_nop 0
	global_load_lds_dwordx4 v[220:221], off
	s_setprio 1
	s_barrier
	s_waitcnt lgkmcnt(0)
	v_mfma_f32_16x16x32_bf16 v[60:63], v[128:131], v[144:147], v[60:63]
	v_mfma_f32_16x16x32_bf16 v[56:59], v[136:139], v[144:147], v[56:59]
	v_mfma_f32_16x16x32_bf16 v[44:47], v[128:131], v[166:169], v[44:47]
	v_mfma_f32_16x16x32_bf16 v[40:43], v[136:139], v[166:169], v[40:43]
	v_mfma_f32_16x16x32_bf16 v[28:31], v[128:131], v[184:187], v[28:31]
	v_mfma_f32_16x16x32_bf16 v[24:27], v[136:139], v[184:187], v[24:27]
	v_mfma_f32_16x16x32_bf16 v[12:15], v[128:131], v[192:195], v[12:15]
	v_mfma_f32_16x16x32_bf16 v[8:11], v[136:139], v[192:195], v[8:11]
	v_mfma_f32_16x16x32_bf16 v[60:63], v[132:135], v[148:151], v[60:63]
	v_mfma_f32_16x16x32_bf16 v[56:59], v[140:143], v[148:151], v[56:59]
	v_mfma_f32_16x16x32_bf16 v[44:47], v[132:135], v[170:173], v[44:47]
	v_mfma_f32_16x16x32_bf16 v[40:43], v[140:143], v[170:173], v[40:43]
	v_mfma_f32_16x16x32_bf16 v[28:31], v[132:135], v[188:191], v[28:31]
	v_mfma_f32_16x16x32_bf16 v[24:27], v[140:143], v[188:191], v[24:27]
	v_mfma_f32_16x16x32_bf16 v[12:15], v[132:135], v[196:199], v[12:15]
	v_mfma_f32_16x16x32_bf16 v[8:11], v[140:143], v[196:199], v[8:11]
	s_barrier
; #define PG8_STAGE(bufoff, gbase, voff) do { _Pragma("unroll") for (int _i = 0; _i < 2; ++_i) \
;     __builtin_amdgcn_global_load_lds((const unsigned*)((const char*)(gbase) + (voff)[_i]), (PG8_LAS unsigned*)(lds + (bufoff) + ldsw + _i * 8192), 16, 0, 0); } while (0)
; #define PG8_LDA(dst, b, h) do { _Pragma("unroll") for (int m = 0; m < 4; ++m) _Pragma("unroll") for (int k = 0; k < 2; ++k) dst[m][k] = *(const PG8_LAS bf16x8*)(lds + PG8_SA(b, h) + aoff + m * 2048 + k * 1024); } while (0)
; #define PG8_LDB(dst, b, h) do { _Pragma("unroll") for (int n = 0; n < 2; ++n) _Pragma("unroll") for (int k = 0; k < 2; ++k) dst[n][k] = *(const PG8_LAS bf16x8*)(lds + PG8_SB(b, h) + boff + n * 2048 + k * 1024); } while (0)
; #define PG8_MMA(ai, bj, At, Bt) do { __builtin_amdgcn_s_setprio(1); _Pragma("unroll") for (int m = 0; m < 4; ++m) _Pragma("unroll") for (int n = 0; n < 2; ++n) _Pragma("unroll") for (int k = 0; k < 2; ++k) \
;     acc[ai][bj][m][n] = __builtin_amdgcn_mfma_f32_16x16x32_bf16(Bt[n][k], At[m][k], acc[ai][bj][m][n], 0, 0, 0); __builtin_amdgcn_s_setprio(0); } while (0)
; template <class Epi>
; DI void gemm_phase(PG8_LAS unsigned char* lds, const Gemm g, const StaticOrder& S, const Epi& E, const int wv) {
;     ...
;       PG8_LDB(B0, 0, 0); PG8_SCHED; PG8_LDA(At, 0, 0); PG8_STAGE(PG8_SA(1, 1), a1 + hstep, voffA);
;       PG8_WAIT_L(8); PG8_BAR; PG8_WAIT_L(0); PG8_MMA(0, 0, At, B0); PG8_BAR; PG8_SCHED;
;       PG8_LDB(B1, 0, 1); PG8_STAGE(PG8_SB(0, 0), b2, voffB);
;       PG8_BAR; PG8_WAIT_L(0); PG8_MMA(0, 1, At, B1); PG8_BAR;
;       PG8_LDA(At, 0, 1); PG8_STAGE(PG8_SA(0, 0), a2, voffA);
;       PG8_BAR; PG8_WAIT_L(0); PG8_MMA(1, 0, At, B0); PG8_BAR; PG8_SCHED;
;       PG8_STAGE(PG8_SB(0, 1), b2 + hstep, voffB);
;       PG8_WAIT_V(6); PG8_BAR; PG8_MMA(1, 1, At, B1); PG8_BAR;
;       PG8_LDB(B0, 1, 0); PG8_SCHED; PG8_LDA(At, 1, 0); PG8_STAGE(PG8_SA(0, 1), a2 + hstep, voffA);
;       PG8_WAIT_L(8); PG8_BAR; PG8_WAIT_L(0); PG8_MMA(0, 0, At, B0); PG8_BAR; PG8_SCHED;
;       PG8_LDB(B1, 1, 1); PG8_STAGE(PG8_SB(1, 0), b3, voffB);
;       PG8_BAR; PG8_WAIT_L(0); PG8_MMA(0, 1, At, B1); PG8_BAR;
;       PG8_LDA(At, 1, 1); PG8_STAGE(PG8_SA(1, 0), a3, voffA);
;       PG8_BAR; PG8_WAIT_L(0); PG8_MMA(1, 0, At, B0); PG8_BAR; PG8_SCHED;
;       PG8_STAGE(PG8_SB(1, 1), b3 + hstep, voffB);
;       PG8_WAIT_V(6); PG8_BAR; PG8_MMA(1, 1, At, B1); PG8_BAR;
	s_setprio 0
	s_add_u32 s66, s38, 0x40000
	s_addc_u32 s67, s39, 0
	s_add_i32 s65, s61, s46
	v_lshl_add_u64 v[128:129], s[66:67], 0, v[154:155]
	s_mov_b32 m0, s65
	s_nop 0
	global_load_lds_dwordx4 v[128:129], off
	v_lshl_add_u64 v[128:129], s[66:67], 0, v[158:159]
	s_add_i32 m0, s65, 0x2000
	s_nop 0
	global_load_lds_dwordx4 v[128:129], off
	s_waitcnt vmcnt(6)
	s_setprio 1
	s_barrier
	v_mfma_f32_16x16x32_bf16 v[52:55], v[200:203], v[144:147], v[52:55]
	v_mfma_f32_16x16x32_bf16 v[48:51], v[208:211], v[144:147], v[48:51]
	v_mfma_f32_16x16x32_bf16 v[36:39], v[200:203], v[166:169], v[36:39]
	v_mfma_f32_16x16x32_bf16 v[32:35], v[208:211], v[166:169], v[32:35]
	v_mfma_f32_16x16x32_bf16 v[20:23], v[200:203], v[184:187], v[20:23]
	v_mfma_f32_16x16x32_bf16 v[16:19], v[208:211], v[184:187], v[16:19]
	v_mfma_f32_16x16x32_bf16 v[4:7], v[200:203], v[192:195], v[4:7]
	v_mfma_f32_16x16x32_bf16 v[0:3], v[208:211], v[192:195], v[0:3]
	v_mfma_f32_16x16x32_bf16 v[52:55], v[204:207], v[148:151], v[52:55]
	v_mfma_f32_16x16x32_bf16 v[48:51], v[212:215], v[148:151], v[48:51]
	v_mfma_f32_16x16x32_bf16 v[36:39], v[204:207], v[170:173], v[36:39]
	v_mfma_f32_16x16x32_bf16 v[32:35], v[212:215], v[170:173], v[32:35]
	v_mfma_f32_16x16x32_bf16 v[20:23], v[204:207], v[188:191], v[20:23]
	v_mfma_f32_16x16x32_bf16 v[16:19], v[212:215], v[188:191], v[16:19]
	v_mfma_f32_16x16x32_bf16 v[4:7], v[204:207], v[196:199], v[4:7]
	v_mfma_f32_16x16x32_bf16 v[0:3], v[212:215], v[196:199], v[0:3]
	s_add_i32 s65, 0, 0x18000
	v_add_u32_e32 v140, s65, v177
	s_barrier
	s_setprio 0
	ds_read_b128 v[128:131], v140
	ds_read_b128 v[132:135], v140 offset:1024
	ds_read_b128 v[136:139], v140 offset:2048
	ds_read_b128 v[140:143], v140 offset:3072
	s_add_u32 s40, s40, 0x40000
	s_addc_u32 s41, s41, 0
	s_mov_b32 m0, s49
	v_lshl_add_u64 v[200:201], s[40:41], 0, v[152:153]
	ds_read_b128 v[144:147], v180 offset:32768
	ds_read_b128 v[148:151], v180 offset:33792
	ds_read_b128 v[166:169], v180 offset:34816
	ds_read_b128 v[170:173], v180 offset:35840
	ds_read_b128 v[184:187], v180 offset:36864
	ds_read_b128 v[188:191], v180 offset:37888
	ds_read_b128 v[192:195], v180 offset:38912
	ds_read_b128 v[196:199], v180 offset:39936
	global_load_lds_dwordx4 v[200:201], off
	v_lshl_add_u64 v[200:201], s[40:41], 0, v[156:157]
	s_mov_b32 m0, s50
	s_nop 0
	global_load_lds_dwordx4 v[200:201], off
	s_waitcnt lgkmcnt(8)
	s_setprio 1
	s_barrier
	s_waitcnt lgkmcnt(0)
	s_waitcnt lgkmcnt(0)
	v_mfma_f32_16x16x32_bf16 v[124:127], v[128:131], v[144:147], v[124:127]
	v_mfma_f32_16x16x32_bf16 v[120:123], v[136:139], v[144:147], v[120:123]
	v_mfma_f32_16x16x32_bf16 v[108:111], v[128:131], v[166:169], v[108:111]
	v_mfma_f32_16x16x32_bf16 v[104:107], v[136:139], v[166:169], v[104:107]
	v_mfma_f32_16x16x32_bf16 v[92:95], v[128:131], v[184:187], v[92:95]
	v_mfma_f32_16x16x32_bf16 v[88:91], v[136:139], v[184:187], v[88:91]
	v_mfma_f32_16x16x32_bf16 v[76:79], v[128:131], v[192:195], v[76:79]
	v_mfma_f32_16x16x32_bf16 v[72:75], v[136:139], v[192:195], v[72:75]
	v_mfma_f32_16x16x32_bf16 v[124:127], v[132:135], v[148:151], v[124:127]
	v_mfma_f32_16x16x32_bf16 v[120:123], v[140:143], v[148:151], v[120:123]
	v_mfma_f32_16x16x32_bf16 v[108:111], v[132:135], v[170:173], v[108:111]
	v_mfma_f32_16x16x32_bf16 v[104:107], v[140:143], v[170:173], v[104:107]
	v_mfma_f32_16x16x32_bf16 v[92:95], v[132:135], v[188:191], v[92:95]
	v_mfma_f32_16x16x32_bf16 v[88:91], v[140:143], v[188:191], v[88:91]
	v_mfma_f32_16x16x32_bf16 v[76:79], v[132:135], v[196:199], v[76:79]
	v_mfma_f32_16x16x32_bf16 v[72:75], v[140:143], v[196:199], v[72:75]
	s_barrier
	s_setprio 0
	s_add_i32 s40, 0, 0x1c000
	s_add_i32 s41, s65, s46
	v_add_u32_e32 v183, s40, v177
	v_lshl_add_u64 v[174:175], v[174:175], 0, s[18:19]
	s_mov_b32 m0, s41
	ds_read_b128 v[200:203], v183
	ds_read_b128 v[204:207], v183 offset:1024
	ds_read_b128 v[208:211], v183 offset:2048
	ds_read_b128 v[212:215], v183 offset:3072
	global_load_lds_dwordx4 v[174:175], off
	v_lshl_add_u64 v[174:175], v[216:217], 0, s[18:19]
	s_add_i32 m0, s41, 0x2000
	s_nop 0
	global_load_lds_dwordx4 v[174:175], off
	s_setprio 1
	s_barrier
	s_waitcnt lgkmcnt(0)
	s_waitcnt lgkmcnt(0)
	v_mfma_f32_16x16x32_bf16 v[116:119], v[200:203], v[144:147], v[116:119]
	v_mfma_f32_16x16x32_bf16 v[112:115], v[208:211], v[144:147], v[112:115]
	v_mfma_f32_16x16x32_bf16 v[100:103], v[200:203], v[166:169], v[100:103]
	v_mfma_f32_16x16x32_bf16 v[96:99], v[208:211], v[166:169], v[96:99]
	v_mfma_f32_16x16x32_bf16 v[84:87], v[200:203], v[184:187], v[84:87]
	v_mfma_f32_16x16x32_bf16 v[80:83], v[208:211], v[184:187], v[80:83]
	v_mfma_f32_16x16x32_bf16 v[68:71], v[200:203], v[192:195], v[68:71]
	v_mfma_f32_16x16x32_bf16 v[64:67], v[208:211], v[192:195], v[64:67]
	v_mfma_f32_16x16x32_bf16 v[116:119], v[204:207], v[148:151], v[116:119]
	v_mfma_f32_16x16x32_bf16 v[112:115], v[212:215], v[148:151], v[112:115]
	v_mfma_f32_16x16x32_bf16 v[100:103], v[204:207], v[170:173], v[100:103]
	v_mfma_f32_16x16x32_bf16 v[96:99], v[212:215], v[170:173], v[96:99]
	v_mfma_f32_16x16x32_bf16 v[84:87], v[204:207], v[188:191], v[84:87]
	v_mfma_f32_16x16x32_bf16 v[80:83], v[212:215], v[188:191], v[80:83]
	v_mfma_f32_16x16x32_bf16 v[68:71], v[204:207], v[196:199], v[68:71]
	v_mfma_f32_16x16x32_bf16 v[64:67], v[212:215], v[196:199], v[64:67]
	s_mov_b32 m0, s53
	v_lshl_add_u64 v[174:175], v[218:219], 0, s[18:19]
	s_barrier
; #define PG8_STAGE(bufoff, gbase, voff) do { _Pragma("unroll") for (int _i = 0; _i < 2; ++_i) \
;     __builtin_amdgcn_global_load_lds((const unsigned*)((const char*)(gbase) + (voff)[_i]), (PG8_LAS unsigned*)(lds + (bufoff) + ldsw + _i * 8192), 16, 0, 0); } while (0)
; #define PG8_LDA(dst, b, h) do { _Pragma("unroll") for (int m = 0; m < 4; ++m) _Pragma("unroll") for (int k = 0; k < 2; ++k) dst[m][k] = *(const PG8_LAS bf16x8*)(lds + PG8_SA(b, h) + aoff + m * 2048 + k * 1024); } while (0)
; #define PG8_WAIT_V(n) asm volatile("s_waitcnt vmcnt(" #n ")" ::: "memory")
; #define PG8_WAIT_L(n) asm volatile("s_waitcnt lgkmcnt(" #n ")" ::: "memory")
; #define PG8_BAR __builtin_amdgcn_s_barrier()
; template <class Epi>
; DI void gemm_phase(PG8_LAS unsigned char* lds, const Gemm g, const StaticOrder& S, const Epi& E, const int wv) {
;     ...
;       PG8_WAIT_V(6); PG8_BAR; PG8_MMA(1, 1, At, B1); PG8_BAR;
;       PG8_LDB(B0, 1, 0); PG8_SCHED; PG8_LDA(At, 1, 0); PG8_STAGE(PG8_SA(0, 1), a2 + hstep, voffA);
;       PG8_WAIT_L(8); PG8_BAR; PG8_WAIT_L(0); PG8_MMA(0, 0, At, B0); PG8_BAR; PG8_SCHED;
;       PG8_LDB(B1, 1, 1); PG8_STAGE(PG8_SB(1, 0), b3, voffB);
;       PG8_BAR; PG8_WAIT_L(0); PG8_MMA(0, 1, At, B1); PG8_BAR;
;       PG8_LDA(At, 1, 1); PG8_STAGE(PG8_SA(1, 0), a3, voffA);
;       PG8_BAR; PG8_WAIT_L(0); PG8_MMA(1, 0, At, B0); PG8_BAR; PG8_SCHED;
;       PG8_STAGE(PG8_SB(1, 1), b3 + hstep, voffB);
;       PG8_WAIT_V(6); PG8_BAR; PG8_MMA(1, 1, At, B1); PG8_BAR;
;     }
;     E(acc, cur, wr, wc, fr, fq);
;   DI void operator()(AccRef acc, const pg8::Unit& u, int wr, int wc, int fr, int fq) const {
;     const int row0 = u.pm * 256 + wr * 64 + fr, col0 = u.pn * 256 + wc * 32 + 8 * fq;
;     EPI_ROWS_BEGIN()
;       f32x4 r[4][2][2];
;       if constexpr (MODE == 0) {
; #pragma unroll
;         for (int m = 0; m < 4; ++m) {
;           const float* src = xrow(P, row0 + ai * 128 + m * 16) + col0;
; #pragma unroll
;           for (int bj = 0; bj < 2; ++bj) { r[m][bj][0] = *(const f32x4*)(src + bj * 128); r[m][bj][1] = *(const f32x4*)(src + bj * 128 + 4); }
;         }
;       } else {
;         u32x4 rb[4][2];
; #pragma unroll
;         for (int m = 0; m < 4; ++m)
; #pragma unroll
;           for (int bj = 0; bj < 2; ++bj) {
;             const int rr = row0 + ai * 128 + m * 16;
;             const int sr = (MODE == 3) ? rr + NMETA * ((rr >> 12) + 1) : rr;
	s_setprio 0
	ds_read_b128 v[144:147], v180 offset:49152
	ds_read_b128 v[148:151], v180 offset:50176
	ds_read_b128 v[166:169], v180 offset:51200
	ds_read_b128 v[170:173], v180 offset:52224
	ds_read_b128 v[184:187], v180 offset:53248
	ds_read_b128 v[188:191], v180 offset:54272
	ds_read_b128 v[192:195], v180 offset:55296
	ds_read_b128 v[196:199], v180 offset:56320
	global_load_lds_dwordx4 v[174:175], off
	v_lshl_add_u64 v[174:175], v[220:221], 0, s[18:19]
	s_mov_b32 m0, s54
	s_nop 0
	global_load_lds_dwordx4 v[174:175], off
	s_setprio 1
	s_barrier
	s_waitcnt lgkmcnt(0)
	v_mfma_f32_16x16x32_bf16 v[60:63], v[128:131], v[144:147], v[60:63]
	v_mfma_f32_16x16x32_bf16 v[56:59], v[136:139], v[144:147], v[56:59]
	v_mfma_f32_16x16x32_bf16 v[44:47], v[128:131], v[166:169], v[44:47]
	v_mfma_f32_16x16x32_bf16 v[40:43], v[136:139], v[166:169], v[40:43]
	v_mfma_f32_16x16x32_bf16 v[28:31], v[128:131], v[184:187], v[28:31]
	v_mfma_f32_16x16x32_bf16 v[24:27], v[136:139], v[184:187], v[24:27]
	v_mfma_f32_16x16x32_bf16 v[12:15], v[128:131], v[192:195], v[12:15]
	v_mfma_f32_16x16x32_bf16 v[8:11], v[136:139], v[192:195], v[8:11]
	v_mfma_f32_16x16x32_bf16 v[60:63], v[132:135], v[148:151], v[60:63]
	v_mfma_f32_16x16x32_bf16 v[56:59], v[140:143], v[148:151], v[56:59]
	v_mfma_f32_16x16x32_bf16 v[44:47], v[132:135], v[170:173], v[44:47]
	v_mfma_f32_16x16x32_bf16 v[40:43], v[140:143], v[170:173], v[40:43]
	v_mfma_f32_16x16x32_bf16 v[28:31], v[132:135], v[188:191], v[28:31]
	v_mfma_f32_16x16x32_bf16 v[24:27], v[140:143], v[188:191], v[24:27]
	v_mfma_f32_16x16x32_bf16 v[12:15], v[132:135], v[196:199], v[12:15]
	v_mfma_f32_16x16x32_bf16 v[8:11], v[140:143], v[196:199], v[8:11]
	s_barrier
	s_setprio 0
	s_add_u32 s38, s38, 0x40080
	s_addc_u32 s39, s39, 0
	s_add_i32 s40, s40, s46
	v_lshl_add_u64 v[128:129], s[38:39], 0, v[154:155]
	s_mov_b32 m0, s40
	s_nop 0
	global_load_lds_dwordx4 v[128:129], off
	v_lshl_add_u64 v[128:129], s[38:39], 0, v[158:159]
	s_add_i32 m0, s40, 0x2000
	s_nop 0
	global_load_lds_dwordx4 v[128:129], off
	s_waitcnt vmcnt(6)
	s_setprio 1
	s_barrier
	v_mfma_f32_16x16x32_bf16 v[52:55], v[200:203], v[144:147], v[52:55]
	v_mfma_f32_16x16x32_bf16 v[48:51], v[208:211], v[144:147], v[48:51]
	v_mfma_f32_16x16x32_bf16 v[36:39], v[200:203], v[166:169], v[36:39]
	v_mfma_f32_16x16x32_bf16 v[32:35], v[208:211], v[166:169], v[32:35]
	v_mfma_f32_16x16x32_bf16 v[20:23], v[200:203], v[184:187], v[20:23]
	v_mfma_f32_16x16x32_bf16 v[16:19], v[208:211], v[184:187], v[16:19]
	v_mfma_f32_16x16x32_bf16 v[4:7], v[200:203], v[192:195], v[4:7]
	v_mfma_f32_16x16x32_bf16 v[0:3], v[208:211], v[192:195], v[0:3]
	v_mfma_f32_16x16x32_bf16 v[52:55], v[204:207], v[148:151], v[52:55]
	v_mfma_f32_16x16x32_bf16 v[48:51], v[212:215], v[148:151], v[48:51]
	v_mfma_f32_16x16x32_bf16 v[36:39], v[204:207], v[170:173], v[36:39]
	v_mfma_f32_16x16x32_bf16 v[32:35], v[212:215], v[170:173], v[32:35]
	v_mfma_f32_16x16x32_bf16 v[20:23], v[204:207], v[188:191], v[20:23]
	v_mfma_f32_16x16x32_bf16 v[16:19], v[212:215], v[188:191], v[16:19]
	v_mfma_f32_16x16x32_bf16 v[4:7], v[204:207], v[196:199], v[4:7]
	v_mfma_f32_16x16x32_bf16 v[0:3], v[212:215], v[196:199], v[0:3]
	s_add_i32 s64, s64, 2
	s_add_u32 s36, s36, 0x100
	s_addc_u32 s37, s37, 0
	s_add_u32 s62, s62, 0x100
	s_addc_u32 s63, s63, 0
	s_cmp_gt_u32 s64, 13
	s_barrier
	s_setprio 0
	s_cbranch_scc0 .LBB0_1284
	v_lshl_or_b32 v166, s34, 8, v178
	s_lshl_b32 s23, s30, 8
	v_ashrrev_i32_e32 v167, 31, v166
	s_add_i32 s23, s23, s52
	v_lshlrev_b64 v[170:171], 1, v[166:167]
	v_or_b32_e32 v168, s23, v176
	s_cmpk_gt_i32 s30, 0x181
	v_lshl_add_u64 v[172:173], s[8:9], 0, v[170:171]
	s_cbranch_scc1 .LBB0_1295
; DI float bf_lo(unsigned u) { return __uint_as_float(u << 16); }
;   DI void operator()(AccRef acc, const pg8::Unit& u, int wr, int wc, int fr, int fq) const {
;     ...
;         u32x4 rb[4][2];
; #pragma unroll
;         for (int m = 0; m < 4; ++m)
; #pragma unroll
;           for (int bj = 0; bj < 2; ++bj) {
;             const int rr = row0 + ai * 128 + m * 16;
;             const int sr = (MODE == 3) ? rr + NMETA * ((rr >> 12) + 1) : rr;
;             rb[m][bj] = *(const u32x4*)(hsrc + (size_t)sr * DM + col0 + bj * 128);
;           }
; #pragma unroll
;         for (int m = 0; m < 4; ++m)
; #pragma unroll
;           for (int bj = 0; bj < 2; ++bj) {
;             r[m][bj][0] = f32x4{bf_lo(rb[m][bj][0]), bf_hi(rb[m][bj][0]), bf_lo(rb[m][bj][1]), bf_hi(rb[m][bj][1])};
;             r[m][bj][1] = f32x4{bf_lo(rb[m][bj][2]), bf_hi(rb[m][bj][2]), bf_lo(rb[m][bj][3]), bf_hi(rb[m][bj][3])};
;           }
;       }
; #pragma unroll
;       for (int m = 0; m < 4; ++m) {
;         const int row = row0 + ai * 128 + m * 16;
;         if constexpr (MODE == 4) {
;           float* dst = P.out + (size_t)row * DM + col0;
; #pragma unroll
;           for (int bj = 0; bj < 2; ++bj) {
;             *(f32x4*)(dst + bj * 128) = r[m][bj][0] + acc[ai][bj][m][0];
;             *(f32x4*)(dst + bj * 128 + 4) = r[m][bj][1] + acc[ai][bj][m][1];
;           }
;         } else if constexpr (MODE == 2) {
;           const int s = row / L, p = row - s * L;
;           if (p >= NMETA) {
;             float* dst = P.out + ((size_t)s * SEQ + (p - NMETA)) * DM + col0;
; #pragma unroll
;             for (int bj = 0; bj < 2; ++bj) {
;               *(f32x4*)(dst + bj * 128) = r[m][bj][0] + acc[ai][bj][m][0];
;               *(f32x4*)(dst + bj * 128 + 4) = r[m][bj][1] + acc[ai][bj][m][1];
;             }
;           }
;         } else {
;           float s2 = 0.f;
; #pragma unroll
;           for (int bj = 0; bj < 2; ++bj) {
;             const f32x4 r0 = r[m][bj][0] + acc[ai][bj][m][0], r1 = r[m][bj][1] + acc[ai][bj][m][1];
;             *(u32x4*)(hdst + (size_t)row * DM + col0 + bj * 128) = pack8v(r0, r1);
;             s2 += r0[0] * r0[0] + r0[1] * r0[1] + r0[2] * r0[2] + r0[3] * r0[3] + r1[0] * r1[0] + r1[1] * r1[1] + r1[2] * r1[2] + r1[3] * r1[3];
;           }
;           s2 += __shfl_xor(s2, 16);
;           s2 += __shfl_xor(s2, 32);
;           if (fq == 0) atomicAdd(ss + row, s2);
	s_ashr_i32 s23, s23, 8
	s_and_b32 s23, s23, -16
	v_or_b32_e32 v174, 16, v168
	v_add_u32_e32 v128, s23, v174
	v_ashrrev_i32_e32 v129, 31, v128
	v_lshlrev_b64 v[130:131], 11, v[128:129]
	v_lshl_add_u64 v[130:131], v[172:173], 0, v[130:131]
	global_load_dwordx4 v[186:189], v[130:131], off
	global_load_dwordx4 v[190:193], v[130:131], off offset:256
	v_add_u32_e32 v130, 16, v128
	v_add_u32_e32 v132, 32, v128
	v_add_u32_e32 v128, 48, v128
	v_ashrrev_i32_e32 v131, 31, v130
	v_ashrrev_i32_e32 v133, 31, v132
	v_ashrrev_i32_e32 v129, 31, v128
	v_lshlrev_b64 v[130:131], 11, v[130:131]
	v_lshlrev_b64 v[132:133], 11, v[132:133]
	v_lshlrev_b64 v[128:129], 11, v[128:129]
	v_lshl_add_u64 v[130:131], v[172:173], 0, v[130:131]
	v_lshl_add_u64 v[132:133], v[172:173], 0, v[132:133]
	v_lshl_add_u64 v[128:129], v[172:173], 0, v[128:129]
	global_load_dwordx4 v[148:151], v[130:131], off
	global_load_dwordx4 v[144:147], v[130:131], off offset:256
	global_load_dwordx4 v[140:143], v[132:133], off
	global_load_dwordx4 v[136:139], v[132:133], off offset:256
	s_nop 0
	global_load_dwordx4 v[132:135], v[128:129], off
	s_nop 0
	global_load_dwordx4 v[128:131], v[128:129], off offset:256
	v_and_b32_e32 v183, 64, v182
	v_xor_b32_e32 v175, 16, v182
	v_add_u32_e32 v183, 64, v183
	v_xor_b32_e32 v184, 32, v182
	v_cmp_lt_i32_e32 vcc, v175, v183
	v_ashrrev_i32_e32 v169, 31, v168
	v_lshlrev_b64 v[194:195], 11, v[168:169]
	v_cndmask_b32_e32 v175, v182, v175, vcc
	v_cmp_lt_i32_e32 vcc, v184, v183
	s_waitcnt vmcnt(0)
	v_lshlrev_b32_e32 v196, 16, v186
	v_and_b32_e32 v197, 0xffff0000, v186
	v_lshlrev_b32_e32 v200, 16, v190
	v_and_b32_e32 v201, 0xffff0000, v190
	v_lshlrev_b32_e32 v198, 16, v188
	v_and_b32_e32 v199, 0xffff0000, v188
	v_lshlrev_b32_e32 v188, 16, v189
	v_and_b32_e32 v189, 0xffff0000, v189
	v_lshlrev_b32_e32 v202, 16, v192
	v_and_b32_e32 v203, 0xffff0000, v192
	v_pk_add_f32 v[124:125], v[124:125], v[196:197]
	v_pk_add_f32 v[116:117], v[116:117], v[200:201]
	v_cndmask_b32_e32 v183, v182, v184, vcc
	v_lshlrev_b32_e32 v184, 2, v175
	v_lshlrev_b32_e32 v186, 16, v187
	v_and_b32_e32 v187, 0xffff0000, v187
	v_lshlrev_b32_e32 v190, 16, v191
	v_and_b32_e32 v191, 0xffff0000, v191
	v_pk_add_f32 v[122:123], v[122:123], v[188:189]
	v_pk_add_f32 v[188:189], v[112:113], v[202:203]
	v_cvt_pk_bf16_f32 v112, v124, v125
	v_mul_f32_e32 v125, v125, v125
	v_mul_f32_e32 v175, v117, v117
	v_pk_add_f32 v[126:127], v[126:127], v[186:187]
	v_pk_add_f32 v[118:119], v[118:119], v[190:191]
	v_fmac_f32_e32 v125, v124, v124
	v_fmac_f32_e32 v175, v116, v116
	v_fmac_f32_e32 v125, v126, v126
	v_fmac_f32_e32 v175, v118, v118
	v_pk_add_f32 v[120:121], v[120:121], v[198:199]
	v_fmac_f32_e32 v125, v127, v127
	v_fmac_f32_e32 v175, v119, v119
	v_lshlrev_b32_e32 v192, 16, v193
	v_and_b32_e32 v193, 0xffff0000, v193
	v_fmac_f32_e32 v125, v120, v120
	v_fmac_f32_e32 v175, v188, v188
	v_pk_add_f32 v[186:187], v[114:115], v[192:193]
	v_fmac_f32_e32 v125, v121, v121
	v_fmac_f32_e32 v175, v189, v189
	v_fmac_f32_e32 v125, v122, v122
	v_fmac_f32_e32 v175, v186, v186
	v_fmac_f32_e32 v125, v123, v123
	v_fmac_f32_e32 v175, v187, v187
	v_cvt_pk_bf16_f32 v115, v122, v123
	v_add_f32_e32 v122, v125, v175
	ds_bpermute_b32 v123, v184, v122
	v_cvt_pk_bf16_f32 v114, v120, v121
	v_lshl_add_u64 v[120:121], s[14:15], 0, v[194:195]
	v_cvt_pk_bf16_f32 v113, v126, v127
	v_lshl_add_u64 v[120:121], v[120:121], 0, v[170:171]
	v_lshlrev_b32_e32 v183, 2, v183
	global_store_dwordx4 v[120:121], v[112:115], off
	s_waitcnt lgkmcnt(0)
	s_nop 0
	v_add_f32_e32 v112, v122, v123
	ds_bpermute_b32 v113, v183, v112
	v_cvt_pk_bf16_f32 v114, v116, v117
	v_cvt_pk_bf16_f32 v115, v118, v119
	v_cvt_pk_bf16_f32 v116, v188, v189
	v_cvt_pk_bf16_f32 v117, v186, v187
	global_store_dwordx4 v[120:121], v[114:117], off offset:256
	s_and_saveexec_b64 s[34:35], s[4:5]
	s_cbranch_execz .LBB0_1288
	v_lshl_add_u64 v[114:115], v[168:169], 2, s[16:17]
	s_waitcnt lgkmcnt(0)
	v_add_f32_e32 v112, v112, v113
	global_atomic_add_f32 v[114:115], v112, off

; #define PG8_STAGE(bufoff, gbase, voff) do { _Pragma("unroll") for (int _i = 0; _i < 2; ++_i) \
;     __builtin_amdgcn_global_load_lds((const unsigned*)((const char*)(gbase) + (voff)[_i]), (PG8_LAS unsigned*)(lds + (bufoff) + ldsw + _i * 8192), 16, 0, 0); } while (0)
; #define PG8_LDA(dst, b, h) do { _Pragma("unroll") for (int m = 0; m < 4; ++m) _Pragma("unroll") for (int k = 0; k < 2; ++k) dst[m][k] = *(const PG8_LAS bf16x8*)(lds + PG8_SA(b, h) + aoff + m * 2048 + k * 1024); } while (0)
; #define PG8_LDB(dst, b, h) do { _Pragma("unroll") for (int n = 0; n < 2; ++n) _Pragma("unroll") for (int k = 0; k < 2; ++k) dst[n][k] = *(const PG8_LAS bf16x8*)(lds + PG8_SB(b, h) + boff + n * 2048 + k * 1024); } while (0)
; #define PG8_MMA(ai, bj, At, Bt) do { __builtin_amdgcn_s_setprio(1); _Pragma("unroll") for (int m = 0; m < 4; ++m) _Pragma("unroll") for (int n = 0; n < 2; ++n) _Pragma("unroll") for (int k = 0; k < 2; ++k) \
;     acc[ai][bj][m][n] = __builtin_amdgcn_mfma_f32_16x16x32_bf16(Bt[n][k], At[m][k], acc[ai][bj][m][n], 0, 0, 0); __builtin_amdgcn_s_setprio(0); } while (0)
; #define PG8_WAIT_V(n) asm volatile("s_waitcnt vmcnt(" #n ")" ::: "memory")
; #define PG8_WAIT_L(n) asm volatile("s_waitcnt lgkmcnt(" #n ")" ::: "memory")
; #define PG8_BAR __builtin_amdgcn_s_barrier()
; #define PG8_SCHED __builtin_amdgcn_sched_barrier(0)
; template <class Epi>
; DI void gemm_phase(PG8_LAS unsigned char* lds, const Gemm g, const StaticOrder& S, const Epi& E, const int wv) {
;     ...
;       PG8_LDB(B0, 0, 0); PG8_SCHED; PG8_LDA(At, 0, 0); PG8_STAGE(PG8_SA(1, 1), a1 + hstep, voffA);
;       PG8_WAIT_L(8); PG8_BAR; PG8_WAIT_L(0); PG8_MMA(0, 0, At, B0); PG8_BAR; PG8_SCHED;
;       PG8_LDB(B1, 0, 1); PG8_STAGE(PG8_SB(0, 0), b2, voffB);
;       PG8_BAR; PG8_WAIT_L(0); PG8_MMA(0, 1, At, B1); PG8_BAR;
;       PG8_LDA(At, 0, 1); PG8_STAGE(PG8_SA(0, 0), a2, voffA);
;       PG8_BAR; PG8_WAIT_L(0); PG8_MMA(1, 0, At, B0); PG8_BAR; PG8_SCHED;
;       PG8_STAGE(PG8_SB(0, 1), b2 + hstep, voffB);
;       PG8_WAIT_V(6); PG8_BAR; PG8_MMA(1, 1, At, B1); PG8_BAR;
;       PG8_LDB(B0, 1, 0); PG8_SCHED; PG8_LDA(At, 1, 0); PG8_STAGE(PG8_SA(0, 1), a2 + hstep, voffA);
;       PG8_WAIT_L(8); PG8_BAR; PG8_WAIT_L(0); PG8_MMA(0, 0, At, B0); PG8_BAR; PG8_SCHED;
.LBB0_1367:
	ds_read_b128 v[142:145], v155
	ds_read_b128 v[146:149], v155 offset:1024
	ds_read_b128 v[160:163], v155 offset:2048
	ds_read_b128 v[164:167], v155 offset:3072
	s_add_u32 s8, s6, 0xfffc0080
	s_addc_u32 s9, s7, -1
	s_cmp_eq_u32 s61, 12
	s_cselect_b32 s35, s5, s9
	s_cselect_b32 s34, s25, s8
	s_cselect_b32 s9, s23, s60
	s_cselect_b32 s8, s58, s59
	v_lshl_add_u64 v[150:151], s[6:7], 0, v[136:137]
	s_add_i32 m0, s31, 0xc000
	ds_read_b128 v[168:171], v156
	ds_read_b128 v[172:175], v156 offset:1024
	ds_read_b128 v[176:179], v156 offset:2048
	ds_read_b128 v[180:183], v156 offset:3072
	ds_read_b128 v[184:187], v156 offset:4096
	ds_read_b128 v[188:191], v156 offset:5120
	ds_read_b128 v[192:195], v156 offset:6144
	ds_read_b128 v[196:199], v156 offset:7168
	global_load_lds_dwordx4 v[150:151], off
	v_lshl_add_u64 v[150:151], s[6:7], 0, v[138:139]
	s_add_i32 m0, s31, 0xe000
	s_nop 0
	global_load_lds_dwordx4 v[150:151], off
	s_waitcnt lgkmcnt(8)
	s_setprio 1
	s_barrier
	s_waitcnt lgkmcnt(0)
	s_waitcnt lgkmcnt(0)
	v_mfma_f32_16x16x32_bf16 v[116:119], v[142:145], v[168:171], v[116:119]
	v_mfma_f32_16x16x32_bf16 v[112:115], v[160:163], v[168:171], v[112:115]
	v_mfma_f32_16x16x32_bf16 v[108:111], v[142:145], v[176:179], v[108:111]
	v_mfma_f32_16x16x32_bf16 v[100:103], v[160:163], v[176:179], v[100:103]
	v_mfma_f32_16x16x32_bf16 v[92:95], v[142:145], v[184:187], v[92:95]
	v_mfma_f32_16x16x32_bf16 v[84:87], v[160:163], v[184:187], v[84:87]
	v_mfma_f32_16x16x32_bf16 v[76:79], v[142:145], v[192:195], v[76:79]
	v_mfma_f32_16x16x32_bf16 v[68:71], v[160:163], v[192:195], v[68:71]
	v_mfma_f32_16x16x32_bf16 v[116:119], v[146:149], v[172:175], v[116:119]
	v_mfma_f32_16x16x32_bf16 v[112:115], v[164:167], v[172:175], v[112:115]
	v_mfma_f32_16x16x32_bf16 v[108:111], v[146:149], v[180:183], v[108:111]
	v_mfma_f32_16x16x32_bf16 v[100:103], v[164:167], v[180:183], v[100:103]
	v_mfma_f32_16x16x32_bf16 v[92:95], v[146:149], v[188:191], v[92:95]
	v_mfma_f32_16x16x32_bf16 v[84:87], v[164:167], v[188:191], v[84:87]
	v_mfma_f32_16x16x32_bf16 v[76:79], v[146:149], v[196:199], v[76:79]
	v_mfma_f32_16x16x32_bf16 v[68:71], v[164:167], v[196:199], v[68:71]
	s_barrier
	s_setprio 0
	s_add_i32 s62, s53, s42
	v_lshl_add_u64 v[150:151], s[8:9], 0, v[132:133]
	s_mov_b32 m0, s62
	ds_read_b128 v[200:203], v157
	ds_read_b128 v[204:207], v157 offset:1024
	ds_read_b128 v[208:211], v157 offset:2048
	ds_read_b128 v[212:215], v157 offset:3072
	global_load_lds_dwordx4 v[150:151], off
	v_lshl_add_u64 v[216:217], s[8:9], 0, v[128:129]
	s_add_i32 m0, s62, 0x2000
	s_nop 0
	global_load_lds_dwordx4 v[216:217], off
	s_setprio 1
	s_barrier
	s_waitcnt lgkmcnt(0)
	v_mfma_f32_16x16x32_bf16 v[124:127], v[200:203], v[168:171], v[124:127]
	v_mfma_f32_16x16x32_bf16 v[120:123], v[208:211], v[168:171], v[120:123]
	v_mfma_f32_16x16x32_bf16 v[104:107], v[200:203], v[176:179], v[104:107]
	v_mfma_f32_16x16x32_bf16 v[96:99], v[208:211], v[176:179], v[96:99]
	v_mfma_f32_16x16x32_bf16 v[88:91], v[200:203], v[184:187], v[88:91]
	v_mfma_f32_16x16x32_bf16 v[80:83], v[208:211], v[184:187], v[80:83]
	v_mfma_f32_16x16x32_bf16 v[72:75], v[200:203], v[192:195], v[72:75]
	v_mfma_f32_16x16x32_bf16 v[64:67], v[208:211], v[192:195], v[64:67]
	v_mfma_f32_16x16x32_bf16 v[124:127], v[204:207], v[172:175], v[124:127]
	v_mfma_f32_16x16x32_bf16 v[120:123], v[212:215], v[172:175], v[120:123]
	v_mfma_f32_16x16x32_bf16 v[104:107], v[204:207], v[180:183], v[104:107]
	v_mfma_f32_16x16x32_bf16 v[96:99], v[212:215], v[180:183], v[96:99]
	v_mfma_f32_16x16x32_bf16 v[88:91], v[204:207], v[188:191], v[88:91]
	v_mfma_f32_16x16x32_bf16 v[80:83], v[212:215], v[188:191], v[80:83]
	v_mfma_f32_16x16x32_bf16 v[72:75], v[204:207], v[196:199], v[72:75]
	v_mfma_f32_16x16x32_bf16 v[64:67], v[212:215], v[196:199], v[64:67]
	s_mov_b32 m0, s31
	v_lshl_add_u64 v[218:219], s[34:35], 0, v[134:135]
	s_barrier
	s_setprio 0
	ds_read_b128 v[168:171], v156 offset:16384
	ds_read_b128 v[172:175], v156 offset:17408
	ds_read_b128 v[176:179], v156 offset:18432
	ds_read_b128 v[180:183], v156 offset:19456
	ds_read_b128 v[184:187], v156 offset:20480
	ds_read_b128 v[188:191], v156 offset:21504
	ds_read_b128 v[192:195], v156 offset:22528
	ds_read_b128 v[196:199], v156 offset:23552
	global_load_lds_dwordx4 v[218:219], off
	v_lshl_add_u64 v[220:221], s[34:35], 0, v[130:131]
	s_mov_b32 m0, s45
	s_nop 0
	global_load_lds_dwordx4 v[220:221], off
	s_setprio 1
	s_barrier
	s_waitcnt lgkmcnt(0)
	v_mfma_f32_16x16x32_bf16 v[52:55], v[142:145], v[168:171], v[52:55]
	v_mfma_f32_16x16x32_bf16 v[48:51], v[160:163], v[168:171], v[48:51]
	v_mfma_f32_16x16x32_bf16 v[44:47], v[142:145], v[176:179], v[44:47]
	v_mfma_f32_16x16x32_bf16 v[36:39], v[160:163], v[176:179], v[36:39]
	v_mfma_f32_16x16x32_bf16 v[28:31], v[142:145], v[184:187], v[28:31]
	v_mfma_f32_16x16x32_bf16 v[20:23], v[160:163], v[184:187], v[20:23]
	v_mfma_f32_16x16x32_bf16 v[12:15], v[142:145], v[192:195], v[12:15]
	v_mfma_f32_16x16x32_bf16 v[4:7], v[160:163], v[192:195], v[4:7]
	v_mfma_f32_16x16x32_bf16 v[52:55], v[146:149], v[172:175], v[52:55]
	v_mfma_f32_16x16x32_bf16 v[48:51], v[164:167], v[172:175], v[48:51]
	v_mfma_f32_16x16x32_bf16 v[44:47], v[146:149], v[180:183], v[44:47]
	v_mfma_f32_16x16x32_bf16 v[36:39], v[164:167], v[180:183], v[36:39]
	v_mfma_f32_16x16x32_bf16 v[28:31], v[146:149], v[188:191], v[28:31]
	v_mfma_f32_16x16x32_bf16 v[20:23], v[164:167], v[188:191], v[20:23]
	v_mfma_f32_16x16x32_bf16 v[12:15], v[146:149], v[196:199], v[12:15]
	v_mfma_f32_16x16x32_bf16 v[4:7], v[164:167], v[196:199], v[4:7]
	s_barrier
; #define PG8_STAGE(bufoff, gbase, voff) do { _Pragma("unroll") for (int _i = 0; _i < 2; ++_i) \
;     __builtin_amdgcn_global_load_lds((const unsigned*)((const char*)(gbase) + (voff)[_i]), (PG8_LAS unsigned*)(lds + (bufoff) + ldsw + _i * 8192), 16, 0, 0); } while (0)
; #define PG8_LDA(dst, b, h) do { _Pragma("unroll") for (int m = 0; m < 4; ++m) _Pragma("unroll") for (int k = 0; k < 2; ++k) dst[m][k] = *(const PG8_LAS bf16x8*)(lds + PG8_SA(b, h) + aoff + m * 2048 + k * 1024); } while (0)
; #define PG8_LDB(dst, b, h) do { _Pragma("unroll") for (int n = 0; n < 2; ++n) _Pragma("unroll") for (int k = 0; k < 2; ++k) dst[n][k] = *(const PG8_LAS bf16x8*)(lds + PG8_SB(b, h) + boff + n * 2048 + k * 1024); } while (0)
; #define PG8_MMA(ai, bj, At, Bt) do { __builtin_amdgcn_s_setprio(1); _Pragma("unroll") for (int m = 0; m < 4; ++m) _Pragma("unroll") for (int n = 0; n < 2; ++n) _Pragma("unroll") for (int k = 0; k < 2; ++k) \
;     acc[ai][bj][m][n] = __builtin_amdgcn_mfma_f32_16x16x32_bf16(Bt[n][k], At[m][k], acc[ai][bj][m][n], 0, 0, 0); __builtin_amdgcn_s_setprio(0); } while (0)
; #define PG8_WAIT_V(n) asm volatile("s_waitcnt vmcnt(" #n ")" ::: "memory")
; #define PG8_WAIT_L(n) asm volatile("s_waitcnt lgkmcnt(" #n ")" ::: "memory")
; #define PG8_BAR __builtin_amdgcn_s_barrier()
; #define PG8_SCHED __builtin_amdgcn_sched_barrier(0)
; template <class Epi>
; DI void gemm_phase(PG8_LAS unsigned char* lds, const Gemm g, const StaticOrder& S, const Epi& E, const int wv) {
;     ...
;       PG8_STAGE(PG8_SB(0, 1), b2 + hstep, voffB);
;       PG8_WAIT_V(6); PG8_BAR; PG8_MMA(1, 1, At, B1); PG8_BAR;
;       PG8_LDB(B0, 1, 0); PG8_SCHED; PG8_LDA(At, 1, 0); PG8_STAGE(PG8_SA(0, 1), a2 + hstep, voffA);
;       PG8_WAIT_L(8); PG8_BAR; PG8_WAIT_L(0); PG8_MMA(0, 0, At, B0); PG8_BAR; PG8_SCHED;
;       PG8_LDB(B1, 1, 1); PG8_STAGE(PG8_SB(1, 0), b3, voffB);
;       PG8_BAR; PG8_WAIT_L(0); PG8_MMA(0, 1, At, B1); PG8_BAR;
	s_setprio 0
	s_add_u32 s62, s8, 0x40000
	s_addc_u32 s63, s9, 0
	s_add_i32 s64, s54, s42
	v_lshl_add_u64 v[142:143], s[62:63], 0, v[132:133]
	s_mov_b32 m0, s64
	s_nop 0
	global_load_lds_dwordx4 v[142:143], off
	v_lshl_add_u64 v[142:143], s[62:63], 0, v[128:129]
	s_add_i32 m0, s64, 0x2000
	s_nop 0
	global_load_lds_dwordx4 v[142:143], off
	s_waitcnt vmcnt(6)
	s_setprio 1
	s_barrier
	v_mfma_f32_16x16x32_bf16 v[60:63], v[200:203], v[168:171], v[60:63]
	v_mfma_f32_16x16x32_bf16 v[56:59], v[208:211], v[168:171], v[56:59]
	v_mfma_f32_16x16x32_bf16 v[40:43], v[200:203], v[176:179], v[40:43]
	v_mfma_f32_16x16x32_bf16 v[32:35], v[208:211], v[176:179], v[32:35]
	v_mfma_f32_16x16x32_bf16 v[24:27], v[200:203], v[184:187], v[24:27]
	v_mfma_f32_16x16x32_bf16 v[16:19], v[208:211], v[184:187], v[16:19]
	v_mfma_f32_16x16x32_bf16 v[8:11], v[200:203], v[192:195], v[8:11]
	v_mfma_f32_16x16x32_bf16 v[0:3], v[208:211], v[192:195], v[0:3]
	v_mfma_f32_16x16x32_bf16 v[60:63], v[204:207], v[172:175], v[60:63]
	v_mfma_f32_16x16x32_bf16 v[56:59], v[212:215], v[172:175], v[56:59]
	v_mfma_f32_16x16x32_bf16 v[40:43], v[204:207], v[180:183], v[40:43]
	v_mfma_f32_16x16x32_bf16 v[32:35], v[212:215], v[180:183], v[32:35]
	v_mfma_f32_16x16x32_bf16 v[24:27], v[204:207], v[188:191], v[24:27]
	v_mfma_f32_16x16x32_bf16 v[16:19], v[212:215], v[188:191], v[16:19]
	v_mfma_f32_16x16x32_bf16 v[8:11], v[204:207], v[196:199], v[8:11]
	v_mfma_f32_16x16x32_bf16 v[0:3], v[212:215], v[196:199], v[0:3]
	s_add_i32 s62, 0, 0x18000
	v_add_u32_e32 v159, s62, v153
	s_barrier
	s_setprio 0
	ds_read_b128 v[142:145], v159
	ds_read_b128 v[146:149], v159 offset:1024
	ds_read_b128 v[160:163], v159 offset:2048
	ds_read_b128 v[164:167], v159 offset:3072
	s_add_u32 s34, s34, 0x40000
	s_addc_u32 s35, s35, 0
	s_mov_b32 m0, s46
	v_lshl_add_u64 v[200:201], s[34:35], 0, v[134:135]
	ds_read_b128 v[168:171], v156 offset:32768
	ds_read_b128 v[172:175], v156 offset:33792
	ds_read_b128 v[176:179], v156 offset:34816
	ds_read_b128 v[180:183], v156 offset:35840
	ds_read_b128 v[184:187], v156 offset:36864
	ds_read_b128 v[188:191], v156 offset:37888
	ds_read_b128 v[192:195], v156 offset:38912
	ds_read_b128 v[196:199], v156 offset:39936
	global_load_lds_dwordx4 v[200:201], off
	v_lshl_add_u64 v[200:201], s[34:35], 0, v[130:131]
	s_mov_b32 m0, s47
	s_nop 0
	global_load_lds_dwordx4 v[200:201], off
	s_waitcnt lgkmcnt(8)
	s_setprio 1
	s_barrier
	s_waitcnt lgkmcnt(0)
	s_waitcnt lgkmcnt(0)
	v_mfma_f32_16x16x32_bf16 v[116:119], v[142:145], v[168:171], v[116:119]
	v_mfma_f32_16x16x32_bf16 v[112:115], v[160:163], v[168:171], v[112:115]
	v_mfma_f32_16x16x32_bf16 v[108:111], v[142:145], v[176:179], v[108:111]
	v_mfma_f32_16x16x32_bf16 v[100:103], v[160:163], v[176:179], v[100:103]
	v_mfma_f32_16x16x32_bf16 v[92:95], v[142:145], v[184:187], v[92:95]
	v_mfma_f32_16x16x32_bf16 v[84:87], v[160:163], v[184:187], v[84:87]
	v_mfma_f32_16x16x32_bf16 v[76:79], v[142:145], v[192:195], v[76:79]
	v_mfma_f32_16x16x32_bf16 v[68:71], v[160:163], v[192:195], v[68:71]
	v_mfma_f32_16x16x32_bf16 v[116:119], v[146:149], v[172:175], v[116:119]
	v_mfma_f32_16x16x32_bf16 v[112:115], v[164:167], v[172:175], v[112:115]
	v_mfma_f32_16x16x32_bf16 v[108:111], v[146:149], v[180:183], v[108:111]
	v_mfma_f32_16x16x32_bf16 v[100:103], v[164:167], v[180:183], v[100:103]
	v_mfma_f32_16x16x32_bf16 v[92:95], v[146:149], v[188:191], v[92:95]
	v_mfma_f32_16x16x32_bf16 v[84:87], v[164:167], v[188:191], v[84:87]
	v_mfma_f32_16x16x32_bf16 v[76:79], v[146:149], v[196:199], v[76:79]
	v_mfma_f32_16x16x32_bf16 v[68:71], v[164:167], v[196:199], v[68:71]
	s_barrier
	s_setprio 0
	s_add_i32 s34, 0, 0x1c000
	s_add_i32 s35, s62, s42
	v_add_u32_e32 v159, s34, v153
	v_lshl_add_u64 v[150:151], v[150:151], 0, s[18:19]
	s_mov_b32 m0, s35
	ds_read_b128 v[200:203], v159
	ds_read_b128 v[204:207], v159 offset:1024
	ds_read_b128 v[208:211], v159 offset:2048
	ds_read_b128 v[212:215], v159 offset:3072
	global_load_lds_dwordx4 v[150:151], off
	v_lshl_add_u64 v[150:151], v[216:217], 0, s[18:19]
	s_add_i32 m0, s35, 0x2000
	s_nop 0
	global_load_lds_dwordx4 v[150:151], off
	s_setprio 1
	s_barrier
	s_waitcnt lgkmcnt(0)
	s_waitcnt lgkmcnt(0)
	v_mfma_f32_16x16x32_bf16 v[124:127], v[200:203], v[168:171], v[124:127]
	v_mfma_f32_16x16x32_bf16 v[120:123], v[208:211], v[168:171], v[120:123]
	v_mfma_f32_16x16x32_bf16 v[104:107], v[200:203], v[176:179], v[104:107]
	v_mfma_f32_16x16x32_bf16 v[96:99], v[208:211], v[176:179], v[96:99]
	v_mfma_f32_16x16x32_bf16 v[88:91], v[200:203], v[184:187], v[88:91]
	v_mfma_f32_16x16x32_bf16 v[80:83], v[208:211], v[184:187], v[80:83]
	v_mfma_f32_16x16x32_bf16 v[72:75], v[200:203], v[192:195], v[72:75]
	v_mfma_f32_16x16x32_bf16 v[64:67], v[208:211], v[192:195], v[64:67]
	v_mfma_f32_16x16x32_bf16 v[124:127], v[204:207], v[172:175], v[124:127]
	v_mfma_f32_16x16x32_bf16 v[120:123], v[212:215], v[172:175], v[120:123]
	v_mfma_f32_16x16x32_bf16 v[104:107], v[204:207], v[180:183], v[104:107]
	v_mfma_f32_16x16x32_bf16 v[96:99], v[212:215], v[180:183], v[96:99]
	v_mfma_f32_16x16x32_bf16 v[88:91], v[204:207], v[188:191], v[88:91]
	v_mfma_f32_16x16x32_bf16 v[80:83], v[212:215], v[188:191], v[80:83]
	v_mfma_f32_16x16x32_bf16 v[72:75], v[204:207], v[196:199], v[72:75]
	v_mfma_f32_16x16x32_bf16 v[64:67], v[212:215], v[196:199], v[64:67]
	s_mov_b32 m0, s49
	v_lshl_add_u64 v[150:151], v[218:219], 0, s[18:19]
	s_barrier
; #define PG8_STAGE(bufoff, gbase, voff) do { _Pragma("unroll") for (int _i = 0; _i < 2; ++_i) \
;     __builtin_amdgcn_global_load_lds((const unsigned*)((const char*)(gbase) + (voff)[_i]), (PG8_LAS unsigned*)(lds + (bufoff) + ldsw + _i * 8192), 16, 0, 0); } while (0)
; #define PG8_LDA(dst, b, h) do { _Pragma("unroll") for (int m = 0; m < 4; ++m) _Pragma("unroll") for (int k = 0; k < 2; ++k) dst[m][k] = *(const PG8_LAS bf16x8*)(lds + PG8_SA(b, h) + aoff + m * 2048 + k * 1024); } while (0)
; #define PG8_MMA(ai, bj, At, Bt) do { __builtin_amdgcn_s_setprio(1); _Pragma("unroll") for (int m = 0; m < 4; ++m) _Pragma("unroll") for (int n = 0; n < 2; ++n) _Pragma("unroll") for (int k = 0; k < 2; ++k) \
;     acc[ai][bj][m][n] = __builtin_amdgcn_mfma_f32_16x16x32_bf16(Bt[n][k], At[m][k], acc[ai][bj][m][n], 0, 0, 0); __builtin_amdgcn_s_setprio(0); } while (0)
; #define PG8_WAIT_V(n) asm volatile("s_waitcnt vmcnt(" #n ")" ::: "memory")
; #define PG8_WAIT_L(n) asm volatile("s_waitcnt lgkmcnt(" #n ")" ::: "memory")
; #define PG8_BAR __builtin_amdgcn_s_barrier()
; #define PG8_SCHED __builtin_amdgcn_sched_barrier(0)
; #define EPI_ROWS_BEGIN() \
;   _Pragma("unroll") for (int ai = 0; ai < 2; ++ai) { if (u.pm * 256 + ai * 128 >= T) continue;
; template <class Epi>
; DI void gemm_phase(PG8_LAS unsigned char* lds, const Gemm g, const StaticOrder& S, const Epi& E, const int wv) {
;     ...
;       PG8_LDA(At, 1, 1); PG8_STAGE(PG8_SA(1, 0), a3, voffA);
;       PG8_BAR; PG8_WAIT_L(0); PG8_MMA(1, 0, At, B0); PG8_BAR; PG8_SCHED;
;       PG8_STAGE(PG8_SB(1, 1), b3 + hstep, voffB);
;       PG8_WAIT_V(6); PG8_BAR; PG8_MMA(1, 1, At, B1); PG8_BAR;
;     }
;     E(acc, cur, wr, wc, fr, fq);
;   DI void operator()(AccRef acc, const pg8::Unit& u, int wr, int wc, int fr, int fq) const {
;     ...
;     EPI_ROWS_BEGIN()
;       float rs[4];
; #pragma unroll
;       for (int m = 0; m < 4; ++m) rs[m] = ss[row0 + ai * 128 + m * 16];
; #pragma unroll
;       for (int m = 0; m < 4; ++m) rs[m] = rsqrtf(rs[m] * (1.f / DM) + EPS);
; #pragma unroll
;       for (int m = 0; m < 4; ++m) {
;         const int row = row0 + ai * 128 + m * 16;
;         const float ne = rs[m] * -1.4426950408889634f, r2 = rs[m] * rs[m];
	s_setprio 0
	ds_read_b128 v[168:171], v156 offset:49152
	ds_read_b128 v[172:175], v156 offset:50176
	ds_read_b128 v[176:179], v156 offset:51200
	ds_read_b128 v[180:183], v156 offset:52224
	ds_read_b128 v[184:187], v156 offset:53248
	ds_read_b128 v[188:191], v156 offset:54272
	ds_read_b128 v[192:195], v156 offset:55296
	ds_read_b128 v[196:199], v156 offset:56320
	global_load_lds_dwordx4 v[150:151], off
	v_lshl_add_u64 v[150:151], v[220:221], 0, s[18:19]
	s_mov_b32 m0, s50
	s_nop 0
	global_load_lds_dwordx4 v[150:151], off
	s_setprio 1
	s_barrier
	s_waitcnt lgkmcnt(0)
	v_mfma_f32_16x16x32_bf16 v[52:55], v[142:145], v[168:171], v[52:55]
	v_mfma_f32_16x16x32_bf16 v[48:51], v[160:163], v[168:171], v[48:51]
	v_mfma_f32_16x16x32_bf16 v[44:47], v[142:145], v[176:179], v[44:47]
	v_mfma_f32_16x16x32_bf16 v[36:39], v[160:163], v[176:179], v[36:39]
	v_mfma_f32_16x16x32_bf16 v[28:31], v[142:145], v[184:187], v[28:31]
	v_mfma_f32_16x16x32_bf16 v[20:23], v[160:163], v[184:187], v[20:23]
	v_mfma_f32_16x16x32_bf16 v[12:15], v[142:145], v[192:195], v[12:15]
	v_mfma_f32_16x16x32_bf16 v[4:7], v[160:163], v[192:195], v[4:7]
	v_mfma_f32_16x16x32_bf16 v[52:55], v[146:149], v[172:175], v[52:55]
	v_mfma_f32_16x16x32_bf16 v[48:51], v[164:167], v[172:175], v[48:51]
	v_mfma_f32_16x16x32_bf16 v[44:47], v[146:149], v[180:183], v[44:47]
	v_mfma_f32_16x16x32_bf16 v[36:39], v[164:167], v[180:183], v[36:39]
	v_mfma_f32_16x16x32_bf16 v[28:31], v[146:149], v[188:191], v[28:31]
	v_mfma_f32_16x16x32_bf16 v[20:23], v[164:167], v[188:191], v[20:23]
	v_mfma_f32_16x16x32_bf16 v[12:15], v[146:149], v[196:199], v[12:15]
	v_mfma_f32_16x16x32_bf16 v[4:7], v[164:167], v[196:199], v[4:7]
	s_barrier
	s_setprio 0
	s_add_u32 s8, s8, 0x40080
	s_addc_u32 s9, s9, 0
	s_add_i32 s34, s34, s42
	v_lshl_add_u64 v[142:143], s[8:9], 0, v[132:133]
	s_mov_b32 m0, s34
	s_nop 0
	global_load_lds_dwordx4 v[142:143], off
	v_lshl_add_u64 v[142:143], s[8:9], 0, v[128:129]
	s_add_i32 m0, s34, 0x2000
	s_nop 0
	global_load_lds_dwordx4 v[142:143], off
	s_waitcnt vmcnt(6)
	s_setprio 1
	s_barrier
	v_mfma_f32_16x16x32_bf16 v[60:63], v[200:203], v[168:171], v[60:63]
	v_mfma_f32_16x16x32_bf16 v[56:59], v[208:211], v[168:171], v[56:59]
	v_mfma_f32_16x16x32_bf16 v[40:43], v[200:203], v[176:179], v[40:43]
	v_mfma_f32_16x16x32_bf16 v[32:35], v[208:211], v[176:179], v[32:35]
	v_mfma_f32_16x16x32_bf16 v[24:27], v[200:203], v[184:187], v[24:27]
	v_mfma_f32_16x16x32_bf16 v[16:19], v[208:211], v[184:187], v[16:19]
	v_mfma_f32_16x16x32_bf16 v[8:11], v[200:203], v[192:195], v[8:11]
	v_mfma_f32_16x16x32_bf16 v[0:3], v[208:211], v[192:195], v[0:3]
	v_mfma_f32_16x16x32_bf16 v[60:63], v[204:207], v[172:175], v[60:63]
	v_mfma_f32_16x16x32_bf16 v[56:59], v[212:215], v[172:175], v[56:59]
	v_mfma_f32_16x16x32_bf16 v[40:43], v[204:207], v[180:183], v[40:43]
	v_mfma_f32_16x16x32_bf16 v[32:35], v[212:215], v[180:183], v[32:35]
	v_mfma_f32_16x16x32_bf16 v[24:27], v[204:207], v[188:191], v[24:27]
	v_mfma_f32_16x16x32_bf16 v[16:19], v[212:215], v[188:191], v[16:19]
	v_mfma_f32_16x16x32_bf16 v[8:11], v[204:207], v[196:199], v[8:11]
	v_mfma_f32_16x16x32_bf16 v[0:3], v[212:215], v[196:199], v[0:3]
	s_add_i32 s61, s61, 2
	s_add_u32 s6, s6, 0x100
	s_addc_u32 s7, s7, 0
	s_add_u32 s59, s59, 0x100
	s_addc_u32 s60, s60, 0
	s_cmp_gt_u32 s61, 13
	s_barrier
	s_setprio 0
	s_cbranch_scc0 .LBB0_1367
	v_lshl_or_b32 v142, s4, 7, v154
	v_ashrrev_i32_e32 v143, 31, v142
	v_lshl_add_u32 v144, s30, 8, v152
	s_cmpk_gt_i32 s30, 0x181
	v_lshlrev_b64 v[142:143], 1, v[142:143]
	s_cbranch_scc1 .LBB0_1370
	v_ashrrev_i32_e32 v145, 31, v144
	v_lshl_add_u64 v[146:147], v[144:145], 2, s[16:17]
	v_or_b32_e32 v150, 16, v144
	global_load_dword v145, v[146:147], off
	v_ashrrev_i32_e32 v151, 31, v150
	v_or_b32_e32 v148, 32, v144
	v_or_b32_e32 v146, 48, v144
	v_lshl_add_u64 v[160:161], v[150:151], 2, s[16:17]
	v_ashrrev_i32_e32 v149, 31, v148
	v_ashrrev_i32_e32 v147, 31, v146
	v_lshl_add_u64 v[162:163], v[148:149], 2, s[16:17]
	v_lshl_add_u64 v[164:165], v[146:147], 2, s[16:17]
	global_load_dword v147, v[160:161], off
	global_load_dword v149, v[162:163], off
	global_load_dword v151, v[164:165], off
	v_add_u32_e32 v224, 0x80, v144
	v_ashrrev_i32_e32 v225, 31, v224
	v_lshl_add_u64 v[226:227], v[224:225], 2, s[16:17]
	global_load_dword v250, v[226:227], off
	global_load_dword v251, v[226:227], off offset:64
	global_load_dword v252, v[226:227], off offset:128
	global_load_dword v253, v[226:227], off offset:192
	v_pk_mul_f32 v[160:161], v[112:113], v[120:121]
	v_mov_b64_e32 v[120:121], s[14:15]
	v_mad_i64_i32 v[162:163], s[4:5], v144, s57, v[120:121]
	v_pk_mul_f32 v[126:127], v[118:119], v[126:127]
	v_pk_mul_f32 v[124:125], v[116:117], v[124:125]
	v_pk_mul_f32 v[122:123], v[114:115], v[122:123]
	v_pk_mul_f32 v[104:105], v[108:109], v[104:105]
	v_pk_mul_f32 v[106:107], v[110:111], v[106:107]
	v_pk_mul_f32 v[98:99], v[102:103], v[98:99]
	v_lshl_add_u64 v[162:163], v[162:163], 0, v[142:143]
	v_pk_mul_f32 v[96:97], v[100:101], v[96:97]
	v_pk_mul_f32 v[88:89], v[92:93], v[88:89]
	v_pk_mul_f32 v[90:91], v[94:95], v[90:91]
	v_pk_mul_f32 v[82:83], v[86:87], v[82:83]
	v_pk_mul_f32 v[80:81], v[84:85], v[80:81]
	v_pk_mul_f32 v[72:73], v[76:77], v[72:73]
	v_pk_mul_f32 v[74:75], v[78:79], v[74:75]
	v_pk_mul_f32 v[66:67], v[70:71], v[66:67]
	v_pk_mul_f32 v[64:65], v[68:69], v[64:65]
	s_waitcnt vmcnt(4)
; DI u32x4 pack8v(f32x4 a, f32x4 b) { return u32x4{cvtpk(a[0], a[1]), cvtpk(a[2], a[3]), cvtpk(b[0], b[1]), cvtpk(b[2], b[3])}; }
;   DI void operator()(AccRef acc, const pg8::Unit& u, int wr, int wc, int fr, int fq) const {
;     ...
;       float rs[4];
; #pragma unroll
;       for (int m = 0; m < 4; ++m) rs[m] = ss[row0 + ai * 128 + m * 16];
; #pragma unroll
;       for (int m = 0; m < 4; ++m) rs[m] = rsqrtf(rs[m] * (1.f / DM) + EPS);
; #pragma unroll
;       for (int m = 0; m < 4; ++m) {
;         const int row = row0 + ai * 128 + m * 16;
;         const float ne = rs[m] * -1.4426950408889634f, r2 = rs[m] * rs[m];
;         f32x4 y[2];
; #pragma unroll
;         for (int n = 0; n < 2; ++n)
; #pragma unroll
;           for (int e = 0; e < 4; ++e) {
;             const float a = acc[ai][0][m][n][e], b = acc[ai][1][m][n][e];
;             y[n][e] = a * b * r2 * __builtin_amdgcn_rcpf(1.f + __builtin_amdgcn_exp2f(a * ne));
;           }
;         *(u32x4*)(act + (size_t)row * FFN + col0) = pack8v(y[0], y[1]);
	v_fmamk_f32 v145, v145, 0x3a800000, v158
	v_mul_f32_e32 v159, 0x4b800000, v145
	v_cmp_gt_f32_e32 vcc, s55, v145
	v_fmamk_f32 v147, v147, 0x3a800000, v158
	v_fmamk_f32 v149, v149, 0x3a800000, v158
	v_fmamk_f32 v151, v151, 0x3a800000, v158
	v_cndmask_b32_e32 v145, v145, v159, vcc
	v_mul_f32_e32 v159, 0x4b800000, v147
	v_cmp_gt_f32_e64 s[4:5], s55, v147
	v_mul_f32_e32 v164, 0x4b800000, v149
	v_mul_f32_e32 v165, 0x4b800000, v151
	v_rsq_f32_e32 v145, v145
	v_cndmask_b32_e64 v147, v147, v159, s[4:5]
	v_cmp_gt_f32_e64 s[6:7], s55, v149
	v_cmp_gt_f32_e64 s[8:9], s55, v151
	v_rsq_f32_e32 v147, v147
	v_cndmask_b32_e64 v149, v149, v164, s[6:7]
	v_cndmask_b32_e64 v151, v151, v165, s[8:9]
	v_rsq_f32_e32 v149, v149
	v_rsq_f32_e32 v151, v151
	v_mul_f32_e32 v159, 0x45800000, v145
	v_cndmask_b32_e32 v145, v145, v159, vcc
	v_mul_f32_e32 v159, 0x45800000, v147
	v_mul_f32_e32 v164, 0x45800000, v149
	v_mul_f32_e32 v165, 0x45800000, v151
	v_cndmask_b32_e64 v147, v147, v159, s[4:5]
	v_mul_f32_e32 v159, 0xbfb8aa3b, v145
	v_cndmask_b32_e64 v149, v149, v164, s[6:7]
	v_cndmask_b32_e64 v151, v151, v165, s[8:9]
	v_mul_f32_e32 v164, v145, v145
	v_mul_f32_e32 v165, v117, v159
	v_mul_f32_e32 v145, v116, v159
	v_pk_mul_f32 v[116:117], v[124:125], v[164:165] op_sel_hi:[1,0]
	v_mul_f32_e32 v124, v118, v159
	v_mul_f32_e32 v125, v119, v159
	v_pk_mul_f32 v[118:119], v[126:127], v[164:165] op_sel_hi:[1,0]
	v_mul_f32_e32 v126, v112, v159
	v_mul_f32_e32 v127, v113, v159
	v_pk_mul_f32 v[112:113], v[160:161], v[164:165] op_sel_hi:[1,0]
	v_mul_f32_e32 v160, v114, v159
	v_mul_f32_e32 v159, v115, v159
	v_pk_mul_f32 v[114:115], v[122:123], v[164:165] op_sel_hi:[1,0]
	v_mul_f32_e32 v123, 0xbfb8aa3b, v147
	v_mul_f32_e32 v161, v108, v123
	v_mul_f32_e32 v164, v109, v123
	v_mul_f32_e32 v108, v110, v123
	v_mul_f32_e32 v109, v111, v123
	v_mul_f32_e32 v122, v147, v147
	v_exp_f32_e32 v145, v145
	v_exp_f32_e32 v147, v165
	v_exp_f32_e32 v124, v124
	v_exp_f32_e32 v125, v125
	v_exp_f32_e32 v126, v126
	v_exp_f32_e32 v127, v127
	v_exp_f32_e32 v160, v160
	v_exp_f32_e32 v159, v159
	v_exp_f32_e32 v108, v108
	v_exp_f32_e32 v109, v109
	v_exp_f32_e32 v166, v161
	v_exp_f32_e32 v167, v164
	v_add_f32_e32 v145, 1.0, v145
	v_add_f32_e32 v147, 1.0, v147
	v_add_f32_e32 v161, 1.0, v124
	v_add_f32_e32 v164, 1.0, v125
	v_add_f32_e32 v165, 1.0, v126
	v_add_f32_e32 v168, 1.0, v127
	v_add_f32_e32 v169, 1.0, v160
	v_add_f32_e32 v159, 1.0, v159
	v_add_f32_e32 v108, 1.0, v108
	v_add_f32_e32 v109, 1.0, v109
	v_mul_f32_e32 v110, v100, v123
	v_mul_f32_e32 v111, v101, v123
	v_rcp_f32_e32 v124, v145
	v_rcp_f32_e32 v125, v147
	v_rcp_f32_e32 v126, v161
	v_rcp_f32_e32 v127, v164
	v_rcp_f32_e32 v160, v165
	v_rcp_f32_e32 v161, v168
	v_rcp_f32_e32 v164, v169
	v_rcp_f32_e32 v165, v159
	v_rcp_f32_e32 v108, v108
	v_rcp_f32_e32 v109, v109
	v_exp_f32_e32 v110, v110
	v_exp_f32_e32 v111, v111
	v_mul_f32_e32 v102, v102, v123
	v_mul_f32_e32 v103, v103, v123
	v_exp_f32_e32 v102, v102
	v_exp_f32_e32 v103, v103
	v_pk_mul_f32 v[106:107], v[106:107], v[122:123] op_sel_hi:[1,0]
	v_pk_mul_f32 v[116:117], v[116:117], v[124:125]
	v_pk_mul_f32 v[118:119], v[118:119], v[126:127]
	v_pk_mul_f32 v[124:125], v[112:113], v[160:161]
	v_pk_mul_f32 v[126:127], v[114:115], v[164:165]
	v_pk_mul_f32 v[106:107], v[106:107], v[108:109]
	v_add_f32_e32 v108, 1.0, v110
	v_add_f32_e32 v109, 1.0, v111
	v_cvt_pk_bf16_f32 v112, v116, v117
	v_cvt_pk_bf16_f32 v113, v118, v119
	v_cvt_pk_bf16_f32 v114, v124, v125
	v_cvt_pk_bf16_f32 v115, v126, v127
	v_rcp_f32_e32 v108, v108
	v_rcp_f32_e32 v109, v109
	v_add_f32_e32 v100, 1.0, v102
	v_add_f32_e32 v101, 1.0, v103
	v_add_f32_e32 v145, 1.0, v166
	global_store_dwordx4 v[162:163], v[112:115], off
	v_rcp_f32_e32 v100, v100
	v_rcp_f32_e32 v101, v101
	v_add_f32_e32 v113, 1.0, v167
	v_rcp_f32_e32 v112, v145
	v_rcp_f32_e32 v113, v113
; DI u32x4 pack8v(f32x4 a, f32x4 b) { return u32x4{cvtpk(a[0], a[1]), cvtpk(a[2], a[3]), cvtpk(b[0], b[1]), cvtpk(b[2], b[3])}; }
;   DI void operator()(AccRef acc, const pg8::Unit& u, int wr, int wc, int fr, int fq) const {
;     ...
; #pragma unroll
;       for (int m = 0; m < 4; ++m) {
;         const int row = row0 + ai * 128 + m * 16;
;         const float ne = rs[m] * -1.4426950408889634f, r2 = rs[m] * rs[m];
;         f32x4 y[2];
; #pragma unroll
;         for (int n = 0; n < 2; ++n)
; #pragma unroll
;           for (int e = 0; e < 4; ++e) {
;             const float a = acc[ai][0][m][n][e], b = acc[ai][1][m][n][e];
;             y[n][e] = a * b * r2 * __builtin_amdgcn_rcpf(1.f + __builtin_amdgcn_exp2f(a * ne));
;           }
;         *(u32x4*)(act + (size_t)row * FFN + col0) = pack8v(y[0], y[1]);
;       }
	v_pk_mul_f32 v[96:97], v[96:97], v[122:123] op_sel_hi:[1,0]
	v_pk_mul_f32 v[104:105], v[104:105], v[122:123] op_sel_hi:[1,0]
	v_pk_mul_f32 v[102:103], v[96:97], v[108:109]
	v_pk_mul_f32 v[96:97], v[98:99], v[122:123] op_sel_hi:[1,0]
	v_pk_mul_f32 v[104:105], v[104:105], v[112:113]
	v_pk_mul_f32 v[100:101], v[96:97], v[100:101]
	v_cvt_pk_bf16_f32 v96, v104, v105
	v_cvt_pk_bf16_f32 v99, v100, v101
	v_mad_i64_i32 v[100:101], s[4:5], v150, s57, v[120:121]
	v_cvt_pk_bf16_f32 v97, v106, v107
	v_cvt_pk_bf16_f32 v98, v102, v103
	v_lshl_add_u64 v[100:101], v[100:101], 0, v[142:143]
	global_store_dwordx4 v[100:101], v[96:99], off
	s_nop 1
	v_mul_f32_e32 v97, 0xbfb8aa3b, v149
	v_mul_f32_e32 v96, v92, v97
	v_exp_f32_e32 v98, v96
	v_mul_f32_e32 v96, v93, v97
	v_mul_f32_e32 v92, v94, v97
	v_mul_f32_e32 v93, v95, v97
	v_exp_f32_e32 v92, v92
	v_exp_f32_e32 v93, v93
	v_mul_f32_e32 v94, v84, v97
	v_mul_f32_e32 v95, v85, v97
	v_add_f32_e32 v92, 1.0, v92
	v_add_f32_e32 v93, 1.0, v93
	v_rcp_f32_e32 v92, v92
	v_rcp_f32_e32 v93, v93
	v_exp_f32_e32 v94, v94
	v_exp_f32_e32 v95, v95
	v_mul_f32_e32 v86, v86, v97
	v_mul_f32_e32 v87, v87, v97
	v_exp_f32_e32 v86, v86
	v_exp_f32_e32 v87, v87
	v_exp_f32_e32 v99, v96
	v_mul_f32_e32 v96, v149, v149
	v_pk_mul_f32 v[90:91], v[90:91], v[96:97] op_sel_hi:[1,0]
	v_add_f32_e32 v84, 1.0, v86
	v_pk_mul_f32 v[90:91], v[90:91], v[92:93]
	v_add_f32_e32 v92, 1.0, v94
	v_add_f32_e32 v93, 1.0, v95
	v_rcp_f32_e32 v92, v92
	v_rcp_f32_e32 v93, v93
	v_add_f32_e32 v85, 1.0, v87
	v_add_f32_e32 v98, 1.0, v98
	v_add_f32_e32 v99, 1.0, v99
	v_rcp_f32_e32 v84, v84
	v_rcp_f32_e32 v85, v85
	v_rcp_f32_e32 v98, v98
	v_rcp_f32_e32 v99, v99
	v_pk_mul_f32 v[80:81], v[80:81], v[96:97] op_sel_hi:[1,0]
	v_pk_mul_f32 v[88:89], v[88:89], v[96:97] op_sel_hi:[1,0]
	v_pk_mul_f32 v[86:87], v[80:81], v[92:93]
	v_pk_mul_f32 v[80:81], v[82:83], v[96:97] op_sel_hi:[1,0]
	v_pk_mul_f32 v[88:89], v[88:89], v[98:99]
	v_pk_mul_f32 v[84:85], v[80:81], v[84:85]
	v_cvt_pk_bf16_f32 v80, v88, v89
	v_cvt_pk_bf16_f32 v83, v84, v85
	v_mad_i64_i32 v[84:85], s[4:5], v148, s57, v[120:121]
	v_cvt_pk_bf16_f32 v81, v90, v91
	v_cvt_pk_bf16_f32 v82, v86, v87
	v_lshl_add_u64 v[84:85], v[84:85], 0, v[142:143]
	global_store_dwordx4 v[84:85], v[80:83], off
	s_nop 1
	v_mul_f32_e32 v81, 0xbfb8aa3b, v151
	v_mul_f32_e32 v80, v76, v81
	v_exp_f32_e32 v82, v80
	v_mul_f32_e32 v80, v77, v81
	v_mul_f32_e32 v76, v78, v81
	v_mul_f32_e32 v77, v79, v81
	v_exp_f32_e32 v76, v76
	v_exp_f32_e32 v77, v77
	v_mul_f32_e32 v78, v68, v81
	v_mul_f32_e32 v79, v69, v81
	v_add_f32_e32 v76, 1.0, v76
	v_add_f32_e32 v77, 1.0, v77
	v_rcp_f32_e32 v76, v76
	v_rcp_f32_e32 v77, v77
	v_exp_f32_e32 v78, v78
	v_exp_f32_e32 v79, v79
	v_mul_f32_e32 v70, v70, v81
	v_mul_f32_e32 v71, v71, v81
	v_exp_f32_e32 v70, v70
	v_exp_f32_e32 v71, v71
	v_exp_f32_e32 v83, v80
	v_mul_f32_e32 v80, v151, v151
	v_pk_mul_f32 v[74:75], v[74:75], v[80:81] op_sel_hi:[1,0]
	v_add_f32_e32 v68, 1.0, v70
	v_pk_mul_f32 v[74:75], v[74:75], v[76:77]
	v_add_f32_e32 v76, 1.0, v78
	v_add_f32_e32 v77, 1.0, v79
	v_rcp_f32_e32 v76, v76
	v_rcp_f32_e32 v77, v77
	v_add_f32_e32 v69, 1.0, v71
	v_add_f32_e32 v82, 1.0, v82
	v_add_f32_e32 v83, 1.0, v83
	v_rcp_f32_e32 v68, v68
	v_rcp_f32_e32 v69, v69
	v_rcp_f32_e32 v82, v82
	v_rcp_f32_e32 v83, v83
	v_pk_mul_f32 v[64:65], v[64:65], v[80:81] op_sel_hi:[1,0]
	v_pk_mul_f32 v[72:73], v[72:73], v[80:81] op_sel_hi:[1,0]
	v_pk_mul_f32 v[70:71], v[64:65], v[76:77]
	v_pk_mul_f32 v[64:65], v[66:67], v[80:81] op_sel_hi:[1,0]
	v_pk_mul_f32 v[72:73], v[72:73], v[82:83]
	v_pk_mul_f32 v[68:69], v[64:65], v[68:69]
	v_cvt_pk_bf16_f32 v64, v72, v73
	v_cvt_pk_bf16_f32 v67, v68, v69
	v_mad_i64_i32 v[68:69], s[4:5], v146, s57, v[120:121]
	v_cvt_pk_bf16_f32 v65, v74, v75
	v_cvt_pk_bf16_f32 v66, v70, v71
	v_lshl_add_u64 v[68:69], v[68:69], 0, v[142:143]
	global_store_dwordx4 v[68:69], v[64:67], off

; #define PG8_STAGE(bufoff, gbase, voff) do { _Pragma("unroll") for (int _i = 0; _i < 2; ++_i) \
;     __builtin_amdgcn_global_load_lds((const unsigned*)((const char*)(gbase) + (voff)[_i]), (PG8_LAS unsigned*)(lds + (bufoff) + ldsw + _i * 8192), 16, 0, 0); } while (0)
; #define PG8_LDA(dst, b, h) do { _Pragma("unroll") for (int m = 0; m < 4; ++m) _Pragma("unroll") for (int k = 0; k < 2; ++k) dst[m][k] = *(const PG8_LAS bf16x8*)(lds + PG8_SA(b, h) + aoff + m * 2048 + k * 1024); } while (0)
; #define PG8_LDB(dst, b, h) do { _Pragma("unroll") for (int n = 0; n < 2; ++n) _Pragma("unroll") for (int k = 0; k < 2; ++k) dst[n][k] = *(const PG8_LAS bf16x8*)(lds + PG8_SB(b, h) + boff + n * 2048 + k * 1024); } while (0)
; #define PG8_MMA(ai, bj, At, Bt) do { __builtin_amdgcn_s_setprio(1); _Pragma("unroll") for (int m = 0; m < 4; ++m) _Pragma("unroll") for (int n = 0; n < 2; ++n) _Pragma("unroll") for (int k = 0; k < 2; ++k) \
;     acc[ai][bj][m][n] = __builtin_amdgcn_mfma_f32_16x16x32_bf16(Bt[n][k], At[m][k], acc[ai][bj][m][n], 0, 0, 0); __builtin_amdgcn_s_setprio(0); } while (0)
; #define PG8_WAIT_L(n) asm volatile("s_waitcnt lgkmcnt(" #n ")" ::: "memory")
; #define PG8_BAR __builtin_amdgcn_s_barrier()
; #define PG8_SCHED __builtin_amdgcn_sched_barrier(0)
; template <class Epi>
; DI void gemm_phase(PG8_LAS unsigned char* lds, const Gemm g, const StaticOrder& S, const Epi& E, const int wv) {
;     ...
;       PG8_LDB(B0, 0, 0); PG8_SCHED; PG8_LDA(At, 0, 0); PG8_STAGE(PG8_SA(1, 1), a1 + hstep, voffA);
;       PG8_WAIT_L(8); PG8_BAR; PG8_WAIT_L(0); PG8_MMA(0, 0, At, B0); PG8_BAR; PG8_SCHED;
;       PG8_LDB(B1, 0, 1); PG8_STAGE(PG8_SB(0, 0), b2, voffB);
;       PG8_BAR; PG8_WAIT_L(0); PG8_MMA(0, 1, At, B1); PG8_BAR;
;       PG8_LDA(At, 0, 1); PG8_STAGE(PG8_SA(0, 0), a2, voffA);
;       PG8_BAR; PG8_WAIT_L(0); PG8_MMA(1, 0, At, B0); PG8_BAR; PG8_SCHED;
.LBB0_1439:
	ds_read_b128 v[142:145], v151
	ds_read_b128 v[154:157], v151 offset:1024
	ds_read_b128 v[158:161], v151 offset:2048
	ds_read_b128 v[162:165], v151 offset:3072
	s_add_u32 s16, s14, 0x100
	s_addc_u32 s17, s15, 0
	s_cmp_eq_u32 s47, 40
	s_cselect_b32 s21, s11, s17
	s_cselect_b32 s20, s10, s16
	s_cselect_b32 s19, s1, s46
	s_cselect_b32 s18, s0, s45
	v_lshl_add_u64 v[146:147], s[14:15], 0, v[136:137]
	s_add_i32 m0, s30, 0xc000
	ds_read_b128 v[166:169], v152
	ds_read_b128 v[170:173], v152 offset:1024
	ds_read_b128 v[174:177], v152 offset:2048
	ds_read_b128 v[178:181], v152 offset:3072
	ds_read_b128 v[182:185], v152 offset:4096
	ds_read_b128 v[186:189], v152 offset:5120
	ds_read_b128 v[190:193], v152 offset:6144
	ds_read_b128 v[194:197], v152 offset:7168
	global_load_lds_dwordx4 v[146:147], off
	v_lshl_add_u64 v[146:147], s[14:15], 0, v[138:139]
	s_add_i32 m0, s30, 0xe000
	s_nop 0
	global_load_lds_dwordx4 v[146:147], off
	s_waitcnt lgkmcnt(8)
	s_setprio 1
	s_barrier
	s_waitcnt lgkmcnt(0)
	s_waitcnt lgkmcnt(0)
	v_mfma_f32_16x16x32_bf16 v[124:127], v[142:145], v[166:169], v[124:127]
	v_mfma_f32_16x16x32_bf16 v[120:123], v[158:161], v[166:169], v[120:123]
	v_mfma_f32_16x16x32_bf16 v[112:115], v[142:145], v[174:177], v[112:115]
	v_mfma_f32_16x16x32_bf16 v[104:107], v[158:161], v[174:177], v[104:107]
	v_mfma_f32_16x16x32_bf16 v[96:99], v[142:145], v[182:185], v[96:99]
	v_mfma_f32_16x16x32_bf16 v[88:91], v[158:161], v[182:185], v[88:91]
	v_mfma_f32_16x16x32_bf16 v[80:83], v[142:145], v[190:193], v[80:83]
	v_mfma_f32_16x16x32_bf16 v[72:75], v[158:161], v[190:193], v[72:75]
	v_mfma_f32_16x16x32_bf16 v[124:127], v[154:157], v[170:173], v[124:127]
	v_mfma_f32_16x16x32_bf16 v[120:123], v[162:165], v[170:173], v[120:123]
	v_mfma_f32_16x16x32_bf16 v[112:115], v[154:157], v[178:181], v[112:115]
	v_mfma_f32_16x16x32_bf16 v[104:107], v[162:165], v[178:181], v[104:107]
	v_mfma_f32_16x16x32_bf16 v[96:99], v[154:157], v[186:189], v[96:99]
	v_mfma_f32_16x16x32_bf16 v[88:91], v[162:165], v[186:189], v[88:91]
	v_mfma_f32_16x16x32_bf16 v[80:83], v[154:157], v[194:197], v[80:83]
	v_mfma_f32_16x16x32_bf16 v[72:75], v[162:165], v[194:197], v[72:75]
	s_barrier
	s_setprio 0
	s_add_i32 s14, s39, s27
	v_lshl_add_u64 v[146:147], s[18:19], 0, v[132:133]
	s_mov_b32 m0, s14
	ds_read_b128 v[198:201], v153
	ds_read_b128 v[202:205], v153 offset:1024
	ds_read_b128 v[206:209], v153 offset:2048
	ds_read_b128 v[210:213], v153 offset:3072
	global_load_lds_dwordx4 v[146:147], off
	v_lshl_add_u64 v[214:215], s[18:19], 0, v[128:129]
	s_add_i32 m0, s14, 0x2000
	s_nop 0
	global_load_lds_dwordx4 v[214:215], off
	s_setprio 1
	s_barrier
	s_waitcnt lgkmcnt(0)
	v_mfma_f32_16x16x32_bf16 v[116:119], v[198:201], v[166:169], v[116:119]
	v_mfma_f32_16x16x32_bf16 v[108:111], v[206:209], v[166:169], v[108:111]
	v_mfma_f32_16x16x32_bf16 v[100:103], v[198:201], v[174:177], v[100:103]
	v_mfma_f32_16x16x32_bf16 v[92:95], v[206:209], v[174:177], v[92:95]
	v_mfma_f32_16x16x32_bf16 v[84:87], v[198:201], v[182:185], v[84:87]
	v_mfma_f32_16x16x32_bf16 v[76:79], v[206:209], v[182:185], v[76:79]
	v_mfma_f32_16x16x32_bf16 v[68:71], v[198:201], v[190:193], v[68:71]
	v_mfma_f32_16x16x32_bf16 v[64:67], v[206:209], v[190:193], v[64:67]
	v_mfma_f32_16x16x32_bf16 v[116:119], v[202:205], v[170:173], v[116:119]
	v_mfma_f32_16x16x32_bf16 v[108:111], v[210:213], v[170:173], v[108:111]
	v_mfma_f32_16x16x32_bf16 v[100:103], v[202:205], v[178:181], v[100:103]
	v_mfma_f32_16x16x32_bf16 v[92:95], v[210:213], v[178:181], v[92:95]
	v_mfma_f32_16x16x32_bf16 v[84:87], v[202:205], v[186:189], v[84:87]
	v_mfma_f32_16x16x32_bf16 v[76:79], v[210:213], v[186:189], v[76:79]
	v_mfma_f32_16x16x32_bf16 v[68:71], v[202:205], v[194:197], v[68:71]
	v_mfma_f32_16x16x32_bf16 v[64:67], v[210:213], v[194:197], v[64:67]
	s_mov_b32 m0, s30
	v_lshl_add_u64 v[216:217], s[20:21], 0, v[134:135]
	s_barrier
	s_setprio 0
	ds_read_b128 v[166:169], v152 offset:16384
	ds_read_b128 v[170:173], v152 offset:17408
	ds_read_b128 v[174:177], v152 offset:18432
	ds_read_b128 v[178:181], v152 offset:19456
	ds_read_b128 v[182:185], v152 offset:20480
	ds_read_b128 v[186:189], v152 offset:21504
	ds_read_b128 v[190:193], v152 offset:22528
	ds_read_b128 v[194:197], v152 offset:23552
	global_load_lds_dwordx4 v[216:217], off
	v_lshl_add_u64 v[218:219], s[20:21], 0, v[130:131]
	s_mov_b32 m0, s31
	s_nop 0
	global_load_lds_dwordx4 v[218:219], off
	s_setprio 1
	s_barrier
	s_waitcnt lgkmcnt(0)
	v_mfma_f32_16x16x32_bf16 v[60:63], v[142:145], v[166:169], v[60:63]
	v_mfma_f32_16x16x32_bf16 v[56:59], v[158:161], v[166:169], v[56:59]
	v_mfma_f32_16x16x32_bf16 v[48:51], v[142:145], v[174:177], v[48:51]
	v_mfma_f32_16x16x32_bf16 v[40:43], v[158:161], v[174:177], v[40:43]
	v_mfma_f32_16x16x32_bf16 v[32:35], v[142:145], v[182:185], v[32:35]
	v_mfma_f32_16x16x32_bf16 v[24:27], v[158:161], v[182:185], v[24:27]
	v_mfma_f32_16x16x32_bf16 v[16:19], v[142:145], v[190:193], v[16:19]
	v_mfma_f32_16x16x32_bf16 v[8:11], v[158:161], v[190:193], v[8:11]
	v_mfma_f32_16x16x32_bf16 v[60:63], v[154:157], v[170:173], v[60:63]
	v_mfma_f32_16x16x32_bf16 v[56:59], v[162:165], v[170:173], v[56:59]
	v_mfma_f32_16x16x32_bf16 v[48:51], v[154:157], v[178:181], v[48:51]
	v_mfma_f32_16x16x32_bf16 v[40:43], v[162:165], v[178:181], v[40:43]
	v_mfma_f32_16x16x32_bf16 v[32:35], v[154:157], v[186:189], v[32:35]
	v_mfma_f32_16x16x32_bf16 v[24:27], v[162:165], v[186:189], v[24:27]
	v_mfma_f32_16x16x32_bf16 v[16:19], v[154:157], v[194:197], v[16:19]
	v_mfma_f32_16x16x32_bf16 v[8:11], v[162:165], v[194:197], v[8:11]
	s_barrier
; #define PG8_STAGE(bufoff, gbase, voff) do { _Pragma("unroll") for (int _i = 0; _i < 2; ++_i) \
;     __builtin_amdgcn_global_load_lds((const unsigned*)((const char*)(gbase) + (voff)[_i]), (PG8_LAS unsigned*)(lds + (bufoff) + ldsw + _i * 8192), 16, 0, 0); } while (0)
; #define PG8_LDA(dst, b, h) do { _Pragma("unroll") for (int m = 0; m < 4; ++m) _Pragma("unroll") for (int k = 0; k < 2; ++k) dst[m][k] = *(const PG8_LAS bf16x8*)(lds + PG8_SA(b, h) + aoff + m * 2048 + k * 1024); } while (0)
; #define PG8_LDB(dst, b, h) do { _Pragma("unroll") for (int n = 0; n < 2; ++n) _Pragma("unroll") for (int k = 0; k < 2; ++k) dst[n][k] = *(const PG8_LAS bf16x8*)(lds + PG8_SB(b, h) + boff + n * 2048 + k * 1024); } while (0)
; #define PG8_MMA(ai, bj, At, Bt) do { __builtin_amdgcn_s_setprio(1); _Pragma("unroll") for (int m = 0; m < 4; ++m) _Pragma("unroll") for (int n = 0; n < 2; ++n) _Pragma("unroll") for (int k = 0; k < 2; ++k) \
;     acc[ai][bj][m][n] = __builtin_amdgcn_mfma_f32_16x16x32_bf16(Bt[n][k], At[m][k], acc[ai][bj][m][n], 0, 0, 0); __builtin_amdgcn_s_setprio(0); } while (0)
; #define PG8_WAIT_V(n) asm volatile("s_waitcnt vmcnt(" #n ")" ::: "memory")
; #define PG8_WAIT_L(n) asm volatile("s_waitcnt lgkmcnt(" #n ")" ::: "memory")
; #define PG8_BAR __builtin_amdgcn_s_barrier()
; #define PG8_SCHED __builtin_amdgcn_sched_barrier(0)
; template <class Epi>
; DI void gemm_phase(PG8_LAS unsigned char* lds, const Gemm g, const StaticOrder& S, const Epi& E, const int wv) {
;     ...
;       PG8_STAGE(PG8_SB(0, 1), b2 + hstep, voffB);
;       PG8_WAIT_V(6); PG8_BAR; PG8_MMA(1, 1, At, B1); PG8_BAR;
;       PG8_LDB(B0, 1, 0); PG8_SCHED; PG8_LDA(At, 1, 0); PG8_STAGE(PG8_SA(0, 1), a2 + hstep, voffA);
;       PG8_WAIT_L(8); PG8_BAR; PG8_WAIT_L(0); PG8_MMA(0, 0, At, B0); PG8_BAR; PG8_SCHED;
;       PG8_LDB(B1, 1, 1); PG8_STAGE(PG8_SB(1, 0), b3, voffB);
;       PG8_BAR; PG8_WAIT_L(0); PG8_MMA(0, 1, At, B1); PG8_BAR;
;       PG8_LDA(At, 1, 1); PG8_STAGE(PG8_SA(1, 0), a3, voffA);
	s_setprio 0
	s_add_u32 s14, s18, 0xb0000
	s_addc_u32 s15, s19, 0
	s_add_i32 s48, s40, s27
	v_lshl_add_u64 v[142:143], s[14:15], 0, v[132:133]
	s_mov_b32 m0, s48
	s_nop 0
	global_load_lds_dwordx4 v[142:143], off
	v_lshl_add_u64 v[142:143], s[14:15], 0, v[128:129]
	s_add_i32 m0, s48, 0x2000
	s_nop 0
	global_load_lds_dwordx4 v[142:143], off
	s_waitcnt vmcnt(6)
	s_setprio 1
	s_barrier
	v_mfma_f32_16x16x32_bf16 v[52:55], v[198:201], v[166:169], v[52:55]
	v_mfma_f32_16x16x32_bf16 v[44:47], v[206:209], v[166:169], v[44:47]
	v_mfma_f32_16x16x32_bf16 v[36:39], v[198:201], v[174:177], v[36:39]
	v_mfma_f32_16x16x32_bf16 v[28:31], v[206:209], v[174:177], v[28:31]
	v_mfma_f32_16x16x32_bf16 v[20:23], v[198:201], v[182:185], v[20:23]
	v_mfma_f32_16x16x32_bf16 v[12:15], v[206:209], v[182:185], v[12:15]
	v_mfma_f32_16x16x32_bf16 v[4:7], v[198:201], v[190:193], v[4:7]
	v_mfma_f32_16x16x32_bf16 v[0:3], v[206:209], v[190:193], v[0:3]
	v_mfma_f32_16x16x32_bf16 v[52:55], v[202:205], v[170:173], v[52:55]
	v_mfma_f32_16x16x32_bf16 v[44:47], v[210:213], v[170:173], v[44:47]
	v_mfma_f32_16x16x32_bf16 v[36:39], v[202:205], v[178:181], v[36:39]
	v_mfma_f32_16x16x32_bf16 v[28:31], v[210:213], v[178:181], v[28:31]
	v_mfma_f32_16x16x32_bf16 v[20:23], v[202:205], v[186:189], v[20:23]
	v_mfma_f32_16x16x32_bf16 v[12:15], v[210:213], v[186:189], v[12:15]
	v_mfma_f32_16x16x32_bf16 v[4:7], v[202:205], v[194:197], v[4:7]
	v_mfma_f32_16x16x32_bf16 v[0:3], v[210:213], v[194:197], v[0:3]
	s_add_i32 s48, 0, 0x18000
	v_add_u32_e32 v162, s48, v149
	s_barrier
	s_setprio 0
	ds_read_b128 v[142:145], v162
	ds_read_b128 v[154:157], v162 offset:1024
	ds_read_b128 v[158:161], v162 offset:2048
	ds_read_b128 v[162:165], v162 offset:3072
	s_add_u32 s14, s20, 0xb0000
	s_addc_u32 s15, s21, 0
	s_mov_b32 m0, s33
	v_lshl_add_u64 v[198:199], s[14:15], 0, v[134:135]
	ds_read_b128 v[166:169], v152 offset:32768
	ds_read_b128 v[170:173], v152 offset:33792
	ds_read_b128 v[174:177], v152 offset:34816
	ds_read_b128 v[178:181], v152 offset:35840
	ds_read_b128 v[182:185], v152 offset:36864
	ds_read_b128 v[186:189], v152 offset:37888
	ds_read_b128 v[190:193], v152 offset:38912
	ds_read_b128 v[194:197], v152 offset:39936
	global_load_lds_dwordx4 v[198:199], off
	v_lshl_add_u64 v[198:199], s[14:15], 0, v[130:131]
	s_mov_b32 m0, s34
	s_nop 0
	global_load_lds_dwordx4 v[198:199], off
	s_waitcnt lgkmcnt(8)
	s_setprio 1
	s_barrier
	s_waitcnt lgkmcnt(0)
	s_waitcnt lgkmcnt(0)
	v_mfma_f32_16x16x32_bf16 v[124:127], v[142:145], v[166:169], v[124:127]
	v_mfma_f32_16x16x32_bf16 v[120:123], v[158:161], v[166:169], v[120:123]
	v_mfma_f32_16x16x32_bf16 v[112:115], v[142:145], v[174:177], v[112:115]
	v_mfma_f32_16x16x32_bf16 v[104:107], v[158:161], v[174:177], v[104:107]
	v_mfma_f32_16x16x32_bf16 v[96:99], v[142:145], v[182:185], v[96:99]
	v_mfma_f32_16x16x32_bf16 v[88:91], v[158:161], v[182:185], v[88:91]
	v_mfma_f32_16x16x32_bf16 v[80:83], v[142:145], v[190:193], v[80:83]
	v_mfma_f32_16x16x32_bf16 v[72:75], v[158:161], v[190:193], v[72:75]
	v_mfma_f32_16x16x32_bf16 v[124:127], v[154:157], v[170:173], v[124:127]
	v_mfma_f32_16x16x32_bf16 v[120:123], v[162:165], v[170:173], v[120:123]
	v_mfma_f32_16x16x32_bf16 v[112:115], v[154:157], v[178:181], v[112:115]
	v_mfma_f32_16x16x32_bf16 v[104:107], v[162:165], v[178:181], v[104:107]
	v_mfma_f32_16x16x32_bf16 v[96:99], v[154:157], v[186:189], v[96:99]
	v_mfma_f32_16x16x32_bf16 v[88:91], v[162:165], v[186:189], v[88:91]
	v_mfma_f32_16x16x32_bf16 v[80:83], v[154:157], v[194:197], v[80:83]
	v_mfma_f32_16x16x32_bf16 v[72:75], v[162:165], v[194:197], v[72:75]
	s_barrier
	s_setprio 0
	s_add_i32 s20, 0, 0x1c000
	s_add_i32 s14, s48, s27
	v_add_u32_e32 v210, s20, v149
	v_lshl_add_u64 v[146:147], v[146:147], 0, s[6:7]
	s_mov_b32 m0, s14
	ds_read_b128 v[198:201], v210
	ds_read_b128 v[202:205], v210 offset:1024
	ds_read_b128 v[206:209], v210 offset:2048
	ds_read_b128 v[210:213], v210 offset:3072
	global_load_lds_dwordx4 v[146:147], off
	v_lshl_add_u64 v[146:147], v[214:215], 0, s[6:7]
	s_add_i32 m0, s14, 0x2000
	s_nop 0
	global_load_lds_dwordx4 v[146:147], off
	s_setprio 1
	s_barrier
	s_waitcnt lgkmcnt(0)
	s_waitcnt lgkmcnt(0)
	v_mfma_f32_16x16x32_bf16 v[116:119], v[198:201], v[166:169], v[116:119]
	v_mfma_f32_16x16x32_bf16 v[108:111], v[206:209], v[166:169], v[108:111]
	v_mfma_f32_16x16x32_bf16 v[100:103], v[198:201], v[174:177], v[100:103]
	v_mfma_f32_16x16x32_bf16 v[92:95], v[206:209], v[174:177], v[92:95]
	v_mfma_f32_16x16x32_bf16 v[84:87], v[198:201], v[182:185], v[84:87]
	v_mfma_f32_16x16x32_bf16 v[76:79], v[206:209], v[182:185], v[76:79]
	v_mfma_f32_16x16x32_bf16 v[68:71], v[198:201], v[190:193], v[68:71]
	v_mfma_f32_16x16x32_bf16 v[64:67], v[206:209], v[190:193], v[64:67]
	v_mfma_f32_16x16x32_bf16 v[116:119], v[202:205], v[170:173], v[116:119]
	v_mfma_f32_16x16x32_bf16 v[108:111], v[210:213], v[170:173], v[108:111]
	v_mfma_f32_16x16x32_bf16 v[100:103], v[202:205], v[178:181], v[100:103]
	v_mfma_f32_16x16x32_bf16 v[92:95], v[210:213], v[178:181], v[92:95]
	v_mfma_f32_16x16x32_bf16 v[84:87], v[202:205], v[186:189], v[84:87]
	v_mfma_f32_16x16x32_bf16 v[76:79], v[210:213], v[186:189], v[76:79]
	v_mfma_f32_16x16x32_bf16 v[68:71], v[202:205], v[194:197], v[68:71]
	v_mfma_f32_16x16x32_bf16 v[64:67], v[210:213], v[194:197], v[64:67]
	s_mov_b32 m0, s36
	v_lshl_add_u64 v[146:147], v[216:217], 0, s[6:7]
	s_barrier
	s_setprio 0
	ds_read_b128 v[166:169], v152 offset:49152
	ds_read_b128 v[170:173], v152 offset:50176
	ds_read_b128 v[174:177], v152 offset:51200
	ds_read_b128 v[178:181], v152 offset:52224
	ds_read_b128 v[182:185], v152 offset:53248
	ds_read_b128 v[186:189], v152 offset:54272
	ds_read_b128 v[190:193], v152 offset:55296
	ds_read_b128 v[194:197], v152 offset:56320
	global_load_lds_dwordx4 v[146:147], off
	v_lshl_add_u64 v[146:147], v[218:219], 0, s[6:7]
	s_mov_b32 m0, s37
	s_nop 0
	global_load_lds_dwordx4 v[146:147], off
	s_setprio 1
	s_barrier
; #define PG8_STAGE(bufoff, gbase, voff) do { _Pragma("unroll") for (int _i = 0; _i < 2; ++_i) \
;     __builtin_amdgcn_global_load_lds((const unsigned*)((const char*)(gbase) + (voff)[_i]), (PG8_LAS unsigned*)(lds + (bufoff) + ldsw + _i * 8192), 16, 0, 0); } while (0)
; #define PG8_MMA(ai, bj, At, Bt) do { __builtin_amdgcn_s_setprio(1); _Pragma("unroll") for (int m = 0; m < 4; ++m) _Pragma("unroll") for (int n = 0; n < 2; ++n) _Pragma("unroll") for (int k = 0; k < 2; ++k) \
;     acc[ai][bj][m][n] = __builtin_amdgcn_mfma_f32_16x16x32_bf16(Bt[n][k], At[m][k], acc[ai][bj][m][n], 0, 0, 0); __builtin_amdgcn_s_setprio(0); } while (0)
; #define PG8_WAIT_V(n) asm volatile("s_waitcnt vmcnt(" #n ")" ::: "memory")
; #define PG8_WAIT_L(n) asm volatile("s_waitcnt lgkmcnt(" #n ")" ::: "memory")
; #define PG8_BAR __builtin_amdgcn_s_barrier()
; #define PG8_SCHED __builtin_amdgcn_sched_barrier(0)
; #define EPI_ROWS_BEGIN() \
;   _Pragma("unroll") for (int ai = 0; ai < 2; ++ai) { if (u.pm * 256 + ai * 128 >= T) continue;
; template <class Epi>
; DI void gemm_phase(PG8_LAS unsigned char* lds, const Gemm g, const StaticOrder& S, const Epi& E, const int wv) {
;     ...
;       PG8_BAR; PG8_WAIT_L(0); PG8_MMA(1, 0, At, B0); PG8_BAR; PG8_SCHED;
;       PG8_STAGE(PG8_SB(1, 1), b3 + hstep, voffB);
;       PG8_WAIT_V(6); PG8_BAR; PG8_MMA(1, 1, At, B1); PG8_BAR;
;     }
;     E(acc, cur, wr, wc, fr, fq);
;   DI void operator()(AccRef acc, const pg8::Unit& u, int wr, int wc, int fr, int fq) const {
;     const int row0 = u.pm * 256 + wr * 64 + fr, col0 = u.pn * 256 + wc * 32 + 8 * fq;
;     EPI_ROWS_BEGIN()
	s_waitcnt lgkmcnt(0)
	v_mfma_f32_16x16x32_bf16 v[60:63], v[142:145], v[166:169], v[60:63]
	v_mfma_f32_16x16x32_bf16 v[56:59], v[158:161], v[166:169], v[56:59]
	v_mfma_f32_16x16x32_bf16 v[48:51], v[142:145], v[174:177], v[48:51]
	v_mfma_f32_16x16x32_bf16 v[40:43], v[158:161], v[174:177], v[40:43]
	v_mfma_f32_16x16x32_bf16 v[32:35], v[142:145], v[182:185], v[32:35]
	v_mfma_f32_16x16x32_bf16 v[24:27], v[158:161], v[182:185], v[24:27]
	v_mfma_f32_16x16x32_bf16 v[16:19], v[142:145], v[190:193], v[16:19]
	v_mfma_f32_16x16x32_bf16 v[8:11], v[158:161], v[190:193], v[8:11]
	v_mfma_f32_16x16x32_bf16 v[60:63], v[154:157], v[170:173], v[60:63]
	v_mfma_f32_16x16x32_bf16 v[56:59], v[162:165], v[170:173], v[56:59]
	v_mfma_f32_16x16x32_bf16 v[48:51], v[154:157], v[178:181], v[48:51]
	v_mfma_f32_16x16x32_bf16 v[40:43], v[162:165], v[178:181], v[40:43]
	v_mfma_f32_16x16x32_bf16 v[32:35], v[154:157], v[186:189], v[32:35]
	v_mfma_f32_16x16x32_bf16 v[24:27], v[162:165], v[186:189], v[24:27]
	v_mfma_f32_16x16x32_bf16 v[16:19], v[154:157], v[194:197], v[16:19]
	v_mfma_f32_16x16x32_bf16 v[8:11], v[162:165], v[194:197], v[8:11]
	s_barrier
	s_setprio 0
	s_add_u32 s14, s18, 0xb0080
	s_addc_u32 s15, s19, 0
	s_add_i32 s18, s20, s27
	v_lshl_add_u64 v[142:143], s[14:15], 0, v[132:133]
	s_mov_b32 m0, s18
	s_nop 0
	global_load_lds_dwordx4 v[142:143], off
	v_lshl_add_u64 v[142:143], s[14:15], 0, v[128:129]
	s_add_i32 m0, s18, 0x2000
	s_nop 0
	global_load_lds_dwordx4 v[142:143], off
	s_waitcnt vmcnt(6)
	s_setprio 1
	s_barrier
	v_mfma_f32_16x16x32_bf16 v[52:55], v[198:201], v[166:169], v[52:55]
	v_mfma_f32_16x16x32_bf16 v[44:47], v[206:209], v[166:169], v[44:47]
	v_mfma_f32_16x16x32_bf16 v[36:39], v[198:201], v[174:177], v[36:39]
	v_mfma_f32_16x16x32_bf16 v[28:31], v[206:209], v[174:177], v[28:31]
	v_mfma_f32_16x16x32_bf16 v[20:23], v[198:201], v[182:185], v[20:23]
	v_mfma_f32_16x16x32_bf16 v[12:15], v[206:209], v[182:185], v[12:15]
	v_mfma_f32_16x16x32_bf16 v[4:7], v[198:201], v[190:193], v[4:7]
	v_mfma_f32_16x16x32_bf16 v[0:3], v[206:209], v[190:193], v[0:3]
	v_mfma_f32_16x16x32_bf16 v[52:55], v[202:205], v[170:173], v[52:55]
	v_mfma_f32_16x16x32_bf16 v[44:47], v[210:213], v[170:173], v[44:47]
	v_mfma_f32_16x16x32_bf16 v[36:39], v[202:205], v[178:181], v[36:39]
	v_mfma_f32_16x16x32_bf16 v[28:31], v[210:213], v[178:181], v[28:31]
	v_mfma_f32_16x16x32_bf16 v[20:23], v[202:205], v[186:189], v[20:23]
	v_mfma_f32_16x16x32_bf16 v[12:15], v[210:213], v[186:189], v[12:15]
	v_mfma_f32_16x16x32_bf16 v[4:7], v[202:205], v[194:197], v[4:7]
	v_mfma_f32_16x16x32_bf16 v[0:3], v[210:213], v[194:197], v[0:3]
	s_add_i32 s47, s47, 2
	s_add_u32 s45, s45, 0x100
	s_addc_u32 s46, s46, 0
	s_cmp_gt_u32 s47, 41
	s_mov_b64 s[14:15], s[16:17]
	s_barrier
	s_setprio 0
	s_cbranch_scc0 .LBB0_1439
	v_lshl_or_b32 v146, s44, 8, v150
	v_ashrrev_i32_e32 v147, 31, v146
	v_lshl_add_u32 v144, s43, 8, v148
	s_cmpk_gt_i32 s43, 0x181
	v_lshlrev_b64 v[142:143], 2, v[146:147]
	v_lshl_add_u64 v[146:147], v[146:147], 1, s[2:3]
	s_cbranch_scc1 .LBB0_1442
; DI float bf_lo(unsigned u) { return __uint_as_float(u << 16); }
; DI float bf_hi(unsigned u) { return __uint_as_float(u & 0xffff0000u); }
;   DI void operator()(AccRef acc, const pg8::Unit& u, int wr, int wc, int fr, int fq) const {
;     ...
;         u32x4 rb[4][2];
; #pragma unroll
;         for (int m = 0; m < 4; ++m)
; #pragma unroll
;           for (int bj = 0; bj < 2; ++bj) {
;             const int rr = row0 + ai * 128 + m * 16;
;             const int sr = (MODE == 3) ? rr + NMETA * ((rr >> 12) + 1) : rr;
;             rb[m][bj] = *(const u32x4*)(hsrc + (size_t)sr * DM + col0 + bj * 128);
;           }
; #pragma unroll
;         for (int m = 0; m < 4; ++m)
; #pragma unroll
;           for (int bj = 0; bj < 2; ++bj) {
;             r[m][bj][0] = f32x4{bf_lo(rb[m][bj][0]), bf_hi(rb[m][bj][0]), bf_lo(rb[m][bj][1]), bf_hi(rb[m][bj][1])};
;             r[m][bj][1] = f32x4{bf_lo(rb[m][bj][2]), bf_hi(rb[m][bj][2]), bf_lo(rb[m][bj][3]), bf_hi(rb[m][bj][3])};
;           }
;       }
; #pragma unroll
;       for (int m = 0; m < 4; ++m) {
;         const int row = row0 + ai * 128 + m * 16;
;         if constexpr (MODE == 4) {
;           float* dst = P.out + (size_t)row * DM + col0;
; #pragma unroll
;           for (int bj = 0; bj < 2; ++bj) {
;             *(f32x4*)(dst + bj * 128) = r[m][bj][0] + acc[ai][bj][m][0];
;             *(f32x4*)(dst + bj * 128 + 4) = r[m][bj][1] + acc[ai][bj][m][1];
;           }
	v_ashrrev_i32_e32 v145, 31, v144
	v_lshlrev_b64 v[154:155], 11, v[144:145]
	v_lshl_add_u64 v[158:159], v[146:147], 0, v[154:155]
	v_or_b32_e32 v186, 16, v144
	global_load_dwordx4 v[154:157], v[158:159], off
	s_nop 0
	global_load_dwordx4 v[158:161], v[158:159], off offset:256
	v_ashrrev_i32_e32 v187, 31, v186
	v_lshlrev_b64 v[162:163], 11, v[186:187]
	v_lshl_add_u64 v[166:167], v[146:147], 0, v[162:163]
	v_or_b32_e32 v188, 32, v144
	global_load_dwordx4 v[162:165], v[166:167], off
	s_nop 0
	global_load_dwordx4 v[166:169], v[166:167], off offset:256
	v_ashrrev_i32_e32 v189, 31, v188
	v_lshlrev_b64 v[170:171], 11, v[188:189]
	v_lshl_add_u64 v[174:175], v[146:147], 0, v[170:171]
	v_or_b32_e32 v190, 48, v144
	global_load_dwordx4 v[170:173], v[174:175], off
	s_nop 0
	global_load_dwordx4 v[174:177], v[174:175], off offset:256
	v_ashrrev_i32_e32 v191, 31, v190
	v_lshlrev_b64 v[178:179], 11, v[190:191]
	v_lshl_add_u64 v[182:183], v[146:147], 0, v[178:179]
	global_load_dwordx4 v[178:181], v[182:183], off
	s_nop 0
	global_load_dwordx4 v[182:185], v[182:183], off offset:256
	v_lshlrev_b64 v[224:225], 12, v[144:145]
	v_lshl_add_u64 v[224:225], s[4:5], 0, v[224:225]
	v_lshl_add_u64 v[224:225], v[224:225], 0, v[142:143]
	s_waitcnt vmcnt(0)
	v_lshlrev_b32_e32 v192, 16, v154
	v_lshlrev_b32_e32 v198, 16, v160
	v_and_b32_e32 v199, 0xffff0000, v160
	v_lshlrev_b32_e32 v160, 16, v161
	v_and_b32_e32 v161, 0xffff0000, v161
	v_pk_add_f32 v[110:111], v[110:111], v[160:161]
	v_pk_add_f32 v[108:109], v[108:109], v[198:199]
	v_lshlrev_b32_e32 v196, 16, v158
	v_and_b32_e32 v197, 0xffff0000, v158
	v_lshlrev_b32_e32 v158, 16, v159
	v_and_b32_e32 v159, 0xffff0000, v159
	global_store_dwordx4 v[224:225], v[108:111], off offset:528
	v_lshlrev_b32_e32 v206, 16, v168
	v_and_b32_e32 v207, 0xffff0000, v168
	v_lshlrev_b64 v[108:109], 12, v[186:187]
	v_lshlrev_b32_e32 v168, 16, v169
	v_and_b32_e32 v169, 0xffff0000, v169
	v_pk_add_f32 v[118:119], v[118:119], v[158:159]
	v_pk_add_f32 v[116:117], v[116:117], v[196:197]
	v_lshl_add_u64 v[108:109], s[4:5], 0, v[108:109]
	global_store_dwordx4 v[224:225], v[116:119], off offset:512
	v_pk_add_f32 v[94:95], v[94:95], v[168:169]
	v_pk_add_f32 v[92:93], v[92:93], v[206:207]
	v_lshl_add_u64 v[116:117], v[108:109], 0, v[142:143]
	v_lshlrev_b32_e32 v204, 16, v166
	v_and_b32_e32 v205, 0xffff0000, v166
	v_lshlrev_b32_e32 v166, 16, v167
	v_and_b32_e32 v167, 0xffff0000, v167
	global_store_dwordx4 v[116:117], v[92:95], off offset:528
	v_lshlrev_b32_e32 v214, 16, v176
	v_and_b32_e32 v215, 0xffff0000, v176
	v_lshlrev_b64 v[92:93], 12, v[188:189]
	v_lshlrev_b32_e32 v176, 16, v177
	v_and_b32_e32 v177, 0xffff0000, v177
	v_pk_add_f32 v[102:103], v[102:103], v[166:167]
	v_pk_add_f32 v[100:101], v[100:101], v[204:205]
	v_lshl_add_u64 v[92:93], s[4:5], 0, v[92:93]
	global_store_dwordx4 v[116:117], v[100:103], off offset:512
	v_pk_add_f32 v[78:79], v[78:79], v[176:177]
	v_pk_add_f32 v[76:77], v[76:77], v[214:215]
	v_lshl_add_u64 v[100:101], v[92:93], 0, v[142:143]
	v_lshlrev_b32_e32 v212, 16, v174
	v_and_b32_e32 v213, 0xffff0000, v174
	v_lshlrev_b32_e32 v174, 16, v175
	v_and_b32_e32 v175, 0xffff0000, v175
	global_store_dwordx4 v[100:101], v[76:79], off offset:528
	v_and_b32_e32 v193, 0xffff0000, v154
	v_lshlrev_b32_e32 v154, 16, v155
	v_lshlrev_b64 v[76:77], 12, v[190:191]
	v_and_b32_e32 v155, 0xffff0000, v155
	v_lshlrev_b32_e32 v194, 16, v156
	v_and_b32_e32 v195, 0xffff0000, v156
	v_lshlrev_b32_e32 v156, 16, v157
	v_and_b32_e32 v157, 0xffff0000, v157
	v_lshlrev_b32_e32 v200, 16, v162
	v_and_b32_e32 v201, 0xffff0000, v162
	v_lshlrev_b32_e32 v162, 16, v163
	v_and_b32_e32 v163, 0xffff0000, v163
	v_lshlrev_b32_e32 v202, 16, v164
	v_and_b32_e32 v203, 0xffff0000, v164
	v_lshlrev_b32_e32 v164, 16, v165
	v_and_b32_e32 v165, 0xffff0000, v165
	v_lshlrev_b32_e32 v208, 16, v170
	v_and_b32_e32 v209, 0xffff0000, v170
	v_lshlrev_b32_e32 v170, 16, v171
	v_and_b32_e32 v171, 0xffff0000, v171
	v_lshlrev_b32_e32 v210, 16, v172
	v_and_b32_e32 v211, 0xffff0000, v172
	v_lshlrev_b32_e32 v172, 16, v173
	v_and_b32_e32 v173, 0xffff0000, v173
	v_lshlrev_b32_e32 v216, 16, v178
	v_and_b32_e32 v217, 0xffff0000, v178
	v_lshlrev_b32_e32 v178, 16, v179
	v_and_b32_e32 v179, 0xffff0000, v179
	v_lshlrev_b32_e32 v218, 16, v180
	v_and_b32_e32 v219, 0xffff0000, v180
	v_lshlrev_b32_e32 v180, 16, v181
	v_and_b32_e32 v181, 0xffff0000, v181
	v_lshlrev_b32_e32 v220, 16, v182
	v_and_b32_e32 v221, 0xffff0000, v182
	v_lshlrev_b32_e32 v182, 16, v183
	v_and_b32_e32 v183, 0xffff0000, v183
	v_lshlrev_b32_e32 v222, 16, v184
	v_and_b32_e32 v223, 0xffff0000, v184
	v_lshlrev_b32_e32 v184, 16, v185
	v_and_b32_e32 v185, 0xffff0000, v185
	v_pk_add_f32 v[86:87], v[86:87], v[174:175]
	v_pk_add_f32 v[84:85], v[84:85], v[212:213]
	v_lshl_add_u64 v[76:77], s[4:5], 0, v[76:77]
	v_pk_add_f32 v[126:127], v[126:127], v[154:155]
	v_pk_add_f32 v[124:125], v[124:125], v[192:193]
	v_pk_add_f32 v[122:123], v[122:123], v[156:157]
	v_pk_add_f32 v[120:121], v[120:121], v[194:195]
	v_pk_add_f32 v[110:111], v[114:115], v[162:163]
	v_pk_add_f32 v[108:109], v[112:113], v[200:201]
	v_pk_add_f32 v[106:107], v[106:107], v[164:165]
	v_pk_add_f32 v[104:105], v[104:105], v[202:203]
	v_pk_add_f32 v[94:95], v[98:99], v[170:171]
	v_pk_add_f32 v[92:93], v[96:97], v[208:209]
	v_pk_add_f32 v[90:91], v[90:91], v[172:173]
	v_pk_add_f32 v[88:89], v[88:89], v[210:211]
	global_store_dwordx4 v[100:101], v[84:87], off offset:512
	v_pk_add_f32 v[78:79], v[82:83], v[178:179]
	v_pk_add_f32 v[74:75], v[74:75], v[180:181]
	v_lshl_add_u64 v[84:85], v[76:77], 0, v[142:143]
	v_pk_add_f32 v[76:77], v[80:81], v[216:217]
	v_pk_add_f32 v[72:73], v[72:73], v[218:219]
	v_pk_add_f32 v[70:71], v[70:71], v[182:183]
	v_pk_add_f32 v[68:69], v[68:69], v[220:221]
	v_pk_add_f32 v[66:67], v[66:67], v[184:185]
	v_pk_add_f32 v[64:65], v[64:65], v[222:223]
	global_store_dwordx4 v[224:225], v[124:127], off
	global_store_dwordx4 v[224:225], v[120:123], off offset:16
	global_store_dwordx4 v[116:117], v[108:111], off
	global_store_dwordx4 v[116:117], v[104:107], off offset:16
	global_store_dwordx4 v[100:101], v[92:95], off
	global_store_dwordx4 v[100:101], v[88:91], off offset:16
	global_store_dwordx4 v[84:85], v[76:79], off
	global_store_dwordx4 v[84:85], v[72:75], off offset:16
	global_store_dwordx4 v[84:85], v[68:71], off offset:512
	global_store_dwordx4 v[84:85], v[64:67], off offset:528
